# RES1/RES2 residual+norm row passes hand-written: loads of a row issued together, y/x rows of the next two iterations prefetched (3 register buffers)
# speedup vs baseline: 1.0188x; 1.0090x over previous
; DI int TIDX() { int t = threadIdx.x; asm volatile("" : "+v"(t)); return t; }
; DI int BIDX() { int b = blockIdx.x; asm volatile("" : "+s"(b)); return b; }
; DI void rows_resid_norm(const P& p, const float* xlat, const float* xctx, const h16* y, int l, int gate_idx, const float* post_g,
;                         bool do_next, int l2, const float* gain2, int sh_idx, int sc_idx, h16* dst, int nrows) {
;   const int lane = TIDX() & 63;
;   const int gw = BIDX() * 4 + (TIDX() >> 6), nw = gridDim.x * 4;
;   const float* mod = (const float*)(p.ws + OFF_MOD);
;   float* xc = (float*)(p.ws + OFF_XC);
;   for (int row = gw; row < nrows; row += nw) {
;     const float* xr = row < TL ? xlat + (size_t)row * 1024 : xctx + (size_t)(row - TL) * 1024;
;     float* xo = row < TL ? p.out + (size_t)row * 1024 : xc + (size_t)(row - TL) * 1024;
;     const int mrow = row < TL ? (row >> 12) : 8;
;     const float* mr = mod + ((size_t)l * 9 + mrow) * 6144;
;     const float* mr2 = mod + ((size_t)l2 * 9 + mrow) * 6144;
;     f32x4 yv[4], xv[4];
;     float ss = 0.f;
; #pragma unroll
;     for (int i = 0; i < 4; ++i) {
;       h16x4 t = *(const h16x4*)(y + (size_t)row * 1024 + lane * 4 + 256 * i);
;       yv[i].x = (float)t.x; yv[i].y = (float)t.y; yv[i].z = (float)t.z; yv[i].w = (float)t.w;
;       ss += yv[i].x * yv[i].x + yv[i].y * yv[i].y + yv[i].z * yv[i].z + yv[i].w * yv[i].w;
;       xv[i] = *(const f32x4*)(xr + lane * 4 + 256 * i);
;     }
;     ss = wave_sum(ss);
;     const float rstd = rsqrtf(ss * (1.f / 1024.f) + EPS);
;     float s2 = 0.f;
; #pragma unroll
;     for (int i = 0; i < 4; ++i) {
;       const int c = lane * 4 + 256 * i;
;       f32x4 g = *(const f32x4*)(post_g + c), gt = *(const f32x4*)(mr + gate_idx * 1024 + c);
;       xv[i].x += gt.x * (yv[i].x * rstd * g.x);
;       xv[i].y += gt.y * (yv[i].y * rstd * g.y);
;       xv[i].z += gt.z * (yv[i].z * rstd * g.z);
;       xv[i].w += gt.w * (yv[i].w * rstd * g.w);
;       *(f32x4*)(xo + c) = xv[i];
;       s2 += xv[i].x * xv[i].x + xv[i].y * xv[i].y + xv[i].z * xv[i].z + xv[i].w * xv[i].w;
;     }
.LBB0_20:
	v_readlane_b32 s38, v252, 17
	v_readlane_b32 s39, v252, 18
	s_lshl_b32 s63, s78, 12
	s_add_u32 s38, s38, s63
	s_addc_u32 s39, s39, 0
	s_mul_i32 s63, s78, 0x36000
	s_add_u32 s42, s48, 0x2345000
	s_addc_u32 s43, s49, 0
	s_add_u32 s42, s42, s63
	s_addc_u32 s43, s43, 0
	s_add_u32 s44, s48, 0x138ec000
	s_addc_u32 s45, s49, 0
	v_readlane_b32 s46, v252, 0
	v_readlane_b32 s47, v252, 1
	s_add_u32 s50, s48, 0x252c000
	s_addc_u32 s51, s49, 0
	v_readlane_b32 s52, v252, 9
	v_readlane_b32 s53, v252, 10
	s_add_u32 s54, s48, 0x2376000
	s_addc_u32 s55, s49, 0
	s_add_u32 s56, s48, 0x316c000
	s_addc_u32 s57, s49, 0
	v_and_b32_e32 v0, 63, v203
	v_lshlrev_b32_e32 v202, 3, v0
	v_lshlrev_b32_e32 v0, 4, v0
	global_load_dwordx4 v[80:83], v0, s[38:39]
	global_load_dwordx4 v[84:87], v0, s[38:39] offset:1024
	global_load_dwordx4 v[88:91], v0, s[38:39] offset:2048
	global_load_dwordx4 v[92:95], v0, s[38:39] offset:3072
	v_readfirstlane_b32 s58, v34
	s_nop 3
	s_cmp_eq_u32 s78, 0
	s_cbranch_scc1 .Lrr21_start
.Lrr20_start:
	s_lshl_b32 s59, s58, 11
	s_add_u32 s20, s44, s59
	s_addc_u32 s21, s45, 0
	s_sub_u32 s60, s58, 0x8000
	s_cmp_lt_u32 s58, 0x8000
	s_cselect_b32 s60, s58, s60
	s_cselect_b32 s12, s46, s50
	s_cselect_b32 s13, s47, s51
	s_lshl_b32 s60, s60, 12
	s_add_u32 s12, s12, s60
	s_addc_u32 s13, s13, 0
	global_load_dwordx2 v[2:3], v202, s[20:21]
	global_load_dwordx2 v[4:5], v202, s[20:21] offset:512
	global_load_dwordx2 v[6:7], v202, s[20:21] offset:1024
	global_load_dwordx2 v[8:9], v202, s[20:21] offset:1536
	global_load_dwordx4 v[32:35], v0, s[12:13]
	global_load_dwordx4 v[36:39], v0, s[12:13] offset:1024
	global_load_dwordx4 v[40:43], v0, s[12:13] offset:2048
	global_load_dwordx4 v[44:47], v0, s[12:13] offset:3072
	s_add_i32 s61, s58, s8
	s_cmp_lt_i32 s61, s36
	s_cbranch_scc0 .Lrr20_pre0
	s_lshl_b32 s59, s61, 11
	s_add_u32 s20, s44, s59
	s_addc_u32 s21, s45, 0
	s_sub_u32 s60, s61, 0x8000
	s_cmp_lt_u32 s61, 0x8000
	s_cselect_b32 s60, s61, s60
	s_cselect_b32 s12, s46, s50
	s_cselect_b32 s13, s47, s51
	s_lshl_b32 s60, s60, 12
	s_add_u32 s12, s12, s60
	s_addc_u32 s13, s13, 0
	global_load_dwordx2 v[10:11], v202, s[20:21]
	global_load_dwordx2 v[12:13], v202, s[20:21] offset:512
	global_load_dwordx2 v[14:15], v202, s[20:21] offset:1024
	global_load_dwordx2 v[16:17], v202, s[20:21] offset:1536
	global_load_dwordx4 v[48:51], v0, s[12:13]
	global_load_dwordx4 v[52:55], v0, s[12:13] offset:1024
	global_load_dwordx4 v[56:59], v0, s[12:13] offset:2048
	global_load_dwordx4 v[60:63], v0, s[12:13] offset:3072
.Lrr20_pre0:
	s_lshr_b32 s59, s58, 12
	s_cmp_lt_u32 s58, 0x8000
	s_cselect_b32 s59, s59, 8
	s_mul_i32 s59, s59, 0x6000
	s_add_u32 s24, s42, s59
	s_addc_u32 s25, s43, 0
	s_sub_u32 s60, s58, 0x8000
	s_cmp_lt_u32 s58, 0x8000
	s_cselect_b32 s60, s58, s60
	s_cselect_b32 s22, s46, s50
	s_cselect_b32 s23, s47, s51
	s_lshl_b32 s60, s60, 12
	s_add_u32 s22, s22, s60
	s_addc_u32 s23, s23, 0
	global_load_dwordx4 v[112:115], v0, s[24:25]
	global_load_dwordx4 v[116:119], v0, s[24:25] offset:1024
	global_load_dwordx4 v[120:123], v0, s[24:25] offset:2048
	global_load_dwordx4 v[124:127], v0, s[24:25] offset:3072
	s_add_i32 s62, s58, s8
	s_add_i32 s62, s62, s8
	s_cmp_lt_i32 s62, s36
	s_cbranch_scc0 .Lrr20_tail0
	s_lshl_b32 s59, s62, 11
	s_add_u32 s20, s44, s59
	s_addc_u32 s21, s45, 0
	s_sub_u32 s60, s62, 0x8000
	s_cmp_lt_u32 s62, 0x8000
	s_cselect_b32 s60, s62, s60
	s_cselect_b32 s12, s46, s50
	s_cselect_b32 s13, s47, s51
	s_lshl_b32 s60, s60, 12
	s_add_u32 s12, s12, s60
	s_addc_u32 s13, s13, 0
	global_load_dwordx2 v[18:19], v202, s[20:21]
	global_load_dwordx2 v[20:21], v202, s[20:21] offset:512
	global_load_dwordx2 v[22:23], v202, s[20:21] offset:1024
	global_load_dwordx2 v[24:25], v202, s[20:21] offset:1536
	global_load_dwordx4 v[64:67], v0, s[12:13]
	global_load_dwordx4 v[68:71], v0, s[12:13] offset:1024
	global_load_dwordx4 v[72:75], v0, s[12:13] offset:2048
	global_load_dwordx4 v[76:79], v0, s[12:13] offset:3072
	s_waitcnt vmcnt(20)
	v_cvt_f32_f16_e32 v226, v2
	v_cvt_f32_f16_sdwa v227, v2 dst_sel:DWORD dst_unused:UNUSED_PAD src0_sel:WORD_1
	v_cvt_f32_f16_e32 v228, v3
	v_cvt_f32_f16_sdwa v229, v3 dst_sel:DWORD dst_unused:UNUSED_PAD src0_sel:WORD_1
	v_cvt_f32_f16_e32 v230, v4
	v_cvt_f32_f16_sdwa v231, v4 dst_sel:DWORD dst_unused:UNUSED_PAD src0_sel:WORD_1
	v_cvt_f32_f16_e32 v232, v5
	v_cvt_f32_f16_sdwa v233, v5 dst_sel:DWORD dst_unused:UNUSED_PAD src0_sel:WORD_1
	v_cvt_f32_f16_e32 v234, v6
	v_cvt_f32_f16_sdwa v235, v6 dst_sel:DWORD dst_unused:UNUSED_PAD src0_sel:WORD_1
	v_cvt_f32_f16_e32 v236, v7
	v_cvt_f32_f16_sdwa v237, v7 dst_sel:DWORD dst_unused:UNUSED_PAD src0_sel:WORD_1
	v_cvt_f32_f16_e32 v238, v8
	v_cvt_f32_f16_sdwa v239, v8 dst_sel:DWORD dst_unused:UNUSED_PAD src0_sel:WORD_1
	v_cvt_f32_f16_e32 v240, v9
	v_cvt_f32_f16_sdwa v241, v9 dst_sel:DWORD dst_unused:UNUSED_PAD src0_sel:WORD_1
	v_mul_f32_e32 v242, v227, v227
	v_mul_f32_e32 v243, v231, v231
	v_mul_f32_e32 v244, v235, v235
	v_mul_f32_e32 v245, v239, v239
	v_fmac_f32_e32 v242, v226, v226
	v_fmac_f32_e32 v243, v230, v230
	v_fmac_f32_e32 v244, v234, v234
	v_fmac_f32_e32 v245, v238, v238
	v_fmac_f32_e32 v242, v228, v228
	v_fmac_f32_e32 v243, v232, v232
	v_fmac_f32_e32 v244, v236, v236
	v_fmac_f32_e32 v245, v240, v240
	v_fmac_f32_e32 v242, v229, v229
	v_fmac_f32_e32 v243, v233, v233
	v_fmac_f32_e32 v244, v237, v237
	v_fmac_f32_e32 v245, v241, v241
	v_add_f32_e32 v242, v242, v243
	v_add_f32_e32 v242, v242, v244
	v_add_f32_e32 v242, v242, v245
	s_nop 1
	v_add_f32_dpp v242, v242, v242 quad_perm:[1,0,3,2] row_mask:0xf bank_mask:0xf bound_ctrl:1
	s_nop 1
	v_add_f32_dpp v242, v242, v242 quad_perm:[2,3,0,1] row_mask:0xf bank_mask:0xf bound_ctrl:1
	s_nop 1
	v_add_f32_dpp v242, v242, v242 row_half_mirror row_mask:0xf bank_mask:0xf bound_ctrl:1
	s_nop 1
	v_add_f32_dpp v242, v242, v242 row_mirror row_mask:0xf bank_mask:0xf bound_ctrl:1
	s_nop 1
	ds_swizzle_b32 v243, v242 offset:swizzle(SWAP,16)
	s_waitcnt lgkmcnt(0)
; DI int TIDX() { int t = threadIdx.x; asm volatile("" : "+v"(t)); return t; }
; DI int BIDX() { int b = blockIdx.x; asm volatile("" : "+s"(b)); return b; }
; DI void rows_resid_norm(const P& p, const float* xlat, const float* xctx, const h16* y, int l, int gate_idx, const float* post_g,
;                         bool do_next, int l2, const float* gain2, int sh_idx, int sc_idx, h16* dst, int nrows) {
;   const int lane = TIDX() & 63;
;   const int gw = BIDX() * 4 + (TIDX() >> 6), nw = gridDim.x * 4;
;   const float* mod = (const float*)(p.ws + OFF_MOD);
;   float* xc = (float*)(p.ws + OFF_XC);
;   for (int row = gw; row < nrows; row += nw) {
;     const float* xr = row < TL ? xlat + (size_t)row * 1024 : xctx + (size_t)(row - TL) * 1024;
;     float* xo = row < TL ? p.out + (size_t)row * 1024 : xc + (size_t)(row - TL) * 1024;
;     const int mrow = row < TL ? (row >> 12) : 8;
;     const float* mr = mod + ((size_t)l * 9 + mrow) * 6144;
;     const float* mr2 = mod + ((size_t)l2 * 9 + mrow) * 6144;
;     f32x4 yv[4], xv[4];
;     float ss = 0.f;
; #pragma unroll
;     for (int i = 0; i < 4; ++i) {
;       h16x4 t = *(const h16x4*)(y + (size_t)row * 1024 + lane * 4 + 256 * i);
;       yv[i].x = (float)t.x; yv[i].y = (float)t.y; yv[i].z = (float)t.z; yv[i].w = (float)t.w;
;       ss += yv[i].x * yv[i].x + yv[i].y * yv[i].y + yv[i].z * yv[i].z + yv[i].w * yv[i].w;
;       xv[i] = *(const f32x4*)(xr + lane * 4 + 256 * i);
;     }
;     ss = wave_sum(ss);
;     const float rstd = rsqrtf(ss * (1.f / 1024.f) + EPS);
;     float s2 = 0.f;
; #pragma unroll
;     for (int i = 0; i < 4; ++i) {
;       const int c = lane * 4 + 256 * i;
;       f32x4 g = *(const f32x4*)(post_g + c), gt = *(const f32x4*)(mr + gate_idx * 1024 + c);
;       xv[i].x += gt.x * (yv[i].x * rstd * g.x);
;       xv[i].y += gt.y * (yv[i].y * rstd * g.y);
;       xv[i].z += gt.z * (yv[i].z * rstd * g.z);
;       xv[i].w += gt.w * (yv[i].w * rstd * g.w);
;       *(f32x4*)(xo + c) = xv[i];
;       s2 += xv[i].x * xv[i].x + xv[i].y * xv[i].y + xv[i].z * xv[i].z + xv[i].w * xv[i].w;
;     }
	v_add_f32_e32 v242, v242, v243
	v_mov_b32_e32 v243, v242
	s_nop 1
	v_permlane32_swap_b32_e32 v242, v243
	v_add_f32_e32 v242, v242, v243
	v_fmamk_f32 v242, v242, 0x3a800000, v224
	v_rsq_f32_e32 v242, v242
	s_waitcnt vmcnt(8)
	v_mul_f32_e32 v226, v226, v242
	v_mul_f32_e32 v227, v227, v242
	v_mul_f32_e32 v228, v228, v242
	v_mul_f32_e32 v229, v229, v242
	v_mul_f32_e32 v230, v230, v242
	v_mul_f32_e32 v231, v231, v242
	v_mul_f32_e32 v232, v232, v242
	v_mul_f32_e32 v233, v233, v242
	v_mul_f32_e32 v234, v234, v242
	v_mul_f32_e32 v235, v235, v242
	v_mul_f32_e32 v236, v236, v242
	v_mul_f32_e32 v237, v237, v242
	v_mul_f32_e32 v238, v238, v242
	v_mul_f32_e32 v239, v239, v242
	v_mul_f32_e32 v240, v240, v242
	v_mul_f32_e32 v241, v241, v242
	v_mul_f32_e32 v226, v80, v226
	v_mul_f32_e32 v227, v81, v227
	v_mul_f32_e32 v228, v82, v228
	v_mul_f32_e32 v229, v83, v229
	v_mul_f32_e32 v230, v84, v230
	v_mul_f32_e32 v231, v85, v231
	v_mul_f32_e32 v232, v86, v232
	v_mul_f32_e32 v233, v87, v233
	v_mul_f32_e32 v234, v88, v234
	v_mul_f32_e32 v235, v89, v235
	v_mul_f32_e32 v236, v90, v236
	v_mul_f32_e32 v237, v91, v237
	v_mul_f32_e32 v238, v92, v238
	v_mul_f32_e32 v239, v93, v239
	v_mul_f32_e32 v240, v94, v240
	v_mul_f32_e32 v241, v95, v241
	v_fmac_f32_e32 v32, v112, v226
	v_fmac_f32_e32 v33, v113, v227
	v_fmac_f32_e32 v34, v114, v228
	v_fmac_f32_e32 v35, v115, v229
	v_fmac_f32_e32 v36, v116, v230
	v_fmac_f32_e32 v37, v117, v231
	v_fmac_f32_e32 v38, v118, v232
	v_fmac_f32_e32 v39, v119, v233
	v_fmac_f32_e32 v40, v120, v234
	v_fmac_f32_e32 v41, v121, v235
	v_fmac_f32_e32 v42, v122, v236
	v_fmac_f32_e32 v43, v123, v237
	v_fmac_f32_e32 v44, v124, v238
	v_fmac_f32_e32 v45, v125, v239
	v_fmac_f32_e32 v46, v126, v240
	v_fmac_f32_e32 v47, v127, v241
	global_store_dwordx4 v0, v[32:35], s[22:23]
	global_store_dwordx4 v0, v[36:39], s[22:23] offset:1024
	global_store_dwordx4 v0, v[40:43], s[22:23] offset:2048
	global_store_dwordx4 v0, v[44:47], s[22:23] offset:3072
	s_add_i32 s58, s58, s8
.Lrr20_pre1:
	s_lshr_b32 s59, s58, 12
	s_cmp_lt_u32 s58, 0x8000
	s_cselect_b32 s59, s59, 8
	s_mul_i32 s59, s59, 0x6000
	s_add_u32 s24, s42, s59
	s_addc_u32 s25, s43, 0
	s_sub_u32 s60, s58, 0x8000
	s_cmp_lt_u32 s58, 0x8000
	s_cselect_b32 s60, s58, s60
	s_cselect_b32 s22, s46, s50
	s_cselect_b32 s23, s47, s51
	s_lshl_b32 s60, s60, 12
	s_add_u32 s22, s22, s60
	s_addc_u32 s23, s23, 0
	global_load_dwordx4 v[112:115], v0, s[24:25]
	global_load_dwordx4 v[116:119], v0, s[24:25] offset:1024
	global_load_dwordx4 v[120:123], v0, s[24:25] offset:2048
	global_load_dwordx4 v[124:127], v0, s[24:25] offset:3072
	s_add_i32 s62, s58, s8
	s_add_i32 s62, s62, s8
	s_cmp_lt_i32 s62, s36
	s_cbranch_scc0 .Lrr20_tail1
	s_lshl_b32 s59, s62, 11
	s_add_u32 s20, s44, s59
	s_addc_u32 s21, s45, 0
	s_sub_u32 s60, s62, 0x8000
	s_cmp_lt_u32 s62, 0x8000
	s_cselect_b32 s60, s62, s60
	s_cselect_b32 s12, s46, s50
	s_cselect_b32 s13, s47, s51
	s_lshl_b32 s60, s60, 12
	s_add_u32 s12, s12, s60
	s_addc_u32 s13, s13, 0
	global_load_dwordx2 v[2:3], v202, s[20:21]
	global_load_dwordx2 v[4:5], v202, s[20:21] offset:512
	global_load_dwordx2 v[6:7], v202, s[20:21] offset:1024
	global_load_dwordx2 v[8:9], v202, s[20:21] offset:1536
	global_load_dwordx4 v[32:35], v0, s[12:13]
	global_load_dwordx4 v[36:39], v0, s[12:13] offset:1024
	global_load_dwordx4 v[40:43], v0, s[12:13] offset:2048
	global_load_dwordx4 v[44:47], v0, s[12:13] offset:3072
	s_waitcnt vmcnt(20)
	v_cvt_f32_f16_e32 v226, v10
	v_cvt_f32_f16_sdwa v227, v10 dst_sel:DWORD dst_unused:UNUSED_PAD src0_sel:WORD_1
	v_cvt_f32_f16_e32 v228, v11
	v_cvt_f32_f16_sdwa v229, v11 dst_sel:DWORD dst_unused:UNUSED_PAD src0_sel:WORD_1
	v_cvt_f32_f16_e32 v230, v12
	v_cvt_f32_f16_sdwa v231, v12 dst_sel:DWORD dst_unused:UNUSED_PAD src0_sel:WORD_1
	v_cvt_f32_f16_e32 v232, v13
	v_cvt_f32_f16_sdwa v233, v13 dst_sel:DWORD dst_unused:UNUSED_PAD src0_sel:WORD_1
	v_cvt_f32_f16_e32 v234, v14
	v_cvt_f32_f16_sdwa v235, v14 dst_sel:DWORD dst_unused:UNUSED_PAD src0_sel:WORD_1
	v_cvt_f32_f16_e32 v236, v15
	v_cvt_f32_f16_sdwa v237, v15 dst_sel:DWORD dst_unused:UNUSED_PAD src0_sel:WORD_1
	v_cvt_f32_f16_e32 v238, v16
	v_cvt_f32_f16_sdwa v239, v16 dst_sel:DWORD dst_unused:UNUSED_PAD src0_sel:WORD_1
	v_cvt_f32_f16_e32 v240, v17
	v_cvt_f32_f16_sdwa v241, v17 dst_sel:DWORD dst_unused:UNUSED_PAD src0_sel:WORD_1
	v_mul_f32_e32 v242, v227, v227
	v_mul_f32_e32 v243, v231, v231
	v_mul_f32_e32 v244, v235, v235
	v_mul_f32_e32 v245, v239, v239
	v_fmac_f32_e32 v242, v226, v226
	v_fmac_f32_e32 v243, v230, v230
	v_fmac_f32_e32 v244, v234, v234
	v_fmac_f32_e32 v245, v238, v238
	v_fmac_f32_e32 v242, v228, v228
	v_fmac_f32_e32 v243, v232, v232
	v_fmac_f32_e32 v244, v236, v236
	v_fmac_f32_e32 v245, v240, v240
	v_fmac_f32_e32 v242, v229, v229
	v_fmac_f32_e32 v243, v233, v233
	v_fmac_f32_e32 v244, v237, v237
	v_fmac_f32_e32 v245, v241, v241
	v_add_f32_e32 v242, v242, v243
	v_add_f32_e32 v242, v242, v244
	v_add_f32_e32 v242, v242, v245
	s_nop 1
	v_add_f32_dpp v242, v242, v242 quad_perm:[1,0,3,2] row_mask:0xf bank_mask:0xf bound_ctrl:1
	s_nop 1
	v_add_f32_dpp v242, v242, v242 quad_perm:[2,3,0,1] row_mask:0xf bank_mask:0xf bound_ctrl:1
	s_nop 1
	v_add_f32_dpp v242, v242, v242 row_half_mirror row_mask:0xf bank_mask:0xf bound_ctrl:1
	s_nop 1
	v_add_f32_dpp v242, v242, v242 row_mirror row_mask:0xf bank_mask:0xf bound_ctrl:1
	s_nop 1
	ds_swizzle_b32 v243, v242 offset:swizzle(SWAP,16)
	s_waitcnt lgkmcnt(0)
	v_add_f32_e32 v242, v242, v243
	v_mov_b32_e32 v243, v242
	s_nop 1
	v_permlane32_swap_b32_e32 v242, v243
	v_add_f32_e32 v242, v242, v243
	v_fmamk_f32 v242, v242, 0x3a800000, v224
	v_rsq_f32_e32 v242, v242
	s_waitcnt vmcnt(8)
; DI int TIDX() { int t = threadIdx.x; asm volatile("" : "+v"(t)); return t; }
; DI int BIDX() { int b = blockIdx.x; asm volatile("" : "+s"(b)); return b; }
; DI void rows_resid_norm(const P& p, const float* xlat, const float* xctx, const h16* y, int l, int gate_idx, const float* post_g,
;                         bool do_next, int l2, const float* gain2, int sh_idx, int sc_idx, h16* dst, int nrows) {
;   const int lane = TIDX() & 63;
;   const int gw = BIDX() * 4 + (TIDX() >> 6), nw = gridDim.x * 4;
;   const float* mod = (const float*)(p.ws + OFF_MOD);
;   float* xc = (float*)(p.ws + OFF_XC);
;   for (int row = gw; row < nrows; row += nw) {
;     const float* xr = row < TL ? xlat + (size_t)row * 1024 : xctx + (size_t)(row - TL) * 1024;
;     float* xo = row < TL ? p.out + (size_t)row * 1024 : xc + (size_t)(row - TL) * 1024;
;     const int mrow = row < TL ? (row >> 12) : 8;
;     const float* mr = mod + ((size_t)l * 9 + mrow) * 6144;
;     const float* mr2 = mod + ((size_t)l2 * 9 + mrow) * 6144;
;     f32x4 yv[4], xv[4];
;     float ss = 0.f;
; #pragma unroll
;     for (int i = 0; i < 4; ++i) {
;       h16x4 t = *(const h16x4*)(y + (size_t)row * 1024 + lane * 4 + 256 * i);
;       yv[i].x = (float)t.x; yv[i].y = (float)t.y; yv[i].z = (float)t.z; yv[i].w = (float)t.w;
;       ss += yv[i].x * yv[i].x + yv[i].y * yv[i].y + yv[i].z * yv[i].z + yv[i].w * yv[i].w;
;       xv[i] = *(const f32x4*)(xr + lane * 4 + 256 * i);
;     }
;     ss = wave_sum(ss);
;     const float rstd = rsqrtf(ss * (1.f / 1024.f) + EPS);
;     float s2 = 0.f;
; #pragma unroll
;     for (int i = 0; i < 4; ++i) {
;       const int c = lane * 4 + 256 * i;
;       f32x4 g = *(const f32x4*)(post_g + c), gt = *(const f32x4*)(mr + gate_idx * 1024 + c);
;       xv[i].x += gt.x * (yv[i].x * rstd * g.x);
;       xv[i].y += gt.y * (yv[i].y * rstd * g.y);
;       xv[i].z += gt.z * (yv[i].z * rstd * g.z);
;       xv[i].w += gt.w * (yv[i].w * rstd * g.w);
;       *(f32x4*)(xo + c) = xv[i];
;       s2 += xv[i].x * xv[i].x + xv[i].y * xv[i].y + xv[i].z * xv[i].z + xv[i].w * xv[i].w;
;     }
	v_mul_f32_e32 v226, v226, v242
	v_mul_f32_e32 v227, v227, v242
	v_mul_f32_e32 v228, v228, v242
	v_mul_f32_e32 v229, v229, v242
	v_mul_f32_e32 v230, v230, v242
	v_mul_f32_e32 v231, v231, v242
	v_mul_f32_e32 v232, v232, v242
	v_mul_f32_e32 v233, v233, v242
	v_mul_f32_e32 v234, v234, v242
	v_mul_f32_e32 v235, v235, v242
	v_mul_f32_e32 v236, v236, v242
	v_mul_f32_e32 v237, v237, v242
	v_mul_f32_e32 v238, v238, v242
	v_mul_f32_e32 v239, v239, v242
	v_mul_f32_e32 v240, v240, v242
	v_mul_f32_e32 v241, v241, v242
	v_mul_f32_e32 v226, v80, v226
	v_mul_f32_e32 v227, v81, v227
	v_mul_f32_e32 v228, v82, v228
	v_mul_f32_e32 v229, v83, v229
	v_mul_f32_e32 v230, v84, v230
	v_mul_f32_e32 v231, v85, v231
	v_mul_f32_e32 v232, v86, v232
	v_mul_f32_e32 v233, v87, v233
	v_mul_f32_e32 v234, v88, v234
	v_mul_f32_e32 v235, v89, v235
	v_mul_f32_e32 v236, v90, v236
	v_mul_f32_e32 v237, v91, v237
	v_mul_f32_e32 v238, v92, v238
	v_mul_f32_e32 v239, v93, v239
	v_mul_f32_e32 v240, v94, v240
	v_mul_f32_e32 v241, v95, v241
	v_fmac_f32_e32 v48, v112, v226
	v_fmac_f32_e32 v49, v113, v227
	v_fmac_f32_e32 v50, v114, v228
	v_fmac_f32_e32 v51, v115, v229
	v_fmac_f32_e32 v52, v116, v230
	v_fmac_f32_e32 v53, v117, v231
	v_fmac_f32_e32 v54, v118, v232
	v_fmac_f32_e32 v55, v119, v233
	v_fmac_f32_e32 v56, v120, v234
	v_fmac_f32_e32 v57, v121, v235
	v_fmac_f32_e32 v58, v122, v236
	v_fmac_f32_e32 v59, v123, v237
	v_fmac_f32_e32 v60, v124, v238
	v_fmac_f32_e32 v61, v125, v239
	v_fmac_f32_e32 v62, v126, v240
	v_fmac_f32_e32 v63, v127, v241
	global_store_dwordx4 v0, v[48:51], s[22:23]
	global_store_dwordx4 v0, v[52:55], s[22:23] offset:1024
	global_store_dwordx4 v0, v[56:59], s[22:23] offset:2048
	global_store_dwordx4 v0, v[60:63], s[22:23] offset:3072
	s_add_i32 s58, s58, s8
.Lrr20_l2:
	s_lshr_b32 s59, s58, 12
	s_cmp_lt_u32 s58, 0x8000
	s_cselect_b32 s59, s59, 8
	s_mul_i32 s59, s59, 0x6000
	s_add_u32 s24, s42, s59
	s_addc_u32 s25, s43, 0
	s_sub_u32 s60, s58, 0x8000
	s_cmp_lt_u32 s58, 0x8000
	s_cselect_b32 s60, s58, s60
	s_cselect_b32 s22, s46, s50
	s_cselect_b32 s23, s47, s51
	s_lshl_b32 s60, s60, 12
	s_add_u32 s22, s22, s60
	s_addc_u32 s23, s23, 0
	global_load_dwordx4 v[112:115], v0, s[24:25]
	global_load_dwordx4 v[116:119], v0, s[24:25] offset:1024
	global_load_dwordx4 v[120:123], v0, s[24:25] offset:2048
	global_load_dwordx4 v[124:127], v0, s[24:25] offset:3072
	s_add_i32 s62, s58, s8
	s_add_i32 s62, s62, s8
	s_cmp_lt_i32 s62, s36
	s_cbranch_scc0 .Lrr20_tail2
	s_lshl_b32 s59, s62, 11
	s_add_u32 s20, s44, s59
	s_addc_u32 s21, s45, 0
	s_sub_u32 s60, s62, 0x8000
	s_cmp_lt_u32 s62, 0x8000
	s_cselect_b32 s60, s62, s60
	s_cselect_b32 s12, s46, s50
	s_cselect_b32 s13, s47, s51
	s_lshl_b32 s60, s60, 12
	s_add_u32 s12, s12, s60
	s_addc_u32 s13, s13, 0
	global_load_dwordx2 v[10:11], v202, s[20:21]
	global_load_dwordx2 v[12:13], v202, s[20:21] offset:512
	global_load_dwordx2 v[14:15], v202, s[20:21] offset:1024
	global_load_dwordx2 v[16:17], v202, s[20:21] offset:1536
	global_load_dwordx4 v[48:51], v0, s[12:13]
	global_load_dwordx4 v[52:55], v0, s[12:13] offset:1024
	global_load_dwordx4 v[56:59], v0, s[12:13] offset:2048
	global_load_dwordx4 v[60:63], v0, s[12:13] offset:3072
	s_waitcnt vmcnt(32)
	v_cvt_f32_f16_e32 v226, v18
	v_cvt_f32_f16_sdwa v227, v18 dst_sel:DWORD dst_unused:UNUSED_PAD src0_sel:WORD_1
	v_cvt_f32_f16_e32 v228, v19
	v_cvt_f32_f16_sdwa v229, v19 dst_sel:DWORD dst_unused:UNUSED_PAD src0_sel:WORD_1
	v_cvt_f32_f16_e32 v230, v20
	v_cvt_f32_f16_sdwa v231, v20 dst_sel:DWORD dst_unused:UNUSED_PAD src0_sel:WORD_1
	v_cvt_f32_f16_e32 v232, v21
	v_cvt_f32_f16_sdwa v233, v21 dst_sel:DWORD dst_unused:UNUSED_PAD src0_sel:WORD_1
	v_cvt_f32_f16_e32 v234, v22
	v_cvt_f32_f16_sdwa v235, v22 dst_sel:DWORD dst_unused:UNUSED_PAD src0_sel:WORD_1
	v_cvt_f32_f16_e32 v236, v23
	v_cvt_f32_f16_sdwa v237, v23 dst_sel:DWORD dst_unused:UNUSED_PAD src0_sel:WORD_1
	v_cvt_f32_f16_e32 v238, v24
	v_cvt_f32_f16_sdwa v239, v24 dst_sel:DWORD dst_unused:UNUSED_PAD src0_sel:WORD_1
	v_cvt_f32_f16_e32 v240, v25
	v_cvt_f32_f16_sdwa v241, v25 dst_sel:DWORD dst_unused:UNUSED_PAD src0_sel:WORD_1
	v_mul_f32_e32 v242, v227, v227
	v_mul_f32_e32 v243, v231, v231
	v_mul_f32_e32 v244, v235, v235
	v_mul_f32_e32 v245, v239, v239
	v_fmac_f32_e32 v242, v226, v226
	v_fmac_f32_e32 v243, v230, v230
	v_fmac_f32_e32 v244, v234, v234
	v_fmac_f32_e32 v245, v238, v238
	v_fmac_f32_e32 v242, v228, v228
	v_fmac_f32_e32 v243, v232, v232
	v_fmac_f32_e32 v244, v236, v236
	v_fmac_f32_e32 v245, v240, v240
	v_fmac_f32_e32 v242, v229, v229
	v_fmac_f32_e32 v243, v233, v233
	v_fmac_f32_e32 v244, v237, v237
	v_fmac_f32_e32 v245, v241, v241
	v_add_f32_e32 v242, v242, v243
	v_add_f32_e32 v242, v242, v244
	v_add_f32_e32 v242, v242, v245
	s_nop 1
	v_add_f32_dpp v242, v242, v242 quad_perm:[1,0,3,2] row_mask:0xf bank_mask:0xf bound_ctrl:1
	s_nop 1
	v_add_f32_dpp v242, v242, v242 quad_perm:[2,3,0,1] row_mask:0xf bank_mask:0xf bound_ctrl:1
	s_nop 1
	v_add_f32_dpp v242, v242, v242 row_half_mirror row_mask:0xf bank_mask:0xf bound_ctrl:1
	s_nop 1
	v_add_f32_dpp v242, v242, v242 row_mirror row_mask:0xf bank_mask:0xf bound_ctrl:1
	s_nop 1
	ds_swizzle_b32 v243, v242 offset:swizzle(SWAP,16)
	s_waitcnt lgkmcnt(0)
	v_add_f32_e32 v242, v242, v243
	v_mov_b32_e32 v243, v242
	s_nop 1
	v_permlane32_swap_b32_e32 v242, v243
	v_add_f32_e32 v242, v242, v243
	v_fmamk_f32 v242, v242, 0x3a800000, v224
	v_rsq_f32_e32 v242, v242
	s_waitcnt vmcnt(8)
; DI int TIDX() { int t = threadIdx.x; asm volatile("" : "+v"(t)); return t; }
; DI int BIDX() { int b = blockIdx.x; asm volatile("" : "+s"(b)); return b; }
; DI void rows_resid_norm(const P& p, const float* xlat, const float* xctx, const h16* y, int l, int gate_idx, const float* post_g,
;                         bool do_next, int l2, const float* gain2, int sh_idx, int sc_idx, h16* dst, int nrows) {
;   const int lane = TIDX() & 63;
;   const int gw = BIDX() * 4 + (TIDX() >> 6), nw = gridDim.x * 4;
;   const float* mod = (const float*)(p.ws + OFF_MOD);
;   float* xc = (float*)(p.ws + OFF_XC);
;   for (int row = gw; row < nrows; row += nw) {
;     const float* xr = row < TL ? xlat + (size_t)row * 1024 : xctx + (size_t)(row - TL) * 1024;
;     float* xo = row < TL ? p.out + (size_t)row * 1024 : xc + (size_t)(row - TL) * 1024;
;     const int mrow = row < TL ? (row >> 12) : 8;
;     const float* mr = mod + ((size_t)l * 9 + mrow) * 6144;
;     const float* mr2 = mod + ((size_t)l2 * 9 + mrow) * 6144;
;     f32x4 yv[4], xv[4];
;     float ss = 0.f;
; #pragma unroll
;     for (int i = 0; i < 4; ++i) {
;       h16x4 t = *(const h16x4*)(y + (size_t)row * 1024 + lane * 4 + 256 * i);
;       yv[i].x = (float)t.x; yv[i].y = (float)t.y; yv[i].z = (float)t.z; yv[i].w = (float)t.w;
;       ss += yv[i].x * yv[i].x + yv[i].y * yv[i].y + yv[i].z * yv[i].z + yv[i].w * yv[i].w;
;       xv[i] = *(const f32x4*)(xr + lane * 4 + 256 * i);
;     }
;     ss = wave_sum(ss);
;     const float rstd = rsqrtf(ss * (1.f / 1024.f) + EPS);
;     float s2 = 0.f;
; #pragma unroll
;     for (int i = 0; i < 4; ++i) {
;       const int c = lane * 4 + 256 * i;
;       f32x4 g = *(const f32x4*)(post_g + c), gt = *(const f32x4*)(mr + gate_idx * 1024 + c);
;       xv[i].x += gt.x * (yv[i].x * rstd * g.x);
;       xv[i].y += gt.y * (yv[i].y * rstd * g.y);
;       xv[i].z += gt.z * (yv[i].z * rstd * g.z);
;       xv[i].w += gt.w * (yv[i].w * rstd * g.w);
;       *(f32x4*)(xo + c) = xv[i];
;       s2 += xv[i].x * xv[i].x + xv[i].y * xv[i].y + xv[i].z * xv[i].z + xv[i].w * xv[i].w;
;     }
	v_mul_f32_e32 v226, v226, v242
	v_mul_f32_e32 v227, v227, v242
	v_mul_f32_e32 v228, v228, v242
	v_mul_f32_e32 v229, v229, v242
	v_mul_f32_e32 v230, v230, v242
	v_mul_f32_e32 v231, v231, v242
	v_mul_f32_e32 v232, v232, v242
	v_mul_f32_e32 v233, v233, v242
	v_mul_f32_e32 v234, v234, v242
	v_mul_f32_e32 v235, v235, v242
	v_mul_f32_e32 v236, v236, v242
	v_mul_f32_e32 v237, v237, v242
	v_mul_f32_e32 v238, v238, v242
	v_mul_f32_e32 v239, v239, v242
	v_mul_f32_e32 v240, v240, v242
	v_mul_f32_e32 v241, v241, v242
	v_mul_f32_e32 v226, v80, v226
	v_mul_f32_e32 v227, v81, v227
	v_mul_f32_e32 v228, v82, v228
	v_mul_f32_e32 v229, v83, v229
	v_mul_f32_e32 v230, v84, v230
	v_mul_f32_e32 v231, v85, v231
	v_mul_f32_e32 v232, v86, v232
	v_mul_f32_e32 v233, v87, v233
	v_mul_f32_e32 v234, v88, v234
	v_mul_f32_e32 v235, v89, v235
	v_mul_f32_e32 v236, v90, v236
	v_mul_f32_e32 v237, v91, v237
	v_mul_f32_e32 v238, v92, v238
	v_mul_f32_e32 v239, v93, v239
	v_mul_f32_e32 v240, v94, v240
	v_mul_f32_e32 v241, v95, v241
	v_fmac_f32_e32 v64, v112, v226
	v_fmac_f32_e32 v65, v113, v227
	v_fmac_f32_e32 v66, v114, v228
	v_fmac_f32_e32 v67, v115, v229
	v_fmac_f32_e32 v68, v116, v230
	v_fmac_f32_e32 v69, v117, v231
	v_fmac_f32_e32 v70, v118, v232
	v_fmac_f32_e32 v71, v119, v233
	v_fmac_f32_e32 v72, v120, v234
	v_fmac_f32_e32 v73, v121, v235
	v_fmac_f32_e32 v74, v122, v236
	v_fmac_f32_e32 v75, v123, v237
	v_fmac_f32_e32 v76, v124, v238
	v_fmac_f32_e32 v77, v125, v239
	v_fmac_f32_e32 v78, v126, v240
	v_fmac_f32_e32 v79, v127, v241
	global_store_dwordx4 v0, v[64:67], s[22:23]
	global_store_dwordx4 v0, v[68:71], s[22:23] offset:1024
	global_store_dwordx4 v0, v[72:75], s[22:23] offset:2048
	global_store_dwordx4 v0, v[76:79], s[22:23] offset:3072
	s_add_i32 s58, s58, s8
.Lrr20_l0:
	s_lshr_b32 s59, s58, 12
	s_cmp_lt_u32 s58, 0x8000
	s_cselect_b32 s59, s59, 8
	s_mul_i32 s59, s59, 0x6000
	s_add_u32 s24, s42, s59
	s_addc_u32 s25, s43, 0
	s_sub_u32 s60, s58, 0x8000
	s_cmp_lt_u32 s58, 0x8000
	s_cselect_b32 s60, s58, s60
	s_cselect_b32 s22, s46, s50
	s_cselect_b32 s23, s47, s51
	s_lshl_b32 s60, s60, 12
	s_add_u32 s22, s22, s60
	s_addc_u32 s23, s23, 0
	global_load_dwordx4 v[112:115], v0, s[24:25]
	global_load_dwordx4 v[116:119], v0, s[24:25] offset:1024
	global_load_dwordx4 v[120:123], v0, s[24:25] offset:2048
	global_load_dwordx4 v[124:127], v0, s[24:25] offset:3072
	s_add_i32 s62, s58, s8
	s_add_i32 s62, s62, s8
	s_cmp_lt_i32 s62, s36
	s_cbranch_scc0 .Lrr20_tail0
	s_lshl_b32 s59, s62, 11
	s_add_u32 s20, s44, s59
	s_addc_u32 s21, s45, 0
	s_sub_u32 s60, s62, 0x8000
	s_cmp_lt_u32 s62, 0x8000
	s_cselect_b32 s60, s62, s60
	s_cselect_b32 s12, s46, s50
	s_cselect_b32 s13, s47, s51
	s_lshl_b32 s60, s60, 12
	s_add_u32 s12, s12, s60
	s_addc_u32 s13, s13, 0
	global_load_dwordx2 v[18:19], v202, s[20:21]
	global_load_dwordx2 v[20:21], v202, s[20:21] offset:512
	global_load_dwordx2 v[22:23], v202, s[20:21] offset:1024
	global_load_dwordx2 v[24:25], v202, s[20:21] offset:1536
	global_load_dwordx4 v[64:67], v0, s[12:13]
	global_load_dwordx4 v[68:71], v0, s[12:13] offset:1024
	global_load_dwordx4 v[72:75], v0, s[12:13] offset:2048
	global_load_dwordx4 v[76:79], v0, s[12:13] offset:3072
	s_waitcnt vmcnt(32)
	v_cvt_f32_f16_e32 v226, v2
	v_cvt_f32_f16_sdwa v227, v2 dst_sel:DWORD dst_unused:UNUSED_PAD src0_sel:WORD_1
	v_cvt_f32_f16_e32 v228, v3
	v_cvt_f32_f16_sdwa v229, v3 dst_sel:DWORD dst_unused:UNUSED_PAD src0_sel:WORD_1
	v_cvt_f32_f16_e32 v230, v4
	v_cvt_f32_f16_sdwa v231, v4 dst_sel:DWORD dst_unused:UNUSED_PAD src0_sel:WORD_1
	v_cvt_f32_f16_e32 v232, v5
	v_cvt_f32_f16_sdwa v233, v5 dst_sel:DWORD dst_unused:UNUSED_PAD src0_sel:WORD_1
	v_cvt_f32_f16_e32 v234, v6
	v_cvt_f32_f16_sdwa v235, v6 dst_sel:DWORD dst_unused:UNUSED_PAD src0_sel:WORD_1
	v_cvt_f32_f16_e32 v236, v7
	v_cvt_f32_f16_sdwa v237, v7 dst_sel:DWORD dst_unused:UNUSED_PAD src0_sel:WORD_1
	v_cvt_f32_f16_e32 v238, v8
	v_cvt_f32_f16_sdwa v239, v8 dst_sel:DWORD dst_unused:UNUSED_PAD src0_sel:WORD_1
	v_cvt_f32_f16_e32 v240, v9
	v_cvt_f32_f16_sdwa v241, v9 dst_sel:DWORD dst_unused:UNUSED_PAD src0_sel:WORD_1
	v_mul_f32_e32 v242, v227, v227
	v_mul_f32_e32 v243, v231, v231
	v_mul_f32_e32 v244, v235, v235
	v_mul_f32_e32 v245, v239, v239
	v_fmac_f32_e32 v242, v226, v226
	v_fmac_f32_e32 v243, v230, v230
	v_fmac_f32_e32 v244, v234, v234
	v_fmac_f32_e32 v245, v238, v238
	v_fmac_f32_e32 v242, v228, v228
	v_fmac_f32_e32 v243, v232, v232
	v_fmac_f32_e32 v244, v236, v236
	v_fmac_f32_e32 v245, v240, v240
	v_fmac_f32_e32 v242, v229, v229
	v_fmac_f32_e32 v243, v233, v233
	v_fmac_f32_e32 v244, v237, v237
	v_fmac_f32_e32 v245, v241, v241
	v_add_f32_e32 v242, v242, v243
	v_add_f32_e32 v242, v242, v244
	v_add_f32_e32 v242, v242, v245
	s_nop 1
	v_add_f32_dpp v242, v242, v242 quad_perm:[1,0,3,2] row_mask:0xf bank_mask:0xf bound_ctrl:1
	s_nop 1
	v_add_f32_dpp v242, v242, v242 quad_perm:[2,3,0,1] row_mask:0xf bank_mask:0xf bound_ctrl:1
	s_nop 1
	v_add_f32_dpp v242, v242, v242 row_half_mirror row_mask:0xf bank_mask:0xf bound_ctrl:1
	s_nop 1
	v_add_f32_dpp v242, v242, v242 row_mirror row_mask:0xf bank_mask:0xf bound_ctrl:1
	s_nop 1
	ds_swizzle_b32 v243, v242 offset:swizzle(SWAP,16)
	s_waitcnt lgkmcnt(0)
	v_add_f32_e32 v242, v242, v243
	v_mov_b32_e32 v243, v242
	s_nop 1
	v_permlane32_swap_b32_e32 v242, v243
	v_add_f32_e32 v242, v242, v243
	v_fmamk_f32 v242, v242, 0x3a800000, v224
	v_rsq_f32_e32 v242, v242
	s_waitcnt vmcnt(8)
; DI int TIDX() { int t = threadIdx.x; asm volatile("" : "+v"(t)); return t; }
; DI int BIDX() { int b = blockIdx.x; asm volatile("" : "+s"(b)); return b; }
; DI void rows_resid_norm(const P& p, const float* xlat, const float* xctx, const h16* y, int l, int gate_idx, const float* post_g,
;                         bool do_next, int l2, const float* gain2, int sh_idx, int sc_idx, h16* dst, int nrows) {
;   const int lane = TIDX() & 63;
;   const int gw = BIDX() * 4 + (TIDX() >> 6), nw = gridDim.x * 4;
;   const float* mod = (const float*)(p.ws + OFF_MOD);
;   float* xc = (float*)(p.ws + OFF_XC);
;   for (int row = gw; row < nrows; row += nw) {
;     const float* xr = row < TL ? xlat + (size_t)row * 1024 : xctx + (size_t)(row - TL) * 1024;
;     float* xo = row < TL ? p.out + (size_t)row * 1024 : xc + (size_t)(row - TL) * 1024;
;     const int mrow = row < TL ? (row >> 12) : 8;
;     const float* mr = mod + ((size_t)l * 9 + mrow) * 6144;
;     const float* mr2 = mod + ((size_t)l2 * 9 + mrow) * 6144;
;     f32x4 yv[4], xv[4];
;     float ss = 0.f;
; #pragma unroll
;     for (int i = 0; i < 4; ++i) {
;       h16x4 t = *(const h16x4*)(y + (size_t)row * 1024 + lane * 4 + 256 * i);
;       yv[i].x = (float)t.x; yv[i].y = (float)t.y; yv[i].z = (float)t.z; yv[i].w = (float)t.w;
;       ss += yv[i].x * yv[i].x + yv[i].y * yv[i].y + yv[i].z * yv[i].z + yv[i].w * yv[i].w;
;       xv[i] = *(const f32x4*)(xr + lane * 4 + 256 * i);
;     }
;     ss = wave_sum(ss);
;     const float rstd = rsqrtf(ss * (1.f / 1024.f) + EPS);
;     float s2 = 0.f;
; #pragma unroll
;     for (int i = 0; i < 4; ++i) {
;       const int c = lane * 4 + 256 * i;
;       f32x4 g = *(const f32x4*)(post_g + c), gt = *(const f32x4*)(mr + gate_idx * 1024 + c);
;       xv[i].x += gt.x * (yv[i].x * rstd * g.x);
;       xv[i].y += gt.y * (yv[i].y * rstd * g.y);
;       xv[i].z += gt.z * (yv[i].z * rstd * g.z);
;       xv[i].w += gt.w * (yv[i].w * rstd * g.w);
;       *(f32x4*)(xo + c) = xv[i];
;       s2 += xv[i].x * xv[i].x + xv[i].y * xv[i].y + xv[i].z * xv[i].z + xv[i].w * xv[i].w;
;     }
	v_mul_f32_e32 v226, v226, v242
	v_mul_f32_e32 v227, v227, v242
	v_mul_f32_e32 v228, v228, v242
	v_mul_f32_e32 v229, v229, v242
	v_mul_f32_e32 v230, v230, v242
	v_mul_f32_e32 v231, v231, v242
	v_mul_f32_e32 v232, v232, v242
	v_mul_f32_e32 v233, v233, v242
	v_mul_f32_e32 v234, v234, v242
	v_mul_f32_e32 v235, v235, v242
	v_mul_f32_e32 v236, v236, v242
	v_mul_f32_e32 v237, v237, v242
	v_mul_f32_e32 v238, v238, v242
	v_mul_f32_e32 v239, v239, v242
	v_mul_f32_e32 v240, v240, v242
	v_mul_f32_e32 v241, v241, v242
	v_mul_f32_e32 v226, v80, v226
	v_mul_f32_e32 v227, v81, v227
	v_mul_f32_e32 v228, v82, v228
	v_mul_f32_e32 v229, v83, v229
	v_mul_f32_e32 v230, v84, v230
	v_mul_f32_e32 v231, v85, v231
	v_mul_f32_e32 v232, v86, v232
	v_mul_f32_e32 v233, v87, v233
	v_mul_f32_e32 v234, v88, v234
	v_mul_f32_e32 v235, v89, v235
	v_mul_f32_e32 v236, v90, v236
	v_mul_f32_e32 v237, v91, v237
	v_mul_f32_e32 v238, v92, v238
	v_mul_f32_e32 v239, v93, v239
	v_mul_f32_e32 v240, v94, v240
	v_mul_f32_e32 v241, v95, v241
	v_fmac_f32_e32 v32, v112, v226
	v_fmac_f32_e32 v33, v113, v227
	v_fmac_f32_e32 v34, v114, v228
	v_fmac_f32_e32 v35, v115, v229
	v_fmac_f32_e32 v36, v116, v230
	v_fmac_f32_e32 v37, v117, v231
	v_fmac_f32_e32 v38, v118, v232
	v_fmac_f32_e32 v39, v119, v233
	v_fmac_f32_e32 v40, v120, v234
	v_fmac_f32_e32 v41, v121, v235
	v_fmac_f32_e32 v42, v122, v236
	v_fmac_f32_e32 v43, v123, v237
	v_fmac_f32_e32 v44, v124, v238
	v_fmac_f32_e32 v45, v125, v239
	v_fmac_f32_e32 v46, v126, v240
	v_fmac_f32_e32 v47, v127, v241
	global_store_dwordx4 v0, v[32:35], s[22:23]
	global_store_dwordx4 v0, v[36:39], s[22:23] offset:1024
	global_store_dwordx4 v0, v[40:43], s[22:23] offset:2048
	global_store_dwordx4 v0, v[44:47], s[22:23] offset:3072
	s_add_i32 s58, s58, s8
.Lrr20_l1:
	s_lshr_b32 s59, s58, 12
	s_cmp_lt_u32 s58, 0x8000
	s_cselect_b32 s59, s59, 8
	s_mul_i32 s59, s59, 0x6000
	s_add_u32 s24, s42, s59
	s_addc_u32 s25, s43, 0
	s_sub_u32 s60, s58, 0x8000
	s_cmp_lt_u32 s58, 0x8000
	s_cselect_b32 s60, s58, s60
	s_cselect_b32 s22, s46, s50
	s_cselect_b32 s23, s47, s51
	s_lshl_b32 s60, s60, 12
	s_add_u32 s22, s22, s60
	s_addc_u32 s23, s23, 0
	global_load_dwordx4 v[112:115], v0, s[24:25]
	global_load_dwordx4 v[116:119], v0, s[24:25] offset:1024
	global_load_dwordx4 v[120:123], v0, s[24:25] offset:2048
	global_load_dwordx4 v[124:127], v0, s[24:25] offset:3072
	s_add_i32 s62, s58, s8
	s_add_i32 s62, s62, s8
	s_cmp_lt_i32 s62, s36
	s_cbranch_scc0 .Lrr20_tail1
	s_lshl_b32 s59, s62, 11
	s_add_u32 s20, s44, s59
	s_addc_u32 s21, s45, 0
	s_sub_u32 s60, s62, 0x8000
	s_cmp_lt_u32 s62, 0x8000
	s_cselect_b32 s60, s62, s60
	s_cselect_b32 s12, s46, s50
	s_cselect_b32 s13, s47, s51
	s_lshl_b32 s60, s60, 12
	s_add_u32 s12, s12, s60
	s_addc_u32 s13, s13, 0
	global_load_dwordx2 v[2:3], v202, s[20:21]
	global_load_dwordx2 v[4:5], v202, s[20:21] offset:512
	global_load_dwordx2 v[6:7], v202, s[20:21] offset:1024
	global_load_dwordx2 v[8:9], v202, s[20:21] offset:1536
	global_load_dwordx4 v[32:35], v0, s[12:13]
	global_load_dwordx4 v[36:39], v0, s[12:13] offset:1024
	global_load_dwordx4 v[40:43], v0, s[12:13] offset:2048
	global_load_dwordx4 v[44:47], v0, s[12:13] offset:3072
	s_waitcnt vmcnt(32)
	v_cvt_f32_f16_e32 v226, v10
	v_cvt_f32_f16_sdwa v227, v10 dst_sel:DWORD dst_unused:UNUSED_PAD src0_sel:WORD_1
	v_cvt_f32_f16_e32 v228, v11
	v_cvt_f32_f16_sdwa v229, v11 dst_sel:DWORD dst_unused:UNUSED_PAD src0_sel:WORD_1
	v_cvt_f32_f16_e32 v230, v12
	v_cvt_f32_f16_sdwa v231, v12 dst_sel:DWORD dst_unused:UNUSED_PAD src0_sel:WORD_1
	v_cvt_f32_f16_e32 v232, v13
	v_cvt_f32_f16_sdwa v233, v13 dst_sel:DWORD dst_unused:UNUSED_PAD src0_sel:WORD_1
	v_cvt_f32_f16_e32 v234, v14
	v_cvt_f32_f16_sdwa v235, v14 dst_sel:DWORD dst_unused:UNUSED_PAD src0_sel:WORD_1
	v_cvt_f32_f16_e32 v236, v15
	v_cvt_f32_f16_sdwa v237, v15 dst_sel:DWORD dst_unused:UNUSED_PAD src0_sel:WORD_1
	v_cvt_f32_f16_e32 v238, v16
	v_cvt_f32_f16_sdwa v239, v16 dst_sel:DWORD dst_unused:UNUSED_PAD src0_sel:WORD_1
	v_cvt_f32_f16_e32 v240, v17
	v_cvt_f32_f16_sdwa v241, v17 dst_sel:DWORD dst_unused:UNUSED_PAD src0_sel:WORD_1
	v_mul_f32_e32 v242, v227, v227
	v_mul_f32_e32 v243, v231, v231
	v_mul_f32_e32 v244, v235, v235
	v_mul_f32_e32 v245, v239, v239
	v_fmac_f32_e32 v242, v226, v226
	v_fmac_f32_e32 v243, v230, v230
	v_fmac_f32_e32 v244, v234, v234
	v_fmac_f32_e32 v245, v238, v238
	v_fmac_f32_e32 v242, v228, v228
	v_fmac_f32_e32 v243, v232, v232
	v_fmac_f32_e32 v244, v236, v236
	v_fmac_f32_e32 v245, v240, v240
	v_fmac_f32_e32 v242, v229, v229
	v_fmac_f32_e32 v243, v233, v233
	v_fmac_f32_e32 v244, v237, v237
	v_fmac_f32_e32 v245, v241, v241
	v_add_f32_e32 v242, v242, v243
	v_add_f32_e32 v242, v242, v244
	v_add_f32_e32 v242, v242, v245
	s_nop 1
	v_add_f32_dpp v242, v242, v242 quad_perm:[1,0,3,2] row_mask:0xf bank_mask:0xf bound_ctrl:1
	s_nop 1
	v_add_f32_dpp v242, v242, v242 quad_perm:[2,3,0,1] row_mask:0xf bank_mask:0xf bound_ctrl:1
	s_nop 1
	v_add_f32_dpp v242, v242, v242 row_half_mirror row_mask:0xf bank_mask:0xf bound_ctrl:1
	s_nop 1
	v_add_f32_dpp v242, v242, v242 row_mirror row_mask:0xf bank_mask:0xf bound_ctrl:1
	s_nop 1
	ds_swizzle_b32 v243, v242 offset:swizzle(SWAP,16)
	s_waitcnt lgkmcnt(0)
	v_add_f32_e32 v242, v242, v243
	v_mov_b32_e32 v243, v242
	s_nop 1
	v_permlane32_swap_b32_e32 v242, v243
	v_add_f32_e32 v242, v242, v243
	v_fmamk_f32 v242, v242, 0x3a800000, v224
	v_rsq_f32_e32 v242, v242
	s_waitcnt vmcnt(8)
; DI int TIDX() { int t = threadIdx.x; asm volatile("" : "+v"(t)); return t; }
; DI int BIDX() { int b = blockIdx.x; asm volatile("" : "+s"(b)); return b; }
; DI void rows_resid_norm(const P& p, const float* xlat, const float* xctx, const h16* y, int l, int gate_idx, const float* post_g,
;                         bool do_next, int l2, const float* gain2, int sh_idx, int sc_idx, h16* dst, int nrows) {
;   const int lane = TIDX() & 63;
;   const int gw = BIDX() * 4 + (TIDX() >> 6), nw = gridDim.x * 4;
;   const float* mod = (const float*)(p.ws + OFF_MOD);
;   float* xc = (float*)(p.ws + OFF_XC);
;   for (int row = gw; row < nrows; row += nw) {
;     const float* xr = row < TL ? xlat + (size_t)row * 1024 : xctx + (size_t)(row - TL) * 1024;
;     float* xo = row < TL ? p.out + (size_t)row * 1024 : xc + (size_t)(row - TL) * 1024;
;     const int mrow = row < TL ? (row >> 12) : 8;
;     const float* mr = mod + ((size_t)l * 9 + mrow) * 6144;
;     const float* mr2 = mod + ((size_t)l2 * 9 + mrow) * 6144;
;     f32x4 yv[4], xv[4];
;     float ss = 0.f;
; #pragma unroll
;     for (int i = 0; i < 4; ++i) {
;       h16x4 t = *(const h16x4*)(y + (size_t)row * 1024 + lane * 4 + 256 * i);
;       yv[i].x = (float)t.x; yv[i].y = (float)t.y; yv[i].z = (float)t.z; yv[i].w = (float)t.w;
;       ss += yv[i].x * yv[i].x + yv[i].y * yv[i].y + yv[i].z * yv[i].z + yv[i].w * yv[i].w;
;       xv[i] = *(const f32x4*)(xr + lane * 4 + 256 * i);
;     }
;     ss = wave_sum(ss);
;     const float rstd = rsqrtf(ss * (1.f / 1024.f) + EPS);
;     float s2 = 0.f;
; #pragma unroll
;     for (int i = 0; i < 4; ++i) {
;       const int c = lane * 4 + 256 * i;
;       f32x4 g = *(const f32x4*)(post_g + c), gt = *(const f32x4*)(mr + gate_idx * 1024 + c);
;       xv[i].x += gt.x * (yv[i].x * rstd * g.x);
;       xv[i].y += gt.y * (yv[i].y * rstd * g.y);
;       xv[i].z += gt.z * (yv[i].z * rstd * g.z);
;       xv[i].w += gt.w * (yv[i].w * rstd * g.w);
;       *(f32x4*)(xo + c) = xv[i];
;       s2 += xv[i].x * xv[i].x + xv[i].y * xv[i].y + xv[i].z * xv[i].z + xv[i].w * xv[i].w;
;     }
	v_mul_f32_e32 v226, v226, v242
	v_mul_f32_e32 v227, v227, v242
	v_mul_f32_e32 v228, v228, v242
	v_mul_f32_e32 v229, v229, v242
	v_mul_f32_e32 v230, v230, v242
	v_mul_f32_e32 v231, v231, v242
	v_mul_f32_e32 v232, v232, v242
	v_mul_f32_e32 v233, v233, v242
	v_mul_f32_e32 v234, v234, v242
	v_mul_f32_e32 v235, v235, v242
	v_mul_f32_e32 v236, v236, v242
	v_mul_f32_e32 v237, v237, v242
	v_mul_f32_e32 v238, v238, v242
	v_mul_f32_e32 v239, v239, v242
	v_mul_f32_e32 v240, v240, v242
	v_mul_f32_e32 v241, v241, v242
	v_mul_f32_e32 v226, v80, v226
	v_mul_f32_e32 v227, v81, v227
	v_mul_f32_e32 v228, v82, v228
	v_mul_f32_e32 v229, v83, v229
	v_mul_f32_e32 v230, v84, v230
	v_mul_f32_e32 v231, v85, v231
	v_mul_f32_e32 v232, v86, v232
	v_mul_f32_e32 v233, v87, v233
	v_mul_f32_e32 v234, v88, v234
	v_mul_f32_e32 v235, v89, v235
	v_mul_f32_e32 v236, v90, v236
	v_mul_f32_e32 v237, v91, v237
	v_mul_f32_e32 v238, v92, v238
	v_mul_f32_e32 v239, v93, v239
	v_mul_f32_e32 v240, v94, v240
	v_mul_f32_e32 v241, v95, v241
	v_fmac_f32_e32 v48, v112, v226
	v_fmac_f32_e32 v49, v113, v227
	v_fmac_f32_e32 v50, v114, v228
	v_fmac_f32_e32 v51, v115, v229
	v_fmac_f32_e32 v52, v116, v230
	v_fmac_f32_e32 v53, v117, v231
	v_fmac_f32_e32 v54, v118, v232
	v_fmac_f32_e32 v55, v119, v233
	v_fmac_f32_e32 v56, v120, v234
	v_fmac_f32_e32 v57, v121, v235
	v_fmac_f32_e32 v58, v122, v236
	v_fmac_f32_e32 v59, v123, v237
	v_fmac_f32_e32 v60, v124, v238
	v_fmac_f32_e32 v61, v125, v239
	v_fmac_f32_e32 v62, v126, v240
	v_fmac_f32_e32 v63, v127, v241
	global_store_dwordx4 v0, v[48:51], s[22:23]
	global_store_dwordx4 v0, v[52:55], s[22:23] offset:1024
	global_store_dwordx4 v0, v[56:59], s[22:23] offset:2048
	global_store_dwordx4 v0, v[60:63], s[22:23] offset:3072
	s_add_i32 s58, s58, s8
	s_branch .Lrr20_l2
.Lrr20_tail0:
	s_waitcnt vmcnt(4)
	v_cvt_f32_f16_e32 v226, v2
	v_cvt_f32_f16_sdwa v227, v2 dst_sel:DWORD dst_unused:UNUSED_PAD src0_sel:WORD_1
	v_cvt_f32_f16_e32 v228, v3
	v_cvt_f32_f16_sdwa v229, v3 dst_sel:DWORD dst_unused:UNUSED_PAD src0_sel:WORD_1
	v_cvt_f32_f16_e32 v230, v4
	v_cvt_f32_f16_sdwa v231, v4 dst_sel:DWORD dst_unused:UNUSED_PAD src0_sel:WORD_1
	v_cvt_f32_f16_e32 v232, v5
	v_cvt_f32_f16_sdwa v233, v5 dst_sel:DWORD dst_unused:UNUSED_PAD src0_sel:WORD_1
	v_cvt_f32_f16_e32 v234, v6
	v_cvt_f32_f16_sdwa v235, v6 dst_sel:DWORD dst_unused:UNUSED_PAD src0_sel:WORD_1
	v_cvt_f32_f16_e32 v236, v7
	v_cvt_f32_f16_sdwa v237, v7 dst_sel:DWORD dst_unused:UNUSED_PAD src0_sel:WORD_1
	v_cvt_f32_f16_e32 v238, v8
	v_cvt_f32_f16_sdwa v239, v8 dst_sel:DWORD dst_unused:UNUSED_PAD src0_sel:WORD_1
	v_cvt_f32_f16_e32 v240, v9
	v_cvt_f32_f16_sdwa v241, v9 dst_sel:DWORD dst_unused:UNUSED_PAD src0_sel:WORD_1
	v_mul_f32_e32 v242, v227, v227
	v_mul_f32_e32 v243, v231, v231
	v_mul_f32_e32 v244, v235, v235
	v_mul_f32_e32 v245, v239, v239
	v_fmac_f32_e32 v242, v226, v226
	v_fmac_f32_e32 v243, v230, v230
	v_fmac_f32_e32 v244, v234, v234
	v_fmac_f32_e32 v245, v238, v238
	v_fmac_f32_e32 v242, v228, v228
	v_fmac_f32_e32 v243, v232, v232
	v_fmac_f32_e32 v244, v236, v236
	v_fmac_f32_e32 v245, v240, v240
	v_fmac_f32_e32 v242, v229, v229
	v_fmac_f32_e32 v243, v233, v233
	v_fmac_f32_e32 v244, v237, v237
	v_fmac_f32_e32 v245, v241, v241
	v_add_f32_e32 v242, v242, v243
	v_add_f32_e32 v242, v242, v244
	v_add_f32_e32 v242, v242, v245
	s_nop 1
	v_add_f32_dpp v242, v242, v242 quad_perm:[1,0,3,2] row_mask:0xf bank_mask:0xf bound_ctrl:1
	s_nop 1
	v_add_f32_dpp v242, v242, v242 quad_perm:[2,3,0,1] row_mask:0xf bank_mask:0xf bound_ctrl:1
	s_nop 1
	v_add_f32_dpp v242, v242, v242 row_half_mirror row_mask:0xf bank_mask:0xf bound_ctrl:1
	s_nop 1
	v_add_f32_dpp v242, v242, v242 row_mirror row_mask:0xf bank_mask:0xf bound_ctrl:1
	s_nop 1
	ds_swizzle_b32 v243, v242 offset:swizzle(SWAP,16)
	s_waitcnt lgkmcnt(0)
	v_add_f32_e32 v242, v242, v243
	v_mov_b32_e32 v243, v242
	s_nop 1
	v_permlane32_swap_b32_e32 v242, v243
	v_add_f32_e32 v242, v242, v243
	v_fmamk_f32 v242, v242, 0x3a800000, v224
	v_rsq_f32_e32 v242, v242
	s_waitcnt vmcnt(0)
	v_mul_f32_e32 v226, v226, v242
	v_mul_f32_e32 v227, v227, v242
	v_mul_f32_e32 v228, v228, v242
	v_mul_f32_e32 v229, v229, v242
	v_mul_f32_e32 v230, v230, v242
	v_mul_f32_e32 v231, v231, v242
	v_mul_f32_e32 v232, v232, v242
	v_mul_f32_e32 v233, v233, v242
	v_mul_f32_e32 v234, v234, v242
	v_mul_f32_e32 v235, v235, v242
	v_mul_f32_e32 v236, v236, v242
	v_mul_f32_e32 v237, v237, v242
	v_mul_f32_e32 v238, v238, v242
	v_mul_f32_e32 v239, v239, v242
	v_mul_f32_e32 v240, v240, v242
	v_mul_f32_e32 v241, v241, v242
	v_mul_f32_e32 v226, v80, v226
	v_mul_f32_e32 v227, v81, v227
	v_mul_f32_e32 v228, v82, v228
	v_mul_f32_e32 v229, v83, v229
	v_mul_f32_e32 v230, v84, v230
	v_mul_f32_e32 v231, v85, v231
	v_mul_f32_e32 v232, v86, v232
	v_mul_f32_e32 v233, v87, v233
	v_mul_f32_e32 v234, v88, v234
	v_mul_f32_e32 v235, v89, v235
	v_mul_f32_e32 v236, v90, v236
	v_mul_f32_e32 v237, v91, v237
	v_mul_f32_e32 v238, v92, v238
	v_mul_f32_e32 v239, v93, v239
	v_mul_f32_e32 v240, v94, v240
	v_mul_f32_e32 v241, v95, v241
	v_fmac_f32_e32 v32, v112, v226
	v_fmac_f32_e32 v33, v113, v227
	v_fmac_f32_e32 v34, v114, v228
	v_fmac_f32_e32 v35, v115, v229
	v_fmac_f32_e32 v36, v116, v230
	v_fmac_f32_e32 v37, v117, v231
	v_fmac_f32_e32 v38, v118, v232
	v_fmac_f32_e32 v39, v119, v233
	v_fmac_f32_e32 v40, v120, v234
	v_fmac_f32_e32 v41, v121, v235
	v_fmac_f32_e32 v42, v122, v236
	v_fmac_f32_e32 v43, v123, v237
	v_fmac_f32_e32 v44, v124, v238
	v_fmac_f32_e32 v45, v125, v239
	v_fmac_f32_e32 v46, v126, v240
	v_fmac_f32_e32 v47, v127, v241
	global_store_dwordx4 v0, v[32:35], s[22:23]
	global_store_dwordx4 v0, v[36:39], s[22:23] offset:1024
	global_store_dwordx4 v0, v[40:43], s[22:23] offset:2048
	global_store_dwordx4 v0, v[44:47], s[22:23] offset:3072
	s_add_i32 s58, s58, s8
	s_cmp_lt_i32 s58, s36
	s_cbranch_scc0 .Lrr2_exit
; DI int TIDX() { int t = threadIdx.x; asm volatile("" : "+v"(t)); return t; }
; DI int BIDX() { int b = blockIdx.x; asm volatile("" : "+s"(b)); return b; }
; DI void rows_resid_norm(const P& p, const float* xlat, const float* xctx, const h16* y, int l, int gate_idx, const float* post_g,
;                         bool do_next, int l2, const float* gain2, int sh_idx, int sc_idx, h16* dst, int nrows) {
;   const int lane = TIDX() & 63;
;   const int gw = BIDX() * 4 + (TIDX() >> 6), nw = gridDim.x * 4;
;   const float* mod = (const float*)(p.ws + OFF_MOD);
;   float* xc = (float*)(p.ws + OFF_XC);
;   for (int row = gw; row < nrows; row += nw) {
;     const float* xr = row < TL ? xlat + (size_t)row * 1024 : xctx + (size_t)(row - TL) * 1024;
;     float* xo = row < TL ? p.out + (size_t)row * 1024 : xc + (size_t)(row - TL) * 1024;
;     const int mrow = row < TL ? (row >> 12) : 8;
;     const float* mr = mod + ((size_t)l * 9 + mrow) * 6144;
;     const float* mr2 = mod + ((size_t)l2 * 9 + mrow) * 6144;
;     f32x4 yv[4], xv[4];
;     float ss = 0.f;
; #pragma unroll
;     for (int i = 0; i < 4; ++i) {
;       h16x4 t = *(const h16x4*)(y + (size_t)row * 1024 + lane * 4 + 256 * i);
;       yv[i].x = (float)t.x; yv[i].y = (float)t.y; yv[i].z = (float)t.z; yv[i].w = (float)t.w;
;       ss += yv[i].x * yv[i].x + yv[i].y * yv[i].y + yv[i].z * yv[i].z + yv[i].w * yv[i].w;
;       xv[i] = *(const f32x4*)(xr + lane * 4 + 256 * i);
;     }
;     ss = wave_sum(ss);
;     const float rstd = rsqrtf(ss * (1.f / 1024.f) + EPS);
;     float s2 = 0.f;
; #pragma unroll
;     for (int i = 0; i < 4; ++i) {
;       const int c = lane * 4 + 256 * i;
;       f32x4 g = *(const f32x4*)(post_g + c), gt = *(const f32x4*)(mr + gate_idx * 1024 + c);
;       xv[i].x += gt.x * (yv[i].x * rstd * g.x);
;       xv[i].y += gt.y * (yv[i].y * rstd * g.y);
;       xv[i].z += gt.z * (yv[i].z * rstd * g.z);
;       xv[i].w += gt.w * (yv[i].w * rstd * g.w);
;       *(f32x4*)(xo + c) = xv[i];
;       s2 += xv[i].x * xv[i].x + xv[i].y * xv[i].y + xv[i].z * xv[i].z + xv[i].w * xv[i].w;
;     }
	s_lshr_b32 s59, s58, 12
	s_cmp_lt_u32 s58, 0x8000
	s_cselect_b32 s59, s59, 8
	s_mul_i32 s59, s59, 0x6000
	s_add_u32 s24, s42, s59
	s_addc_u32 s25, s43, 0
	s_sub_u32 s60, s58, 0x8000
	s_cmp_lt_u32 s58, 0x8000
	s_cselect_b32 s60, s58, s60
	s_cselect_b32 s22, s46, s50
	s_cselect_b32 s23, s47, s51
	s_lshl_b32 s60, s60, 12
	s_add_u32 s22, s22, s60
	s_addc_u32 s23, s23, 0
	global_load_dwordx4 v[112:115], v0, s[24:25]
	global_load_dwordx4 v[116:119], v0, s[24:25] offset:1024
	global_load_dwordx4 v[120:123], v0, s[24:25] offset:2048
	global_load_dwordx4 v[124:127], v0, s[24:25] offset:3072
	s_waitcnt vmcnt(4)
	v_cvt_f32_f16_e32 v226, v10
	v_cvt_f32_f16_sdwa v227, v10 dst_sel:DWORD dst_unused:UNUSED_PAD src0_sel:WORD_1
	v_cvt_f32_f16_e32 v228, v11
	v_cvt_f32_f16_sdwa v229, v11 dst_sel:DWORD dst_unused:UNUSED_PAD src0_sel:WORD_1
	v_cvt_f32_f16_e32 v230, v12
	v_cvt_f32_f16_sdwa v231, v12 dst_sel:DWORD dst_unused:UNUSED_PAD src0_sel:WORD_1
	v_cvt_f32_f16_e32 v232, v13
	v_cvt_f32_f16_sdwa v233, v13 dst_sel:DWORD dst_unused:UNUSED_PAD src0_sel:WORD_1
	v_cvt_f32_f16_e32 v234, v14
	v_cvt_f32_f16_sdwa v235, v14 dst_sel:DWORD dst_unused:UNUSED_PAD src0_sel:WORD_1
	v_cvt_f32_f16_e32 v236, v15
	v_cvt_f32_f16_sdwa v237, v15 dst_sel:DWORD dst_unused:UNUSED_PAD src0_sel:WORD_1
	v_cvt_f32_f16_e32 v238, v16
	v_cvt_f32_f16_sdwa v239, v16 dst_sel:DWORD dst_unused:UNUSED_PAD src0_sel:WORD_1
	v_cvt_f32_f16_e32 v240, v17
	v_cvt_f32_f16_sdwa v241, v17 dst_sel:DWORD dst_unused:UNUSED_PAD src0_sel:WORD_1
	v_mul_f32_e32 v242, v227, v227
	v_mul_f32_e32 v243, v231, v231
	v_mul_f32_e32 v244, v235, v235
	v_mul_f32_e32 v245, v239, v239
	v_fmac_f32_e32 v242, v226, v226
	v_fmac_f32_e32 v243, v230, v230
	v_fmac_f32_e32 v244, v234, v234
	v_fmac_f32_e32 v245, v238, v238
	v_fmac_f32_e32 v242, v228, v228
	v_fmac_f32_e32 v243, v232, v232
	v_fmac_f32_e32 v244, v236, v236
	v_fmac_f32_e32 v245, v240, v240
	v_fmac_f32_e32 v242, v229, v229
	v_fmac_f32_e32 v243, v233, v233
	v_fmac_f32_e32 v244, v237, v237
	v_fmac_f32_e32 v245, v241, v241
	v_add_f32_e32 v242, v242, v243
	v_add_f32_e32 v242, v242, v244
	v_add_f32_e32 v242, v242, v245
	s_nop 1
	v_add_f32_dpp v242, v242, v242 quad_perm:[1,0,3,2] row_mask:0xf bank_mask:0xf bound_ctrl:1
	s_nop 1
	v_add_f32_dpp v242, v242, v242 quad_perm:[2,3,0,1] row_mask:0xf bank_mask:0xf bound_ctrl:1
	s_nop 1
	v_add_f32_dpp v242, v242, v242 row_half_mirror row_mask:0xf bank_mask:0xf bound_ctrl:1
	s_nop 1
	v_add_f32_dpp v242, v242, v242 row_mirror row_mask:0xf bank_mask:0xf bound_ctrl:1
	s_nop 1
	ds_swizzle_b32 v243, v242 offset:swizzle(SWAP,16)
	s_waitcnt lgkmcnt(0)
	v_add_f32_e32 v242, v242, v243
	v_mov_b32_e32 v243, v242
	s_nop 1
	v_permlane32_swap_b32_e32 v242, v243
	v_add_f32_e32 v242, v242, v243
	v_fmamk_f32 v242, v242, 0x3a800000, v224
	v_rsq_f32_e32 v242, v242
	s_waitcnt vmcnt(0)
	v_mul_f32_e32 v226, v226, v242
	v_mul_f32_e32 v227, v227, v242
	v_mul_f32_e32 v228, v228, v242
	v_mul_f32_e32 v229, v229, v242
	v_mul_f32_e32 v230, v230, v242
	v_mul_f32_e32 v231, v231, v242
	v_mul_f32_e32 v232, v232, v242
	v_mul_f32_e32 v233, v233, v242
	v_mul_f32_e32 v234, v234, v242
	v_mul_f32_e32 v235, v235, v242
	v_mul_f32_e32 v236, v236, v242
	v_mul_f32_e32 v237, v237, v242
	v_mul_f32_e32 v238, v238, v242
	v_mul_f32_e32 v239, v239, v242
	v_mul_f32_e32 v240, v240, v242
	v_mul_f32_e32 v241, v241, v242
	v_mul_f32_e32 v226, v80, v226
	v_mul_f32_e32 v227, v81, v227
	v_mul_f32_e32 v228, v82, v228
	v_mul_f32_e32 v229, v83, v229
	v_mul_f32_e32 v230, v84, v230
	v_mul_f32_e32 v231, v85, v231
	v_mul_f32_e32 v232, v86, v232
	v_mul_f32_e32 v233, v87, v233
	v_mul_f32_e32 v234, v88, v234
	v_mul_f32_e32 v235, v89, v235
	v_mul_f32_e32 v236, v90, v236
	v_mul_f32_e32 v237, v91, v237
	v_mul_f32_e32 v238, v92, v238
	v_mul_f32_e32 v239, v93, v239
	v_mul_f32_e32 v240, v94, v240
	v_mul_f32_e32 v241, v95, v241
	v_fmac_f32_e32 v48, v112, v226
	v_fmac_f32_e32 v49, v113, v227
	v_fmac_f32_e32 v50, v114, v228
	v_fmac_f32_e32 v51, v115, v229
	v_fmac_f32_e32 v52, v116, v230
	v_fmac_f32_e32 v53, v117, v231
	v_fmac_f32_e32 v54, v118, v232
	v_fmac_f32_e32 v55, v119, v233
	v_fmac_f32_e32 v56, v120, v234
	v_fmac_f32_e32 v57, v121, v235
	v_fmac_f32_e32 v58, v122, v236
	v_fmac_f32_e32 v59, v123, v237
	v_fmac_f32_e32 v60, v124, v238
	v_fmac_f32_e32 v61, v125, v239
	v_fmac_f32_e32 v62, v126, v240
	v_fmac_f32_e32 v63, v127, v241
	global_store_dwordx4 v0, v[48:51], s[22:23]
	global_store_dwordx4 v0, v[52:55], s[22:23] offset:1024
	global_store_dwordx4 v0, v[56:59], s[22:23] offset:2048
	global_store_dwordx4 v0, v[60:63], s[22:23] offset:3072
	s_add_i32 s58, s58, s8
	s_branch .Lrr2_exit
; DI int TIDX() { int t = threadIdx.x; asm volatile("" : "+v"(t)); return t; }
; DI int BIDX() { int b = blockIdx.x; asm volatile("" : "+s"(b)); return b; }
; DI void rows_resid_norm(const P& p, const float* xlat, const float* xctx, const h16* y, int l, int gate_idx, const float* post_g,
;                         bool do_next, int l2, const float* gain2, int sh_idx, int sc_idx, h16* dst, int nrows) {
;   const int lane = TIDX() & 63;
;   const int gw = BIDX() * 4 + (TIDX() >> 6), nw = gridDim.x * 4;
;   const float* mod = (const float*)(p.ws + OFF_MOD);
;   float* xc = (float*)(p.ws + OFF_XC);
;   for (int row = gw; row < nrows; row += nw) {
;     const float* xr = row < TL ? xlat + (size_t)row * 1024 : xctx + (size_t)(row - TL) * 1024;
;     float* xo = row < TL ? p.out + (size_t)row * 1024 : xc + (size_t)(row - TL) * 1024;
;     const int mrow = row < TL ? (row >> 12) : 8;
;     const float* mr = mod + ((size_t)l * 9 + mrow) * 6144;
;     const float* mr2 = mod + ((size_t)l2 * 9 + mrow) * 6144;
;     f32x4 yv[4], xv[4];
;     float ss = 0.f;
; #pragma unroll
;     for (int i = 0; i < 4; ++i) {
;       h16x4 t = *(const h16x4*)(y + (size_t)row * 1024 + lane * 4 + 256 * i);
;       yv[i].x = (float)t.x; yv[i].y = (float)t.y; yv[i].z = (float)t.z; yv[i].w = (float)t.w;
;       ss += yv[i].x * yv[i].x + yv[i].y * yv[i].y + yv[i].z * yv[i].z + yv[i].w * yv[i].w;
;       xv[i] = *(const f32x4*)(xr + lane * 4 + 256 * i);
;     }
;     ss = wave_sum(ss);
;     const float rstd = rsqrtf(ss * (1.f / 1024.f) + EPS);
;     float s2 = 0.f;
; #pragma unroll
;     for (int i = 0; i < 4; ++i) {
;       const int c = lane * 4 + 256 * i;
;       f32x4 g = *(const f32x4*)(post_g + c), gt = *(const f32x4*)(mr + gate_idx * 1024 + c);
;       xv[i].x += gt.x * (yv[i].x * rstd * g.x);
;       xv[i].y += gt.y * (yv[i].y * rstd * g.y);
;       xv[i].z += gt.z * (yv[i].z * rstd * g.z);
;       xv[i].w += gt.w * (yv[i].w * rstd * g.w);
;       *(f32x4*)(xo + c) = xv[i];
;       s2 += xv[i].x * xv[i].x + xv[i].y * xv[i].y + xv[i].z * xv[i].z + xv[i].w * xv[i].w;
;     }
.Lrr20_tail1:
	s_waitcnt vmcnt(4)
	v_cvt_f32_f16_e32 v226, v10
	v_cvt_f32_f16_sdwa v227, v10 dst_sel:DWORD dst_unused:UNUSED_PAD src0_sel:WORD_1
	v_cvt_f32_f16_e32 v228, v11
	v_cvt_f32_f16_sdwa v229, v11 dst_sel:DWORD dst_unused:UNUSED_PAD src0_sel:WORD_1
	v_cvt_f32_f16_e32 v230, v12
	v_cvt_f32_f16_sdwa v231, v12 dst_sel:DWORD dst_unused:UNUSED_PAD src0_sel:WORD_1
	v_cvt_f32_f16_e32 v232, v13
	v_cvt_f32_f16_sdwa v233, v13 dst_sel:DWORD dst_unused:UNUSED_PAD src0_sel:WORD_1
	v_cvt_f32_f16_e32 v234, v14
	v_cvt_f32_f16_sdwa v235, v14 dst_sel:DWORD dst_unused:UNUSED_PAD src0_sel:WORD_1
	v_cvt_f32_f16_e32 v236, v15
	v_cvt_f32_f16_sdwa v237, v15 dst_sel:DWORD dst_unused:UNUSED_PAD src0_sel:WORD_1
	v_cvt_f32_f16_e32 v238, v16
	v_cvt_f32_f16_sdwa v239, v16 dst_sel:DWORD dst_unused:UNUSED_PAD src0_sel:WORD_1
	v_cvt_f32_f16_e32 v240, v17
	v_cvt_f32_f16_sdwa v241, v17 dst_sel:DWORD dst_unused:UNUSED_PAD src0_sel:WORD_1
	v_mul_f32_e32 v242, v227, v227
	v_mul_f32_e32 v243, v231, v231
	v_mul_f32_e32 v244, v235, v235
	v_mul_f32_e32 v245, v239, v239
	v_fmac_f32_e32 v242, v226, v226
	v_fmac_f32_e32 v243, v230, v230
	v_fmac_f32_e32 v244, v234, v234
	v_fmac_f32_e32 v245, v238, v238
	v_fmac_f32_e32 v242, v228, v228
	v_fmac_f32_e32 v243, v232, v232
	v_fmac_f32_e32 v244, v236, v236
	v_fmac_f32_e32 v245, v240, v240
	v_fmac_f32_e32 v242, v229, v229
	v_fmac_f32_e32 v243, v233, v233
	v_fmac_f32_e32 v244, v237, v237
	v_fmac_f32_e32 v245, v241, v241
	v_add_f32_e32 v242, v242, v243
	v_add_f32_e32 v242, v242, v244
	v_add_f32_e32 v242, v242, v245
	s_nop 1
	v_add_f32_dpp v242, v242, v242 quad_perm:[1,0,3,2] row_mask:0xf bank_mask:0xf bound_ctrl:1
	s_nop 1
	v_add_f32_dpp v242, v242, v242 quad_perm:[2,3,0,1] row_mask:0xf bank_mask:0xf bound_ctrl:1
	s_nop 1
	v_add_f32_dpp v242, v242, v242 row_half_mirror row_mask:0xf bank_mask:0xf bound_ctrl:1
	s_nop 1
	v_add_f32_dpp v242, v242, v242 row_mirror row_mask:0xf bank_mask:0xf bound_ctrl:1
	s_nop 1
	ds_swizzle_b32 v243, v242 offset:swizzle(SWAP,16)
	s_waitcnt lgkmcnt(0)
	v_add_f32_e32 v242, v242, v243
	v_mov_b32_e32 v243, v242
	s_nop 1
	v_permlane32_swap_b32_e32 v242, v243
	v_add_f32_e32 v242, v242, v243
	v_fmamk_f32 v242, v242, 0x3a800000, v224
	v_rsq_f32_e32 v242, v242
	s_waitcnt vmcnt(0)
	v_mul_f32_e32 v226, v226, v242
	v_mul_f32_e32 v227, v227, v242
	v_mul_f32_e32 v228, v228, v242
	v_mul_f32_e32 v229, v229, v242
	v_mul_f32_e32 v230, v230, v242
	v_mul_f32_e32 v231, v231, v242
	v_mul_f32_e32 v232, v232, v242
	v_mul_f32_e32 v233, v233, v242
	v_mul_f32_e32 v234, v234, v242
	v_mul_f32_e32 v235, v235, v242
	v_mul_f32_e32 v236, v236, v242
	v_mul_f32_e32 v237, v237, v242
	v_mul_f32_e32 v238, v238, v242
	v_mul_f32_e32 v239, v239, v242
	v_mul_f32_e32 v240, v240, v242
	v_mul_f32_e32 v241, v241, v242
	v_mul_f32_e32 v226, v80, v226
	v_mul_f32_e32 v227, v81, v227
	v_mul_f32_e32 v228, v82, v228
	v_mul_f32_e32 v229, v83, v229
	v_mul_f32_e32 v230, v84, v230
	v_mul_f32_e32 v231, v85, v231
	v_mul_f32_e32 v232, v86, v232
	v_mul_f32_e32 v233, v87, v233
	v_mul_f32_e32 v234, v88, v234
	v_mul_f32_e32 v235, v89, v235
	v_mul_f32_e32 v236, v90, v236
	v_mul_f32_e32 v237, v91, v237
	v_mul_f32_e32 v238, v92, v238
	v_mul_f32_e32 v239, v93, v239
	v_mul_f32_e32 v240, v94, v240
	v_mul_f32_e32 v241, v95, v241
	v_fmac_f32_e32 v48, v112, v226
	v_fmac_f32_e32 v49, v113, v227
	v_fmac_f32_e32 v50, v114, v228
	v_fmac_f32_e32 v51, v115, v229
	v_fmac_f32_e32 v52, v116, v230
	v_fmac_f32_e32 v53, v117, v231
	v_fmac_f32_e32 v54, v118, v232
	v_fmac_f32_e32 v55, v119, v233
	v_fmac_f32_e32 v56, v120, v234
	v_fmac_f32_e32 v57, v121, v235
	v_fmac_f32_e32 v58, v122, v236
	v_fmac_f32_e32 v59, v123, v237
	v_fmac_f32_e32 v60, v124, v238
	v_fmac_f32_e32 v61, v125, v239
	v_fmac_f32_e32 v62, v126, v240
	v_fmac_f32_e32 v63, v127, v241
	global_store_dwordx4 v0, v[48:51], s[22:23]
	global_store_dwordx4 v0, v[52:55], s[22:23] offset:1024
	global_store_dwordx4 v0, v[56:59], s[22:23] offset:2048
	global_store_dwordx4 v0, v[60:63], s[22:23] offset:3072
	s_add_i32 s58, s58, s8
	s_cmp_lt_i32 s58, s36
	s_cbranch_scc0 .Lrr2_exit
	s_lshr_b32 s59, s58, 12
	s_cmp_lt_u32 s58, 0x8000
	s_cselect_b32 s59, s59, 8
	s_mul_i32 s59, s59, 0x6000
	s_add_u32 s24, s42, s59
	s_addc_u32 s25, s43, 0
	s_sub_u32 s60, s58, 0x8000
	s_cmp_lt_u32 s58, 0x8000
	s_cselect_b32 s60, s58, s60
	s_cselect_b32 s22, s46, s50
	s_cselect_b32 s23, s47, s51
	s_lshl_b32 s60, s60, 12
	s_add_u32 s22, s22, s60
	s_addc_u32 s23, s23, 0
	global_load_dwordx4 v[112:115], v0, s[24:25]
	global_load_dwordx4 v[116:119], v0, s[24:25] offset:1024
	global_load_dwordx4 v[120:123], v0, s[24:25] offset:2048
	global_load_dwordx4 v[124:127], v0, s[24:25] offset:3072
	s_waitcnt vmcnt(4)
; DI int TIDX() { int t = threadIdx.x; asm volatile("" : "+v"(t)); return t; }
; DI int BIDX() { int b = blockIdx.x; asm volatile("" : "+s"(b)); return b; }
; DI void rows_resid_norm(const P& p, const float* xlat, const float* xctx, const h16* y, int l, int gate_idx, const float* post_g,
;                         bool do_next, int l2, const float* gain2, int sh_idx, int sc_idx, h16* dst, int nrows) {
;   const int lane = TIDX() & 63;
;   const int gw = BIDX() * 4 + (TIDX() >> 6), nw = gridDim.x * 4;
;   const float* mod = (const float*)(p.ws + OFF_MOD);
;   float* xc = (float*)(p.ws + OFF_XC);
;   for (int row = gw; row < nrows; row += nw) {
;     const float* xr = row < TL ? xlat + (size_t)row * 1024 : xctx + (size_t)(row - TL) * 1024;
;     float* xo = row < TL ? p.out + (size_t)row * 1024 : xc + (size_t)(row - TL) * 1024;
;     const int mrow = row < TL ? (row >> 12) : 8;
;     const float* mr = mod + ((size_t)l * 9 + mrow) * 6144;
;     const float* mr2 = mod + ((size_t)l2 * 9 + mrow) * 6144;
;     f32x4 yv[4], xv[4];
;     float ss = 0.f;
; #pragma unroll
;     for (int i = 0; i < 4; ++i) {
;       h16x4 t = *(const h16x4*)(y + (size_t)row * 1024 + lane * 4 + 256 * i);
;       yv[i].x = (float)t.x; yv[i].y = (float)t.y; yv[i].z = (float)t.z; yv[i].w = (float)t.w;
;       ss += yv[i].x * yv[i].x + yv[i].y * yv[i].y + yv[i].z * yv[i].z + yv[i].w * yv[i].w;
;       xv[i] = *(const f32x4*)(xr + lane * 4 + 256 * i);
;     }
;     ss = wave_sum(ss);
;     const float rstd = rsqrtf(ss * (1.f / 1024.f) + EPS);
;     float s2 = 0.f;
; #pragma unroll
;     for (int i = 0; i < 4; ++i) {
;       const int c = lane * 4 + 256 * i;
;       f32x4 g = *(const f32x4*)(post_g + c), gt = *(const f32x4*)(mr + gate_idx * 1024 + c);
;       xv[i].x += gt.x * (yv[i].x * rstd * g.x);
;       xv[i].y += gt.y * (yv[i].y * rstd * g.y);
;       xv[i].z += gt.z * (yv[i].z * rstd * g.z);
;       xv[i].w += gt.w * (yv[i].w * rstd * g.w);
;       *(f32x4*)(xo + c) = xv[i];
;       s2 += xv[i].x * xv[i].x + xv[i].y * xv[i].y + xv[i].z * xv[i].z + xv[i].w * xv[i].w;
;     }
	v_cvt_f32_f16_e32 v226, v18
	v_cvt_f32_f16_sdwa v227, v18 dst_sel:DWORD dst_unused:UNUSED_PAD src0_sel:WORD_1
	v_cvt_f32_f16_e32 v228, v19
	v_cvt_f32_f16_sdwa v229, v19 dst_sel:DWORD dst_unused:UNUSED_PAD src0_sel:WORD_1
	v_cvt_f32_f16_e32 v230, v20
	v_cvt_f32_f16_sdwa v231, v20 dst_sel:DWORD dst_unused:UNUSED_PAD src0_sel:WORD_1
	v_cvt_f32_f16_e32 v232, v21
	v_cvt_f32_f16_sdwa v233, v21 dst_sel:DWORD dst_unused:UNUSED_PAD src0_sel:WORD_1
	v_cvt_f32_f16_e32 v234, v22
	v_cvt_f32_f16_sdwa v235, v22 dst_sel:DWORD dst_unused:UNUSED_PAD src0_sel:WORD_1
	v_cvt_f32_f16_e32 v236, v23
	v_cvt_f32_f16_sdwa v237, v23 dst_sel:DWORD dst_unused:UNUSED_PAD src0_sel:WORD_1
	v_cvt_f32_f16_e32 v238, v24
	v_cvt_f32_f16_sdwa v239, v24 dst_sel:DWORD dst_unused:UNUSED_PAD src0_sel:WORD_1
	v_cvt_f32_f16_e32 v240, v25
	v_cvt_f32_f16_sdwa v241, v25 dst_sel:DWORD dst_unused:UNUSED_PAD src0_sel:WORD_1
	v_mul_f32_e32 v242, v227, v227
	v_mul_f32_e32 v243, v231, v231
	v_mul_f32_e32 v244, v235, v235
	v_mul_f32_e32 v245, v239, v239
	v_fmac_f32_e32 v242, v226, v226
	v_fmac_f32_e32 v243, v230, v230
	v_fmac_f32_e32 v244, v234, v234
	v_fmac_f32_e32 v245, v238, v238
	v_fmac_f32_e32 v242, v228, v228
	v_fmac_f32_e32 v243, v232, v232
	v_fmac_f32_e32 v244, v236, v236
	v_fmac_f32_e32 v245, v240, v240
	v_fmac_f32_e32 v242, v229, v229
	v_fmac_f32_e32 v243, v233, v233
	v_fmac_f32_e32 v244, v237, v237
	v_fmac_f32_e32 v245, v241, v241
	v_add_f32_e32 v242, v242, v243
	v_add_f32_e32 v242, v242, v244
	v_add_f32_e32 v242, v242, v245
	s_nop 1
	v_add_f32_dpp v242, v242, v242 quad_perm:[1,0,3,2] row_mask:0xf bank_mask:0xf bound_ctrl:1
	s_nop 1
	v_add_f32_dpp v242, v242, v242 quad_perm:[2,3,0,1] row_mask:0xf bank_mask:0xf bound_ctrl:1
	s_nop 1
	v_add_f32_dpp v242, v242, v242 row_half_mirror row_mask:0xf bank_mask:0xf bound_ctrl:1
	s_nop 1
	v_add_f32_dpp v242, v242, v242 row_mirror row_mask:0xf bank_mask:0xf bound_ctrl:1
	s_nop 1
	ds_swizzle_b32 v243, v242 offset:swizzle(SWAP,16)
	s_waitcnt lgkmcnt(0)
	v_add_f32_e32 v242, v242, v243
	v_mov_b32_e32 v243, v242
	s_nop 1
	v_permlane32_swap_b32_e32 v242, v243
	v_add_f32_e32 v242, v242, v243
	v_fmamk_f32 v242, v242, 0x3a800000, v224
	v_rsq_f32_e32 v242, v242
	s_waitcnt vmcnt(0)
	v_mul_f32_e32 v226, v226, v242
	v_mul_f32_e32 v227, v227, v242
	v_mul_f32_e32 v228, v228, v242
	v_mul_f32_e32 v229, v229, v242
	v_mul_f32_e32 v230, v230, v242
	v_mul_f32_e32 v231, v231, v242
	v_mul_f32_e32 v232, v232, v242
	v_mul_f32_e32 v233, v233, v242
	v_mul_f32_e32 v234, v234, v242
	v_mul_f32_e32 v235, v235, v242
	v_mul_f32_e32 v236, v236, v242
	v_mul_f32_e32 v237, v237, v242
	v_mul_f32_e32 v238, v238, v242
	v_mul_f32_e32 v239, v239, v242
	v_mul_f32_e32 v240, v240, v242
	v_mul_f32_e32 v241, v241, v242
	v_mul_f32_e32 v226, v80, v226
	v_mul_f32_e32 v227, v81, v227
	v_mul_f32_e32 v228, v82, v228
	v_mul_f32_e32 v229, v83, v229
	v_mul_f32_e32 v230, v84, v230
	v_mul_f32_e32 v231, v85, v231
	v_mul_f32_e32 v232, v86, v232
	v_mul_f32_e32 v233, v87, v233
	v_mul_f32_e32 v234, v88, v234
	v_mul_f32_e32 v235, v89, v235
	v_mul_f32_e32 v236, v90, v236
	v_mul_f32_e32 v237, v91, v237
	v_mul_f32_e32 v238, v92, v238
	v_mul_f32_e32 v239, v93, v239
	v_mul_f32_e32 v240, v94, v240
	v_mul_f32_e32 v241, v95, v241
	v_fmac_f32_e32 v64, v112, v226
	v_fmac_f32_e32 v65, v113, v227
	v_fmac_f32_e32 v66, v114, v228
	v_fmac_f32_e32 v67, v115, v229
	v_fmac_f32_e32 v68, v116, v230
	v_fmac_f32_e32 v69, v117, v231
	v_fmac_f32_e32 v70, v118, v232
	v_fmac_f32_e32 v71, v119, v233
	v_fmac_f32_e32 v72, v120, v234
	v_fmac_f32_e32 v73, v121, v235
	v_fmac_f32_e32 v74, v122, v236
	v_fmac_f32_e32 v75, v123, v237
	v_fmac_f32_e32 v76, v124, v238
	v_fmac_f32_e32 v77, v125, v239
	v_fmac_f32_e32 v78, v126, v240
	v_fmac_f32_e32 v79, v127, v241
	global_store_dwordx4 v0, v[64:67], s[22:23]
	global_store_dwordx4 v0, v[68:71], s[22:23] offset:1024
	global_store_dwordx4 v0, v[72:75], s[22:23] offset:2048
	global_store_dwordx4 v0, v[76:79], s[22:23] offset:3072
	s_add_i32 s58, s58, s8
	s_branch .Lrr2_exit
.Lrr20_tail2:
	s_waitcnt vmcnt(4)
	v_cvt_f32_f16_e32 v226, v18
	v_cvt_f32_f16_sdwa v227, v18 dst_sel:DWORD dst_unused:UNUSED_PAD src0_sel:WORD_1
	v_cvt_f32_f16_e32 v228, v19
	v_cvt_f32_f16_sdwa v229, v19 dst_sel:DWORD dst_unused:UNUSED_PAD src0_sel:WORD_1
	v_cvt_f32_f16_e32 v230, v20
	v_cvt_f32_f16_sdwa v231, v20 dst_sel:DWORD dst_unused:UNUSED_PAD src0_sel:WORD_1
	v_cvt_f32_f16_e32 v232, v21
	v_cvt_f32_f16_sdwa v233, v21 dst_sel:DWORD dst_unused:UNUSED_PAD src0_sel:WORD_1
	v_cvt_f32_f16_e32 v234, v22
	v_cvt_f32_f16_sdwa v235, v22 dst_sel:DWORD dst_unused:UNUSED_PAD src0_sel:WORD_1
	v_cvt_f32_f16_e32 v236, v23
	v_cvt_f32_f16_sdwa v237, v23 dst_sel:DWORD dst_unused:UNUSED_PAD src0_sel:WORD_1
	v_cvt_f32_f16_e32 v238, v24
	v_cvt_f32_f16_sdwa v239, v24 dst_sel:DWORD dst_unused:UNUSED_PAD src0_sel:WORD_1
	v_cvt_f32_f16_e32 v240, v25
	v_cvt_f32_f16_sdwa v241, v25 dst_sel:DWORD dst_unused:UNUSED_PAD src0_sel:WORD_1
	v_mul_f32_e32 v242, v227, v227
	v_mul_f32_e32 v243, v231, v231
	v_mul_f32_e32 v244, v235, v235
	v_mul_f32_e32 v245, v239, v239
	v_fmac_f32_e32 v242, v226, v226
	v_fmac_f32_e32 v243, v230, v230
	v_fmac_f32_e32 v244, v234, v234
	v_fmac_f32_e32 v245, v238, v238
	v_fmac_f32_e32 v242, v228, v228
	v_fmac_f32_e32 v243, v232, v232
	v_fmac_f32_e32 v244, v236, v236
	v_fmac_f32_e32 v245, v240, v240
	v_fmac_f32_e32 v242, v229, v229
	v_fmac_f32_e32 v243, v233, v233
	v_fmac_f32_e32 v244, v237, v237
	v_fmac_f32_e32 v245, v241, v241
	v_add_f32_e32 v242, v242, v243
	v_add_f32_e32 v242, v242, v244
	v_add_f32_e32 v242, v242, v245
	s_nop 1
	v_add_f32_dpp v242, v242, v242 quad_perm:[1,0,3,2] row_mask:0xf bank_mask:0xf bound_ctrl:1
	s_nop 1
	v_add_f32_dpp v242, v242, v242 quad_perm:[2,3,0,1] row_mask:0xf bank_mask:0xf bound_ctrl:1
	s_nop 1
	v_add_f32_dpp v242, v242, v242 row_half_mirror row_mask:0xf bank_mask:0xf bound_ctrl:1
	s_nop 1
	v_add_f32_dpp v242, v242, v242 row_mirror row_mask:0xf bank_mask:0xf bound_ctrl:1
	s_nop 1
	ds_swizzle_b32 v243, v242 offset:swizzle(SWAP,16)
	s_waitcnt lgkmcnt(0)
; DI int TIDX() { int t = threadIdx.x; asm volatile("" : "+v"(t)); return t; }
; DI int BIDX() { int b = blockIdx.x; asm volatile("" : "+s"(b)); return b; }
; DI void rows_resid_norm(const P& p, const float* xlat, const float* xctx, const h16* y, int l, int gate_idx, const float* post_g,
;                         bool do_next, int l2, const float* gain2, int sh_idx, int sc_idx, h16* dst, int nrows) {
;   const int lane = TIDX() & 63;
;   const int gw = BIDX() * 4 + (TIDX() >> 6), nw = gridDim.x * 4;
;   const float* mod = (const float*)(p.ws + OFF_MOD);
;   float* xc = (float*)(p.ws + OFF_XC);
;   for (int row = gw; row < nrows; row += nw) {
;     const float* xr = row < TL ? xlat + (size_t)row * 1024 : xctx + (size_t)(row - TL) * 1024;
;     float* xo = row < TL ? p.out + (size_t)row * 1024 : xc + (size_t)(row - TL) * 1024;
;     const int mrow = row < TL ? (row >> 12) : 8;
;     const float* mr = mod + ((size_t)l * 9 + mrow) * 6144;
;     const float* mr2 = mod + ((size_t)l2 * 9 + mrow) * 6144;
;     f32x4 yv[4], xv[4];
;     float ss = 0.f;
; #pragma unroll
;     for (int i = 0; i < 4; ++i) {
;       h16x4 t = *(const h16x4*)(y + (size_t)row * 1024 + lane * 4 + 256 * i);
;       yv[i].x = (float)t.x; yv[i].y = (float)t.y; yv[i].z = (float)t.z; yv[i].w = (float)t.w;
;       ss += yv[i].x * yv[i].x + yv[i].y * yv[i].y + yv[i].z * yv[i].z + yv[i].w * yv[i].w;
;       xv[i] = *(const f32x4*)(xr + lane * 4 + 256 * i);
;     }
;     ss = wave_sum(ss);
;     const float rstd = rsqrtf(ss * (1.f / 1024.f) + EPS);
;     float s2 = 0.f;
; #pragma unroll
;     for (int i = 0; i < 4; ++i) {
;       const int c = lane * 4 + 256 * i;
;       f32x4 g = *(const f32x4*)(post_g + c), gt = *(const f32x4*)(mr + gate_idx * 1024 + c);
;       xv[i].x += gt.x * (yv[i].x * rstd * g.x);
;       xv[i].y += gt.y * (yv[i].y * rstd * g.y);
;       xv[i].z += gt.z * (yv[i].z * rstd * g.z);
;       xv[i].w += gt.w * (yv[i].w * rstd * g.w);
;       *(f32x4*)(xo + c) = xv[i];
;       s2 += xv[i].x * xv[i].x + xv[i].y * xv[i].y + xv[i].z * xv[i].z + xv[i].w * xv[i].w;
;     }
	v_add_f32_e32 v242, v242, v243
	v_mov_b32_e32 v243, v242
	s_nop 1
	v_permlane32_swap_b32_e32 v242, v243
	v_add_f32_e32 v242, v242, v243
	v_fmamk_f32 v242, v242, 0x3a800000, v224
	v_rsq_f32_e32 v242, v242
	s_waitcnt vmcnt(0)
	v_mul_f32_e32 v226, v226, v242
	v_mul_f32_e32 v227, v227, v242
	v_mul_f32_e32 v228, v228, v242
	v_mul_f32_e32 v229, v229, v242
	v_mul_f32_e32 v230, v230, v242
	v_mul_f32_e32 v231, v231, v242
	v_mul_f32_e32 v232, v232, v242
	v_mul_f32_e32 v233, v233, v242
	v_mul_f32_e32 v234, v234, v242
	v_mul_f32_e32 v235, v235, v242
	v_mul_f32_e32 v236, v236, v242
	v_mul_f32_e32 v237, v237, v242
	v_mul_f32_e32 v238, v238, v242
	v_mul_f32_e32 v239, v239, v242
	v_mul_f32_e32 v240, v240, v242
	v_mul_f32_e32 v241, v241, v242
	v_mul_f32_e32 v226, v80, v226
	v_mul_f32_e32 v227, v81, v227
	v_mul_f32_e32 v228, v82, v228
	v_mul_f32_e32 v229, v83, v229
	v_mul_f32_e32 v230, v84, v230
	v_mul_f32_e32 v231, v85, v231
	v_mul_f32_e32 v232, v86, v232
	v_mul_f32_e32 v233, v87, v233
	v_mul_f32_e32 v234, v88, v234
	v_mul_f32_e32 v235, v89, v235
	v_mul_f32_e32 v236, v90, v236
	v_mul_f32_e32 v237, v91, v237
	v_mul_f32_e32 v238, v92, v238
	v_mul_f32_e32 v239, v93, v239
	v_mul_f32_e32 v240, v94, v240
	v_mul_f32_e32 v241, v95, v241
	v_fmac_f32_e32 v64, v112, v226
	v_fmac_f32_e32 v65, v113, v227
	v_fmac_f32_e32 v66, v114, v228
	v_fmac_f32_e32 v67, v115, v229
	v_fmac_f32_e32 v68, v116, v230
	v_fmac_f32_e32 v69, v117, v231
	v_fmac_f32_e32 v70, v118, v232
	v_fmac_f32_e32 v71, v119, v233
	v_fmac_f32_e32 v72, v120, v234
	v_fmac_f32_e32 v73, v121, v235
	v_fmac_f32_e32 v74, v122, v236
	v_fmac_f32_e32 v75, v123, v237
	v_fmac_f32_e32 v76, v124, v238
	v_fmac_f32_e32 v77, v125, v239
	v_fmac_f32_e32 v78, v126, v240
	v_fmac_f32_e32 v79, v127, v241
	global_store_dwordx4 v0, v[64:67], s[22:23]
	global_store_dwordx4 v0, v[68:71], s[22:23] offset:1024
	global_store_dwordx4 v0, v[72:75], s[22:23] offset:2048
	global_store_dwordx4 v0, v[76:79], s[22:23] offset:3072
	s_add_i32 s58, s58, s8
	s_cmp_lt_i32 s58, s36
	s_cbranch_scc0 .Lrr2_exit
	s_lshr_b32 s59, s58, 12
	s_cmp_lt_u32 s58, 0x8000
	s_cselect_b32 s59, s59, 8
	s_mul_i32 s59, s59, 0x6000
	s_add_u32 s24, s42, s59
	s_addc_u32 s25, s43, 0
	s_sub_u32 s60, s58, 0x8000
	s_cmp_lt_u32 s58, 0x8000
	s_cselect_b32 s60, s58, s60
	s_cselect_b32 s22, s46, s50
	s_cselect_b32 s23, s47, s51
	s_lshl_b32 s60, s60, 12
	s_add_u32 s22, s22, s60
	s_addc_u32 s23, s23, 0
	global_load_dwordx4 v[112:115], v0, s[24:25]
	global_load_dwordx4 v[116:119], v0, s[24:25] offset:1024
	global_load_dwordx4 v[120:123], v0, s[24:25] offset:2048
	global_load_dwordx4 v[124:127], v0, s[24:25] offset:3072
	s_waitcnt vmcnt(4)
	v_cvt_f32_f16_e32 v226, v2
	v_cvt_f32_f16_sdwa v227, v2 dst_sel:DWORD dst_unused:UNUSED_PAD src0_sel:WORD_1
	v_cvt_f32_f16_e32 v228, v3
	v_cvt_f32_f16_sdwa v229, v3 dst_sel:DWORD dst_unused:UNUSED_PAD src0_sel:WORD_1
	v_cvt_f32_f16_e32 v230, v4
	v_cvt_f32_f16_sdwa v231, v4 dst_sel:DWORD dst_unused:UNUSED_PAD src0_sel:WORD_1
	v_cvt_f32_f16_e32 v232, v5
	v_cvt_f32_f16_sdwa v233, v5 dst_sel:DWORD dst_unused:UNUSED_PAD src0_sel:WORD_1
	v_cvt_f32_f16_e32 v234, v6
	v_cvt_f32_f16_sdwa v235, v6 dst_sel:DWORD dst_unused:UNUSED_PAD src0_sel:WORD_1
	v_cvt_f32_f16_e32 v236, v7
	v_cvt_f32_f16_sdwa v237, v7 dst_sel:DWORD dst_unused:UNUSED_PAD src0_sel:WORD_1
	v_cvt_f32_f16_e32 v238, v8
	v_cvt_f32_f16_sdwa v239, v8 dst_sel:DWORD dst_unused:UNUSED_PAD src0_sel:WORD_1
	v_cvt_f32_f16_e32 v240, v9
	v_cvt_f32_f16_sdwa v241, v9 dst_sel:DWORD dst_unused:UNUSED_PAD src0_sel:WORD_1
	v_mul_f32_e32 v242, v227, v227
	v_mul_f32_e32 v243, v231, v231
	v_mul_f32_e32 v244, v235, v235
	v_mul_f32_e32 v245, v239, v239
	v_fmac_f32_e32 v242, v226, v226
	v_fmac_f32_e32 v243, v230, v230
	v_fmac_f32_e32 v244, v234, v234
	v_fmac_f32_e32 v245, v238, v238
	v_fmac_f32_e32 v242, v228, v228
	v_fmac_f32_e32 v243, v232, v232
	v_fmac_f32_e32 v244, v236, v236
	v_fmac_f32_e32 v245, v240, v240
	v_fmac_f32_e32 v242, v229, v229
	v_fmac_f32_e32 v243, v233, v233
	v_fmac_f32_e32 v244, v237, v237
	v_fmac_f32_e32 v245, v241, v241
	v_add_f32_e32 v242, v242, v243
	v_add_f32_e32 v242, v242, v244
	v_add_f32_e32 v242, v242, v245
	s_nop 1
	v_add_f32_dpp v242, v242, v242 quad_perm:[1,0,3,2] row_mask:0xf bank_mask:0xf bound_ctrl:1
	s_nop 1
	v_add_f32_dpp v242, v242, v242 quad_perm:[2,3,0,1] row_mask:0xf bank_mask:0xf bound_ctrl:1
	s_nop 1
	v_add_f32_dpp v242, v242, v242 row_half_mirror row_mask:0xf bank_mask:0xf bound_ctrl:1
	s_nop 1
	v_add_f32_dpp v242, v242, v242 row_mirror row_mask:0xf bank_mask:0xf bound_ctrl:1
	s_nop 1
	ds_swizzle_b32 v243, v242 offset:swizzle(SWAP,16)
	s_waitcnt lgkmcnt(0)
	v_add_f32_e32 v242, v242, v243
	v_mov_b32_e32 v243, v242
	s_nop 1
	v_permlane32_swap_b32_e32 v242, v243
	v_add_f32_e32 v242, v242, v243
	v_fmamk_f32 v242, v242, 0x3a800000, v224
	v_rsq_f32_e32 v242, v242
	s_waitcnt vmcnt(0)
	v_mul_f32_e32 v226, v226, v242
	v_mul_f32_e32 v227, v227, v242
	v_mul_f32_e32 v228, v228, v242
	v_mul_f32_e32 v229, v229, v242
	v_mul_f32_e32 v230, v230, v242
	v_mul_f32_e32 v231, v231, v242
	v_mul_f32_e32 v232, v232, v242
	v_mul_f32_e32 v233, v233, v242
	v_mul_f32_e32 v234, v234, v242
	v_mul_f32_e32 v235, v235, v242
	v_mul_f32_e32 v236, v236, v242
	v_mul_f32_e32 v237, v237, v242
	v_mul_f32_e32 v238, v238, v242
	v_mul_f32_e32 v239, v239, v242
	v_mul_f32_e32 v240, v240, v242
	v_mul_f32_e32 v241, v241, v242
	v_mul_f32_e32 v226, v80, v226
	v_mul_f32_e32 v227, v81, v227
	v_mul_f32_e32 v228, v82, v228
	v_mul_f32_e32 v229, v83, v229
	v_mul_f32_e32 v230, v84, v230
	v_mul_f32_e32 v231, v85, v231
	v_mul_f32_e32 v232, v86, v232
	v_mul_f32_e32 v233, v87, v233
	v_mul_f32_e32 v234, v88, v234
	v_mul_f32_e32 v235, v89, v235
	v_mul_f32_e32 v236, v90, v236
	v_mul_f32_e32 v237, v91, v237
	v_mul_f32_e32 v238, v92, v238
	v_mul_f32_e32 v239, v93, v239
	v_mul_f32_e32 v240, v94, v240
	v_mul_f32_e32 v241, v95, v241
	v_fmac_f32_e32 v32, v112, v226
	v_fmac_f32_e32 v33, v113, v227
	v_fmac_f32_e32 v34, v114, v228
	v_fmac_f32_e32 v35, v115, v229
	v_fmac_f32_e32 v36, v116, v230
	v_fmac_f32_e32 v37, v117, v231
	v_fmac_f32_e32 v38, v118, v232
	v_fmac_f32_e32 v39, v119, v233
	v_fmac_f32_e32 v40, v120, v234
	v_fmac_f32_e32 v41, v121, v235
	v_fmac_f32_e32 v42, v122, v236
	v_fmac_f32_e32 v43, v123, v237
	v_fmac_f32_e32 v44, v124, v238
	v_fmac_f32_e32 v45, v125, v239
	v_fmac_f32_e32 v46, v126, v240
	v_fmac_f32_e32 v47, v127, v241
	global_store_dwordx4 v0, v[32:35], s[22:23]
	global_store_dwordx4 v0, v[36:39], s[22:23] offset:1024
	global_store_dwordx4 v0, v[40:43], s[22:23] offset:2048
	global_store_dwordx4 v0, v[44:47], s[22:23] offset:3072
	s_add_i32 s58, s58, s8
	s_branch .Lrr2_exit
; DI void rows_resid_norm(const P& p, const float* xlat, const float* xctx, const h16* y, int l, int gate_idx, const float* post_g,
;                         bool do_next, int l2, const float* gain2, int sh_idx, int sc_idx, h16* dst, int nrows) {
;   const int lane = TIDX() & 63;
;   const int gw = BIDX() * 4 + (TIDX() >> 6), nw = gridDim.x * 4;
;   const float* mod = (const float*)(p.ws + OFF_MOD);
;   float* xc = (float*)(p.ws + OFF_XC);
;   for (int row = gw; row < nrows; row += nw) {
;     const float* xr = row < TL ? xlat + (size_t)row * 1024 : xctx + (size_t)(row - TL) * 1024;
;     float* xo = row < TL ? p.out + (size_t)row * 1024 : xc + (size_t)(row - TL) * 1024;
;     const int mrow = row < TL ? (row >> 12) : 8;
;     const float* mr = mod + ((size_t)l * 9 + mrow) * 6144;
;     const float* mr2 = mod + ((size_t)l2 * 9 + mrow) * 6144;
;     f32x4 yv[4], xv[4];
;     float ss = 0.f;
; #pragma unroll
;     for (int i = 0; i < 4; ++i) {
;       h16x4 t = *(const h16x4*)(y + (size_t)row * 1024 + lane * 4 + 256 * i);
;       yv[i].x = (float)t.x; yv[i].y = (float)t.y; yv[i].z = (float)t.z; yv[i].w = (float)t.w;
;       ss += yv[i].x * yv[i].x + yv[i].y * yv[i].y + yv[i].z * yv[i].z + yv[i].w * yv[i].w;
;       xv[i] = *(const f32x4*)(xr + lane * 4 + 256 * i);
;     }
;     ss = wave_sum(ss);
;     const float rstd = rsqrtf(ss * (1.f / 1024.f) + EPS);
;     float s2 = 0.f;
; #pragma unroll
;     for (int i = 0; i < 4; ++i) {
;       const int c = lane * 4 + 256 * i;
;       f32x4 g = *(const f32x4*)(post_g + c), gt = *(const f32x4*)(mr + gate_idx * 1024 + c);
;       xv[i].x += gt.x * (yv[i].x * rstd * g.x);
;       xv[i].y += gt.y * (yv[i].y * rstd * g.y);
;       xv[i].z += gt.z * (yv[i].z * rstd * g.z);
;       xv[i].w += gt.w * (yv[i].w * rstd * g.w);
;       *(f32x4*)(xo + c) = xv[i];
;       s2 += xv[i].x * xv[i].x + xv[i].y * xv[i].y + xv[i].z * xv[i].z + xv[i].w * xv[i].w;
;     }
;     if (do_next) {
;       s2 = wave_sum(s2);
;       const float r2 = rsqrtf(s2 * (1.f / 1024.f) + EPS);
; #pragma unroll
;       for (int i = 0; i < 4; ++i) {
;         const int c = lane * 4 + 256 * i;
;         f32x4 g = *(const f32x4*)(gain2 + c), sc = *(const f32x4*)(mr2 + sc_idx * 1024 + c), sh = *(const f32x4*)(mr2 + sh_idx * 1024 + c);
;         h16x4 o;
;         o.x = (h16)(xv[i].x * r2 * g.x * (1.f + sc.x) + sh.x);
.Lrr21_start:
	global_load_dwordx4 v[96:99], v0, s[52:53]
	global_load_dwordx4 v[100:103], v0, s[52:53] offset:1024
	global_load_dwordx4 v[104:107], v0, s[52:53] offset:2048
	global_load_dwordx4 v[108:111], v0, s[52:53] offset:3072
	s_lshl_b32 s59, s58, 11
	s_add_u32 s20, s44, s59
	s_addc_u32 s21, s45, 0
	s_sub_u32 s60, s58, 0x8000
	s_cmp_lt_u32 s58, 0x8000
	s_cselect_b32 s60, s58, s60
	s_cselect_b32 s12, s46, s50
	s_cselect_b32 s13, s47, s51
	s_lshl_b32 s60, s60, 12
	s_add_u32 s12, s12, s60
	s_addc_u32 s13, s13, 0
	global_load_dwordx2 v[2:3], v202, s[20:21]
	global_load_dwordx2 v[4:5], v202, s[20:21] offset:512
	global_load_dwordx2 v[6:7], v202, s[20:21] offset:1024
	global_load_dwordx2 v[8:9], v202, s[20:21] offset:1536
	global_load_dwordx4 v[32:35], v0, s[12:13]
	global_load_dwordx4 v[36:39], v0, s[12:13] offset:1024
	global_load_dwordx4 v[40:43], v0, s[12:13] offset:2048
	global_load_dwordx4 v[44:47], v0, s[12:13] offset:3072
	s_add_i32 s61, s58, s8
	s_cmp_lt_i32 s61, s36
	s_cbranch_scc0 .Lrr21_pre0
	s_lshl_b32 s59, s61, 11
	s_add_u32 s20, s44, s59
	s_addc_u32 s21, s45, 0
	s_sub_u32 s60, s61, 0x8000
	s_cmp_lt_u32 s61, 0x8000
	s_cselect_b32 s60, s61, s60
	s_cselect_b32 s12, s46, s50
	s_cselect_b32 s13, s47, s51
	s_lshl_b32 s60, s60, 12
	s_add_u32 s12, s12, s60
	s_addc_u32 s13, s13, 0
	global_load_dwordx2 v[10:11], v202, s[20:21]
	global_load_dwordx2 v[12:13], v202, s[20:21] offset:512
	global_load_dwordx2 v[14:15], v202, s[20:21] offset:1024
	global_load_dwordx2 v[16:17], v202, s[20:21] offset:1536
	global_load_dwordx4 v[48:51], v0, s[12:13]
	global_load_dwordx4 v[52:55], v0, s[12:13] offset:1024
	global_load_dwordx4 v[56:59], v0, s[12:13] offset:2048
	global_load_dwordx4 v[60:63], v0, s[12:13] offset:3072
.Lrr21_pre0:
	s_lshr_b32 s59, s58, 12
	s_cmp_lt_u32 s58, 0x8000
	s_cselect_b32 s59, s59, 8
	s_mul_i32 s59, s59, 0x6000
	s_add_u32 s24, s42, s59
	s_addc_u32 s25, s43, 0
	s_add_u32 s18, s54, s59
	s_addc_u32 s19, s55, 0
	s_add_u32 s34, s18, 0x1000
	s_addc_u32 s35, s19, 0
	s_lshl_b32 s59, s58, 11
	s_add_u32 s40, s56, s59
	s_addc_u32 s41, s57, 0
	s_sub_u32 s60, s58, 0x8000
	s_cmp_lt_u32 s58, 0x8000
	s_cselect_b32 s60, s58, s60
	s_cselect_b32 s22, s46, s50
	s_cselect_b32 s23, s47, s51
	s_lshl_b32 s60, s60, 12
	s_add_u32 s22, s22, s60
	s_addc_u32 s23, s23, 0
	global_load_dwordx4 v[112:115], v0, s[24:25]
	global_load_dwordx4 v[116:119], v0, s[24:25] offset:1024
	global_load_dwordx4 v[120:123], v0, s[24:25] offset:2048
	global_load_dwordx4 v[124:127], v0, s[24:25] offset:3072
	global_load_dwordx4 v[162:165], v0, s[34:35]
	global_load_dwordx4 v[166:169], v0, s[34:35] offset:1024
	global_load_dwordx4 v[170:173], v0, s[34:35] offset:2048
	global_load_dwordx4 v[174:177], v0, s[34:35] offset:3072
	global_load_dwordx4 v[178:181], v0, s[18:19]
	global_load_dwordx4 v[182:185], v0, s[18:19] offset:1024
	global_load_dwordx4 v[186:189], v0, s[18:19] offset:2048
	global_load_dwordx4 v[190:193], v0, s[18:19] offset:3072
	s_add_i32 s62, s58, s8
	s_add_i32 s62, s62, s8
	s_cmp_lt_i32 s62, s36
	s_cbranch_scc0 .Lrr21_tail0
	s_lshl_b32 s59, s62, 11
	s_add_u32 s20, s44, s59
	s_addc_u32 s21, s45, 0
	s_sub_u32 s60, s62, 0x8000
	s_cmp_lt_u32 s62, 0x8000
	s_cselect_b32 s60, s62, s60
	s_cselect_b32 s12, s46, s50
	s_cselect_b32 s13, s47, s51
	s_lshl_b32 s60, s60, 12
	s_add_u32 s12, s12, s60
	s_addc_u32 s13, s13, 0
	global_load_dwordx2 v[18:19], v202, s[20:21]
	global_load_dwordx2 v[20:21], v202, s[20:21] offset:512
	global_load_dwordx2 v[22:23], v202, s[20:21] offset:1024
	global_load_dwordx2 v[24:25], v202, s[20:21] offset:1536
	global_load_dwordx4 v[64:67], v0, s[12:13]
	global_load_dwordx4 v[68:71], v0, s[12:13] offset:1024
	global_load_dwordx4 v[72:75], v0, s[12:13] offset:2048
	global_load_dwordx4 v[76:79], v0, s[12:13] offset:3072
	s_waitcnt vmcnt(28)
	v_cvt_f32_f16_e32 v226, v2
	v_cvt_f32_f16_sdwa v227, v2 dst_sel:DWORD dst_unused:UNUSED_PAD src0_sel:WORD_1
	v_cvt_f32_f16_e32 v228, v3
	v_cvt_f32_f16_sdwa v229, v3 dst_sel:DWORD dst_unused:UNUSED_PAD src0_sel:WORD_1
	v_cvt_f32_f16_e32 v230, v4
	v_cvt_f32_f16_sdwa v231, v4 dst_sel:DWORD dst_unused:UNUSED_PAD src0_sel:WORD_1
	v_cvt_f32_f16_e32 v232, v5
	v_cvt_f32_f16_sdwa v233, v5 dst_sel:DWORD dst_unused:UNUSED_PAD src0_sel:WORD_1
	v_cvt_f32_f16_e32 v234, v6
	v_cvt_f32_f16_sdwa v235, v6 dst_sel:DWORD dst_unused:UNUSED_PAD src0_sel:WORD_1
	v_cvt_f32_f16_e32 v236, v7
	v_cvt_f32_f16_sdwa v237, v7 dst_sel:DWORD dst_unused:UNUSED_PAD src0_sel:WORD_1
	v_cvt_f32_f16_e32 v238, v8
	v_cvt_f32_f16_sdwa v239, v8 dst_sel:DWORD dst_unused:UNUSED_PAD src0_sel:WORD_1
	v_cvt_f32_f16_e32 v240, v9
	v_cvt_f32_f16_sdwa v241, v9 dst_sel:DWORD dst_unused:UNUSED_PAD src0_sel:WORD_1
	v_mul_f32_e32 v242, v227, v227
	v_mul_f32_e32 v243, v231, v231
	v_mul_f32_e32 v244, v235, v235
	v_mul_f32_e32 v245, v239, v239
	v_fmac_f32_e32 v242, v226, v226
	v_fmac_f32_e32 v243, v230, v230
	v_fmac_f32_e32 v244, v234, v234
	v_fmac_f32_e32 v245, v238, v238
	v_fmac_f32_e32 v242, v228, v228
	v_fmac_f32_e32 v243, v232, v232
	v_fmac_f32_e32 v244, v236, v236
	v_fmac_f32_e32 v245, v240, v240
	v_fmac_f32_e32 v242, v229, v229
	v_fmac_f32_e32 v243, v233, v233
	v_fmac_f32_e32 v244, v237, v237
	v_fmac_f32_e32 v245, v241, v241
	v_add_f32_e32 v242, v242, v243
	v_add_f32_e32 v242, v242, v244
	v_add_f32_e32 v242, v242, v245
	s_nop 1
	v_add_f32_dpp v242, v242, v242 quad_perm:[1,0,3,2] row_mask:0xf bank_mask:0xf bound_ctrl:1
	s_nop 1
	v_add_f32_dpp v242, v242, v242 quad_perm:[2,3,0,1] row_mask:0xf bank_mask:0xf bound_ctrl:1
	s_nop 1
	v_add_f32_dpp v242, v242, v242 row_half_mirror row_mask:0xf bank_mask:0xf bound_ctrl:1
	s_nop 1
	v_add_f32_dpp v242, v242, v242 row_mirror row_mask:0xf bank_mask:0xf bound_ctrl:1
	s_nop 1
	ds_swizzle_b32 v243, v242 offset:swizzle(SWAP,16)
	s_waitcnt lgkmcnt(0)
; DI void rows_resid_norm(const P& p, const float* xlat, const float* xctx, const h16* y, int l, int gate_idx, const float* post_g,
;                         bool do_next, int l2, const float* gain2, int sh_idx, int sc_idx, h16* dst, int nrows) {
;   const int lane = TIDX() & 63;
;   const int gw = BIDX() * 4 + (TIDX() >> 6), nw = gridDim.x * 4;
;   const float* mod = (const float*)(p.ws + OFF_MOD);
;   float* xc = (float*)(p.ws + OFF_XC);
;   for (int row = gw; row < nrows; row += nw) {
;     const float* xr = row < TL ? xlat + (size_t)row * 1024 : xctx + (size_t)(row - TL) * 1024;
;     float* xo = row < TL ? p.out + (size_t)row * 1024 : xc + (size_t)(row - TL) * 1024;
;     const int mrow = row < TL ? (row >> 12) : 8;
;     const float* mr = mod + ((size_t)l * 9 + mrow) * 6144;
;     const float* mr2 = mod + ((size_t)l2 * 9 + mrow) * 6144;
;     f32x4 yv[4], xv[4];
;     float ss = 0.f;
; #pragma unroll
;     for (int i = 0; i < 4; ++i) {
;       h16x4 t = *(const h16x4*)(y + (size_t)row * 1024 + lane * 4 + 256 * i);
;       yv[i].x = (float)t.x; yv[i].y = (float)t.y; yv[i].z = (float)t.z; yv[i].w = (float)t.w;
;       ss += yv[i].x * yv[i].x + yv[i].y * yv[i].y + yv[i].z * yv[i].z + yv[i].w * yv[i].w;
;       xv[i] = *(const f32x4*)(xr + lane * 4 + 256 * i);
;     }
;     ss = wave_sum(ss);
;     const float rstd = rsqrtf(ss * (1.f / 1024.f) + EPS);
;     float s2 = 0.f;
; #pragma unroll
;     for (int i = 0; i < 4; ++i) {
;       const int c = lane * 4 + 256 * i;
;       f32x4 g = *(const f32x4*)(post_g + c), gt = *(const f32x4*)(mr + gate_idx * 1024 + c);
;       xv[i].x += gt.x * (yv[i].x * rstd * g.x);
;       xv[i].y += gt.y * (yv[i].y * rstd * g.y);
;       xv[i].z += gt.z * (yv[i].z * rstd * g.z);
;       xv[i].w += gt.w * (yv[i].w * rstd * g.w);
;       *(f32x4*)(xo + c) = xv[i];
;       s2 += xv[i].x * xv[i].x + xv[i].y * xv[i].y + xv[i].z * xv[i].z + xv[i].w * xv[i].w;
;     }
;     if (do_next) {
;       s2 = wave_sum(s2);
;       const float r2 = rsqrtf(s2 * (1.f / 1024.f) + EPS);
; #pragma unroll
;       for (int i = 0; i < 4; ++i) {
;         const int c = lane * 4 + 256 * i;
;         f32x4 g = *(const f32x4*)(gain2 + c), sc = *(const f32x4*)(mr2 + sc_idx * 1024 + c), sh = *(const f32x4*)(mr2 + sh_idx * 1024 + c);
;         h16x4 o;
;         o.x = (h16)(xv[i].x * r2 * g.x * (1.f + sc.x) + sh.x);
	v_add_f32_e32 v242, v242, v243
	v_mov_b32_e32 v243, v242
	s_nop 1
	v_permlane32_swap_b32_e32 v242, v243
	v_add_f32_e32 v242, v242, v243
	v_fmamk_f32 v242, v242, 0x3a800000, v224
	v_rsq_f32_e32 v242, v242
	s_waitcnt vmcnt(8)
	v_mul_f32_e32 v226, v226, v242
	v_mul_f32_e32 v227, v227, v242
	v_mul_f32_e32 v228, v228, v242
	v_mul_f32_e32 v229, v229, v242
	v_mul_f32_e32 v230, v230, v242
	v_mul_f32_e32 v231, v231, v242
	v_mul_f32_e32 v232, v232, v242
	v_mul_f32_e32 v233, v233, v242
	v_mul_f32_e32 v234, v234, v242
	v_mul_f32_e32 v235, v235, v242
	v_mul_f32_e32 v236, v236, v242
	v_mul_f32_e32 v237, v237, v242
	v_mul_f32_e32 v238, v238, v242
	v_mul_f32_e32 v239, v239, v242
	v_mul_f32_e32 v240, v240, v242
	v_mul_f32_e32 v241, v241, v242
	v_mul_f32_e32 v226, v80, v226
	v_mul_f32_e32 v227, v81, v227
	v_mul_f32_e32 v228, v82, v228
	v_mul_f32_e32 v229, v83, v229
	v_mul_f32_e32 v230, v84, v230
	v_mul_f32_e32 v231, v85, v231
	v_mul_f32_e32 v232, v86, v232
	v_mul_f32_e32 v233, v87, v233
	v_mul_f32_e32 v234, v88, v234
	v_mul_f32_e32 v235, v89, v235
	v_mul_f32_e32 v236, v90, v236
	v_mul_f32_e32 v237, v91, v237
	v_mul_f32_e32 v238, v92, v238
	v_mul_f32_e32 v239, v93, v239
	v_mul_f32_e32 v240, v94, v240
	v_mul_f32_e32 v241, v95, v241
	v_fmac_f32_e32 v32, v112, v226
	v_fmac_f32_e32 v33, v113, v227
	v_fmac_f32_e32 v34, v114, v228
	v_fmac_f32_e32 v35, v115, v229
	v_fmac_f32_e32 v36, v116, v230
	v_fmac_f32_e32 v37, v117, v231
	v_fmac_f32_e32 v38, v118, v232
	v_fmac_f32_e32 v39, v119, v233
	v_fmac_f32_e32 v40, v120, v234
	v_fmac_f32_e32 v41, v121, v235
	v_fmac_f32_e32 v42, v122, v236
	v_fmac_f32_e32 v43, v123, v237
	v_fmac_f32_e32 v44, v124, v238
	v_fmac_f32_e32 v45, v125, v239
	v_fmac_f32_e32 v46, v126, v240
	v_fmac_f32_e32 v47, v127, v241
	global_store_dwordx4 v0, v[32:35], s[22:23]
	global_store_dwordx4 v0, v[36:39], s[22:23] offset:1024
	global_store_dwordx4 v0, v[40:43], s[22:23] offset:2048
	global_store_dwordx4 v0, v[44:47], s[22:23] offset:3072
	v_mul_f32_e32 v242, v33, v33
	v_mul_f32_e32 v243, v37, v37
	v_mul_f32_e32 v244, v41, v41
	v_mul_f32_e32 v245, v45, v45
	v_fmac_f32_e32 v242, v32, v32
	v_fmac_f32_e32 v243, v36, v36
	v_fmac_f32_e32 v244, v40, v40
	v_fmac_f32_e32 v245, v44, v44
	v_fmac_f32_e32 v242, v34, v34
	v_fmac_f32_e32 v243, v38, v38
	v_fmac_f32_e32 v244, v42, v42
	v_fmac_f32_e32 v245, v46, v46
	v_fmac_f32_e32 v242, v35, v35
	v_fmac_f32_e32 v243, v39, v39
	v_fmac_f32_e32 v244, v43, v43
	v_fmac_f32_e32 v245, v47, v47
	v_add_f32_e32 v242, v242, v243
	v_add_f32_e32 v242, v242, v244
	v_add_f32_e32 v242, v242, v245
	s_nop 1
	v_add_f32_dpp v242, v242, v242 quad_perm:[1,0,3,2] row_mask:0xf bank_mask:0xf bound_ctrl:1
	s_nop 1
	v_add_f32_dpp v242, v242, v242 quad_perm:[2,3,0,1] row_mask:0xf bank_mask:0xf bound_ctrl:1
	s_nop 1
	v_add_f32_dpp v242, v242, v242 row_half_mirror row_mask:0xf bank_mask:0xf bound_ctrl:1
	s_nop 1
	v_add_f32_dpp v242, v242, v242 row_mirror row_mask:0xf bank_mask:0xf bound_ctrl:1
	s_nop 1
	ds_swizzle_b32 v243, v242 offset:swizzle(SWAP,16)
	s_waitcnt lgkmcnt(0)
	v_add_f32_e32 v242, v242, v243
	v_mov_b32_e32 v243, v242
	s_nop 1
	v_permlane32_swap_b32_e32 v242, v243
	v_add_f32_e32 v242, v242, v243
	v_fmamk_f32 v242, v242, 0x3a800000, v224
	v_rsq_f32_e32 v242, v242
	s_nop 0
	v_mul_f32_e32 v226, v32, v242
	v_mul_f32_e32 v227, v33, v242
	v_mul_f32_e32 v228, v34, v242
	v_mul_f32_e32 v229, v35, v242
	v_mul_f32_e32 v230, v36, v242
	v_mul_f32_e32 v231, v37, v242
	v_mul_f32_e32 v232, v38, v242
	v_mul_f32_e32 v233, v39, v242
	v_mul_f32_e32 v234, v40, v242
	v_mul_f32_e32 v235, v41, v242
	v_mul_f32_e32 v236, v42, v242
	v_mul_f32_e32 v237, v43, v242
	v_mul_f32_e32 v238, v44, v242
	v_mul_f32_e32 v239, v45, v242
	v_mul_f32_e32 v240, v46, v242
	v_mul_f32_e32 v241, v47, v242
	v_mul_f32_e32 v226, v96, v226
	v_mul_f32_e32 v227, v97, v227
	v_mul_f32_e32 v228, v98, v228
	v_mul_f32_e32 v229, v99, v229
	v_mul_f32_e32 v230, v100, v230
	v_mul_f32_e32 v231, v101, v231
	v_mul_f32_e32 v232, v102, v232
	v_mul_f32_e32 v233, v103, v233
	v_mul_f32_e32 v234, v104, v234
	v_mul_f32_e32 v235, v105, v235
	v_mul_f32_e32 v236, v106, v236
	v_mul_f32_e32 v237, v107, v237
	v_mul_f32_e32 v238, v108, v238
	v_mul_f32_e32 v239, v109, v239
	v_mul_f32_e32 v240, v110, v240
	v_mul_f32_e32 v241, v111, v241
	v_add_f32_e32 v162, 1.0, v162
	v_add_f32_e32 v163, 1.0, v163
	v_add_f32_e32 v164, 1.0, v164
	v_add_f32_e32 v165, 1.0, v165
	v_add_f32_e32 v166, 1.0, v166
	v_add_f32_e32 v167, 1.0, v167
	v_add_f32_e32 v168, 1.0, v168
	v_add_f32_e32 v169, 1.0, v169
	v_add_f32_e32 v170, 1.0, v170
	v_add_f32_e32 v171, 1.0, v171
	v_add_f32_e32 v172, 1.0, v172
	v_add_f32_e32 v173, 1.0, v173
	v_add_f32_e32 v174, 1.0, v174
	v_add_f32_e32 v175, 1.0, v175
	v_add_f32_e32 v176, 1.0, v176
	v_add_f32_e32 v177, 1.0, v177
	v_fma_f32 v226, v162, v226, v178
	v_fma_f32 v227, v163, v227, v179
	v_fma_f32 v228, v164, v228, v180
	v_fma_f32 v229, v165, v229, v181
	v_fma_f32 v230, v166, v230, v182
	v_fma_f32 v231, v167, v231, v183
	v_fma_f32 v232, v168, v232, v184
	v_fma_f32 v233, v169, v233, v185
	v_fma_f32 v234, v170, v234, v186
	v_fma_f32 v235, v171, v235, v187
	v_fma_f32 v236, v172, v236, v188
	v_fma_f32 v237, v173, v237, v189
	v_fma_f32 v238, v174, v238, v190
	v_fma_f32 v239, v175, v239, v191
	v_fma_f32 v240, v176, v240, v192
	v_fma_f32 v241, v177, v241, v193
	v_cvt_pk_f16_f32 v244, v226, v227
	v_cvt_pk_f16_f32 v245, v228, v229
	v_cvt_pk_f16_f32 v246, v230, v231
	v_cvt_pk_f16_f32 v247, v232, v233
	v_cvt_pk_f16_f32 v248, v234, v235
	v_cvt_pk_f16_f32 v249, v236, v237
	v_cvt_pk_f16_f32 v250, v238, v239
	v_cvt_pk_f16_f32 v251, v240, v241
	global_store_dwordx2 v202, v[244:245], s[40:41]
	global_store_dwordx2 v202, v[246:247], s[40:41] offset:512
	global_store_dwordx2 v202, v[248:249], s[40:41] offset:1024
	global_store_dwordx2 v202, v[250:251], s[40:41] offset:1536
	s_add_i32 s58, s58, s8
; DI void rows_resid_norm(const P& p, const float* xlat, const float* xctx, const h16* y, int l, int gate_idx, const float* post_g,
;                         bool do_next, int l2, const float* gain2, int sh_idx, int sc_idx, h16* dst, int nrows) {
;     ...
;   for (int row = gw; row < nrows; row += nw) {
;     const float* xr = row < TL ? xlat + (size_t)row * 1024 : xctx + (size_t)(row - TL) * 1024;
;     float* xo = row < TL ? p.out + (size_t)row * 1024 : xc + (size_t)(row - TL) * 1024;
;     const int mrow = row < TL ? (row >> 12) : 8;
;     const float* mr = mod + ((size_t)l * 9 + mrow) * 6144;
;     const float* mr2 = mod + ((size_t)l2 * 9 + mrow) * 6144;
;     f32x4 yv[4], xv[4];
;     float ss = 0.f;
; #pragma unroll
;     for (int i = 0; i < 4; ++i) {
;       h16x4 t = *(const h16x4*)(y + (size_t)row * 1024 + lane * 4 + 256 * i);
;       yv[i].x = (float)t.x; yv[i].y = (float)t.y; yv[i].z = (float)t.z; yv[i].w = (float)t.w;
;       ss += yv[i].x * yv[i].x + yv[i].y * yv[i].y + yv[i].z * yv[i].z + yv[i].w * yv[i].w;
;       xv[i] = *(const f32x4*)(xr + lane * 4 + 256 * i);
;     }
;     ss = wave_sum(ss);
;     const float rstd = rsqrtf(ss * (1.f / 1024.f) + EPS);
.Lrr21_pre1:
	s_lshr_b32 s59, s58, 12
	s_cmp_lt_u32 s58, 0x8000
	s_cselect_b32 s59, s59, 8
	s_mul_i32 s59, s59, 0x6000
	s_add_u32 s24, s42, s59
	s_addc_u32 s25, s43, 0
	s_add_u32 s18, s54, s59
	s_addc_u32 s19, s55, 0
	s_add_u32 s34, s18, 0x1000
	s_addc_u32 s35, s19, 0
	s_lshl_b32 s59, s58, 11
	s_add_u32 s40, s56, s59
	s_addc_u32 s41, s57, 0
	s_sub_u32 s60, s58, 0x8000
	s_cmp_lt_u32 s58, 0x8000
	s_cselect_b32 s60, s58, s60
	s_cselect_b32 s22, s46, s50
	s_cselect_b32 s23, s47, s51
	s_lshl_b32 s60, s60, 12
	s_add_u32 s22, s22, s60
	s_addc_u32 s23, s23, 0
	global_load_dwordx4 v[112:115], v0, s[24:25]
	global_load_dwordx4 v[116:119], v0, s[24:25] offset:1024
	global_load_dwordx4 v[120:123], v0, s[24:25] offset:2048
	global_load_dwordx4 v[124:127], v0, s[24:25] offset:3072
	global_load_dwordx4 v[162:165], v0, s[34:35]
	global_load_dwordx4 v[166:169], v0, s[34:35] offset:1024
	global_load_dwordx4 v[170:173], v0, s[34:35] offset:2048
	global_load_dwordx4 v[174:177], v0, s[34:35] offset:3072
	global_load_dwordx4 v[178:181], v0, s[18:19]
	global_load_dwordx4 v[182:185], v0, s[18:19] offset:1024
	global_load_dwordx4 v[186:189], v0, s[18:19] offset:2048
	global_load_dwordx4 v[190:193], v0, s[18:19] offset:3072
	s_add_i32 s62, s58, s8
	s_add_i32 s62, s62, s8
	s_cmp_lt_i32 s62, s36
	s_cbranch_scc0 .Lrr21_tail1
	s_lshl_b32 s59, s62, 11
	s_add_u32 s20, s44, s59
	s_addc_u32 s21, s45, 0
	s_sub_u32 s60, s62, 0x8000
	s_cmp_lt_u32 s62, 0x8000
	s_cselect_b32 s60, s62, s60
	s_cselect_b32 s12, s46, s50
	s_cselect_b32 s13, s47, s51
	s_lshl_b32 s60, s60, 12
	s_add_u32 s12, s12, s60
	s_addc_u32 s13, s13, 0
	global_load_dwordx2 v[2:3], v202, s[20:21]
	global_load_dwordx2 v[4:5], v202, s[20:21] offset:512
	global_load_dwordx2 v[6:7], v202, s[20:21] offset:1024
	global_load_dwordx2 v[8:9], v202, s[20:21] offset:1536
	global_load_dwordx4 v[32:35], v0, s[12:13]
	global_load_dwordx4 v[36:39], v0, s[12:13] offset:1024
	global_load_dwordx4 v[40:43], v0, s[12:13] offset:2048
	global_load_dwordx4 v[44:47], v0, s[12:13] offset:3072
	s_waitcnt vmcnt(28)
	v_cvt_f32_f16_e32 v226, v10
	v_cvt_f32_f16_sdwa v227, v10 dst_sel:DWORD dst_unused:UNUSED_PAD src0_sel:WORD_1
	v_cvt_f32_f16_e32 v228, v11
	v_cvt_f32_f16_sdwa v229, v11 dst_sel:DWORD dst_unused:UNUSED_PAD src0_sel:WORD_1
	v_cvt_f32_f16_e32 v230, v12
	v_cvt_f32_f16_sdwa v231, v12 dst_sel:DWORD dst_unused:UNUSED_PAD src0_sel:WORD_1
	v_cvt_f32_f16_e32 v232, v13
	v_cvt_f32_f16_sdwa v233, v13 dst_sel:DWORD dst_unused:UNUSED_PAD src0_sel:WORD_1
	v_cvt_f32_f16_e32 v234, v14
	v_cvt_f32_f16_sdwa v235, v14 dst_sel:DWORD dst_unused:UNUSED_PAD src0_sel:WORD_1
	v_cvt_f32_f16_e32 v236, v15
	v_cvt_f32_f16_sdwa v237, v15 dst_sel:DWORD dst_unused:UNUSED_PAD src0_sel:WORD_1
	v_cvt_f32_f16_e32 v238, v16
	v_cvt_f32_f16_sdwa v239, v16 dst_sel:DWORD dst_unused:UNUSED_PAD src0_sel:WORD_1
	v_cvt_f32_f16_e32 v240, v17
	v_cvt_f32_f16_sdwa v241, v17 dst_sel:DWORD dst_unused:UNUSED_PAD src0_sel:WORD_1
	v_mul_f32_e32 v242, v227, v227
	v_mul_f32_e32 v243, v231, v231
	v_mul_f32_e32 v244, v235, v235
	v_mul_f32_e32 v245, v239, v239
	v_fmac_f32_e32 v242, v226, v226
	v_fmac_f32_e32 v243, v230, v230
	v_fmac_f32_e32 v244, v234, v234
	v_fmac_f32_e32 v245, v238, v238
	v_fmac_f32_e32 v242, v228, v228
	v_fmac_f32_e32 v243, v232, v232
	v_fmac_f32_e32 v244, v236, v236
	v_fmac_f32_e32 v245, v240, v240
	v_fmac_f32_e32 v242, v229, v229
	v_fmac_f32_e32 v243, v233, v233
	v_fmac_f32_e32 v244, v237, v237
	v_fmac_f32_e32 v245, v241, v241
	v_add_f32_e32 v242, v242, v243
	v_add_f32_e32 v242, v242, v244
	v_add_f32_e32 v242, v242, v245
	s_nop 1
	v_add_f32_dpp v242, v242, v242 quad_perm:[1,0,3,2] row_mask:0xf bank_mask:0xf bound_ctrl:1
	s_nop 1
	v_add_f32_dpp v242, v242, v242 quad_perm:[2,3,0,1] row_mask:0xf bank_mask:0xf bound_ctrl:1
	s_nop 1
	v_add_f32_dpp v242, v242, v242 row_half_mirror row_mask:0xf bank_mask:0xf bound_ctrl:1
	s_nop 1
	v_add_f32_dpp v242, v242, v242 row_mirror row_mask:0xf bank_mask:0xf bound_ctrl:1
	s_nop 1
	ds_swizzle_b32 v243, v242 offset:swizzle(SWAP,16)
	s_waitcnt lgkmcnt(0)
	v_add_f32_e32 v242, v242, v243
	v_mov_b32_e32 v243, v242
	s_nop 1
	v_permlane32_swap_b32_e32 v242, v243
	v_add_f32_e32 v242, v242, v243
	v_fmamk_f32 v242, v242, 0x3a800000, v224
	v_rsq_f32_e32 v242, v242
	s_waitcnt vmcnt(8)
; DI void rows_resid_norm(const P& p, const float* xlat, const float* xctx, const h16* y, int l, int gate_idx, const float* post_g,
;                         bool do_next, int l2, const float* gain2, int sh_idx, int sc_idx, h16* dst, int nrows) {
;     ...
;     float s2 = 0.f;
; #pragma unroll
;     for (int i = 0; i < 4; ++i) {
;       const int c = lane * 4 + 256 * i;
;       f32x4 g = *(const f32x4*)(post_g + c), gt = *(const f32x4*)(mr + gate_idx * 1024 + c);
;       xv[i].x += gt.x * (yv[i].x * rstd * g.x);
;       xv[i].y += gt.y * (yv[i].y * rstd * g.y);
;       xv[i].z += gt.z * (yv[i].z * rstd * g.z);
;       xv[i].w += gt.w * (yv[i].w * rstd * g.w);
;       *(f32x4*)(xo + c) = xv[i];
;       s2 += xv[i].x * xv[i].x + xv[i].y * xv[i].y + xv[i].z * xv[i].z + xv[i].w * xv[i].w;
;     }
;     if (do_next) {
;       s2 = wave_sum(s2);
;       const float r2 = rsqrtf(s2 * (1.f / 1024.f) + EPS);
; #pragma unroll
;       for (int i = 0; i < 4; ++i) {
;         const int c = lane * 4 + 256 * i;
;         f32x4 g = *(const f32x4*)(gain2 + c), sc = *(const f32x4*)(mr2 + sc_idx * 1024 + c), sh = *(const f32x4*)(mr2 + sh_idx * 1024 + c);
;         h16x4 o;
;         o.x = (h16)(xv[i].x * r2 * g.x * (1.f + sc.x) + sh.x);
;         o.y = (h16)(xv[i].y * r2 * g.y * (1.f + sc.y) + sh.y);
;         o.z = (h16)(xv[i].z * r2 * g.z * (1.f + sc.z) + sh.z);
;         o.w = (h16)(xv[i].w * r2 * g.w * (1.f + sc.w) + sh.w);
;         *(h16x4*)(dst + (size_t)row * 1024 + c) = o;
;       }
;     }
	v_mul_f32_e32 v226, v226, v242
	v_mul_f32_e32 v227, v227, v242
	v_mul_f32_e32 v228, v228, v242
	v_mul_f32_e32 v229, v229, v242
	v_mul_f32_e32 v230, v230, v242
	v_mul_f32_e32 v231, v231, v242
	v_mul_f32_e32 v232, v232, v242
	v_mul_f32_e32 v233, v233, v242
	v_mul_f32_e32 v234, v234, v242
	v_mul_f32_e32 v235, v235, v242
	v_mul_f32_e32 v236, v236, v242
	v_mul_f32_e32 v237, v237, v242
	v_mul_f32_e32 v238, v238, v242
	v_mul_f32_e32 v239, v239, v242
	v_mul_f32_e32 v240, v240, v242
	v_mul_f32_e32 v241, v241, v242
	v_mul_f32_e32 v226, v80, v226
	v_mul_f32_e32 v227, v81, v227
	v_mul_f32_e32 v228, v82, v228
	v_mul_f32_e32 v229, v83, v229
	v_mul_f32_e32 v230, v84, v230
	v_mul_f32_e32 v231, v85, v231
	v_mul_f32_e32 v232, v86, v232
	v_mul_f32_e32 v233, v87, v233
	v_mul_f32_e32 v234, v88, v234
	v_mul_f32_e32 v235, v89, v235
	v_mul_f32_e32 v236, v90, v236
	v_mul_f32_e32 v237, v91, v237
	v_mul_f32_e32 v238, v92, v238
	v_mul_f32_e32 v239, v93, v239
	v_mul_f32_e32 v240, v94, v240
	v_mul_f32_e32 v241, v95, v241
	v_fmac_f32_e32 v48, v112, v226
	v_fmac_f32_e32 v49, v113, v227
	v_fmac_f32_e32 v50, v114, v228
	v_fmac_f32_e32 v51, v115, v229
	v_fmac_f32_e32 v52, v116, v230
	v_fmac_f32_e32 v53, v117, v231
	v_fmac_f32_e32 v54, v118, v232
	v_fmac_f32_e32 v55, v119, v233
	v_fmac_f32_e32 v56, v120, v234
	v_fmac_f32_e32 v57, v121, v235
	v_fmac_f32_e32 v58, v122, v236
	v_fmac_f32_e32 v59, v123, v237
	v_fmac_f32_e32 v60, v124, v238
	v_fmac_f32_e32 v61, v125, v239
	v_fmac_f32_e32 v62, v126, v240
	v_fmac_f32_e32 v63, v127, v241
	global_store_dwordx4 v0, v[48:51], s[22:23]
	global_store_dwordx4 v0, v[52:55], s[22:23] offset:1024
	global_store_dwordx4 v0, v[56:59], s[22:23] offset:2048
	global_store_dwordx4 v0, v[60:63], s[22:23] offset:3072
	v_mul_f32_e32 v242, v49, v49
	v_mul_f32_e32 v243, v53, v53
	v_mul_f32_e32 v244, v57, v57
	v_mul_f32_e32 v245, v61, v61
	v_fmac_f32_e32 v242, v48, v48
	v_fmac_f32_e32 v243, v52, v52
	v_fmac_f32_e32 v244, v56, v56
	v_fmac_f32_e32 v245, v60, v60
	v_fmac_f32_e32 v242, v50, v50
	v_fmac_f32_e32 v243, v54, v54
	v_fmac_f32_e32 v244, v58, v58
	v_fmac_f32_e32 v245, v62, v62
	v_fmac_f32_e32 v242, v51, v51
	v_fmac_f32_e32 v243, v55, v55
	v_fmac_f32_e32 v244, v59, v59
	v_fmac_f32_e32 v245, v63, v63
	v_add_f32_e32 v242, v242, v243
	v_add_f32_e32 v242, v242, v244
	v_add_f32_e32 v242, v242, v245
	s_nop 1
	v_add_f32_dpp v242, v242, v242 quad_perm:[1,0,3,2] row_mask:0xf bank_mask:0xf bound_ctrl:1
	s_nop 1
	v_add_f32_dpp v242, v242, v242 quad_perm:[2,3,0,1] row_mask:0xf bank_mask:0xf bound_ctrl:1
	s_nop 1
	v_add_f32_dpp v242, v242, v242 row_half_mirror row_mask:0xf bank_mask:0xf bound_ctrl:1
	s_nop 1
	v_add_f32_dpp v242, v242, v242 row_mirror row_mask:0xf bank_mask:0xf bound_ctrl:1
	s_nop 1
	ds_swizzle_b32 v243, v242 offset:swizzle(SWAP,16)
	s_waitcnt lgkmcnt(0)
	v_add_f32_e32 v242, v242, v243
	v_mov_b32_e32 v243, v242
	s_nop 1
	v_permlane32_swap_b32_e32 v242, v243
	v_add_f32_e32 v242, v242, v243
	v_fmamk_f32 v242, v242, 0x3a800000, v224
	v_rsq_f32_e32 v242, v242
	s_nop 0
	v_mul_f32_e32 v226, v48, v242
	v_mul_f32_e32 v227, v49, v242
	v_mul_f32_e32 v228, v50, v242
	v_mul_f32_e32 v229, v51, v242
	v_mul_f32_e32 v230, v52, v242
	v_mul_f32_e32 v231, v53, v242
	v_mul_f32_e32 v232, v54, v242
	v_mul_f32_e32 v233, v55, v242
	v_mul_f32_e32 v234, v56, v242
	v_mul_f32_e32 v235, v57, v242
	v_mul_f32_e32 v236, v58, v242
	v_mul_f32_e32 v237, v59, v242
	v_mul_f32_e32 v238, v60, v242
	v_mul_f32_e32 v239, v61, v242
	v_mul_f32_e32 v240, v62, v242
	v_mul_f32_e32 v241, v63, v242
	v_mul_f32_e32 v226, v96, v226
	v_mul_f32_e32 v227, v97, v227
	v_mul_f32_e32 v228, v98, v228
	v_mul_f32_e32 v229, v99, v229
	v_mul_f32_e32 v230, v100, v230
	v_mul_f32_e32 v231, v101, v231
	v_mul_f32_e32 v232, v102, v232
	v_mul_f32_e32 v233, v103, v233
	v_mul_f32_e32 v234, v104, v234
	v_mul_f32_e32 v235, v105, v235
	v_mul_f32_e32 v236, v106, v236
	v_mul_f32_e32 v237, v107, v237
	v_mul_f32_e32 v238, v108, v238
	v_mul_f32_e32 v239, v109, v239
	v_mul_f32_e32 v240, v110, v240
	v_mul_f32_e32 v241, v111, v241
	v_add_f32_e32 v162, 1.0, v162
	v_add_f32_e32 v163, 1.0, v163
	v_add_f32_e32 v164, 1.0, v164
	v_add_f32_e32 v165, 1.0, v165
	v_add_f32_e32 v166, 1.0, v166
	v_add_f32_e32 v167, 1.0, v167
	v_add_f32_e32 v168, 1.0, v168
	v_add_f32_e32 v169, 1.0, v169
	v_add_f32_e32 v170, 1.0, v170
	v_add_f32_e32 v171, 1.0, v171
	v_add_f32_e32 v172, 1.0, v172
	v_add_f32_e32 v173, 1.0, v173
	v_add_f32_e32 v174, 1.0, v174
	v_add_f32_e32 v175, 1.0, v175
	v_add_f32_e32 v176, 1.0, v176
	v_add_f32_e32 v177, 1.0, v177
	v_fma_f32 v226, v162, v226, v178
	v_fma_f32 v227, v163, v227, v179
	v_fma_f32 v228, v164, v228, v180
	v_fma_f32 v229, v165, v229, v181
	v_fma_f32 v230, v166, v230, v182
	v_fma_f32 v231, v167, v231, v183
	v_fma_f32 v232, v168, v232, v184
	v_fma_f32 v233, v169, v233, v185
	v_fma_f32 v234, v170, v234, v186
	v_fma_f32 v235, v171, v235, v187
	v_fma_f32 v236, v172, v236, v188
	v_fma_f32 v237, v173, v237, v189
	v_fma_f32 v238, v174, v238, v190
	v_fma_f32 v239, v175, v239, v191
	v_fma_f32 v240, v176, v240, v192
	v_fma_f32 v241, v177, v241, v193
	v_cvt_pk_f16_f32 v244, v226, v227
	v_cvt_pk_f16_f32 v245, v228, v229
	v_cvt_pk_f16_f32 v246, v230, v231
	v_cvt_pk_f16_f32 v247, v232, v233
	v_cvt_pk_f16_f32 v248, v234, v235
	v_cvt_pk_f16_f32 v249, v236, v237
	v_cvt_pk_f16_f32 v250, v238, v239
	v_cvt_pk_f16_f32 v251, v240, v241
	global_store_dwordx2 v202, v[244:245], s[40:41]
	global_store_dwordx2 v202, v[246:247], s[40:41] offset:512
	global_store_dwordx2 v202, v[248:249], s[40:41] offset:1024
	global_store_dwordx2 v202, v[250:251], s[40:41] offset:1536
	s_add_i32 s58, s58, s8
; DI void rows_resid_norm(const P& p, const float* xlat, const float* xctx, const h16* y, int l, int gate_idx, const float* post_g,
;                         bool do_next, int l2, const float* gain2, int sh_idx, int sc_idx, h16* dst, int nrows) {
;     ...
;   for (int row = gw; row < nrows; row += nw) {
;     const float* xr = row < TL ? xlat + (size_t)row * 1024 : xctx + (size_t)(row - TL) * 1024;
;     float* xo = row < TL ? p.out + (size_t)row * 1024 : xc + (size_t)(row - TL) * 1024;
;     const int mrow = row < TL ? (row >> 12) : 8;
;     const float* mr = mod + ((size_t)l * 9 + mrow) * 6144;
;     const float* mr2 = mod + ((size_t)l2 * 9 + mrow) * 6144;
;     f32x4 yv[4], xv[4];
;     float ss = 0.f;
; #pragma unroll
;     for (int i = 0; i < 4; ++i) {
;       h16x4 t = *(const h16x4*)(y + (size_t)row * 1024 + lane * 4 + 256 * i);
;       yv[i].x = (float)t.x; yv[i].y = (float)t.y; yv[i].z = (float)t.z; yv[i].w = (float)t.w;
;       ss += yv[i].x * yv[i].x + yv[i].y * yv[i].y + yv[i].z * yv[i].z + yv[i].w * yv[i].w;
;       xv[i] = *(const f32x4*)(xr + lane * 4 + 256 * i);
;     }
;     ss = wave_sum(ss);
;     const float rstd = rsqrtf(ss * (1.f / 1024.f) + EPS);
.Lrr21_l2:
	s_lshr_b32 s59, s58, 12
	s_cmp_lt_u32 s58, 0x8000
	s_cselect_b32 s59, s59, 8
	s_mul_i32 s59, s59, 0x6000
	s_add_u32 s24, s42, s59
	s_addc_u32 s25, s43, 0
	s_add_u32 s18, s54, s59
	s_addc_u32 s19, s55, 0
	s_add_u32 s34, s18, 0x1000
	s_addc_u32 s35, s19, 0
	s_lshl_b32 s59, s58, 11
	s_add_u32 s40, s56, s59
	s_addc_u32 s41, s57, 0
	s_sub_u32 s60, s58, 0x8000
	s_cmp_lt_u32 s58, 0x8000
	s_cselect_b32 s60, s58, s60
	s_cselect_b32 s22, s46, s50
	s_cselect_b32 s23, s47, s51
	s_lshl_b32 s60, s60, 12
	s_add_u32 s22, s22, s60
	s_addc_u32 s23, s23, 0
	global_load_dwordx4 v[112:115], v0, s[24:25]
	global_load_dwordx4 v[116:119], v0, s[24:25] offset:1024
	global_load_dwordx4 v[120:123], v0, s[24:25] offset:2048
	global_load_dwordx4 v[124:127], v0, s[24:25] offset:3072
	global_load_dwordx4 v[162:165], v0, s[34:35]
	global_load_dwordx4 v[166:169], v0, s[34:35] offset:1024
	global_load_dwordx4 v[170:173], v0, s[34:35] offset:2048
	global_load_dwordx4 v[174:177], v0, s[34:35] offset:3072
	global_load_dwordx4 v[178:181], v0, s[18:19]
	global_load_dwordx4 v[182:185], v0, s[18:19] offset:1024
	global_load_dwordx4 v[186:189], v0, s[18:19] offset:2048
	global_load_dwordx4 v[190:193], v0, s[18:19] offset:3072
	s_add_i32 s62, s58, s8
	s_add_i32 s62, s62, s8
	s_cmp_lt_i32 s62, s36
	s_cbranch_scc0 .Lrr21_tail2
	s_lshl_b32 s59, s62, 11
	s_add_u32 s20, s44, s59
	s_addc_u32 s21, s45, 0
	s_sub_u32 s60, s62, 0x8000
	s_cmp_lt_u32 s62, 0x8000
	s_cselect_b32 s60, s62, s60
	s_cselect_b32 s12, s46, s50
	s_cselect_b32 s13, s47, s51
	s_lshl_b32 s60, s60, 12
	s_add_u32 s12, s12, s60
	s_addc_u32 s13, s13, 0
	global_load_dwordx2 v[10:11], v202, s[20:21]
	global_load_dwordx2 v[12:13], v202, s[20:21] offset:512
	global_load_dwordx2 v[14:15], v202, s[20:21] offset:1024
	global_load_dwordx2 v[16:17], v202, s[20:21] offset:1536
	global_load_dwordx4 v[48:51], v0, s[12:13]
	global_load_dwordx4 v[52:55], v0, s[12:13] offset:1024
	global_load_dwordx4 v[56:59], v0, s[12:13] offset:2048
	global_load_dwordx4 v[60:63], v0, s[12:13] offset:3072
	s_waitcnt vmcnt(56)
	v_cvt_f32_f16_e32 v226, v18
	v_cvt_f32_f16_sdwa v227, v18 dst_sel:DWORD dst_unused:UNUSED_PAD src0_sel:WORD_1
	v_cvt_f32_f16_e32 v228, v19
	v_cvt_f32_f16_sdwa v229, v19 dst_sel:DWORD dst_unused:UNUSED_PAD src0_sel:WORD_1
	v_cvt_f32_f16_e32 v230, v20
	v_cvt_f32_f16_sdwa v231, v20 dst_sel:DWORD dst_unused:UNUSED_PAD src0_sel:WORD_1
	v_cvt_f32_f16_e32 v232, v21
	v_cvt_f32_f16_sdwa v233, v21 dst_sel:DWORD dst_unused:UNUSED_PAD src0_sel:WORD_1
	v_cvt_f32_f16_e32 v234, v22
	v_cvt_f32_f16_sdwa v235, v22 dst_sel:DWORD dst_unused:UNUSED_PAD src0_sel:WORD_1
	v_cvt_f32_f16_e32 v236, v23
	v_cvt_f32_f16_sdwa v237, v23 dst_sel:DWORD dst_unused:UNUSED_PAD src0_sel:WORD_1
	v_cvt_f32_f16_e32 v238, v24
	v_cvt_f32_f16_sdwa v239, v24 dst_sel:DWORD dst_unused:UNUSED_PAD src0_sel:WORD_1
	v_cvt_f32_f16_e32 v240, v25
	v_cvt_f32_f16_sdwa v241, v25 dst_sel:DWORD dst_unused:UNUSED_PAD src0_sel:WORD_1
	v_mul_f32_e32 v242, v227, v227
	v_mul_f32_e32 v243, v231, v231
	v_mul_f32_e32 v244, v235, v235
	v_mul_f32_e32 v245, v239, v239
	v_fmac_f32_e32 v242, v226, v226
	v_fmac_f32_e32 v243, v230, v230
	v_fmac_f32_e32 v244, v234, v234
	v_fmac_f32_e32 v245, v238, v238
	v_fmac_f32_e32 v242, v228, v228
	v_fmac_f32_e32 v243, v232, v232
	v_fmac_f32_e32 v244, v236, v236
	v_fmac_f32_e32 v245, v240, v240
	v_fmac_f32_e32 v242, v229, v229
	v_fmac_f32_e32 v243, v233, v233
	v_fmac_f32_e32 v244, v237, v237
	v_fmac_f32_e32 v245, v241, v241
	v_add_f32_e32 v242, v242, v243
	v_add_f32_e32 v242, v242, v244
	v_add_f32_e32 v242, v242, v245
	s_nop 1
	v_add_f32_dpp v242, v242, v242 quad_perm:[1,0,3,2] row_mask:0xf bank_mask:0xf bound_ctrl:1
	s_nop 1
	v_add_f32_dpp v242, v242, v242 quad_perm:[2,3,0,1] row_mask:0xf bank_mask:0xf bound_ctrl:1
	s_nop 1
	v_add_f32_dpp v242, v242, v242 row_half_mirror row_mask:0xf bank_mask:0xf bound_ctrl:1
	s_nop 1
	v_add_f32_dpp v242, v242, v242 row_mirror row_mask:0xf bank_mask:0xf bound_ctrl:1
	s_nop 1
	ds_swizzle_b32 v243, v242 offset:swizzle(SWAP,16)
	s_waitcnt lgkmcnt(0)
	v_add_f32_e32 v242, v242, v243
	v_mov_b32_e32 v243, v242
	s_nop 1
	v_permlane32_swap_b32_e32 v242, v243
	v_add_f32_e32 v242, v242, v243
	v_fmamk_f32 v242, v242, 0x3a800000, v224
	v_rsq_f32_e32 v242, v242
	s_waitcnt vmcnt(8)
; DI void rows_resid_norm(const P& p, const float* xlat, const float* xctx, const h16* y, int l, int gate_idx, const float* post_g,
;                         bool do_next, int l2, const float* gain2, int sh_idx, int sc_idx, h16* dst, int nrows) {
;     ...
;     float s2 = 0.f;
; #pragma unroll
;     for (int i = 0; i < 4; ++i) {
;       const int c = lane * 4 + 256 * i;
;       f32x4 g = *(const f32x4*)(post_g + c), gt = *(const f32x4*)(mr + gate_idx * 1024 + c);
;       xv[i].x += gt.x * (yv[i].x * rstd * g.x);
;       xv[i].y += gt.y * (yv[i].y * rstd * g.y);
;       xv[i].z += gt.z * (yv[i].z * rstd * g.z);
;       xv[i].w += gt.w * (yv[i].w * rstd * g.w);
;       *(f32x4*)(xo + c) = xv[i];
;       s2 += xv[i].x * xv[i].x + xv[i].y * xv[i].y + xv[i].z * xv[i].z + xv[i].w * xv[i].w;
;     }
;     if (do_next) {
;       s2 = wave_sum(s2);
;       const float r2 = rsqrtf(s2 * (1.f / 1024.f) + EPS);
; #pragma unroll
;       for (int i = 0; i < 4; ++i) {
;         const int c = lane * 4 + 256 * i;
;         f32x4 g = *(const f32x4*)(gain2 + c), sc = *(const f32x4*)(mr2 + sc_idx * 1024 + c), sh = *(const f32x4*)(mr2 + sh_idx * 1024 + c);
;         h16x4 o;
;         o.x = (h16)(xv[i].x * r2 * g.x * (1.f + sc.x) + sh.x);
;         o.y = (h16)(xv[i].y * r2 * g.y * (1.f + sc.y) + sh.y);
;         o.z = (h16)(xv[i].z * r2 * g.z * (1.f + sc.z) + sh.z);
;         o.w = (h16)(xv[i].w * r2 * g.w * (1.f + sc.w) + sh.w);
;         *(h16x4*)(dst + (size_t)row * 1024 + c) = o;
;       }
;     }
	v_mul_f32_e32 v226, v226, v242
	v_mul_f32_e32 v227, v227, v242
	v_mul_f32_e32 v228, v228, v242
	v_mul_f32_e32 v229, v229, v242
	v_mul_f32_e32 v230, v230, v242
	v_mul_f32_e32 v231, v231, v242
	v_mul_f32_e32 v232, v232, v242
	v_mul_f32_e32 v233, v233, v242
	v_mul_f32_e32 v234, v234, v242
	v_mul_f32_e32 v235, v235, v242
	v_mul_f32_e32 v236, v236, v242
	v_mul_f32_e32 v237, v237, v242
	v_mul_f32_e32 v238, v238, v242
	v_mul_f32_e32 v239, v239, v242
	v_mul_f32_e32 v240, v240, v242
	v_mul_f32_e32 v241, v241, v242
	v_mul_f32_e32 v226, v80, v226
	v_mul_f32_e32 v227, v81, v227
	v_mul_f32_e32 v228, v82, v228
	v_mul_f32_e32 v229, v83, v229
	v_mul_f32_e32 v230, v84, v230
	v_mul_f32_e32 v231, v85, v231
	v_mul_f32_e32 v232, v86, v232
	v_mul_f32_e32 v233, v87, v233
	v_mul_f32_e32 v234, v88, v234
	v_mul_f32_e32 v235, v89, v235
	v_mul_f32_e32 v236, v90, v236
	v_mul_f32_e32 v237, v91, v237
	v_mul_f32_e32 v238, v92, v238
	v_mul_f32_e32 v239, v93, v239
	v_mul_f32_e32 v240, v94, v240
	v_mul_f32_e32 v241, v95, v241
	v_fmac_f32_e32 v64, v112, v226
	v_fmac_f32_e32 v65, v113, v227
	v_fmac_f32_e32 v66, v114, v228
	v_fmac_f32_e32 v67, v115, v229
	v_fmac_f32_e32 v68, v116, v230
	v_fmac_f32_e32 v69, v117, v231
	v_fmac_f32_e32 v70, v118, v232
	v_fmac_f32_e32 v71, v119, v233
	v_fmac_f32_e32 v72, v120, v234
	v_fmac_f32_e32 v73, v121, v235
	v_fmac_f32_e32 v74, v122, v236
	v_fmac_f32_e32 v75, v123, v237
	v_fmac_f32_e32 v76, v124, v238
	v_fmac_f32_e32 v77, v125, v239
	v_fmac_f32_e32 v78, v126, v240
	v_fmac_f32_e32 v79, v127, v241
	global_store_dwordx4 v0, v[64:67], s[22:23]
	global_store_dwordx4 v0, v[68:71], s[22:23] offset:1024
	global_store_dwordx4 v0, v[72:75], s[22:23] offset:2048
	global_store_dwordx4 v0, v[76:79], s[22:23] offset:3072
	v_mul_f32_e32 v242, v65, v65
	v_mul_f32_e32 v243, v69, v69
	v_mul_f32_e32 v244, v73, v73
	v_mul_f32_e32 v245, v77, v77
	v_fmac_f32_e32 v242, v64, v64
	v_fmac_f32_e32 v243, v68, v68
	v_fmac_f32_e32 v244, v72, v72
	v_fmac_f32_e32 v245, v76, v76
	v_fmac_f32_e32 v242, v66, v66
	v_fmac_f32_e32 v243, v70, v70
	v_fmac_f32_e32 v244, v74, v74
	v_fmac_f32_e32 v245, v78, v78
	v_fmac_f32_e32 v242, v67, v67
	v_fmac_f32_e32 v243, v71, v71
	v_fmac_f32_e32 v244, v75, v75
	v_fmac_f32_e32 v245, v79, v79
	v_add_f32_e32 v242, v242, v243
	v_add_f32_e32 v242, v242, v244
	v_add_f32_e32 v242, v242, v245
	s_nop 1
	v_add_f32_dpp v242, v242, v242 quad_perm:[1,0,3,2] row_mask:0xf bank_mask:0xf bound_ctrl:1
	s_nop 1
	v_add_f32_dpp v242, v242, v242 quad_perm:[2,3,0,1] row_mask:0xf bank_mask:0xf bound_ctrl:1
	s_nop 1
	v_add_f32_dpp v242, v242, v242 row_half_mirror row_mask:0xf bank_mask:0xf bound_ctrl:1
	s_nop 1
	v_add_f32_dpp v242, v242, v242 row_mirror row_mask:0xf bank_mask:0xf bound_ctrl:1
	s_nop 1
	ds_swizzle_b32 v243, v242 offset:swizzle(SWAP,16)
	s_waitcnt lgkmcnt(0)
	v_add_f32_e32 v242, v242, v243
	v_mov_b32_e32 v243, v242
	s_nop 1
	v_permlane32_swap_b32_e32 v242, v243
	v_add_f32_e32 v242, v242, v243
	v_fmamk_f32 v242, v242, 0x3a800000, v224
	v_rsq_f32_e32 v242, v242
	s_nop 0
	v_mul_f32_e32 v226, v64, v242
	v_mul_f32_e32 v227, v65, v242
	v_mul_f32_e32 v228, v66, v242
	v_mul_f32_e32 v229, v67, v242
	v_mul_f32_e32 v230, v68, v242
	v_mul_f32_e32 v231, v69, v242
	v_mul_f32_e32 v232, v70, v242
	v_mul_f32_e32 v233, v71, v242
	v_mul_f32_e32 v234, v72, v242
	v_mul_f32_e32 v235, v73, v242
	v_mul_f32_e32 v236, v74, v242
	v_mul_f32_e32 v237, v75, v242
	v_mul_f32_e32 v238, v76, v242
	v_mul_f32_e32 v239, v77, v242
	v_mul_f32_e32 v240, v78, v242
	v_mul_f32_e32 v241, v79, v242
	v_mul_f32_e32 v226, v96, v226
	v_mul_f32_e32 v227, v97, v227
	v_mul_f32_e32 v228, v98, v228
	v_mul_f32_e32 v229, v99, v229
	v_mul_f32_e32 v230, v100, v230
	v_mul_f32_e32 v231, v101, v231
	v_mul_f32_e32 v232, v102, v232
	v_mul_f32_e32 v233, v103, v233
	v_mul_f32_e32 v234, v104, v234
	v_mul_f32_e32 v235, v105, v235
	v_mul_f32_e32 v236, v106, v236
	v_mul_f32_e32 v237, v107, v237
	v_mul_f32_e32 v238, v108, v238
	v_mul_f32_e32 v239, v109, v239
	v_mul_f32_e32 v240, v110, v240
	v_mul_f32_e32 v241, v111, v241
	v_add_f32_e32 v162, 1.0, v162
	v_add_f32_e32 v163, 1.0, v163
	v_add_f32_e32 v164, 1.0, v164
	v_add_f32_e32 v165, 1.0, v165
	v_add_f32_e32 v166, 1.0, v166
	v_add_f32_e32 v167, 1.0, v167
	v_add_f32_e32 v168, 1.0, v168
	v_add_f32_e32 v169, 1.0, v169
	v_add_f32_e32 v170, 1.0, v170
	v_add_f32_e32 v171, 1.0, v171
	v_add_f32_e32 v172, 1.0, v172
	v_add_f32_e32 v173, 1.0, v173
	v_add_f32_e32 v174, 1.0, v174
	v_add_f32_e32 v175, 1.0, v175
	v_add_f32_e32 v176, 1.0, v176
	v_add_f32_e32 v177, 1.0, v177
	v_fma_f32 v226, v162, v226, v178
	v_fma_f32 v227, v163, v227, v179
	v_fma_f32 v228, v164, v228, v180
	v_fma_f32 v229, v165, v229, v181
	v_fma_f32 v230, v166, v230, v182
	v_fma_f32 v231, v167, v231, v183
	v_fma_f32 v232, v168, v232, v184
	v_fma_f32 v233, v169, v233, v185
	v_fma_f32 v234, v170, v234, v186
	v_fma_f32 v235, v171, v235, v187
	v_fma_f32 v236, v172, v236, v188
	v_fma_f32 v237, v173, v237, v189
	v_fma_f32 v238, v174, v238, v190
	v_fma_f32 v239, v175, v239, v191
	v_fma_f32 v240, v176, v240, v192
	v_fma_f32 v241, v177, v241, v193
	v_cvt_pk_f16_f32 v244, v226, v227
	v_cvt_pk_f16_f32 v245, v228, v229
	v_cvt_pk_f16_f32 v246, v230, v231
	v_cvt_pk_f16_f32 v247, v232, v233
	v_cvt_pk_f16_f32 v248, v234, v235
	v_cvt_pk_f16_f32 v249, v236, v237
	v_cvt_pk_f16_f32 v250, v238, v239
	v_cvt_pk_f16_f32 v251, v240, v241
	global_store_dwordx2 v202, v[244:245], s[40:41]
	global_store_dwordx2 v202, v[246:247], s[40:41] offset:512
	global_store_dwordx2 v202, v[248:249], s[40:41] offset:1024
	global_store_dwordx2 v202, v[250:251], s[40:41] offset:1536
	s_add_i32 s58, s58, s8
; DI void rows_resid_norm(const P& p, const float* xlat, const float* xctx, const h16* y, int l, int gate_idx, const float* post_g,
;                         bool do_next, int l2, const float* gain2, int sh_idx, int sc_idx, h16* dst, int nrows) {
;     ...
;   for (int row = gw; row < nrows; row += nw) {
;     const float* xr = row < TL ? xlat + (size_t)row * 1024 : xctx + (size_t)(row - TL) * 1024;
;     float* xo = row < TL ? p.out + (size_t)row * 1024 : xc + (size_t)(row - TL) * 1024;
;     const int mrow = row < TL ? (row >> 12) : 8;
;     const float* mr = mod + ((size_t)l * 9 + mrow) * 6144;
;     const float* mr2 = mod + ((size_t)l2 * 9 + mrow) * 6144;
;     f32x4 yv[4], xv[4];
;     float ss = 0.f;
; #pragma unroll
;     for (int i = 0; i < 4; ++i) {
;       h16x4 t = *(const h16x4*)(y + (size_t)row * 1024 + lane * 4 + 256 * i);
;       yv[i].x = (float)t.x; yv[i].y = (float)t.y; yv[i].z = (float)t.z; yv[i].w = (float)t.w;
;       ss += yv[i].x * yv[i].x + yv[i].y * yv[i].y + yv[i].z * yv[i].z + yv[i].w * yv[i].w;
;       xv[i] = *(const f32x4*)(xr + lane * 4 + 256 * i);
;     }
;     ss = wave_sum(ss);
;     const float rstd = rsqrtf(ss * (1.f / 1024.f) + EPS);
.Lrr21_l0:
	s_lshr_b32 s59, s58, 12
	s_cmp_lt_u32 s58, 0x8000
	s_cselect_b32 s59, s59, 8
	s_mul_i32 s59, s59, 0x6000
	s_add_u32 s24, s42, s59
	s_addc_u32 s25, s43, 0
	s_add_u32 s18, s54, s59
	s_addc_u32 s19, s55, 0
	s_add_u32 s34, s18, 0x1000
	s_addc_u32 s35, s19, 0
	s_lshl_b32 s59, s58, 11
	s_add_u32 s40, s56, s59
	s_addc_u32 s41, s57, 0
	s_sub_u32 s60, s58, 0x8000
	s_cmp_lt_u32 s58, 0x8000
	s_cselect_b32 s60, s58, s60
	s_cselect_b32 s22, s46, s50
	s_cselect_b32 s23, s47, s51
	s_lshl_b32 s60, s60, 12
	s_add_u32 s22, s22, s60
	s_addc_u32 s23, s23, 0
	global_load_dwordx4 v[112:115], v0, s[24:25]
	global_load_dwordx4 v[116:119], v0, s[24:25] offset:1024
	global_load_dwordx4 v[120:123], v0, s[24:25] offset:2048
	global_load_dwordx4 v[124:127], v0, s[24:25] offset:3072
	global_load_dwordx4 v[162:165], v0, s[34:35]
	global_load_dwordx4 v[166:169], v0, s[34:35] offset:1024
	global_load_dwordx4 v[170:173], v0, s[34:35] offset:2048
	global_load_dwordx4 v[174:177], v0, s[34:35] offset:3072
	global_load_dwordx4 v[178:181], v0, s[18:19]
	global_load_dwordx4 v[182:185], v0, s[18:19] offset:1024
	global_load_dwordx4 v[186:189], v0, s[18:19] offset:2048
	global_load_dwordx4 v[190:193], v0, s[18:19] offset:3072
	s_add_i32 s62, s58, s8
	s_add_i32 s62, s62, s8
	s_cmp_lt_i32 s62, s36
	s_cbranch_scc0 .Lrr21_tail0
	s_lshl_b32 s59, s62, 11
	s_add_u32 s20, s44, s59
	s_addc_u32 s21, s45, 0
	s_sub_u32 s60, s62, 0x8000
	s_cmp_lt_u32 s62, 0x8000
	s_cselect_b32 s60, s62, s60
	s_cselect_b32 s12, s46, s50
	s_cselect_b32 s13, s47, s51
	s_lshl_b32 s60, s60, 12
	s_add_u32 s12, s12, s60
	s_addc_u32 s13, s13, 0
	global_load_dwordx2 v[18:19], v202, s[20:21]
	global_load_dwordx2 v[20:21], v202, s[20:21] offset:512
	global_load_dwordx2 v[22:23], v202, s[20:21] offset:1024
	global_load_dwordx2 v[24:25], v202, s[20:21] offset:1536
	global_load_dwordx4 v[64:67], v0, s[12:13]
	global_load_dwordx4 v[68:71], v0, s[12:13] offset:1024
	global_load_dwordx4 v[72:75], v0, s[12:13] offset:2048
	global_load_dwordx4 v[76:79], v0, s[12:13] offset:3072
	s_waitcnt vmcnt(56)
	v_cvt_f32_f16_e32 v226, v2
	v_cvt_f32_f16_sdwa v227, v2 dst_sel:DWORD dst_unused:UNUSED_PAD src0_sel:WORD_1
	v_cvt_f32_f16_e32 v228, v3
	v_cvt_f32_f16_sdwa v229, v3 dst_sel:DWORD dst_unused:UNUSED_PAD src0_sel:WORD_1
	v_cvt_f32_f16_e32 v230, v4
	v_cvt_f32_f16_sdwa v231, v4 dst_sel:DWORD dst_unused:UNUSED_PAD src0_sel:WORD_1
	v_cvt_f32_f16_e32 v232, v5
	v_cvt_f32_f16_sdwa v233, v5 dst_sel:DWORD dst_unused:UNUSED_PAD src0_sel:WORD_1
	v_cvt_f32_f16_e32 v234, v6
	v_cvt_f32_f16_sdwa v235, v6 dst_sel:DWORD dst_unused:UNUSED_PAD src0_sel:WORD_1
	v_cvt_f32_f16_e32 v236, v7
	v_cvt_f32_f16_sdwa v237, v7 dst_sel:DWORD dst_unused:UNUSED_PAD src0_sel:WORD_1
	v_cvt_f32_f16_e32 v238, v8
	v_cvt_f32_f16_sdwa v239, v8 dst_sel:DWORD dst_unused:UNUSED_PAD src0_sel:WORD_1
	v_cvt_f32_f16_e32 v240, v9
	v_cvt_f32_f16_sdwa v241, v9 dst_sel:DWORD dst_unused:UNUSED_PAD src0_sel:WORD_1
	v_mul_f32_e32 v242, v227, v227
	v_mul_f32_e32 v243, v231, v231
	v_mul_f32_e32 v244, v235, v235
	v_mul_f32_e32 v245, v239, v239
	v_fmac_f32_e32 v242, v226, v226
	v_fmac_f32_e32 v243, v230, v230
	v_fmac_f32_e32 v244, v234, v234
	v_fmac_f32_e32 v245, v238, v238
	v_fmac_f32_e32 v242, v228, v228
	v_fmac_f32_e32 v243, v232, v232
	v_fmac_f32_e32 v244, v236, v236
	v_fmac_f32_e32 v245, v240, v240
	v_fmac_f32_e32 v242, v229, v229
	v_fmac_f32_e32 v243, v233, v233
	v_fmac_f32_e32 v244, v237, v237
	v_fmac_f32_e32 v245, v241, v241
	v_add_f32_e32 v242, v242, v243
	v_add_f32_e32 v242, v242, v244
	v_add_f32_e32 v242, v242, v245
	s_nop 1
	v_add_f32_dpp v242, v242, v242 quad_perm:[1,0,3,2] row_mask:0xf bank_mask:0xf bound_ctrl:1
	s_nop 1
	v_add_f32_dpp v242, v242, v242 quad_perm:[2,3,0,1] row_mask:0xf bank_mask:0xf bound_ctrl:1
	s_nop 1
	v_add_f32_dpp v242, v242, v242 row_half_mirror row_mask:0xf bank_mask:0xf bound_ctrl:1
	s_nop 1
	v_add_f32_dpp v242, v242, v242 row_mirror row_mask:0xf bank_mask:0xf bound_ctrl:1
	s_nop 1
	ds_swizzle_b32 v243, v242 offset:swizzle(SWAP,16)
	s_waitcnt lgkmcnt(0)
	v_add_f32_e32 v242, v242, v243
	v_mov_b32_e32 v243, v242
	s_nop 1
	v_permlane32_swap_b32_e32 v242, v243
	v_add_f32_e32 v242, v242, v243
	v_fmamk_f32 v242, v242, 0x3a800000, v224
	v_rsq_f32_e32 v242, v242
	s_waitcnt vmcnt(8)
; DI void rows_resid_norm(const P& p, const float* xlat, const float* xctx, const h16* y, int l, int gate_idx, const float* post_g,
;                         bool do_next, int l2, const float* gain2, int sh_idx, int sc_idx, h16* dst, int nrows) {
;     ...
;     float s2 = 0.f;
; #pragma unroll
;     for (int i = 0; i < 4; ++i) {
;       const int c = lane * 4 + 256 * i;
;       f32x4 g = *(const f32x4*)(post_g + c), gt = *(const f32x4*)(mr + gate_idx * 1024 + c);
;       xv[i].x += gt.x * (yv[i].x * rstd * g.x);
;       xv[i].y += gt.y * (yv[i].y * rstd * g.y);
;       xv[i].z += gt.z * (yv[i].z * rstd * g.z);
;       xv[i].w += gt.w * (yv[i].w * rstd * g.w);
;       *(f32x4*)(xo + c) = xv[i];
;       s2 += xv[i].x * xv[i].x + xv[i].y * xv[i].y + xv[i].z * xv[i].z + xv[i].w * xv[i].w;
;     }
;     if (do_next) {
;       s2 = wave_sum(s2);
;       const float r2 = rsqrtf(s2 * (1.f / 1024.f) + EPS);
; #pragma unroll
;       for (int i = 0; i < 4; ++i) {
;         const int c = lane * 4 + 256 * i;
;         f32x4 g = *(const f32x4*)(gain2 + c), sc = *(const f32x4*)(mr2 + sc_idx * 1024 + c), sh = *(const f32x4*)(mr2 + sh_idx * 1024 + c);
;         h16x4 o;
;         o.x = (h16)(xv[i].x * r2 * g.x * (1.f + sc.x) + sh.x);
;         o.y = (h16)(xv[i].y * r2 * g.y * (1.f + sc.y) + sh.y);
;         o.z = (h16)(xv[i].z * r2 * g.z * (1.f + sc.z) + sh.z);
;         o.w = (h16)(xv[i].w * r2 * g.w * (1.f + sc.w) + sh.w);
;         *(h16x4*)(dst + (size_t)row * 1024 + c) = o;
;       }
;     }
	v_mul_f32_e32 v226, v226, v242
	v_mul_f32_e32 v227, v227, v242
	v_mul_f32_e32 v228, v228, v242
	v_mul_f32_e32 v229, v229, v242
	v_mul_f32_e32 v230, v230, v242
	v_mul_f32_e32 v231, v231, v242
	v_mul_f32_e32 v232, v232, v242
	v_mul_f32_e32 v233, v233, v242
	v_mul_f32_e32 v234, v234, v242
	v_mul_f32_e32 v235, v235, v242
	v_mul_f32_e32 v236, v236, v242
	v_mul_f32_e32 v237, v237, v242
	v_mul_f32_e32 v238, v238, v242
	v_mul_f32_e32 v239, v239, v242
	v_mul_f32_e32 v240, v240, v242
	v_mul_f32_e32 v241, v241, v242
	v_mul_f32_e32 v226, v80, v226
	v_mul_f32_e32 v227, v81, v227
	v_mul_f32_e32 v228, v82, v228
	v_mul_f32_e32 v229, v83, v229
	v_mul_f32_e32 v230, v84, v230
	v_mul_f32_e32 v231, v85, v231
	v_mul_f32_e32 v232, v86, v232
	v_mul_f32_e32 v233, v87, v233
	v_mul_f32_e32 v234, v88, v234
	v_mul_f32_e32 v235, v89, v235
	v_mul_f32_e32 v236, v90, v236
	v_mul_f32_e32 v237, v91, v237
	v_mul_f32_e32 v238, v92, v238
	v_mul_f32_e32 v239, v93, v239
	v_mul_f32_e32 v240, v94, v240
	v_mul_f32_e32 v241, v95, v241
	v_fmac_f32_e32 v32, v112, v226
	v_fmac_f32_e32 v33, v113, v227
	v_fmac_f32_e32 v34, v114, v228
	v_fmac_f32_e32 v35, v115, v229
	v_fmac_f32_e32 v36, v116, v230
	v_fmac_f32_e32 v37, v117, v231
	v_fmac_f32_e32 v38, v118, v232
	v_fmac_f32_e32 v39, v119, v233
	v_fmac_f32_e32 v40, v120, v234
	v_fmac_f32_e32 v41, v121, v235
	v_fmac_f32_e32 v42, v122, v236
	v_fmac_f32_e32 v43, v123, v237
	v_fmac_f32_e32 v44, v124, v238
	v_fmac_f32_e32 v45, v125, v239
	v_fmac_f32_e32 v46, v126, v240
	v_fmac_f32_e32 v47, v127, v241
	global_store_dwordx4 v0, v[32:35], s[22:23]
	global_store_dwordx4 v0, v[36:39], s[22:23] offset:1024
	global_store_dwordx4 v0, v[40:43], s[22:23] offset:2048
	global_store_dwordx4 v0, v[44:47], s[22:23] offset:3072
	v_mul_f32_e32 v242, v33, v33
	v_mul_f32_e32 v243, v37, v37
	v_mul_f32_e32 v244, v41, v41
	v_mul_f32_e32 v245, v45, v45
	v_fmac_f32_e32 v242, v32, v32
	v_fmac_f32_e32 v243, v36, v36
	v_fmac_f32_e32 v244, v40, v40
	v_fmac_f32_e32 v245, v44, v44
	v_fmac_f32_e32 v242, v34, v34
	v_fmac_f32_e32 v243, v38, v38
	v_fmac_f32_e32 v244, v42, v42
	v_fmac_f32_e32 v245, v46, v46
	v_fmac_f32_e32 v242, v35, v35
	v_fmac_f32_e32 v243, v39, v39
	v_fmac_f32_e32 v244, v43, v43
	v_fmac_f32_e32 v245, v47, v47
	v_add_f32_e32 v242, v242, v243
	v_add_f32_e32 v242, v242, v244
	v_add_f32_e32 v242, v242, v245
	s_nop 1
	v_add_f32_dpp v242, v242, v242 quad_perm:[1,0,3,2] row_mask:0xf bank_mask:0xf bound_ctrl:1
	s_nop 1
	v_add_f32_dpp v242, v242, v242 quad_perm:[2,3,0,1] row_mask:0xf bank_mask:0xf bound_ctrl:1
	s_nop 1
	v_add_f32_dpp v242, v242, v242 row_half_mirror row_mask:0xf bank_mask:0xf bound_ctrl:1
	s_nop 1
	v_add_f32_dpp v242, v242, v242 row_mirror row_mask:0xf bank_mask:0xf bound_ctrl:1
	s_nop 1
	ds_swizzle_b32 v243, v242 offset:swizzle(SWAP,16)
	s_waitcnt lgkmcnt(0)
	v_add_f32_e32 v242, v242, v243
	v_mov_b32_e32 v243, v242
	s_nop 1
	v_permlane32_swap_b32_e32 v242, v243
	v_add_f32_e32 v242, v242, v243
	v_fmamk_f32 v242, v242, 0x3a800000, v224
	v_rsq_f32_e32 v242, v242
	s_nop 0
	v_mul_f32_e32 v226, v32, v242
	v_mul_f32_e32 v227, v33, v242
	v_mul_f32_e32 v228, v34, v242
	v_mul_f32_e32 v229, v35, v242
	v_mul_f32_e32 v230, v36, v242
	v_mul_f32_e32 v231, v37, v242
	v_mul_f32_e32 v232, v38, v242
	v_mul_f32_e32 v233, v39, v242
	v_mul_f32_e32 v234, v40, v242
	v_mul_f32_e32 v235, v41, v242
	v_mul_f32_e32 v236, v42, v242
	v_mul_f32_e32 v237, v43, v242
	v_mul_f32_e32 v238, v44, v242
	v_mul_f32_e32 v239, v45, v242
	v_mul_f32_e32 v240, v46, v242
	v_mul_f32_e32 v241, v47, v242
	v_mul_f32_e32 v226, v96, v226
	v_mul_f32_e32 v227, v97, v227
	v_mul_f32_e32 v228, v98, v228
	v_mul_f32_e32 v229, v99, v229
	v_mul_f32_e32 v230, v100, v230
	v_mul_f32_e32 v231, v101, v231
	v_mul_f32_e32 v232, v102, v232
	v_mul_f32_e32 v233, v103, v233
	v_mul_f32_e32 v234, v104, v234
	v_mul_f32_e32 v235, v105, v235
	v_mul_f32_e32 v236, v106, v236
	v_mul_f32_e32 v237, v107, v237
	v_mul_f32_e32 v238, v108, v238
	v_mul_f32_e32 v239, v109, v239
	v_mul_f32_e32 v240, v110, v240
	v_mul_f32_e32 v241, v111, v241
	v_add_f32_e32 v162, 1.0, v162
	v_add_f32_e32 v163, 1.0, v163
	v_add_f32_e32 v164, 1.0, v164
	v_add_f32_e32 v165, 1.0, v165
	v_add_f32_e32 v166, 1.0, v166
	v_add_f32_e32 v167, 1.0, v167
	v_add_f32_e32 v168, 1.0, v168
	v_add_f32_e32 v169, 1.0, v169
	v_add_f32_e32 v170, 1.0, v170
	v_add_f32_e32 v171, 1.0, v171
	v_add_f32_e32 v172, 1.0, v172
	v_add_f32_e32 v173, 1.0, v173
	v_add_f32_e32 v174, 1.0, v174
	v_add_f32_e32 v175, 1.0, v175
	v_add_f32_e32 v176, 1.0, v176
	v_add_f32_e32 v177, 1.0, v177
	v_fma_f32 v226, v162, v226, v178
	v_fma_f32 v227, v163, v227, v179
	v_fma_f32 v228, v164, v228, v180
	v_fma_f32 v229, v165, v229, v181
	v_fma_f32 v230, v166, v230, v182
	v_fma_f32 v231, v167, v231, v183
	v_fma_f32 v232, v168, v232, v184
	v_fma_f32 v233, v169, v233, v185
	v_fma_f32 v234, v170, v234, v186
	v_fma_f32 v235, v171, v235, v187
	v_fma_f32 v236, v172, v236, v188
	v_fma_f32 v237, v173, v237, v189
	v_fma_f32 v238, v174, v238, v190
	v_fma_f32 v239, v175, v239, v191
	v_fma_f32 v240, v176, v240, v192
	v_fma_f32 v241, v177, v241, v193
	v_cvt_pk_f16_f32 v244, v226, v227
	v_cvt_pk_f16_f32 v245, v228, v229
	v_cvt_pk_f16_f32 v246, v230, v231
	v_cvt_pk_f16_f32 v247, v232, v233
	v_cvt_pk_f16_f32 v248, v234, v235
	v_cvt_pk_f16_f32 v249, v236, v237
	v_cvt_pk_f16_f32 v250, v238, v239
	v_cvt_pk_f16_f32 v251, v240, v241
	global_store_dwordx2 v202, v[244:245], s[40:41]
	global_store_dwordx2 v202, v[246:247], s[40:41] offset:512
	global_store_dwordx2 v202, v[248:249], s[40:41] offset:1024
	global_store_dwordx2 v202, v[250:251], s[40:41] offset:1536
	s_add_i32 s58, s58, s8
; DI void rows_resid_norm(const P& p, const float* xlat, const float* xctx, const h16* y, int l, int gate_idx, const float* post_g,
;                         bool do_next, int l2, const float* gain2, int sh_idx, int sc_idx, h16* dst, int nrows) {
;     ...
;   for (int row = gw; row < nrows; row += nw) {
;     const float* xr = row < TL ? xlat + (size_t)row * 1024 : xctx + (size_t)(row - TL) * 1024;
;     float* xo = row < TL ? p.out + (size_t)row * 1024 : xc + (size_t)(row - TL) * 1024;
;     const int mrow = row < TL ? (row >> 12) : 8;
;     const float* mr = mod + ((size_t)l * 9 + mrow) * 6144;
;     const float* mr2 = mod + ((size_t)l2 * 9 + mrow) * 6144;
;     f32x4 yv[4], xv[4];
;     float ss = 0.f;
; #pragma unroll
;     for (int i = 0; i < 4; ++i) {
;       h16x4 t = *(const h16x4*)(y + (size_t)row * 1024 + lane * 4 + 256 * i);
;       yv[i].x = (float)t.x; yv[i].y = (float)t.y; yv[i].z = (float)t.z; yv[i].w = (float)t.w;
;       ss += yv[i].x * yv[i].x + yv[i].y * yv[i].y + yv[i].z * yv[i].z + yv[i].w * yv[i].w;
;       xv[i] = *(const f32x4*)(xr + lane * 4 + 256 * i);
;     }
;     ss = wave_sum(ss);
;     const float rstd = rsqrtf(ss * (1.f / 1024.f) + EPS);
.Lrr21_l1:
	s_lshr_b32 s59, s58, 12
	s_cmp_lt_u32 s58, 0x8000
	s_cselect_b32 s59, s59, 8
	s_mul_i32 s59, s59, 0x6000
	s_add_u32 s24, s42, s59
	s_addc_u32 s25, s43, 0
	s_add_u32 s18, s54, s59
	s_addc_u32 s19, s55, 0
	s_add_u32 s34, s18, 0x1000
	s_addc_u32 s35, s19, 0
	s_lshl_b32 s59, s58, 11
	s_add_u32 s40, s56, s59
	s_addc_u32 s41, s57, 0
	s_sub_u32 s60, s58, 0x8000
	s_cmp_lt_u32 s58, 0x8000
	s_cselect_b32 s60, s58, s60
	s_cselect_b32 s22, s46, s50
	s_cselect_b32 s23, s47, s51
	s_lshl_b32 s60, s60, 12
	s_add_u32 s22, s22, s60
	s_addc_u32 s23, s23, 0
	global_load_dwordx4 v[112:115], v0, s[24:25]
	global_load_dwordx4 v[116:119], v0, s[24:25] offset:1024
	global_load_dwordx4 v[120:123], v0, s[24:25] offset:2048
	global_load_dwordx4 v[124:127], v0, s[24:25] offset:3072
	global_load_dwordx4 v[162:165], v0, s[34:35]
	global_load_dwordx4 v[166:169], v0, s[34:35] offset:1024
	global_load_dwordx4 v[170:173], v0, s[34:35] offset:2048
	global_load_dwordx4 v[174:177], v0, s[34:35] offset:3072
	global_load_dwordx4 v[178:181], v0, s[18:19]
	global_load_dwordx4 v[182:185], v0, s[18:19] offset:1024
	global_load_dwordx4 v[186:189], v0, s[18:19] offset:2048
	global_load_dwordx4 v[190:193], v0, s[18:19] offset:3072
	s_add_i32 s62, s58, s8
	s_add_i32 s62, s62, s8
	s_cmp_lt_i32 s62, s36
	s_cbranch_scc0 .Lrr21_tail1
	s_lshl_b32 s59, s62, 11
	s_add_u32 s20, s44, s59
	s_addc_u32 s21, s45, 0
	s_sub_u32 s60, s62, 0x8000
	s_cmp_lt_u32 s62, 0x8000
	s_cselect_b32 s60, s62, s60
	s_cselect_b32 s12, s46, s50
	s_cselect_b32 s13, s47, s51
	s_lshl_b32 s60, s60, 12
	s_add_u32 s12, s12, s60
	s_addc_u32 s13, s13, 0
	global_load_dwordx2 v[2:3], v202, s[20:21]
	global_load_dwordx2 v[4:5], v202, s[20:21] offset:512
	global_load_dwordx2 v[6:7], v202, s[20:21] offset:1024
	global_load_dwordx2 v[8:9], v202, s[20:21] offset:1536
	global_load_dwordx4 v[32:35], v0, s[12:13]
	global_load_dwordx4 v[36:39], v0, s[12:13] offset:1024
	global_load_dwordx4 v[40:43], v0, s[12:13] offset:2048
	global_load_dwordx4 v[44:47], v0, s[12:13] offset:3072
	s_waitcnt vmcnt(56)
	v_cvt_f32_f16_e32 v226, v10
	v_cvt_f32_f16_sdwa v227, v10 dst_sel:DWORD dst_unused:UNUSED_PAD src0_sel:WORD_1
	v_cvt_f32_f16_e32 v228, v11
	v_cvt_f32_f16_sdwa v229, v11 dst_sel:DWORD dst_unused:UNUSED_PAD src0_sel:WORD_1
	v_cvt_f32_f16_e32 v230, v12
	v_cvt_f32_f16_sdwa v231, v12 dst_sel:DWORD dst_unused:UNUSED_PAD src0_sel:WORD_1
	v_cvt_f32_f16_e32 v232, v13
	v_cvt_f32_f16_sdwa v233, v13 dst_sel:DWORD dst_unused:UNUSED_PAD src0_sel:WORD_1
	v_cvt_f32_f16_e32 v234, v14
	v_cvt_f32_f16_sdwa v235, v14 dst_sel:DWORD dst_unused:UNUSED_PAD src0_sel:WORD_1
	v_cvt_f32_f16_e32 v236, v15
	v_cvt_f32_f16_sdwa v237, v15 dst_sel:DWORD dst_unused:UNUSED_PAD src0_sel:WORD_1
	v_cvt_f32_f16_e32 v238, v16
	v_cvt_f32_f16_sdwa v239, v16 dst_sel:DWORD dst_unused:UNUSED_PAD src0_sel:WORD_1
	v_cvt_f32_f16_e32 v240, v17
	v_cvt_f32_f16_sdwa v241, v17 dst_sel:DWORD dst_unused:UNUSED_PAD src0_sel:WORD_1
	v_mul_f32_e32 v242, v227, v227
	v_mul_f32_e32 v243, v231, v231
	v_mul_f32_e32 v244, v235, v235
	v_mul_f32_e32 v245, v239, v239
	v_fmac_f32_e32 v242, v226, v226
	v_fmac_f32_e32 v243, v230, v230
	v_fmac_f32_e32 v244, v234, v234
	v_fmac_f32_e32 v245, v238, v238
	v_fmac_f32_e32 v242, v228, v228
	v_fmac_f32_e32 v243, v232, v232
	v_fmac_f32_e32 v244, v236, v236
	v_fmac_f32_e32 v245, v240, v240
	v_fmac_f32_e32 v242, v229, v229
	v_fmac_f32_e32 v243, v233, v233
	v_fmac_f32_e32 v244, v237, v237
	v_fmac_f32_e32 v245, v241, v241
	v_add_f32_e32 v242, v242, v243
	v_add_f32_e32 v242, v242, v244
	v_add_f32_e32 v242, v242, v245
	s_nop 1
	v_add_f32_dpp v242, v242, v242 quad_perm:[1,0,3,2] row_mask:0xf bank_mask:0xf bound_ctrl:1
	s_nop 1
	v_add_f32_dpp v242, v242, v242 quad_perm:[2,3,0,1] row_mask:0xf bank_mask:0xf bound_ctrl:1
	s_nop 1
	v_add_f32_dpp v242, v242, v242 row_half_mirror row_mask:0xf bank_mask:0xf bound_ctrl:1
	s_nop 1
	v_add_f32_dpp v242, v242, v242 row_mirror row_mask:0xf bank_mask:0xf bound_ctrl:1
	s_nop 1
	ds_swizzle_b32 v243, v242 offset:swizzle(SWAP,16)
	s_waitcnt lgkmcnt(0)
	v_add_f32_e32 v242, v242, v243
	v_mov_b32_e32 v243, v242
	s_nop 1
	v_permlane32_swap_b32_e32 v242, v243
	v_add_f32_e32 v242, v242, v243
	v_fmamk_f32 v242, v242, 0x3a800000, v224
	v_rsq_f32_e32 v242, v242
	s_waitcnt vmcnt(8)
; DI void rows_resid_norm(const P& p, const float* xlat, const float* xctx, const h16* y, int l, int gate_idx, const float* post_g,
;                         bool do_next, int l2, const float* gain2, int sh_idx, int sc_idx, h16* dst, int nrows) {
;     ...
;     float s2 = 0.f;
; #pragma unroll
;     for (int i = 0; i < 4; ++i) {
;       const int c = lane * 4 + 256 * i;
;       f32x4 g = *(const f32x4*)(post_g + c), gt = *(const f32x4*)(mr + gate_idx * 1024 + c);
;       xv[i].x += gt.x * (yv[i].x * rstd * g.x);
;       xv[i].y += gt.y * (yv[i].y * rstd * g.y);
;       xv[i].z += gt.z * (yv[i].z * rstd * g.z);
;       xv[i].w += gt.w * (yv[i].w * rstd * g.w);
;       *(f32x4*)(xo + c) = xv[i];
;       s2 += xv[i].x * xv[i].x + xv[i].y * xv[i].y + xv[i].z * xv[i].z + xv[i].w * xv[i].w;
;     }
;     if (do_next) {
;       s2 = wave_sum(s2);
;       const float r2 = rsqrtf(s2 * (1.f / 1024.f) + EPS);
; #pragma unroll
;       for (int i = 0; i < 4; ++i) {
;         const int c = lane * 4 + 256 * i;
;         f32x4 g = *(const f32x4*)(gain2 + c), sc = *(const f32x4*)(mr2 + sc_idx * 1024 + c), sh = *(const f32x4*)(mr2 + sh_idx * 1024 + c);
;         h16x4 o;
;         o.x = (h16)(xv[i].x * r2 * g.x * (1.f + sc.x) + sh.x);
;         o.y = (h16)(xv[i].y * r2 * g.y * (1.f + sc.y) + sh.y);
;         o.z = (h16)(xv[i].z * r2 * g.z * (1.f + sc.z) + sh.z);
;         o.w = (h16)(xv[i].w * r2 * g.w * (1.f + sc.w) + sh.w);
;         *(h16x4*)(dst + (size_t)row * 1024 + c) = o;
;       }
;     }
	v_mul_f32_e32 v226, v226, v242
	v_mul_f32_e32 v227, v227, v242
	v_mul_f32_e32 v228, v228, v242
	v_mul_f32_e32 v229, v229, v242
	v_mul_f32_e32 v230, v230, v242
	v_mul_f32_e32 v231, v231, v242
	v_mul_f32_e32 v232, v232, v242
	v_mul_f32_e32 v233, v233, v242
	v_mul_f32_e32 v234, v234, v242
	v_mul_f32_e32 v235, v235, v242
	v_mul_f32_e32 v236, v236, v242
	v_mul_f32_e32 v237, v237, v242
	v_mul_f32_e32 v238, v238, v242
	v_mul_f32_e32 v239, v239, v242
	v_mul_f32_e32 v240, v240, v242
	v_mul_f32_e32 v241, v241, v242
	v_mul_f32_e32 v226, v80, v226
	v_mul_f32_e32 v227, v81, v227
	v_mul_f32_e32 v228, v82, v228
	v_mul_f32_e32 v229, v83, v229
	v_mul_f32_e32 v230, v84, v230
	v_mul_f32_e32 v231, v85, v231
	v_mul_f32_e32 v232, v86, v232
	v_mul_f32_e32 v233, v87, v233
	v_mul_f32_e32 v234, v88, v234
	v_mul_f32_e32 v235, v89, v235
	v_mul_f32_e32 v236, v90, v236
	v_mul_f32_e32 v237, v91, v237
	v_mul_f32_e32 v238, v92, v238
	v_mul_f32_e32 v239, v93, v239
	v_mul_f32_e32 v240, v94, v240
	v_mul_f32_e32 v241, v95, v241
	v_fmac_f32_e32 v48, v112, v226
	v_fmac_f32_e32 v49, v113, v227
	v_fmac_f32_e32 v50, v114, v228
	v_fmac_f32_e32 v51, v115, v229
	v_fmac_f32_e32 v52, v116, v230
	v_fmac_f32_e32 v53, v117, v231
	v_fmac_f32_e32 v54, v118, v232
	v_fmac_f32_e32 v55, v119, v233
	v_fmac_f32_e32 v56, v120, v234
	v_fmac_f32_e32 v57, v121, v235
	v_fmac_f32_e32 v58, v122, v236
	v_fmac_f32_e32 v59, v123, v237
	v_fmac_f32_e32 v60, v124, v238
	v_fmac_f32_e32 v61, v125, v239
	v_fmac_f32_e32 v62, v126, v240
	v_fmac_f32_e32 v63, v127, v241
	global_store_dwordx4 v0, v[48:51], s[22:23]
	global_store_dwordx4 v0, v[52:55], s[22:23] offset:1024
	global_store_dwordx4 v0, v[56:59], s[22:23] offset:2048
	global_store_dwordx4 v0, v[60:63], s[22:23] offset:3072
	v_mul_f32_e32 v242, v49, v49
	v_mul_f32_e32 v243, v53, v53
	v_mul_f32_e32 v244, v57, v57
	v_mul_f32_e32 v245, v61, v61
	v_fmac_f32_e32 v242, v48, v48
	v_fmac_f32_e32 v243, v52, v52
	v_fmac_f32_e32 v244, v56, v56
	v_fmac_f32_e32 v245, v60, v60
	v_fmac_f32_e32 v242, v50, v50
	v_fmac_f32_e32 v243, v54, v54
	v_fmac_f32_e32 v244, v58, v58
	v_fmac_f32_e32 v245, v62, v62
	v_fmac_f32_e32 v242, v51, v51
	v_fmac_f32_e32 v243, v55, v55
	v_fmac_f32_e32 v244, v59, v59
	v_fmac_f32_e32 v245, v63, v63
	v_add_f32_e32 v242, v242, v243
	v_add_f32_e32 v242, v242, v244
	v_add_f32_e32 v242, v242, v245
	s_nop 1
	v_add_f32_dpp v242, v242, v242 quad_perm:[1,0,3,2] row_mask:0xf bank_mask:0xf bound_ctrl:1
	s_nop 1
	v_add_f32_dpp v242, v242, v242 quad_perm:[2,3,0,1] row_mask:0xf bank_mask:0xf bound_ctrl:1
	s_nop 1
	v_add_f32_dpp v242, v242, v242 row_half_mirror row_mask:0xf bank_mask:0xf bound_ctrl:1
	s_nop 1
	v_add_f32_dpp v242, v242, v242 row_mirror row_mask:0xf bank_mask:0xf bound_ctrl:1
	s_nop 1
	ds_swizzle_b32 v243, v242 offset:swizzle(SWAP,16)
	s_waitcnt lgkmcnt(0)
	v_add_f32_e32 v242, v242, v243
	v_mov_b32_e32 v243, v242
	s_nop 1
	v_permlane32_swap_b32_e32 v242, v243
	v_add_f32_e32 v242, v242, v243
	v_fmamk_f32 v242, v242, 0x3a800000, v224
	v_rsq_f32_e32 v242, v242
	s_nop 0
	v_mul_f32_e32 v226, v48, v242
	v_mul_f32_e32 v227, v49, v242
	v_mul_f32_e32 v228, v50, v242
	v_mul_f32_e32 v229, v51, v242
	v_mul_f32_e32 v230, v52, v242
	v_mul_f32_e32 v231, v53, v242
	v_mul_f32_e32 v232, v54, v242
	v_mul_f32_e32 v233, v55, v242
	v_mul_f32_e32 v234, v56, v242
	v_mul_f32_e32 v235, v57, v242
	v_mul_f32_e32 v236, v58, v242
	v_mul_f32_e32 v237, v59, v242
	v_mul_f32_e32 v238, v60, v242
	v_mul_f32_e32 v239, v61, v242
	v_mul_f32_e32 v240, v62, v242
	v_mul_f32_e32 v241, v63, v242
	v_mul_f32_e32 v226, v96, v226
	v_mul_f32_e32 v227, v97, v227
	v_mul_f32_e32 v228, v98, v228
	v_mul_f32_e32 v229, v99, v229
	v_mul_f32_e32 v230, v100, v230
	v_mul_f32_e32 v231, v101, v231
	v_mul_f32_e32 v232, v102, v232
	v_mul_f32_e32 v233, v103, v233
	v_mul_f32_e32 v234, v104, v234
	v_mul_f32_e32 v235, v105, v235
	v_mul_f32_e32 v236, v106, v236
	v_mul_f32_e32 v237, v107, v237
	v_mul_f32_e32 v238, v108, v238
	v_mul_f32_e32 v239, v109, v239
	v_mul_f32_e32 v240, v110, v240
	v_mul_f32_e32 v241, v111, v241
	v_add_f32_e32 v162, 1.0, v162
	v_add_f32_e32 v163, 1.0, v163
	v_add_f32_e32 v164, 1.0, v164
	v_add_f32_e32 v165, 1.0, v165
	v_add_f32_e32 v166, 1.0, v166
	v_add_f32_e32 v167, 1.0, v167
	v_add_f32_e32 v168, 1.0, v168
	v_add_f32_e32 v169, 1.0, v169
	v_add_f32_e32 v170, 1.0, v170
	v_add_f32_e32 v171, 1.0, v171
	v_add_f32_e32 v172, 1.0, v172
	v_add_f32_e32 v173, 1.0, v173
	v_add_f32_e32 v174, 1.0, v174
	v_add_f32_e32 v175, 1.0, v175
	v_add_f32_e32 v176, 1.0, v176
	v_add_f32_e32 v177, 1.0, v177
	v_fma_f32 v226, v162, v226, v178
	v_fma_f32 v227, v163, v227, v179
	v_fma_f32 v228, v164, v228, v180
	v_fma_f32 v229, v165, v229, v181
	v_fma_f32 v230, v166, v230, v182
	v_fma_f32 v231, v167, v231, v183
	v_fma_f32 v232, v168, v232, v184
	v_fma_f32 v233, v169, v233, v185
	v_fma_f32 v234, v170, v234, v186
	v_fma_f32 v235, v171, v235, v187
	v_fma_f32 v236, v172, v236, v188
	v_fma_f32 v237, v173, v237, v189
	v_fma_f32 v238, v174, v238, v190
	v_fma_f32 v239, v175, v239, v191
	v_fma_f32 v240, v176, v240, v192
	v_fma_f32 v241, v177, v241, v193
	v_cvt_pk_f16_f32 v244, v226, v227
	v_cvt_pk_f16_f32 v245, v228, v229
	v_cvt_pk_f16_f32 v246, v230, v231
	v_cvt_pk_f16_f32 v247, v232, v233
	v_cvt_pk_f16_f32 v248, v234, v235
	v_cvt_pk_f16_f32 v249, v236, v237
	v_cvt_pk_f16_f32 v250, v238, v239
	v_cvt_pk_f16_f32 v251, v240, v241
	global_store_dwordx2 v202, v[244:245], s[40:41]
	global_store_dwordx2 v202, v[246:247], s[40:41] offset:512
	global_store_dwordx2 v202, v[248:249], s[40:41] offset:1024
	global_store_dwordx2 v202, v[250:251], s[40:41] offset:1536
	s_add_i32 s58, s58, s8
	s_branch .Lrr21_l2
; DI void rows_resid_norm(const P& p, const float* xlat, const float* xctx, const h16* y, int l, int gate_idx, const float* post_g,
;                         bool do_next, int l2, const float* gain2, int sh_idx, int sc_idx, h16* dst, int nrows) {
;     ...
;     f32x4 yv[4], xv[4];
;     float ss = 0.f;
; #pragma unroll
;     for (int i = 0; i < 4; ++i) {
;       h16x4 t = *(const h16x4*)(y + (size_t)row * 1024 + lane * 4 + 256 * i);
;       yv[i].x = (float)t.x; yv[i].y = (float)t.y; yv[i].z = (float)t.z; yv[i].w = (float)t.w;
;       ss += yv[i].x * yv[i].x + yv[i].y * yv[i].y + yv[i].z * yv[i].z + yv[i].w * yv[i].w;
;       xv[i] = *(const f32x4*)(xr + lane * 4 + 256 * i);
;     }
;     ss = wave_sum(ss);
;     const float rstd = rsqrtf(ss * (1.f / 1024.f) + EPS);
;     float s2 = 0.f;
; #pragma unroll
;     for (int i = 0; i < 4; ++i) {
;       const int c = lane * 4 + 256 * i;
;       f32x4 g = *(const f32x4*)(post_g + c), gt = *(const f32x4*)(mr + gate_idx * 1024 + c);
;       xv[i].x += gt.x * (yv[i].x * rstd * g.x);
;       xv[i].y += gt.y * (yv[i].y * rstd * g.y);
;       xv[i].z += gt.z * (yv[i].z * rstd * g.z);
;       xv[i].w += gt.w * (yv[i].w * rstd * g.w);
;       *(f32x4*)(xo + c) = xv[i];
;       s2 += xv[i].x * xv[i].x + xv[i].y * xv[i].y + xv[i].z * xv[i].z + xv[i].w * xv[i].w;
;     }
;     if (do_next) {
;       s2 = wave_sum(s2);
.Lrr21_tail0:
	s_waitcnt vmcnt(12)
	v_cvt_f32_f16_e32 v226, v2
	v_cvt_f32_f16_sdwa v227, v2 dst_sel:DWORD dst_unused:UNUSED_PAD src0_sel:WORD_1
	v_cvt_f32_f16_e32 v228, v3
	v_cvt_f32_f16_sdwa v229, v3 dst_sel:DWORD dst_unused:UNUSED_PAD src0_sel:WORD_1
	v_cvt_f32_f16_e32 v230, v4
	v_cvt_f32_f16_sdwa v231, v4 dst_sel:DWORD dst_unused:UNUSED_PAD src0_sel:WORD_1
	v_cvt_f32_f16_e32 v232, v5
	v_cvt_f32_f16_sdwa v233, v5 dst_sel:DWORD dst_unused:UNUSED_PAD src0_sel:WORD_1
	v_cvt_f32_f16_e32 v234, v6
	v_cvt_f32_f16_sdwa v235, v6 dst_sel:DWORD dst_unused:UNUSED_PAD src0_sel:WORD_1
	v_cvt_f32_f16_e32 v236, v7
	v_cvt_f32_f16_sdwa v237, v7 dst_sel:DWORD dst_unused:UNUSED_PAD src0_sel:WORD_1
	v_cvt_f32_f16_e32 v238, v8
	v_cvt_f32_f16_sdwa v239, v8 dst_sel:DWORD dst_unused:UNUSED_PAD src0_sel:WORD_1
	v_cvt_f32_f16_e32 v240, v9
	v_cvt_f32_f16_sdwa v241, v9 dst_sel:DWORD dst_unused:UNUSED_PAD src0_sel:WORD_1
	v_mul_f32_e32 v242, v227, v227
	v_mul_f32_e32 v243, v231, v231
	v_mul_f32_e32 v244, v235, v235
	v_mul_f32_e32 v245, v239, v239
	v_fmac_f32_e32 v242, v226, v226
	v_fmac_f32_e32 v243, v230, v230
	v_fmac_f32_e32 v244, v234, v234
	v_fmac_f32_e32 v245, v238, v238
	v_fmac_f32_e32 v242, v228, v228
	v_fmac_f32_e32 v243, v232, v232
	v_fmac_f32_e32 v244, v236, v236
	v_fmac_f32_e32 v245, v240, v240
	v_fmac_f32_e32 v242, v229, v229
	v_fmac_f32_e32 v243, v233, v233
	v_fmac_f32_e32 v244, v237, v237
	v_fmac_f32_e32 v245, v241, v241
	v_add_f32_e32 v242, v242, v243
	v_add_f32_e32 v242, v242, v244
	v_add_f32_e32 v242, v242, v245
	s_nop 1
	v_add_f32_dpp v242, v242, v242 quad_perm:[1,0,3,2] row_mask:0xf bank_mask:0xf bound_ctrl:1
	s_nop 1
	v_add_f32_dpp v242, v242, v242 quad_perm:[2,3,0,1] row_mask:0xf bank_mask:0xf bound_ctrl:1
	s_nop 1
	v_add_f32_dpp v242, v242, v242 row_half_mirror row_mask:0xf bank_mask:0xf bound_ctrl:1
	s_nop 1
	v_add_f32_dpp v242, v242, v242 row_mirror row_mask:0xf bank_mask:0xf bound_ctrl:1
	s_nop 1
	ds_swizzle_b32 v243, v242 offset:swizzle(SWAP,16)
	s_waitcnt lgkmcnt(0)
	v_add_f32_e32 v242, v242, v243
	v_mov_b32_e32 v243, v242
	s_nop 1
	v_permlane32_swap_b32_e32 v242, v243
	v_add_f32_e32 v242, v242, v243
	v_fmamk_f32 v242, v242, 0x3a800000, v224
	v_rsq_f32_e32 v242, v242
	s_waitcnt vmcnt(0)
	v_mul_f32_e32 v226, v226, v242
	v_mul_f32_e32 v227, v227, v242
	v_mul_f32_e32 v228, v228, v242
	v_mul_f32_e32 v229, v229, v242
	v_mul_f32_e32 v230, v230, v242
	v_mul_f32_e32 v231, v231, v242
	v_mul_f32_e32 v232, v232, v242
	v_mul_f32_e32 v233, v233, v242
	v_mul_f32_e32 v234, v234, v242
	v_mul_f32_e32 v235, v235, v242
	v_mul_f32_e32 v236, v236, v242
	v_mul_f32_e32 v237, v237, v242
	v_mul_f32_e32 v238, v238, v242
	v_mul_f32_e32 v239, v239, v242
	v_mul_f32_e32 v240, v240, v242
	v_mul_f32_e32 v241, v241, v242
	v_mul_f32_e32 v226, v80, v226
	v_mul_f32_e32 v227, v81, v227
	v_mul_f32_e32 v228, v82, v228
	v_mul_f32_e32 v229, v83, v229
	v_mul_f32_e32 v230, v84, v230
	v_mul_f32_e32 v231, v85, v231
	v_mul_f32_e32 v232, v86, v232
	v_mul_f32_e32 v233, v87, v233
	v_mul_f32_e32 v234, v88, v234
	v_mul_f32_e32 v235, v89, v235
	v_mul_f32_e32 v236, v90, v236
	v_mul_f32_e32 v237, v91, v237
	v_mul_f32_e32 v238, v92, v238
	v_mul_f32_e32 v239, v93, v239
	v_mul_f32_e32 v240, v94, v240
	v_mul_f32_e32 v241, v95, v241
	v_fmac_f32_e32 v32, v112, v226
	v_fmac_f32_e32 v33, v113, v227
	v_fmac_f32_e32 v34, v114, v228
	v_fmac_f32_e32 v35, v115, v229
	v_fmac_f32_e32 v36, v116, v230
	v_fmac_f32_e32 v37, v117, v231
	v_fmac_f32_e32 v38, v118, v232
	v_fmac_f32_e32 v39, v119, v233
	v_fmac_f32_e32 v40, v120, v234
	v_fmac_f32_e32 v41, v121, v235
	v_fmac_f32_e32 v42, v122, v236
	v_fmac_f32_e32 v43, v123, v237
	v_fmac_f32_e32 v44, v124, v238
	v_fmac_f32_e32 v45, v125, v239
	v_fmac_f32_e32 v46, v126, v240
	v_fmac_f32_e32 v47, v127, v241
	global_store_dwordx4 v0, v[32:35], s[22:23]
	global_store_dwordx4 v0, v[36:39], s[22:23] offset:1024
	global_store_dwordx4 v0, v[40:43], s[22:23] offset:2048
	global_store_dwordx4 v0, v[44:47], s[22:23] offset:3072
	v_mul_f32_e32 v242, v33, v33
	v_mul_f32_e32 v243, v37, v37
	v_mul_f32_e32 v244, v41, v41
	v_mul_f32_e32 v245, v45, v45
	v_fmac_f32_e32 v242, v32, v32
	v_fmac_f32_e32 v243, v36, v36
	v_fmac_f32_e32 v244, v40, v40
	v_fmac_f32_e32 v245, v44, v44
	v_fmac_f32_e32 v242, v34, v34
	v_fmac_f32_e32 v243, v38, v38
	v_fmac_f32_e32 v244, v42, v42
	v_fmac_f32_e32 v245, v46, v46
	v_fmac_f32_e32 v242, v35, v35
	v_fmac_f32_e32 v243, v39, v39
	v_fmac_f32_e32 v244, v43, v43
	v_fmac_f32_e32 v245, v47, v47
	v_add_f32_e32 v242, v242, v243
	v_add_f32_e32 v242, v242, v244
	v_add_f32_e32 v242, v242, v245
	s_nop 1
	v_add_f32_dpp v242, v242, v242 quad_perm:[1,0,3,2] row_mask:0xf bank_mask:0xf bound_ctrl:1
	s_nop 1
	v_add_f32_dpp v242, v242, v242 quad_perm:[2,3,0,1] row_mask:0xf bank_mask:0xf bound_ctrl:1
	s_nop 1
	v_add_f32_dpp v242, v242, v242 row_half_mirror row_mask:0xf bank_mask:0xf bound_ctrl:1
	s_nop 1
	v_add_f32_dpp v242, v242, v242 row_mirror row_mask:0xf bank_mask:0xf bound_ctrl:1
	s_nop 1
	ds_swizzle_b32 v243, v242 offset:swizzle(SWAP,16)
	s_waitcnt lgkmcnt(0)
; DI void rows_resid_norm(const P& p, const float* xlat, const float* xctx, const h16* y, int l, int gate_idx, const float* post_g,
;                         bool do_next, int l2, const float* gain2, int sh_idx, int sc_idx, h16* dst, int nrows) {
;     ...
;   for (int row = gw; row < nrows; row += nw) {
;     const float* xr = row < TL ? xlat + (size_t)row * 1024 : xctx + (size_t)(row - TL) * 1024;
;     float* xo = row < TL ? p.out + (size_t)row * 1024 : xc + (size_t)(row - TL) * 1024;
;     const int mrow = row < TL ? (row >> 12) : 8;
;     const float* mr = mod + ((size_t)l * 9 + mrow) * 6144;
;     const float* mr2 = mod + ((size_t)l2 * 9 + mrow) * 6144;
;     f32x4 yv[4], xv[4];
;     float ss = 0.f;
; #pragma unroll
;     for (int i = 0; i < 4; ++i) {
;       h16x4 t = *(const h16x4*)(y + (size_t)row * 1024 + lane * 4 + 256 * i);
;       yv[i].x = (float)t.x; yv[i].y = (float)t.y; yv[i].z = (float)t.z; yv[i].w = (float)t.w;
;       ss += yv[i].x * yv[i].x + yv[i].y * yv[i].y + yv[i].z * yv[i].z + yv[i].w * yv[i].w;
;       xv[i] = *(const f32x4*)(xr + lane * 4 + 256 * i);
;     }
;     ss = wave_sum(ss);
;     const float rstd = rsqrtf(ss * (1.f / 1024.f) + EPS);
;     ...
;       const float r2 = rsqrtf(s2 * (1.f / 1024.f) + EPS);
; #pragma unroll
;       for (int i = 0; i < 4; ++i) {
;         const int c = lane * 4 + 256 * i;
;         f32x4 g = *(const f32x4*)(gain2 + c), sc = *(const f32x4*)(mr2 + sc_idx * 1024 + c), sh = *(const f32x4*)(mr2 + sh_idx * 1024 + c);
;         h16x4 o;
;         o.x = (h16)(xv[i].x * r2 * g.x * (1.f + sc.x) + sh.x);
;         o.y = (h16)(xv[i].y * r2 * g.y * (1.f + sc.y) + sh.y);
;         o.z = (h16)(xv[i].z * r2 * g.z * (1.f + sc.z) + sh.z);
;         o.w = (h16)(xv[i].w * r2 * g.w * (1.f + sc.w) + sh.w);
;         *(h16x4*)(dst + (size_t)row * 1024 + c) = o;
;       }
;     }
	v_add_f32_e32 v242, v242, v243
	v_mov_b32_e32 v243, v242
	s_nop 1
	v_permlane32_swap_b32_e32 v242, v243
	v_add_f32_e32 v242, v242, v243
	v_fmamk_f32 v242, v242, 0x3a800000, v224
	v_rsq_f32_e32 v242, v242
	s_nop 0
	v_mul_f32_e32 v226, v32, v242
	v_mul_f32_e32 v227, v33, v242
	v_mul_f32_e32 v228, v34, v242
	v_mul_f32_e32 v229, v35, v242
	v_mul_f32_e32 v230, v36, v242
	v_mul_f32_e32 v231, v37, v242
	v_mul_f32_e32 v232, v38, v242
	v_mul_f32_e32 v233, v39, v242
	v_mul_f32_e32 v234, v40, v242
	v_mul_f32_e32 v235, v41, v242
	v_mul_f32_e32 v236, v42, v242
	v_mul_f32_e32 v237, v43, v242
	v_mul_f32_e32 v238, v44, v242
	v_mul_f32_e32 v239, v45, v242
	v_mul_f32_e32 v240, v46, v242
	v_mul_f32_e32 v241, v47, v242
	v_mul_f32_e32 v226, v96, v226
	v_mul_f32_e32 v227, v97, v227
	v_mul_f32_e32 v228, v98, v228
	v_mul_f32_e32 v229, v99, v229
	v_mul_f32_e32 v230, v100, v230
	v_mul_f32_e32 v231, v101, v231
	v_mul_f32_e32 v232, v102, v232
	v_mul_f32_e32 v233, v103, v233
	v_mul_f32_e32 v234, v104, v234
	v_mul_f32_e32 v235, v105, v235
	v_mul_f32_e32 v236, v106, v236
	v_mul_f32_e32 v237, v107, v237
	v_mul_f32_e32 v238, v108, v238
	v_mul_f32_e32 v239, v109, v239
	v_mul_f32_e32 v240, v110, v240
	v_mul_f32_e32 v241, v111, v241
	v_add_f32_e32 v162, 1.0, v162
	v_add_f32_e32 v163, 1.0, v163
	v_add_f32_e32 v164, 1.0, v164
	v_add_f32_e32 v165, 1.0, v165
	v_add_f32_e32 v166, 1.0, v166
	v_add_f32_e32 v167, 1.0, v167
	v_add_f32_e32 v168, 1.0, v168
	v_add_f32_e32 v169, 1.0, v169
	v_add_f32_e32 v170, 1.0, v170
	v_add_f32_e32 v171, 1.0, v171
	v_add_f32_e32 v172, 1.0, v172
	v_add_f32_e32 v173, 1.0, v173
	v_add_f32_e32 v174, 1.0, v174
	v_add_f32_e32 v175, 1.0, v175
	v_add_f32_e32 v176, 1.0, v176
	v_add_f32_e32 v177, 1.0, v177
	v_fma_f32 v226, v162, v226, v178
	v_fma_f32 v227, v163, v227, v179
	v_fma_f32 v228, v164, v228, v180
	v_fma_f32 v229, v165, v229, v181
	v_fma_f32 v230, v166, v230, v182
	v_fma_f32 v231, v167, v231, v183
	v_fma_f32 v232, v168, v232, v184
	v_fma_f32 v233, v169, v233, v185
	v_fma_f32 v234, v170, v234, v186
	v_fma_f32 v235, v171, v235, v187
	v_fma_f32 v236, v172, v236, v188
	v_fma_f32 v237, v173, v237, v189
	v_fma_f32 v238, v174, v238, v190
	v_fma_f32 v239, v175, v239, v191
	v_fma_f32 v240, v176, v240, v192
	v_fma_f32 v241, v177, v241, v193
	v_cvt_pk_f16_f32 v244, v226, v227
	v_cvt_pk_f16_f32 v245, v228, v229
	v_cvt_pk_f16_f32 v246, v230, v231
	v_cvt_pk_f16_f32 v247, v232, v233
	v_cvt_pk_f16_f32 v248, v234, v235
	v_cvt_pk_f16_f32 v249, v236, v237
	v_cvt_pk_f16_f32 v250, v238, v239
	v_cvt_pk_f16_f32 v251, v240, v241
	global_store_dwordx2 v202, v[244:245], s[40:41]
	global_store_dwordx2 v202, v[246:247], s[40:41] offset:512
	global_store_dwordx2 v202, v[248:249], s[40:41] offset:1024
	global_store_dwordx2 v202, v[250:251], s[40:41] offset:1536
	s_add_i32 s58, s58, s8
	s_cmp_lt_i32 s58, s36
	s_cbranch_scc0 .Lrr2_exit
	s_lshr_b32 s59, s58, 12
	s_cmp_lt_u32 s58, 0x8000
	s_cselect_b32 s59, s59, 8
	s_mul_i32 s59, s59, 0x6000
	s_add_u32 s24, s42, s59
	s_addc_u32 s25, s43, 0
	s_add_u32 s18, s54, s59
	s_addc_u32 s19, s55, 0
	s_add_u32 s34, s18, 0x1000
	s_addc_u32 s35, s19, 0
	s_lshl_b32 s59, s58, 11
	s_add_u32 s40, s56, s59
	s_addc_u32 s41, s57, 0
	s_sub_u32 s60, s58, 0x8000
	s_cmp_lt_u32 s58, 0x8000
	s_cselect_b32 s60, s58, s60
	s_cselect_b32 s22, s46, s50
	s_cselect_b32 s23, s47, s51
	s_lshl_b32 s60, s60, 12
	s_add_u32 s22, s22, s60
	s_addc_u32 s23, s23, 0
	global_load_dwordx4 v[112:115], v0, s[24:25]
	global_load_dwordx4 v[116:119], v0, s[24:25] offset:1024
	global_load_dwordx4 v[120:123], v0, s[24:25] offset:2048
	global_load_dwordx4 v[124:127], v0, s[24:25] offset:3072
	global_load_dwordx4 v[162:165], v0, s[34:35]
	global_load_dwordx4 v[166:169], v0, s[34:35] offset:1024
	global_load_dwordx4 v[170:173], v0, s[34:35] offset:2048
	global_load_dwordx4 v[174:177], v0, s[34:35] offset:3072
	global_load_dwordx4 v[178:181], v0, s[18:19]
	global_load_dwordx4 v[182:185], v0, s[18:19] offset:1024
	global_load_dwordx4 v[186:189], v0, s[18:19] offset:2048
	global_load_dwordx4 v[190:193], v0, s[18:19] offset:3072
	s_waitcnt vmcnt(12)
	v_cvt_f32_f16_e32 v226, v10
	v_cvt_f32_f16_sdwa v227, v10 dst_sel:DWORD dst_unused:UNUSED_PAD src0_sel:WORD_1
	v_cvt_f32_f16_e32 v228, v11
	v_cvt_f32_f16_sdwa v229, v11 dst_sel:DWORD dst_unused:UNUSED_PAD src0_sel:WORD_1
	v_cvt_f32_f16_e32 v230, v12
	v_cvt_f32_f16_sdwa v231, v12 dst_sel:DWORD dst_unused:UNUSED_PAD src0_sel:WORD_1
	v_cvt_f32_f16_e32 v232, v13
	v_cvt_f32_f16_sdwa v233, v13 dst_sel:DWORD dst_unused:UNUSED_PAD src0_sel:WORD_1
	v_cvt_f32_f16_e32 v234, v14
	v_cvt_f32_f16_sdwa v235, v14 dst_sel:DWORD dst_unused:UNUSED_PAD src0_sel:WORD_1
	v_cvt_f32_f16_e32 v236, v15
	v_cvt_f32_f16_sdwa v237, v15 dst_sel:DWORD dst_unused:UNUSED_PAD src0_sel:WORD_1
	v_cvt_f32_f16_e32 v238, v16
	v_cvt_f32_f16_sdwa v239, v16 dst_sel:DWORD dst_unused:UNUSED_PAD src0_sel:WORD_1
	v_cvt_f32_f16_e32 v240, v17
	v_cvt_f32_f16_sdwa v241, v17 dst_sel:DWORD dst_unused:UNUSED_PAD src0_sel:WORD_1
	v_mul_f32_e32 v242, v227, v227
	v_mul_f32_e32 v243, v231, v231
	v_mul_f32_e32 v244, v235, v235
	v_mul_f32_e32 v245, v239, v239
	v_fmac_f32_e32 v242, v226, v226
	v_fmac_f32_e32 v243, v230, v230
	v_fmac_f32_e32 v244, v234, v234
	v_fmac_f32_e32 v245, v238, v238
	v_fmac_f32_e32 v242, v228, v228
	v_fmac_f32_e32 v243, v232, v232
	v_fmac_f32_e32 v244, v236, v236
	v_fmac_f32_e32 v245, v240, v240
	v_fmac_f32_e32 v242, v229, v229
	v_fmac_f32_e32 v243, v233, v233
	v_fmac_f32_e32 v244, v237, v237
	v_fmac_f32_e32 v245, v241, v241
	v_add_f32_e32 v242, v242, v243
	v_add_f32_e32 v242, v242, v244
	v_add_f32_e32 v242, v242, v245
	s_nop 1
	v_add_f32_dpp v242, v242, v242 quad_perm:[1,0,3,2] row_mask:0xf bank_mask:0xf bound_ctrl:1
	s_nop 1
	v_add_f32_dpp v242, v242, v242 quad_perm:[2,3,0,1] row_mask:0xf bank_mask:0xf bound_ctrl:1
	s_nop 1
	v_add_f32_dpp v242, v242, v242 row_half_mirror row_mask:0xf bank_mask:0xf bound_ctrl:1
	s_nop 1
	v_add_f32_dpp v242, v242, v242 row_mirror row_mask:0xf bank_mask:0xf bound_ctrl:1
	s_nop 1
	ds_swizzle_b32 v243, v242 offset:swizzle(SWAP,16)
	s_waitcnt lgkmcnt(0)
; DI void rows_resid_norm(const P& p, const float* xlat, const float* xctx, const h16* y, int l, int gate_idx, const float* post_g,
;                         bool do_next, int l2, const float* gain2, int sh_idx, int sc_idx, h16* dst, int nrows) {
;     ...
;     const float rstd = rsqrtf(ss * (1.f / 1024.f) + EPS);
;     float s2 = 0.f;
; #pragma unroll
;     for (int i = 0; i < 4; ++i) {
;       const int c = lane * 4 + 256 * i;
;       f32x4 g = *(const f32x4*)(post_g + c), gt = *(const f32x4*)(mr + gate_idx * 1024 + c);
;       xv[i].x += gt.x * (yv[i].x * rstd * g.x);
;       xv[i].y += gt.y * (yv[i].y * rstd * g.y);
;       xv[i].z += gt.z * (yv[i].z * rstd * g.z);
;       xv[i].w += gt.w * (yv[i].w * rstd * g.w);
;       *(f32x4*)(xo + c) = xv[i];
;       s2 += xv[i].x * xv[i].x + xv[i].y * xv[i].y + xv[i].z * xv[i].z + xv[i].w * xv[i].w;
;     }
;     if (do_next) {
;       s2 = wave_sum(s2);
;       const float r2 = rsqrtf(s2 * (1.f / 1024.f) + EPS);
; #pragma unroll
;       for (int i = 0; i < 4; ++i) {
;         const int c = lane * 4 + 256 * i;
;         f32x4 g = *(const f32x4*)(gain2 + c), sc = *(const f32x4*)(mr2 + sc_idx * 1024 + c), sh = *(const f32x4*)(mr2 + sh_idx * 1024 + c);
;         h16x4 o;
;         o.x = (h16)(xv[i].x * r2 * g.x * (1.f + sc.x) + sh.x);
;         o.y = (h16)(xv[i].y * r2 * g.y * (1.f + sc.y) + sh.y);
;         o.z = (h16)(xv[i].z * r2 * g.z * (1.f + sc.z) + sh.z);
;         o.w = (h16)(xv[i].w * r2 * g.w * (1.f + sc.w) + sh.w);
;         *(h16x4*)(dst + (size_t)row * 1024 + c) = o;
;       }
;     }
	v_add_f32_e32 v242, v242, v243
	v_mov_b32_e32 v243, v242
	s_nop 1
	v_permlane32_swap_b32_e32 v242, v243
	v_add_f32_e32 v242, v242, v243
	v_fmamk_f32 v242, v242, 0x3a800000, v224
	v_rsq_f32_e32 v242, v242
	s_waitcnt vmcnt(0)
	v_mul_f32_e32 v226, v226, v242
	v_mul_f32_e32 v227, v227, v242
	v_mul_f32_e32 v228, v228, v242
	v_mul_f32_e32 v229, v229, v242
	v_mul_f32_e32 v230, v230, v242
	v_mul_f32_e32 v231, v231, v242
	v_mul_f32_e32 v232, v232, v242
	v_mul_f32_e32 v233, v233, v242
	v_mul_f32_e32 v234, v234, v242
	v_mul_f32_e32 v235, v235, v242
	v_mul_f32_e32 v236, v236, v242
	v_mul_f32_e32 v237, v237, v242
	v_mul_f32_e32 v238, v238, v242
	v_mul_f32_e32 v239, v239, v242
	v_mul_f32_e32 v240, v240, v242
	v_mul_f32_e32 v241, v241, v242
	v_mul_f32_e32 v226, v80, v226
	v_mul_f32_e32 v227, v81, v227
	v_mul_f32_e32 v228, v82, v228
	v_mul_f32_e32 v229, v83, v229
	v_mul_f32_e32 v230, v84, v230
	v_mul_f32_e32 v231, v85, v231
	v_mul_f32_e32 v232, v86, v232
	v_mul_f32_e32 v233, v87, v233
	v_mul_f32_e32 v234, v88, v234
	v_mul_f32_e32 v235, v89, v235
	v_mul_f32_e32 v236, v90, v236
	v_mul_f32_e32 v237, v91, v237
	v_mul_f32_e32 v238, v92, v238
	v_mul_f32_e32 v239, v93, v239
	v_mul_f32_e32 v240, v94, v240
	v_mul_f32_e32 v241, v95, v241
	v_fmac_f32_e32 v48, v112, v226
	v_fmac_f32_e32 v49, v113, v227
	v_fmac_f32_e32 v50, v114, v228
	v_fmac_f32_e32 v51, v115, v229
	v_fmac_f32_e32 v52, v116, v230
	v_fmac_f32_e32 v53, v117, v231
	v_fmac_f32_e32 v54, v118, v232
	v_fmac_f32_e32 v55, v119, v233
	v_fmac_f32_e32 v56, v120, v234
	v_fmac_f32_e32 v57, v121, v235
	v_fmac_f32_e32 v58, v122, v236
	v_fmac_f32_e32 v59, v123, v237
	v_fmac_f32_e32 v60, v124, v238
	v_fmac_f32_e32 v61, v125, v239
	v_fmac_f32_e32 v62, v126, v240
	v_fmac_f32_e32 v63, v127, v241
	global_store_dwordx4 v0, v[48:51], s[22:23]
	global_store_dwordx4 v0, v[52:55], s[22:23] offset:1024
	global_store_dwordx4 v0, v[56:59], s[22:23] offset:2048
	global_store_dwordx4 v0, v[60:63], s[22:23] offset:3072
	v_mul_f32_e32 v242, v49, v49
	v_mul_f32_e32 v243, v53, v53
	v_mul_f32_e32 v244, v57, v57
	v_mul_f32_e32 v245, v61, v61
	v_fmac_f32_e32 v242, v48, v48
	v_fmac_f32_e32 v243, v52, v52
	v_fmac_f32_e32 v244, v56, v56
	v_fmac_f32_e32 v245, v60, v60
	v_fmac_f32_e32 v242, v50, v50
	v_fmac_f32_e32 v243, v54, v54
	v_fmac_f32_e32 v244, v58, v58
	v_fmac_f32_e32 v245, v62, v62
	v_fmac_f32_e32 v242, v51, v51
	v_fmac_f32_e32 v243, v55, v55
	v_fmac_f32_e32 v244, v59, v59
	v_fmac_f32_e32 v245, v63, v63
	v_add_f32_e32 v242, v242, v243
	v_add_f32_e32 v242, v242, v244
	v_add_f32_e32 v242, v242, v245
	s_nop 1
	v_add_f32_dpp v242, v242, v242 quad_perm:[1,0,3,2] row_mask:0xf bank_mask:0xf bound_ctrl:1
	s_nop 1
	v_add_f32_dpp v242, v242, v242 quad_perm:[2,3,0,1] row_mask:0xf bank_mask:0xf bound_ctrl:1
	s_nop 1
	v_add_f32_dpp v242, v242, v242 row_half_mirror row_mask:0xf bank_mask:0xf bound_ctrl:1
	s_nop 1
	v_add_f32_dpp v242, v242, v242 row_mirror row_mask:0xf bank_mask:0xf bound_ctrl:1
	s_nop 1
	ds_swizzle_b32 v243, v242 offset:swizzle(SWAP,16)
	s_waitcnt lgkmcnt(0)
	v_add_f32_e32 v242, v242, v243
	v_mov_b32_e32 v243, v242
	s_nop 1
	v_permlane32_swap_b32_e32 v242, v243
	v_add_f32_e32 v242, v242, v243
	v_fmamk_f32 v242, v242, 0x3a800000, v224
	v_rsq_f32_e32 v242, v242
	s_nop 0
	v_mul_f32_e32 v226, v48, v242
	v_mul_f32_e32 v227, v49, v242
	v_mul_f32_e32 v228, v50, v242
	v_mul_f32_e32 v229, v51, v242
	v_mul_f32_e32 v230, v52, v242
	v_mul_f32_e32 v231, v53, v242
	v_mul_f32_e32 v232, v54, v242
	v_mul_f32_e32 v233, v55, v242
	v_mul_f32_e32 v234, v56, v242
	v_mul_f32_e32 v235, v57, v242
	v_mul_f32_e32 v236, v58, v242
	v_mul_f32_e32 v237, v59, v242
	v_mul_f32_e32 v238, v60, v242
	v_mul_f32_e32 v239, v61, v242
	v_mul_f32_e32 v240, v62, v242
	v_mul_f32_e32 v241, v63, v242
	v_mul_f32_e32 v226, v96, v226
	v_mul_f32_e32 v227, v97, v227
	v_mul_f32_e32 v228, v98, v228
	v_mul_f32_e32 v229, v99, v229
	v_mul_f32_e32 v230, v100, v230
	v_mul_f32_e32 v231, v101, v231
	v_mul_f32_e32 v232, v102, v232
	v_mul_f32_e32 v233, v103, v233
	v_mul_f32_e32 v234, v104, v234
	v_mul_f32_e32 v235, v105, v235
	v_mul_f32_e32 v236, v106, v236
	v_mul_f32_e32 v237, v107, v237
	v_mul_f32_e32 v238, v108, v238
	v_mul_f32_e32 v239, v109, v239
	v_mul_f32_e32 v240, v110, v240
	v_mul_f32_e32 v241, v111, v241
	v_add_f32_e32 v162, 1.0, v162
	v_add_f32_e32 v163, 1.0, v163
	v_add_f32_e32 v164, 1.0, v164
	v_add_f32_e32 v165, 1.0, v165
	v_add_f32_e32 v166, 1.0, v166
	v_add_f32_e32 v167, 1.0, v167
	v_add_f32_e32 v168, 1.0, v168
	v_add_f32_e32 v169, 1.0, v169
	v_add_f32_e32 v170, 1.0, v170
	v_add_f32_e32 v171, 1.0, v171
	v_add_f32_e32 v172, 1.0, v172
	v_add_f32_e32 v173, 1.0, v173
	v_add_f32_e32 v174, 1.0, v174
	v_add_f32_e32 v175, 1.0, v175
	v_add_f32_e32 v176, 1.0, v176
	v_add_f32_e32 v177, 1.0, v177
	v_fma_f32 v226, v162, v226, v178
	v_fma_f32 v227, v163, v227, v179
	v_fma_f32 v228, v164, v228, v180
	v_fma_f32 v229, v165, v229, v181
	v_fma_f32 v230, v166, v230, v182
	v_fma_f32 v231, v167, v231, v183
	v_fma_f32 v232, v168, v232, v184
	v_fma_f32 v233, v169, v233, v185
	v_fma_f32 v234, v170, v234, v186
	v_fma_f32 v235, v171, v235, v187
	v_fma_f32 v236, v172, v236, v188
	v_fma_f32 v237, v173, v237, v189
	v_fma_f32 v238, v174, v238, v190
	v_fma_f32 v239, v175, v239, v191
	v_fma_f32 v240, v176, v240, v192
	v_fma_f32 v241, v177, v241, v193
	v_cvt_pk_f16_f32 v244, v226, v227
	v_cvt_pk_f16_f32 v245, v228, v229
	v_cvt_pk_f16_f32 v246, v230, v231
	v_cvt_pk_f16_f32 v247, v232, v233
	v_cvt_pk_f16_f32 v248, v234, v235
	v_cvt_pk_f16_f32 v249, v236, v237
	v_cvt_pk_f16_f32 v250, v238, v239
	v_cvt_pk_f16_f32 v251, v240, v241
	global_store_dwordx2 v202, v[244:245], s[40:41]
	global_store_dwordx2 v202, v[246:247], s[40:41] offset:512
	global_store_dwordx2 v202, v[248:249], s[40:41] offset:1024
	global_store_dwordx2 v202, v[250:251], s[40:41] offset:1536
	s_add_i32 s58, s58, s8
	s_branch .Lrr2_exit
; DI void rows_resid_norm(const P& p, const float* xlat, const float* xctx, const h16* y, int l, int gate_idx, const float* post_g,
;                         bool do_next, int l2, const float* gain2, int sh_idx, int sc_idx, h16* dst, int nrows) {
;     ...
;     f32x4 yv[4], xv[4];
;     float ss = 0.f;
; #pragma unroll
;     for (int i = 0; i < 4; ++i) {
;       h16x4 t = *(const h16x4*)(y + (size_t)row * 1024 + lane * 4 + 256 * i);
;       yv[i].x = (float)t.x; yv[i].y = (float)t.y; yv[i].z = (float)t.z; yv[i].w = (float)t.w;
;       ss += yv[i].x * yv[i].x + yv[i].y * yv[i].y + yv[i].z * yv[i].z + yv[i].w * yv[i].w;
;       xv[i] = *(const f32x4*)(xr + lane * 4 + 256 * i);
;     }
;     ss = wave_sum(ss);
;     const float rstd = rsqrtf(ss * (1.f / 1024.f) + EPS);
;     float s2 = 0.f;
; #pragma unroll
;     for (int i = 0; i < 4; ++i) {
;       const int c = lane * 4 + 256 * i;
;       f32x4 g = *(const f32x4*)(post_g + c), gt = *(const f32x4*)(mr + gate_idx * 1024 + c);
;       xv[i].x += gt.x * (yv[i].x * rstd * g.x);
;       xv[i].y += gt.y * (yv[i].y * rstd * g.y);
;       xv[i].z += gt.z * (yv[i].z * rstd * g.z);
;       xv[i].w += gt.w * (yv[i].w * rstd * g.w);
;       *(f32x4*)(xo + c) = xv[i];
;       s2 += xv[i].x * xv[i].x + xv[i].y * xv[i].y + xv[i].z * xv[i].z + xv[i].w * xv[i].w;
;     }
;     if (do_next) {
;       s2 = wave_sum(s2);
.Lrr21_tail1:
	s_waitcnt vmcnt(12)
	v_cvt_f32_f16_e32 v226, v10
	v_cvt_f32_f16_sdwa v227, v10 dst_sel:DWORD dst_unused:UNUSED_PAD src0_sel:WORD_1
	v_cvt_f32_f16_e32 v228, v11
	v_cvt_f32_f16_sdwa v229, v11 dst_sel:DWORD dst_unused:UNUSED_PAD src0_sel:WORD_1
	v_cvt_f32_f16_e32 v230, v12
	v_cvt_f32_f16_sdwa v231, v12 dst_sel:DWORD dst_unused:UNUSED_PAD src0_sel:WORD_1
	v_cvt_f32_f16_e32 v232, v13
	v_cvt_f32_f16_sdwa v233, v13 dst_sel:DWORD dst_unused:UNUSED_PAD src0_sel:WORD_1
	v_cvt_f32_f16_e32 v234, v14
	v_cvt_f32_f16_sdwa v235, v14 dst_sel:DWORD dst_unused:UNUSED_PAD src0_sel:WORD_1
	v_cvt_f32_f16_e32 v236, v15
	v_cvt_f32_f16_sdwa v237, v15 dst_sel:DWORD dst_unused:UNUSED_PAD src0_sel:WORD_1
	v_cvt_f32_f16_e32 v238, v16
	v_cvt_f32_f16_sdwa v239, v16 dst_sel:DWORD dst_unused:UNUSED_PAD src0_sel:WORD_1
	v_cvt_f32_f16_e32 v240, v17
	v_cvt_f32_f16_sdwa v241, v17 dst_sel:DWORD dst_unused:UNUSED_PAD src0_sel:WORD_1
	v_mul_f32_e32 v242, v227, v227
	v_mul_f32_e32 v243, v231, v231
	v_mul_f32_e32 v244, v235, v235
	v_mul_f32_e32 v245, v239, v239
	v_fmac_f32_e32 v242, v226, v226
	v_fmac_f32_e32 v243, v230, v230
	v_fmac_f32_e32 v244, v234, v234
	v_fmac_f32_e32 v245, v238, v238
	v_fmac_f32_e32 v242, v228, v228
	v_fmac_f32_e32 v243, v232, v232
	v_fmac_f32_e32 v244, v236, v236
	v_fmac_f32_e32 v245, v240, v240
	v_fmac_f32_e32 v242, v229, v229
	v_fmac_f32_e32 v243, v233, v233
	v_fmac_f32_e32 v244, v237, v237
	v_fmac_f32_e32 v245, v241, v241
	v_add_f32_e32 v242, v242, v243
	v_add_f32_e32 v242, v242, v244
	v_add_f32_e32 v242, v242, v245
	s_nop 1
	v_add_f32_dpp v242, v242, v242 quad_perm:[1,0,3,2] row_mask:0xf bank_mask:0xf bound_ctrl:1
	s_nop 1
	v_add_f32_dpp v242, v242, v242 quad_perm:[2,3,0,1] row_mask:0xf bank_mask:0xf bound_ctrl:1
	s_nop 1
	v_add_f32_dpp v242, v242, v242 row_half_mirror row_mask:0xf bank_mask:0xf bound_ctrl:1
	s_nop 1
	v_add_f32_dpp v242, v242, v242 row_mirror row_mask:0xf bank_mask:0xf bound_ctrl:1
	s_nop 1
	ds_swizzle_b32 v243, v242 offset:swizzle(SWAP,16)
	s_waitcnt lgkmcnt(0)
	v_add_f32_e32 v242, v242, v243
	v_mov_b32_e32 v243, v242
	s_nop 1
	v_permlane32_swap_b32_e32 v242, v243
	v_add_f32_e32 v242, v242, v243
	v_fmamk_f32 v242, v242, 0x3a800000, v224
	v_rsq_f32_e32 v242, v242
	s_waitcnt vmcnt(0)
	v_mul_f32_e32 v226, v226, v242
	v_mul_f32_e32 v227, v227, v242
	v_mul_f32_e32 v228, v228, v242
	v_mul_f32_e32 v229, v229, v242
	v_mul_f32_e32 v230, v230, v242
	v_mul_f32_e32 v231, v231, v242
	v_mul_f32_e32 v232, v232, v242
	v_mul_f32_e32 v233, v233, v242
	v_mul_f32_e32 v234, v234, v242
	v_mul_f32_e32 v235, v235, v242
	v_mul_f32_e32 v236, v236, v242
	v_mul_f32_e32 v237, v237, v242
	v_mul_f32_e32 v238, v238, v242
	v_mul_f32_e32 v239, v239, v242
	v_mul_f32_e32 v240, v240, v242
	v_mul_f32_e32 v241, v241, v242
	v_mul_f32_e32 v226, v80, v226
	v_mul_f32_e32 v227, v81, v227
	v_mul_f32_e32 v228, v82, v228
	v_mul_f32_e32 v229, v83, v229
	v_mul_f32_e32 v230, v84, v230
	v_mul_f32_e32 v231, v85, v231
	v_mul_f32_e32 v232, v86, v232
	v_mul_f32_e32 v233, v87, v233
	v_mul_f32_e32 v234, v88, v234
	v_mul_f32_e32 v235, v89, v235
	v_mul_f32_e32 v236, v90, v236
	v_mul_f32_e32 v237, v91, v237
	v_mul_f32_e32 v238, v92, v238
	v_mul_f32_e32 v239, v93, v239
	v_mul_f32_e32 v240, v94, v240
	v_mul_f32_e32 v241, v95, v241
	v_fmac_f32_e32 v48, v112, v226
	v_fmac_f32_e32 v49, v113, v227
	v_fmac_f32_e32 v50, v114, v228
	v_fmac_f32_e32 v51, v115, v229
	v_fmac_f32_e32 v52, v116, v230
	v_fmac_f32_e32 v53, v117, v231
	v_fmac_f32_e32 v54, v118, v232
	v_fmac_f32_e32 v55, v119, v233
	v_fmac_f32_e32 v56, v120, v234
	v_fmac_f32_e32 v57, v121, v235
	v_fmac_f32_e32 v58, v122, v236
	v_fmac_f32_e32 v59, v123, v237
	v_fmac_f32_e32 v60, v124, v238
	v_fmac_f32_e32 v61, v125, v239
	v_fmac_f32_e32 v62, v126, v240
	v_fmac_f32_e32 v63, v127, v241
	global_store_dwordx4 v0, v[48:51], s[22:23]
	global_store_dwordx4 v0, v[52:55], s[22:23] offset:1024
	global_store_dwordx4 v0, v[56:59], s[22:23] offset:2048
	global_store_dwordx4 v0, v[60:63], s[22:23] offset:3072
	v_mul_f32_e32 v242, v49, v49
	v_mul_f32_e32 v243, v53, v53
	v_mul_f32_e32 v244, v57, v57
	v_mul_f32_e32 v245, v61, v61
	v_fmac_f32_e32 v242, v48, v48
	v_fmac_f32_e32 v243, v52, v52
	v_fmac_f32_e32 v244, v56, v56
	v_fmac_f32_e32 v245, v60, v60
	v_fmac_f32_e32 v242, v50, v50
	v_fmac_f32_e32 v243, v54, v54
	v_fmac_f32_e32 v244, v58, v58
	v_fmac_f32_e32 v245, v62, v62
	v_fmac_f32_e32 v242, v51, v51
	v_fmac_f32_e32 v243, v55, v55
	v_fmac_f32_e32 v244, v59, v59
	v_fmac_f32_e32 v245, v63, v63
	v_add_f32_e32 v242, v242, v243
	v_add_f32_e32 v242, v242, v244
	v_add_f32_e32 v242, v242, v245
	s_nop 1
	v_add_f32_dpp v242, v242, v242 quad_perm:[1,0,3,2] row_mask:0xf bank_mask:0xf bound_ctrl:1
	s_nop 1
	v_add_f32_dpp v242, v242, v242 quad_perm:[2,3,0,1] row_mask:0xf bank_mask:0xf bound_ctrl:1
	s_nop 1
	v_add_f32_dpp v242, v242, v242 row_half_mirror row_mask:0xf bank_mask:0xf bound_ctrl:1
	s_nop 1
	v_add_f32_dpp v242, v242, v242 row_mirror row_mask:0xf bank_mask:0xf bound_ctrl:1
	s_nop 1
	ds_swizzle_b32 v243, v242 offset:swizzle(SWAP,16)
	s_waitcnt lgkmcnt(0)
; DI void rows_resid_norm(const P& p, const float* xlat, const float* xctx, const h16* y, int l, int gate_idx, const float* post_g,
;                         bool do_next, int l2, const float* gain2, int sh_idx, int sc_idx, h16* dst, int nrows) {
;     ...
;   for (int row = gw; row < nrows; row += nw) {
;     const float* xr = row < TL ? xlat + (size_t)row * 1024 : xctx + (size_t)(row - TL) * 1024;
;     float* xo = row < TL ? p.out + (size_t)row * 1024 : xc + (size_t)(row - TL) * 1024;
;     const int mrow = row < TL ? (row >> 12) : 8;
;     const float* mr = mod + ((size_t)l * 9 + mrow) * 6144;
;     const float* mr2 = mod + ((size_t)l2 * 9 + mrow) * 6144;
;     f32x4 yv[4], xv[4];
;     float ss = 0.f;
; #pragma unroll
;     for (int i = 0; i < 4; ++i) {
;       h16x4 t = *(const h16x4*)(y + (size_t)row * 1024 + lane * 4 + 256 * i);
;       yv[i].x = (float)t.x; yv[i].y = (float)t.y; yv[i].z = (float)t.z; yv[i].w = (float)t.w;
;       ss += yv[i].x * yv[i].x + yv[i].y * yv[i].y + yv[i].z * yv[i].z + yv[i].w * yv[i].w;
;       xv[i] = *(const f32x4*)(xr + lane * 4 + 256 * i);
;     }
;     ss = wave_sum(ss);
;     const float rstd = rsqrtf(ss * (1.f / 1024.f) + EPS);
;     ...
;       const float r2 = rsqrtf(s2 * (1.f / 1024.f) + EPS);
; #pragma unroll
;       for (int i = 0; i < 4; ++i) {
;         const int c = lane * 4 + 256 * i;
;         f32x4 g = *(const f32x4*)(gain2 + c), sc = *(const f32x4*)(mr2 + sc_idx * 1024 + c), sh = *(const f32x4*)(mr2 + sh_idx * 1024 + c);
;         h16x4 o;
;         o.x = (h16)(xv[i].x * r2 * g.x * (1.f + sc.x) + sh.x);
;         o.y = (h16)(xv[i].y * r2 * g.y * (1.f + sc.y) + sh.y);
;         o.z = (h16)(xv[i].z * r2 * g.z * (1.f + sc.z) + sh.z);
;         o.w = (h16)(xv[i].w * r2 * g.w * (1.f + sc.w) + sh.w);
;         *(h16x4*)(dst + (size_t)row * 1024 + c) = o;
;       }
;     }
	v_add_f32_e32 v242, v242, v243
	v_mov_b32_e32 v243, v242
	s_nop 1
	v_permlane32_swap_b32_e32 v242, v243
	v_add_f32_e32 v242, v242, v243
	v_fmamk_f32 v242, v242, 0x3a800000, v224
	v_rsq_f32_e32 v242, v242
	s_nop 0
	v_mul_f32_e32 v226, v48, v242
	v_mul_f32_e32 v227, v49, v242
	v_mul_f32_e32 v228, v50, v242
	v_mul_f32_e32 v229, v51, v242
	v_mul_f32_e32 v230, v52, v242
	v_mul_f32_e32 v231, v53, v242
	v_mul_f32_e32 v232, v54, v242
	v_mul_f32_e32 v233, v55, v242
	v_mul_f32_e32 v234, v56, v242
	v_mul_f32_e32 v235, v57, v242
	v_mul_f32_e32 v236, v58, v242
	v_mul_f32_e32 v237, v59, v242
	v_mul_f32_e32 v238, v60, v242
	v_mul_f32_e32 v239, v61, v242
	v_mul_f32_e32 v240, v62, v242
	v_mul_f32_e32 v241, v63, v242
	v_mul_f32_e32 v226, v96, v226
	v_mul_f32_e32 v227, v97, v227
	v_mul_f32_e32 v228, v98, v228
	v_mul_f32_e32 v229, v99, v229
	v_mul_f32_e32 v230, v100, v230
	v_mul_f32_e32 v231, v101, v231
	v_mul_f32_e32 v232, v102, v232
	v_mul_f32_e32 v233, v103, v233
	v_mul_f32_e32 v234, v104, v234
	v_mul_f32_e32 v235, v105, v235
	v_mul_f32_e32 v236, v106, v236
	v_mul_f32_e32 v237, v107, v237
	v_mul_f32_e32 v238, v108, v238
	v_mul_f32_e32 v239, v109, v239
	v_mul_f32_e32 v240, v110, v240
	v_mul_f32_e32 v241, v111, v241
	v_add_f32_e32 v162, 1.0, v162
	v_add_f32_e32 v163, 1.0, v163
	v_add_f32_e32 v164, 1.0, v164
	v_add_f32_e32 v165, 1.0, v165
	v_add_f32_e32 v166, 1.0, v166
	v_add_f32_e32 v167, 1.0, v167
	v_add_f32_e32 v168, 1.0, v168
	v_add_f32_e32 v169, 1.0, v169
	v_add_f32_e32 v170, 1.0, v170
	v_add_f32_e32 v171, 1.0, v171
	v_add_f32_e32 v172, 1.0, v172
	v_add_f32_e32 v173, 1.0, v173
	v_add_f32_e32 v174, 1.0, v174
	v_add_f32_e32 v175, 1.0, v175
	v_add_f32_e32 v176, 1.0, v176
	v_add_f32_e32 v177, 1.0, v177
	v_fma_f32 v226, v162, v226, v178
	v_fma_f32 v227, v163, v227, v179
	v_fma_f32 v228, v164, v228, v180
	v_fma_f32 v229, v165, v229, v181
	v_fma_f32 v230, v166, v230, v182
	v_fma_f32 v231, v167, v231, v183
	v_fma_f32 v232, v168, v232, v184
	v_fma_f32 v233, v169, v233, v185
	v_fma_f32 v234, v170, v234, v186
	v_fma_f32 v235, v171, v235, v187
	v_fma_f32 v236, v172, v236, v188
	v_fma_f32 v237, v173, v237, v189
	v_fma_f32 v238, v174, v238, v190
	v_fma_f32 v239, v175, v239, v191
	v_fma_f32 v240, v176, v240, v192
	v_fma_f32 v241, v177, v241, v193
	v_cvt_pk_f16_f32 v244, v226, v227
	v_cvt_pk_f16_f32 v245, v228, v229
	v_cvt_pk_f16_f32 v246, v230, v231
	v_cvt_pk_f16_f32 v247, v232, v233
	v_cvt_pk_f16_f32 v248, v234, v235
	v_cvt_pk_f16_f32 v249, v236, v237
	v_cvt_pk_f16_f32 v250, v238, v239
	v_cvt_pk_f16_f32 v251, v240, v241
	global_store_dwordx2 v202, v[244:245], s[40:41]
	global_store_dwordx2 v202, v[246:247], s[40:41] offset:512
	global_store_dwordx2 v202, v[248:249], s[40:41] offset:1024
	global_store_dwordx2 v202, v[250:251], s[40:41] offset:1536
	s_add_i32 s58, s58, s8
	s_cmp_lt_i32 s58, s36
	s_cbranch_scc0 .Lrr2_exit
	s_lshr_b32 s59, s58, 12
	s_cmp_lt_u32 s58, 0x8000
	s_cselect_b32 s59, s59, 8
	s_mul_i32 s59, s59, 0x6000
	s_add_u32 s24, s42, s59
	s_addc_u32 s25, s43, 0
	s_add_u32 s18, s54, s59
	s_addc_u32 s19, s55, 0
	s_add_u32 s34, s18, 0x1000
	s_addc_u32 s35, s19, 0
	s_lshl_b32 s59, s58, 11
	s_add_u32 s40, s56, s59
	s_addc_u32 s41, s57, 0
	s_sub_u32 s60, s58, 0x8000
	s_cmp_lt_u32 s58, 0x8000
	s_cselect_b32 s60, s58, s60
	s_cselect_b32 s22, s46, s50
	s_cselect_b32 s23, s47, s51
	s_lshl_b32 s60, s60, 12
	s_add_u32 s22, s22, s60
	s_addc_u32 s23, s23, 0
	global_load_dwordx4 v[112:115], v0, s[24:25]
	global_load_dwordx4 v[116:119], v0, s[24:25] offset:1024
	global_load_dwordx4 v[120:123], v0, s[24:25] offset:2048
	global_load_dwordx4 v[124:127], v0, s[24:25] offset:3072
	global_load_dwordx4 v[162:165], v0, s[34:35]
	global_load_dwordx4 v[166:169], v0, s[34:35] offset:1024
	global_load_dwordx4 v[170:173], v0, s[34:35] offset:2048
	global_load_dwordx4 v[174:177], v0, s[34:35] offset:3072
	global_load_dwordx4 v[178:181], v0, s[18:19]
	global_load_dwordx4 v[182:185], v0, s[18:19] offset:1024
	global_load_dwordx4 v[186:189], v0, s[18:19] offset:2048
	global_load_dwordx4 v[190:193], v0, s[18:19] offset:3072
	s_waitcnt vmcnt(12)
	v_cvt_f32_f16_e32 v226, v18
	v_cvt_f32_f16_sdwa v227, v18 dst_sel:DWORD dst_unused:UNUSED_PAD src0_sel:WORD_1
	v_cvt_f32_f16_e32 v228, v19
	v_cvt_f32_f16_sdwa v229, v19 dst_sel:DWORD dst_unused:UNUSED_PAD src0_sel:WORD_1
	v_cvt_f32_f16_e32 v230, v20
	v_cvt_f32_f16_sdwa v231, v20 dst_sel:DWORD dst_unused:UNUSED_PAD src0_sel:WORD_1
	v_cvt_f32_f16_e32 v232, v21
	v_cvt_f32_f16_sdwa v233, v21 dst_sel:DWORD dst_unused:UNUSED_PAD src0_sel:WORD_1
	v_cvt_f32_f16_e32 v234, v22
	v_cvt_f32_f16_sdwa v235, v22 dst_sel:DWORD dst_unused:UNUSED_PAD src0_sel:WORD_1
	v_cvt_f32_f16_e32 v236, v23
	v_cvt_f32_f16_sdwa v237, v23 dst_sel:DWORD dst_unused:UNUSED_PAD src0_sel:WORD_1
	v_cvt_f32_f16_e32 v238, v24
	v_cvt_f32_f16_sdwa v239, v24 dst_sel:DWORD dst_unused:UNUSED_PAD src0_sel:WORD_1
	v_cvt_f32_f16_e32 v240, v25
	v_cvt_f32_f16_sdwa v241, v25 dst_sel:DWORD dst_unused:UNUSED_PAD src0_sel:WORD_1
	v_mul_f32_e32 v242, v227, v227
	v_mul_f32_e32 v243, v231, v231
	v_mul_f32_e32 v244, v235, v235
	v_mul_f32_e32 v245, v239, v239
	v_fmac_f32_e32 v242, v226, v226
	v_fmac_f32_e32 v243, v230, v230
	v_fmac_f32_e32 v244, v234, v234
	v_fmac_f32_e32 v245, v238, v238
	v_fmac_f32_e32 v242, v228, v228
	v_fmac_f32_e32 v243, v232, v232
	v_fmac_f32_e32 v244, v236, v236
	v_fmac_f32_e32 v245, v240, v240
	v_fmac_f32_e32 v242, v229, v229
	v_fmac_f32_e32 v243, v233, v233
	v_fmac_f32_e32 v244, v237, v237
	v_fmac_f32_e32 v245, v241, v241
	v_add_f32_e32 v242, v242, v243
	v_add_f32_e32 v242, v242, v244
	v_add_f32_e32 v242, v242, v245
	s_nop 1
	v_add_f32_dpp v242, v242, v242 quad_perm:[1,0,3,2] row_mask:0xf bank_mask:0xf bound_ctrl:1
	s_nop 1
	v_add_f32_dpp v242, v242, v242 quad_perm:[2,3,0,1] row_mask:0xf bank_mask:0xf bound_ctrl:1
	s_nop 1
	v_add_f32_dpp v242, v242, v242 row_half_mirror row_mask:0xf bank_mask:0xf bound_ctrl:1
	s_nop 1
	v_add_f32_dpp v242, v242, v242 row_mirror row_mask:0xf bank_mask:0xf bound_ctrl:1
	s_nop 1
	ds_swizzle_b32 v243, v242 offset:swizzle(SWAP,16)
	s_waitcnt lgkmcnt(0)
; DI void rows_resid_norm(const P& p, const float* xlat, const float* xctx, const h16* y, int l, int gate_idx, const float* post_g,
;                         bool do_next, int l2, const float* gain2, int sh_idx, int sc_idx, h16* dst, int nrows) {
;     ...
;     const float rstd = rsqrtf(ss * (1.f / 1024.f) + EPS);
;     float s2 = 0.f;
; #pragma unroll
;     for (int i = 0; i < 4; ++i) {
;       const int c = lane * 4 + 256 * i;
;       f32x4 g = *(const f32x4*)(post_g + c), gt = *(const f32x4*)(mr + gate_idx * 1024 + c);
;       xv[i].x += gt.x * (yv[i].x * rstd * g.x);
;       xv[i].y += gt.y * (yv[i].y * rstd * g.y);
;       xv[i].z += gt.z * (yv[i].z * rstd * g.z);
;       xv[i].w += gt.w * (yv[i].w * rstd * g.w);
;       *(f32x4*)(xo + c) = xv[i];
;       s2 += xv[i].x * xv[i].x + xv[i].y * xv[i].y + xv[i].z * xv[i].z + xv[i].w * xv[i].w;
;     }
;     if (do_next) {
;       s2 = wave_sum(s2);
;       const float r2 = rsqrtf(s2 * (1.f / 1024.f) + EPS);
; #pragma unroll
;       for (int i = 0; i < 4; ++i) {
;         const int c = lane * 4 + 256 * i;
;         f32x4 g = *(const f32x4*)(gain2 + c), sc = *(const f32x4*)(mr2 + sc_idx * 1024 + c), sh = *(const f32x4*)(mr2 + sh_idx * 1024 + c);
;         h16x4 o;
;         o.x = (h16)(xv[i].x * r2 * g.x * (1.f + sc.x) + sh.x);
;         o.y = (h16)(xv[i].y * r2 * g.y * (1.f + sc.y) + sh.y);
;         o.z = (h16)(xv[i].z * r2 * g.z * (1.f + sc.z) + sh.z);
;         o.w = (h16)(xv[i].w * r2 * g.w * (1.f + sc.w) + sh.w);
;         *(h16x4*)(dst + (size_t)row * 1024 + c) = o;
;       }
;     }
	v_add_f32_e32 v242, v242, v243
	v_mov_b32_e32 v243, v242
	s_nop 1
	v_permlane32_swap_b32_e32 v242, v243
	v_add_f32_e32 v242, v242, v243
	v_fmamk_f32 v242, v242, 0x3a800000, v224
	v_rsq_f32_e32 v242, v242
	s_waitcnt vmcnt(0)
	v_mul_f32_e32 v226, v226, v242
	v_mul_f32_e32 v227, v227, v242
	v_mul_f32_e32 v228, v228, v242
	v_mul_f32_e32 v229, v229, v242
	v_mul_f32_e32 v230, v230, v242
	v_mul_f32_e32 v231, v231, v242
	v_mul_f32_e32 v232, v232, v242
	v_mul_f32_e32 v233, v233, v242
	v_mul_f32_e32 v234, v234, v242
	v_mul_f32_e32 v235, v235, v242
	v_mul_f32_e32 v236, v236, v242
	v_mul_f32_e32 v237, v237, v242
	v_mul_f32_e32 v238, v238, v242
	v_mul_f32_e32 v239, v239, v242
	v_mul_f32_e32 v240, v240, v242
	v_mul_f32_e32 v241, v241, v242
	v_mul_f32_e32 v226, v80, v226
	v_mul_f32_e32 v227, v81, v227
	v_mul_f32_e32 v228, v82, v228
	v_mul_f32_e32 v229, v83, v229
	v_mul_f32_e32 v230, v84, v230
	v_mul_f32_e32 v231, v85, v231
	v_mul_f32_e32 v232, v86, v232
	v_mul_f32_e32 v233, v87, v233
	v_mul_f32_e32 v234, v88, v234
	v_mul_f32_e32 v235, v89, v235
	v_mul_f32_e32 v236, v90, v236
	v_mul_f32_e32 v237, v91, v237
	v_mul_f32_e32 v238, v92, v238
	v_mul_f32_e32 v239, v93, v239
	v_mul_f32_e32 v240, v94, v240
	v_mul_f32_e32 v241, v95, v241
	v_fmac_f32_e32 v64, v112, v226
	v_fmac_f32_e32 v65, v113, v227
	v_fmac_f32_e32 v66, v114, v228
	v_fmac_f32_e32 v67, v115, v229
	v_fmac_f32_e32 v68, v116, v230
	v_fmac_f32_e32 v69, v117, v231
	v_fmac_f32_e32 v70, v118, v232
	v_fmac_f32_e32 v71, v119, v233
	v_fmac_f32_e32 v72, v120, v234
	v_fmac_f32_e32 v73, v121, v235
	v_fmac_f32_e32 v74, v122, v236
	v_fmac_f32_e32 v75, v123, v237
	v_fmac_f32_e32 v76, v124, v238
	v_fmac_f32_e32 v77, v125, v239
	v_fmac_f32_e32 v78, v126, v240
	v_fmac_f32_e32 v79, v127, v241
	global_store_dwordx4 v0, v[64:67], s[22:23]
	global_store_dwordx4 v0, v[68:71], s[22:23] offset:1024
	global_store_dwordx4 v0, v[72:75], s[22:23] offset:2048
	global_store_dwordx4 v0, v[76:79], s[22:23] offset:3072
	v_mul_f32_e32 v242, v65, v65
	v_mul_f32_e32 v243, v69, v69
	v_mul_f32_e32 v244, v73, v73
	v_mul_f32_e32 v245, v77, v77
	v_fmac_f32_e32 v242, v64, v64
	v_fmac_f32_e32 v243, v68, v68
	v_fmac_f32_e32 v244, v72, v72
	v_fmac_f32_e32 v245, v76, v76
	v_fmac_f32_e32 v242, v66, v66
	v_fmac_f32_e32 v243, v70, v70
	v_fmac_f32_e32 v244, v74, v74
	v_fmac_f32_e32 v245, v78, v78
	v_fmac_f32_e32 v242, v67, v67
	v_fmac_f32_e32 v243, v71, v71
	v_fmac_f32_e32 v244, v75, v75
	v_fmac_f32_e32 v245, v79, v79
	v_add_f32_e32 v242, v242, v243
	v_add_f32_e32 v242, v242, v244
	v_add_f32_e32 v242, v242, v245
	s_nop 1
	v_add_f32_dpp v242, v242, v242 quad_perm:[1,0,3,2] row_mask:0xf bank_mask:0xf bound_ctrl:1
	s_nop 1
	v_add_f32_dpp v242, v242, v242 quad_perm:[2,3,0,1] row_mask:0xf bank_mask:0xf bound_ctrl:1
	s_nop 1
	v_add_f32_dpp v242, v242, v242 row_half_mirror row_mask:0xf bank_mask:0xf bound_ctrl:1
	s_nop 1
	v_add_f32_dpp v242, v242, v242 row_mirror row_mask:0xf bank_mask:0xf bound_ctrl:1
	s_nop 1
	ds_swizzle_b32 v243, v242 offset:swizzle(SWAP,16)
	s_waitcnt lgkmcnt(0)
	v_add_f32_e32 v242, v242, v243
	v_mov_b32_e32 v243, v242
	s_nop 1
	v_permlane32_swap_b32_e32 v242, v243
	v_add_f32_e32 v242, v242, v243
	v_fmamk_f32 v242, v242, 0x3a800000, v224
	v_rsq_f32_e32 v242, v242
	s_nop 0
	v_mul_f32_e32 v226, v64, v242
	v_mul_f32_e32 v227, v65, v242
	v_mul_f32_e32 v228, v66, v242
	v_mul_f32_e32 v229, v67, v242
	v_mul_f32_e32 v230, v68, v242
	v_mul_f32_e32 v231, v69, v242
	v_mul_f32_e32 v232, v70, v242
	v_mul_f32_e32 v233, v71, v242
	v_mul_f32_e32 v234, v72, v242
	v_mul_f32_e32 v235, v73, v242
	v_mul_f32_e32 v236, v74, v242
	v_mul_f32_e32 v237, v75, v242
	v_mul_f32_e32 v238, v76, v242
	v_mul_f32_e32 v239, v77, v242
	v_mul_f32_e32 v240, v78, v242
	v_mul_f32_e32 v241, v79, v242
	v_mul_f32_e32 v226, v96, v226
	v_mul_f32_e32 v227, v97, v227
	v_mul_f32_e32 v228, v98, v228
	v_mul_f32_e32 v229, v99, v229
	v_mul_f32_e32 v230, v100, v230
	v_mul_f32_e32 v231, v101, v231
	v_mul_f32_e32 v232, v102, v232
	v_mul_f32_e32 v233, v103, v233
	v_mul_f32_e32 v234, v104, v234
	v_mul_f32_e32 v235, v105, v235
	v_mul_f32_e32 v236, v106, v236
	v_mul_f32_e32 v237, v107, v237
	v_mul_f32_e32 v238, v108, v238
	v_mul_f32_e32 v239, v109, v239
	v_mul_f32_e32 v240, v110, v240
	v_mul_f32_e32 v241, v111, v241
	v_add_f32_e32 v162, 1.0, v162
	v_add_f32_e32 v163, 1.0, v163
	v_add_f32_e32 v164, 1.0, v164
	v_add_f32_e32 v165, 1.0, v165
	v_add_f32_e32 v166, 1.0, v166
	v_add_f32_e32 v167, 1.0, v167
	v_add_f32_e32 v168, 1.0, v168
	v_add_f32_e32 v169, 1.0, v169
	v_add_f32_e32 v170, 1.0, v170
	v_add_f32_e32 v171, 1.0, v171
	v_add_f32_e32 v172, 1.0, v172
	v_add_f32_e32 v173, 1.0, v173
	v_add_f32_e32 v174, 1.0, v174
	v_add_f32_e32 v175, 1.0, v175
	v_add_f32_e32 v176, 1.0, v176
	v_add_f32_e32 v177, 1.0, v177
	v_fma_f32 v226, v162, v226, v178
	v_fma_f32 v227, v163, v227, v179
	v_fma_f32 v228, v164, v228, v180
	v_fma_f32 v229, v165, v229, v181
	v_fma_f32 v230, v166, v230, v182
	v_fma_f32 v231, v167, v231, v183
	v_fma_f32 v232, v168, v232, v184
	v_fma_f32 v233, v169, v233, v185
	v_fma_f32 v234, v170, v234, v186
	v_fma_f32 v235, v171, v235, v187
	v_fma_f32 v236, v172, v236, v188
	v_fma_f32 v237, v173, v237, v189
	v_fma_f32 v238, v174, v238, v190
	v_fma_f32 v239, v175, v239, v191
	v_fma_f32 v240, v176, v240, v192
	v_fma_f32 v241, v177, v241, v193
	v_cvt_pk_f16_f32 v244, v226, v227
	v_cvt_pk_f16_f32 v245, v228, v229
	v_cvt_pk_f16_f32 v246, v230, v231
	v_cvt_pk_f16_f32 v247, v232, v233
	v_cvt_pk_f16_f32 v248, v234, v235
	v_cvt_pk_f16_f32 v249, v236, v237
	v_cvt_pk_f16_f32 v250, v238, v239
	v_cvt_pk_f16_f32 v251, v240, v241
	global_store_dwordx2 v202, v[244:245], s[40:41]
	global_store_dwordx2 v202, v[246:247], s[40:41] offset:512
	global_store_dwordx2 v202, v[248:249], s[40:41] offset:1024
	global_store_dwordx2 v202, v[250:251], s[40:41] offset:1536
	s_add_i32 s58, s58, s8
	s_branch .Lrr2_exit
; DI void rows_resid_norm(const P& p, const float* xlat, const float* xctx, const h16* y, int l, int gate_idx, const float* post_g,
;                         bool do_next, int l2, const float* gain2, int sh_idx, int sc_idx, h16* dst, int nrows) {
;     ...
;     f32x4 yv[4], xv[4];
;     float ss = 0.f;
; #pragma unroll
;     for (int i = 0; i < 4; ++i) {
;       h16x4 t = *(const h16x4*)(y + (size_t)row * 1024 + lane * 4 + 256 * i);
;       yv[i].x = (float)t.x; yv[i].y = (float)t.y; yv[i].z = (float)t.z; yv[i].w = (float)t.w;
;       ss += yv[i].x * yv[i].x + yv[i].y * yv[i].y + yv[i].z * yv[i].z + yv[i].w * yv[i].w;
;       xv[i] = *(const f32x4*)(xr + lane * 4 + 256 * i);
;     }
;     ss = wave_sum(ss);
;     const float rstd = rsqrtf(ss * (1.f / 1024.f) + EPS);
;     float s2 = 0.f;
; #pragma unroll
;     for (int i = 0; i < 4; ++i) {
;       const int c = lane * 4 + 256 * i;
;       f32x4 g = *(const f32x4*)(post_g + c), gt = *(const f32x4*)(mr + gate_idx * 1024 + c);
;       xv[i].x += gt.x * (yv[i].x * rstd * g.x);
;       xv[i].y += gt.y * (yv[i].y * rstd * g.y);
;       xv[i].z += gt.z * (yv[i].z * rstd * g.z);
;       xv[i].w += gt.w * (yv[i].w * rstd * g.w);
;       *(f32x4*)(xo + c) = xv[i];
;       s2 += xv[i].x * xv[i].x + xv[i].y * xv[i].y + xv[i].z * xv[i].z + xv[i].w * xv[i].w;
;     }
;     if (do_next) {
;       s2 = wave_sum(s2);
.Lrr21_tail2:
	s_waitcnt vmcnt(12)
	v_cvt_f32_f16_e32 v226, v18
	v_cvt_f32_f16_sdwa v227, v18 dst_sel:DWORD dst_unused:UNUSED_PAD src0_sel:WORD_1
	v_cvt_f32_f16_e32 v228, v19
	v_cvt_f32_f16_sdwa v229, v19 dst_sel:DWORD dst_unused:UNUSED_PAD src0_sel:WORD_1
	v_cvt_f32_f16_e32 v230, v20
	v_cvt_f32_f16_sdwa v231, v20 dst_sel:DWORD dst_unused:UNUSED_PAD src0_sel:WORD_1
	v_cvt_f32_f16_e32 v232, v21
	v_cvt_f32_f16_sdwa v233, v21 dst_sel:DWORD dst_unused:UNUSED_PAD src0_sel:WORD_1
	v_cvt_f32_f16_e32 v234, v22
	v_cvt_f32_f16_sdwa v235, v22 dst_sel:DWORD dst_unused:UNUSED_PAD src0_sel:WORD_1
	v_cvt_f32_f16_e32 v236, v23
	v_cvt_f32_f16_sdwa v237, v23 dst_sel:DWORD dst_unused:UNUSED_PAD src0_sel:WORD_1
	v_cvt_f32_f16_e32 v238, v24
	v_cvt_f32_f16_sdwa v239, v24 dst_sel:DWORD dst_unused:UNUSED_PAD src0_sel:WORD_1
	v_cvt_f32_f16_e32 v240, v25
	v_cvt_f32_f16_sdwa v241, v25 dst_sel:DWORD dst_unused:UNUSED_PAD src0_sel:WORD_1
	v_mul_f32_e32 v242, v227, v227
	v_mul_f32_e32 v243, v231, v231
	v_mul_f32_e32 v244, v235, v235
	v_mul_f32_e32 v245, v239, v239
	v_fmac_f32_e32 v242, v226, v226
	v_fmac_f32_e32 v243, v230, v230
	v_fmac_f32_e32 v244, v234, v234
	v_fmac_f32_e32 v245, v238, v238
	v_fmac_f32_e32 v242, v228, v228
	v_fmac_f32_e32 v243, v232, v232
	v_fmac_f32_e32 v244, v236, v236
	v_fmac_f32_e32 v245, v240, v240
	v_fmac_f32_e32 v242, v229, v229
	v_fmac_f32_e32 v243, v233, v233
	v_fmac_f32_e32 v244, v237, v237
	v_fmac_f32_e32 v245, v241, v241
	v_add_f32_e32 v242, v242, v243
	v_add_f32_e32 v242, v242, v244
	v_add_f32_e32 v242, v242, v245
	s_nop 1
	v_add_f32_dpp v242, v242, v242 quad_perm:[1,0,3,2] row_mask:0xf bank_mask:0xf bound_ctrl:1
	s_nop 1
	v_add_f32_dpp v242, v242, v242 quad_perm:[2,3,0,1] row_mask:0xf bank_mask:0xf bound_ctrl:1
	s_nop 1
	v_add_f32_dpp v242, v242, v242 row_half_mirror row_mask:0xf bank_mask:0xf bound_ctrl:1
	s_nop 1
	v_add_f32_dpp v242, v242, v242 row_mirror row_mask:0xf bank_mask:0xf bound_ctrl:1
	s_nop 1
	ds_swizzle_b32 v243, v242 offset:swizzle(SWAP,16)
	s_waitcnt lgkmcnt(0)
	v_add_f32_e32 v242, v242, v243
	v_mov_b32_e32 v243, v242
	s_nop 1
	v_permlane32_swap_b32_e32 v242, v243
	v_add_f32_e32 v242, v242, v243
	v_fmamk_f32 v242, v242, 0x3a800000, v224
	v_rsq_f32_e32 v242, v242
	s_waitcnt vmcnt(0)
	v_mul_f32_e32 v226, v226, v242
	v_mul_f32_e32 v227, v227, v242
	v_mul_f32_e32 v228, v228, v242
	v_mul_f32_e32 v229, v229, v242
	v_mul_f32_e32 v230, v230, v242
	v_mul_f32_e32 v231, v231, v242
	v_mul_f32_e32 v232, v232, v242
	v_mul_f32_e32 v233, v233, v242
	v_mul_f32_e32 v234, v234, v242
	v_mul_f32_e32 v235, v235, v242
	v_mul_f32_e32 v236, v236, v242
	v_mul_f32_e32 v237, v237, v242
	v_mul_f32_e32 v238, v238, v242
	v_mul_f32_e32 v239, v239, v242
	v_mul_f32_e32 v240, v240, v242
	v_mul_f32_e32 v241, v241, v242
	v_mul_f32_e32 v226, v80, v226
	v_mul_f32_e32 v227, v81, v227
	v_mul_f32_e32 v228, v82, v228
	v_mul_f32_e32 v229, v83, v229
	v_mul_f32_e32 v230, v84, v230
	v_mul_f32_e32 v231, v85, v231
	v_mul_f32_e32 v232, v86, v232
	v_mul_f32_e32 v233, v87, v233
	v_mul_f32_e32 v234, v88, v234
	v_mul_f32_e32 v235, v89, v235
	v_mul_f32_e32 v236, v90, v236
	v_mul_f32_e32 v237, v91, v237
	v_mul_f32_e32 v238, v92, v238
	v_mul_f32_e32 v239, v93, v239
	v_mul_f32_e32 v240, v94, v240
	v_mul_f32_e32 v241, v95, v241
	v_fmac_f32_e32 v64, v112, v226
	v_fmac_f32_e32 v65, v113, v227
	v_fmac_f32_e32 v66, v114, v228
	v_fmac_f32_e32 v67, v115, v229
	v_fmac_f32_e32 v68, v116, v230
	v_fmac_f32_e32 v69, v117, v231
	v_fmac_f32_e32 v70, v118, v232
	v_fmac_f32_e32 v71, v119, v233
	v_fmac_f32_e32 v72, v120, v234
	v_fmac_f32_e32 v73, v121, v235
	v_fmac_f32_e32 v74, v122, v236
	v_fmac_f32_e32 v75, v123, v237
	v_fmac_f32_e32 v76, v124, v238
	v_fmac_f32_e32 v77, v125, v239
	v_fmac_f32_e32 v78, v126, v240
	v_fmac_f32_e32 v79, v127, v241
	global_store_dwordx4 v0, v[64:67], s[22:23]
	global_store_dwordx4 v0, v[68:71], s[22:23] offset:1024
	global_store_dwordx4 v0, v[72:75], s[22:23] offset:2048
	global_store_dwordx4 v0, v[76:79], s[22:23] offset:3072
	v_mul_f32_e32 v242, v65, v65
	v_mul_f32_e32 v243, v69, v69
	v_mul_f32_e32 v244, v73, v73
	v_mul_f32_e32 v245, v77, v77
	v_fmac_f32_e32 v242, v64, v64
	v_fmac_f32_e32 v243, v68, v68
	v_fmac_f32_e32 v244, v72, v72
	v_fmac_f32_e32 v245, v76, v76
	v_fmac_f32_e32 v242, v66, v66
	v_fmac_f32_e32 v243, v70, v70
	v_fmac_f32_e32 v244, v74, v74
	v_fmac_f32_e32 v245, v78, v78
	v_fmac_f32_e32 v242, v67, v67
	v_fmac_f32_e32 v243, v71, v71
	v_fmac_f32_e32 v244, v75, v75
	v_fmac_f32_e32 v245, v79, v79
	v_add_f32_e32 v242, v242, v243
	v_add_f32_e32 v242, v242, v244
	v_add_f32_e32 v242, v242, v245
	s_nop 1
	v_add_f32_dpp v242, v242, v242 quad_perm:[1,0,3,2] row_mask:0xf bank_mask:0xf bound_ctrl:1
	s_nop 1
	v_add_f32_dpp v242, v242, v242 quad_perm:[2,3,0,1] row_mask:0xf bank_mask:0xf bound_ctrl:1
	s_nop 1
	v_add_f32_dpp v242, v242, v242 row_half_mirror row_mask:0xf bank_mask:0xf bound_ctrl:1
	s_nop 1
	v_add_f32_dpp v242, v242, v242 row_mirror row_mask:0xf bank_mask:0xf bound_ctrl:1
	s_nop 1
	ds_swizzle_b32 v243, v242 offset:swizzle(SWAP,16)
	s_waitcnt lgkmcnt(0)
; DI void rows_resid_norm(const P& p, const float* xlat, const float* xctx, const h16* y, int l, int gate_idx, const float* post_g,
;                         bool do_next, int l2, const float* gain2, int sh_idx, int sc_idx, h16* dst, int nrows) {
;     ...
;   for (int row = gw; row < nrows; row += nw) {
;     const float* xr = row < TL ? xlat + (size_t)row * 1024 : xctx + (size_t)(row - TL) * 1024;
;     float* xo = row < TL ? p.out + (size_t)row * 1024 : xc + (size_t)(row - TL) * 1024;
;     const int mrow = row < TL ? (row >> 12) : 8;
;     const float* mr = mod + ((size_t)l * 9 + mrow) * 6144;
;     const float* mr2 = mod + ((size_t)l2 * 9 + mrow) * 6144;
;     f32x4 yv[4], xv[4];
;     float ss = 0.f;
; #pragma unroll
;     for (int i = 0; i < 4; ++i) {
;       h16x4 t = *(const h16x4*)(y + (size_t)row * 1024 + lane * 4 + 256 * i);
;       yv[i].x = (float)t.x; yv[i].y = (float)t.y; yv[i].z = (float)t.z; yv[i].w = (float)t.w;
;       ss += yv[i].x * yv[i].x + yv[i].y * yv[i].y + yv[i].z * yv[i].z + yv[i].w * yv[i].w;
;       xv[i] = *(const f32x4*)(xr + lane * 4 + 256 * i);
;     }
;     ss = wave_sum(ss);
;     const float rstd = rsqrtf(ss * (1.f / 1024.f) + EPS);
;     ...
;       const float r2 = rsqrtf(s2 * (1.f / 1024.f) + EPS);
; #pragma unroll
;       for (int i = 0; i < 4; ++i) {
;         const int c = lane * 4 + 256 * i;
;         f32x4 g = *(const f32x4*)(gain2 + c), sc = *(const f32x4*)(mr2 + sc_idx * 1024 + c), sh = *(const f32x4*)(mr2 + sh_idx * 1024 + c);
;         h16x4 o;
;         o.x = (h16)(xv[i].x * r2 * g.x * (1.f + sc.x) + sh.x);
;         o.y = (h16)(xv[i].y * r2 * g.y * (1.f + sc.y) + sh.y);
;         o.z = (h16)(xv[i].z * r2 * g.z * (1.f + sc.z) + sh.z);
;         o.w = (h16)(xv[i].w * r2 * g.w * (1.f + sc.w) + sh.w);
;         *(h16x4*)(dst + (size_t)row * 1024 + c) = o;
;       }
;     }
	v_add_f32_e32 v242, v242, v243
	v_mov_b32_e32 v243, v242
	s_nop 1
	v_permlane32_swap_b32_e32 v242, v243
	v_add_f32_e32 v242, v242, v243
	v_fmamk_f32 v242, v242, 0x3a800000, v224
	v_rsq_f32_e32 v242, v242
	s_nop 0
	v_mul_f32_e32 v226, v64, v242
	v_mul_f32_e32 v227, v65, v242
	v_mul_f32_e32 v228, v66, v242
	v_mul_f32_e32 v229, v67, v242
	v_mul_f32_e32 v230, v68, v242
	v_mul_f32_e32 v231, v69, v242
	v_mul_f32_e32 v232, v70, v242
	v_mul_f32_e32 v233, v71, v242
	v_mul_f32_e32 v234, v72, v242
	v_mul_f32_e32 v235, v73, v242
	v_mul_f32_e32 v236, v74, v242
	v_mul_f32_e32 v237, v75, v242
	v_mul_f32_e32 v238, v76, v242
	v_mul_f32_e32 v239, v77, v242
	v_mul_f32_e32 v240, v78, v242
	v_mul_f32_e32 v241, v79, v242
	v_mul_f32_e32 v226, v96, v226
	v_mul_f32_e32 v227, v97, v227
	v_mul_f32_e32 v228, v98, v228
	v_mul_f32_e32 v229, v99, v229
	v_mul_f32_e32 v230, v100, v230
	v_mul_f32_e32 v231, v101, v231
	v_mul_f32_e32 v232, v102, v232
	v_mul_f32_e32 v233, v103, v233
	v_mul_f32_e32 v234, v104, v234
	v_mul_f32_e32 v235, v105, v235
	v_mul_f32_e32 v236, v106, v236
	v_mul_f32_e32 v237, v107, v237
	v_mul_f32_e32 v238, v108, v238
	v_mul_f32_e32 v239, v109, v239
	v_mul_f32_e32 v240, v110, v240
	v_mul_f32_e32 v241, v111, v241
	v_add_f32_e32 v162, 1.0, v162
	v_add_f32_e32 v163, 1.0, v163
	v_add_f32_e32 v164, 1.0, v164
	v_add_f32_e32 v165, 1.0, v165
	v_add_f32_e32 v166, 1.0, v166
	v_add_f32_e32 v167, 1.0, v167
	v_add_f32_e32 v168, 1.0, v168
	v_add_f32_e32 v169, 1.0, v169
	v_add_f32_e32 v170, 1.0, v170
	v_add_f32_e32 v171, 1.0, v171
	v_add_f32_e32 v172, 1.0, v172
	v_add_f32_e32 v173, 1.0, v173
	v_add_f32_e32 v174, 1.0, v174
	v_add_f32_e32 v175, 1.0, v175
	v_add_f32_e32 v176, 1.0, v176
	v_add_f32_e32 v177, 1.0, v177
	v_fma_f32 v226, v162, v226, v178
	v_fma_f32 v227, v163, v227, v179
	v_fma_f32 v228, v164, v228, v180
	v_fma_f32 v229, v165, v229, v181
	v_fma_f32 v230, v166, v230, v182
	v_fma_f32 v231, v167, v231, v183
	v_fma_f32 v232, v168, v232, v184
	v_fma_f32 v233, v169, v233, v185
	v_fma_f32 v234, v170, v234, v186
	v_fma_f32 v235, v171, v235, v187
	v_fma_f32 v236, v172, v236, v188
	v_fma_f32 v237, v173, v237, v189
	v_fma_f32 v238, v174, v238, v190
	v_fma_f32 v239, v175, v239, v191
	v_fma_f32 v240, v176, v240, v192
	v_fma_f32 v241, v177, v241, v193
	v_cvt_pk_f16_f32 v244, v226, v227
	v_cvt_pk_f16_f32 v245, v228, v229
	v_cvt_pk_f16_f32 v246, v230, v231
	v_cvt_pk_f16_f32 v247, v232, v233
	v_cvt_pk_f16_f32 v248, v234, v235
	v_cvt_pk_f16_f32 v249, v236, v237
	v_cvt_pk_f16_f32 v250, v238, v239
	v_cvt_pk_f16_f32 v251, v240, v241
	global_store_dwordx2 v202, v[244:245], s[40:41]
	global_store_dwordx2 v202, v[246:247], s[40:41] offset:512
	global_store_dwordx2 v202, v[248:249], s[40:41] offset:1024
	global_store_dwordx2 v202, v[250:251], s[40:41] offset:1536
	s_add_i32 s58, s58, s8
	s_cmp_lt_i32 s58, s36
	s_cbranch_scc0 .Lrr2_exit
	s_lshr_b32 s59, s58, 12
	s_cmp_lt_u32 s58, 0x8000
	s_cselect_b32 s59, s59, 8
	s_mul_i32 s59, s59, 0x6000
	s_add_u32 s24, s42, s59
	s_addc_u32 s25, s43, 0
	s_add_u32 s18, s54, s59
	s_addc_u32 s19, s55, 0
	s_add_u32 s34, s18, 0x1000
	s_addc_u32 s35, s19, 0
	s_lshl_b32 s59, s58, 11
	s_add_u32 s40, s56, s59
	s_addc_u32 s41, s57, 0
	s_sub_u32 s60, s58, 0x8000
	s_cmp_lt_u32 s58, 0x8000
	s_cselect_b32 s60, s58, s60
	s_cselect_b32 s22, s46, s50
	s_cselect_b32 s23, s47, s51
	s_lshl_b32 s60, s60, 12
	s_add_u32 s22, s22, s60
	s_addc_u32 s23, s23, 0
	global_load_dwordx4 v[112:115], v0, s[24:25]
	global_load_dwordx4 v[116:119], v0, s[24:25] offset:1024
	global_load_dwordx4 v[120:123], v0, s[24:25] offset:2048
	global_load_dwordx4 v[124:127], v0, s[24:25] offset:3072
	global_load_dwordx4 v[162:165], v0, s[34:35]
	global_load_dwordx4 v[166:169], v0, s[34:35] offset:1024
	global_load_dwordx4 v[170:173], v0, s[34:35] offset:2048
	global_load_dwordx4 v[174:177], v0, s[34:35] offset:3072
	global_load_dwordx4 v[178:181], v0, s[18:19]
	global_load_dwordx4 v[182:185], v0, s[18:19] offset:1024
	global_load_dwordx4 v[186:189], v0, s[18:19] offset:2048
	global_load_dwordx4 v[190:193], v0, s[18:19] offset:3072
	s_waitcnt vmcnt(12)
	v_cvt_f32_f16_e32 v226, v2
	v_cvt_f32_f16_sdwa v227, v2 dst_sel:DWORD dst_unused:UNUSED_PAD src0_sel:WORD_1
	v_cvt_f32_f16_e32 v228, v3
	v_cvt_f32_f16_sdwa v229, v3 dst_sel:DWORD dst_unused:UNUSED_PAD src0_sel:WORD_1
	v_cvt_f32_f16_e32 v230, v4
	v_cvt_f32_f16_sdwa v231, v4 dst_sel:DWORD dst_unused:UNUSED_PAD src0_sel:WORD_1
	v_cvt_f32_f16_e32 v232, v5
	v_cvt_f32_f16_sdwa v233, v5 dst_sel:DWORD dst_unused:UNUSED_PAD src0_sel:WORD_1
	v_cvt_f32_f16_e32 v234, v6
	v_cvt_f32_f16_sdwa v235, v6 dst_sel:DWORD dst_unused:UNUSED_PAD src0_sel:WORD_1
	v_cvt_f32_f16_e32 v236, v7
	v_cvt_f32_f16_sdwa v237, v7 dst_sel:DWORD dst_unused:UNUSED_PAD src0_sel:WORD_1
	v_cvt_f32_f16_e32 v238, v8
	v_cvt_f32_f16_sdwa v239, v8 dst_sel:DWORD dst_unused:UNUSED_PAD src0_sel:WORD_1
	v_cvt_f32_f16_e32 v240, v9
	v_cvt_f32_f16_sdwa v241, v9 dst_sel:DWORD dst_unused:UNUSED_PAD src0_sel:WORD_1
	v_mul_f32_e32 v242, v227, v227
	v_mul_f32_e32 v243, v231, v231
	v_mul_f32_e32 v244, v235, v235
	v_mul_f32_e32 v245, v239, v239
	v_fmac_f32_e32 v242, v226, v226
	v_fmac_f32_e32 v243, v230, v230
	v_fmac_f32_e32 v244, v234, v234
	v_fmac_f32_e32 v245, v238, v238
	v_fmac_f32_e32 v242, v228, v228
	v_fmac_f32_e32 v243, v232, v232
	v_fmac_f32_e32 v244, v236, v236
	v_fmac_f32_e32 v245, v240, v240
	v_fmac_f32_e32 v242, v229, v229
	v_fmac_f32_e32 v243, v233, v233
	v_fmac_f32_e32 v244, v237, v237
	v_fmac_f32_e32 v245, v241, v241
	v_add_f32_e32 v242, v242, v243
	v_add_f32_e32 v242, v242, v244
	v_add_f32_e32 v242, v242, v245
	s_nop 1
	v_add_f32_dpp v242, v242, v242 quad_perm:[1,0,3,2] row_mask:0xf bank_mask:0xf bound_ctrl:1
	s_nop 1
	v_add_f32_dpp v242, v242, v242 quad_perm:[2,3,0,1] row_mask:0xf bank_mask:0xf bound_ctrl:1
	s_nop 1
	v_add_f32_dpp v242, v242, v242 row_half_mirror row_mask:0xf bank_mask:0xf bound_ctrl:1
	s_nop 1
	v_add_f32_dpp v242, v242, v242 row_mirror row_mask:0xf bank_mask:0xf bound_ctrl:1
	s_nop 1
	ds_swizzle_b32 v243, v242 offset:swizzle(SWAP,16)
	s_waitcnt lgkmcnt(0)
; DI void rows_resid_norm(const P& p, const float* xlat, const float* xctx, const h16* y, int l, int gate_idx, const float* post_g,
;                         bool do_next, int l2, const float* gain2, int sh_idx, int sc_idx, h16* dst, int nrows) {
;     ...
;     const float rstd = rsqrtf(ss * (1.f / 1024.f) + EPS);
;     float s2 = 0.f;
; #pragma unroll
;     for (int i = 0; i < 4; ++i) {
;       const int c = lane * 4 + 256 * i;
;       f32x4 g = *(const f32x4*)(post_g + c), gt = *(const f32x4*)(mr + gate_idx * 1024 + c);
;       xv[i].x += gt.x * (yv[i].x * rstd * g.x);
;       xv[i].y += gt.y * (yv[i].y * rstd * g.y);
;       xv[i].z += gt.z * (yv[i].z * rstd * g.z);
;       xv[i].w += gt.w * (yv[i].w * rstd * g.w);
;       *(f32x4*)(xo + c) = xv[i];
;       s2 += xv[i].x * xv[i].x + xv[i].y * xv[i].y + xv[i].z * xv[i].z + xv[i].w * xv[i].w;
;     }
;     if (do_next) {
;       s2 = wave_sum(s2);
;       const float r2 = rsqrtf(s2 * (1.f / 1024.f) + EPS);
; #pragma unroll
;       for (int i = 0; i < 4; ++i) {
;         const int c = lane * 4 + 256 * i;
;         f32x4 g = *(const f32x4*)(gain2 + c), sc = *(const f32x4*)(mr2 + sc_idx * 1024 + c), sh = *(const f32x4*)(mr2 + sh_idx * 1024 + c);
;         h16x4 o;
;         o.x = (h16)(xv[i].x * r2 * g.x * (1.f + sc.x) + sh.x);
;         o.y = (h16)(xv[i].y * r2 * g.y * (1.f + sc.y) + sh.y);
;         o.z = (h16)(xv[i].z * r2 * g.z * (1.f + sc.z) + sh.z);
;         o.w = (h16)(xv[i].w * r2 * g.w * (1.f + sc.w) + sh.w);
;         *(h16x4*)(dst + (size_t)row * 1024 + c) = o;
;       }
;     }
	v_add_f32_e32 v242, v242, v243
	v_mov_b32_e32 v243, v242
	s_nop 1
	v_permlane32_swap_b32_e32 v242, v243
	v_add_f32_e32 v242, v242, v243
	v_fmamk_f32 v242, v242, 0x3a800000, v224
	v_rsq_f32_e32 v242, v242
	s_waitcnt vmcnt(0)
	v_mul_f32_e32 v226, v226, v242
	v_mul_f32_e32 v227, v227, v242
	v_mul_f32_e32 v228, v228, v242
	v_mul_f32_e32 v229, v229, v242
	v_mul_f32_e32 v230, v230, v242
	v_mul_f32_e32 v231, v231, v242
	v_mul_f32_e32 v232, v232, v242
	v_mul_f32_e32 v233, v233, v242
	v_mul_f32_e32 v234, v234, v242
	v_mul_f32_e32 v235, v235, v242
	v_mul_f32_e32 v236, v236, v242
	v_mul_f32_e32 v237, v237, v242
	v_mul_f32_e32 v238, v238, v242
	v_mul_f32_e32 v239, v239, v242
	v_mul_f32_e32 v240, v240, v242
	v_mul_f32_e32 v241, v241, v242
	v_mul_f32_e32 v226, v80, v226
	v_mul_f32_e32 v227, v81, v227
	v_mul_f32_e32 v228, v82, v228
	v_mul_f32_e32 v229, v83, v229
	v_mul_f32_e32 v230, v84, v230
	v_mul_f32_e32 v231, v85, v231
	v_mul_f32_e32 v232, v86, v232
	v_mul_f32_e32 v233, v87, v233
	v_mul_f32_e32 v234, v88, v234
	v_mul_f32_e32 v235, v89, v235
	v_mul_f32_e32 v236, v90, v236
	v_mul_f32_e32 v237, v91, v237
	v_mul_f32_e32 v238, v92, v238
	v_mul_f32_e32 v239, v93, v239
	v_mul_f32_e32 v240, v94, v240
	v_mul_f32_e32 v241, v95, v241
	v_fmac_f32_e32 v32, v112, v226
	v_fmac_f32_e32 v33, v113, v227
	v_fmac_f32_e32 v34, v114, v228
	v_fmac_f32_e32 v35, v115, v229
	v_fmac_f32_e32 v36, v116, v230
	v_fmac_f32_e32 v37, v117, v231
	v_fmac_f32_e32 v38, v118, v232
	v_fmac_f32_e32 v39, v119, v233
	v_fmac_f32_e32 v40, v120, v234
	v_fmac_f32_e32 v41, v121, v235
	v_fmac_f32_e32 v42, v122, v236
	v_fmac_f32_e32 v43, v123, v237
	v_fmac_f32_e32 v44, v124, v238
	v_fmac_f32_e32 v45, v125, v239
	v_fmac_f32_e32 v46, v126, v240
	v_fmac_f32_e32 v47, v127, v241
	global_store_dwordx4 v0, v[32:35], s[22:23]
	global_store_dwordx4 v0, v[36:39], s[22:23] offset:1024
	global_store_dwordx4 v0, v[40:43], s[22:23] offset:2048
	global_store_dwordx4 v0, v[44:47], s[22:23] offset:3072
	v_mul_f32_e32 v242, v33, v33
	v_mul_f32_e32 v243, v37, v37
	v_mul_f32_e32 v244, v41, v41
	v_mul_f32_e32 v245, v45, v45
	v_fmac_f32_e32 v242, v32, v32
	v_fmac_f32_e32 v243, v36, v36
	v_fmac_f32_e32 v244, v40, v40
	v_fmac_f32_e32 v245, v44, v44
	v_fmac_f32_e32 v242, v34, v34
	v_fmac_f32_e32 v243, v38, v38
	v_fmac_f32_e32 v244, v42, v42
	v_fmac_f32_e32 v245, v46, v46
	v_fmac_f32_e32 v242, v35, v35
	v_fmac_f32_e32 v243, v39, v39
	v_fmac_f32_e32 v244, v43, v43
	v_fmac_f32_e32 v245, v47, v47
	v_add_f32_e32 v242, v242, v243
	v_add_f32_e32 v242, v242, v244
	v_add_f32_e32 v242, v242, v245
	s_nop 1
	v_add_f32_dpp v242, v242, v242 quad_perm:[1,0,3,2] row_mask:0xf bank_mask:0xf bound_ctrl:1
	s_nop 1
	v_add_f32_dpp v242, v242, v242 quad_perm:[2,3,0,1] row_mask:0xf bank_mask:0xf bound_ctrl:1
	s_nop 1
	v_add_f32_dpp v242, v242, v242 row_half_mirror row_mask:0xf bank_mask:0xf bound_ctrl:1
	s_nop 1
	v_add_f32_dpp v242, v242, v242 row_mirror row_mask:0xf bank_mask:0xf bound_ctrl:1
	s_nop 1
	ds_swizzle_b32 v243, v242 offset:swizzle(SWAP,16)
	s_waitcnt lgkmcnt(0)
	v_add_f32_e32 v242, v242, v243
	v_mov_b32_e32 v243, v242
	s_nop 1
	v_permlane32_swap_b32_e32 v242, v243
	v_add_f32_e32 v242, v242, v243
	v_fmamk_f32 v242, v242, 0x3a800000, v224
	v_rsq_f32_e32 v242, v242
	s_nop 0
	v_mul_f32_e32 v226, v32, v242
	v_mul_f32_e32 v227, v33, v242
	v_mul_f32_e32 v228, v34, v242
	v_mul_f32_e32 v229, v35, v242
	v_mul_f32_e32 v230, v36, v242
	v_mul_f32_e32 v231, v37, v242
	v_mul_f32_e32 v232, v38, v242
	v_mul_f32_e32 v233, v39, v242
	v_mul_f32_e32 v234, v40, v242
	v_mul_f32_e32 v235, v41, v242
	v_mul_f32_e32 v236, v42, v242
	v_mul_f32_e32 v237, v43, v242
	v_mul_f32_e32 v238, v44, v242
	v_mul_f32_e32 v239, v45, v242
	v_mul_f32_e32 v240, v46, v242
	v_mul_f32_e32 v241, v47, v242
	v_mul_f32_e32 v226, v96, v226
	v_mul_f32_e32 v227, v97, v227
	v_mul_f32_e32 v228, v98, v228
	v_mul_f32_e32 v229, v99, v229
	v_mul_f32_e32 v230, v100, v230
	v_mul_f32_e32 v231, v101, v231
	v_mul_f32_e32 v232, v102, v232
	v_mul_f32_e32 v233, v103, v233
	v_mul_f32_e32 v234, v104, v234
	v_mul_f32_e32 v235, v105, v235
	v_mul_f32_e32 v236, v106, v236
	v_mul_f32_e32 v237, v107, v237
	v_mul_f32_e32 v238, v108, v238
	v_mul_f32_e32 v239, v109, v239
	v_mul_f32_e32 v240, v110, v240
	v_mul_f32_e32 v241, v111, v241
	v_add_f32_e32 v162, 1.0, v162
	v_add_f32_e32 v163, 1.0, v163
	v_add_f32_e32 v164, 1.0, v164
	v_add_f32_e32 v165, 1.0, v165
	v_add_f32_e32 v166, 1.0, v166
	v_add_f32_e32 v167, 1.0, v167
	v_add_f32_e32 v168, 1.0, v168
	v_add_f32_e32 v169, 1.0, v169
	v_add_f32_e32 v170, 1.0, v170
	v_add_f32_e32 v171, 1.0, v171
	v_add_f32_e32 v172, 1.0, v172
	v_add_f32_e32 v173, 1.0, v173
	v_add_f32_e32 v174, 1.0, v174
	v_add_f32_e32 v175, 1.0, v175
	v_add_f32_e32 v176, 1.0, v176
	v_add_f32_e32 v177, 1.0, v177
	v_fma_f32 v226, v162, v226, v178
	v_fma_f32 v227, v163, v227, v179
	v_fma_f32 v228, v164, v228, v180
	v_fma_f32 v229, v165, v229, v181
	v_fma_f32 v230, v166, v230, v182
	v_fma_f32 v231, v167, v231, v183
	v_fma_f32 v232, v168, v232, v184
	v_fma_f32 v233, v169, v233, v185
	v_fma_f32 v234, v170, v234, v186
	v_fma_f32 v235, v171, v235, v187
	v_fma_f32 v236, v172, v236, v188
	v_fma_f32 v237, v173, v237, v189
	v_fma_f32 v238, v174, v238, v190
	v_fma_f32 v239, v175, v239, v191
	v_fma_f32 v240, v176, v240, v192
	v_fma_f32 v241, v177, v241, v193
	v_cvt_pk_f16_f32 v244, v226, v227
	v_cvt_pk_f16_f32 v245, v228, v229
	v_cvt_pk_f16_f32 v246, v230, v231
	v_cvt_pk_f16_f32 v247, v232, v233
	v_cvt_pk_f16_f32 v248, v234, v235
	v_cvt_pk_f16_f32 v249, v236, v237
	v_cvt_pk_f16_f32 v250, v238, v239
	v_cvt_pk_f16_f32 v251, v240, v241
	global_store_dwordx2 v202, v[244:245], s[40:41]
	global_store_dwordx2 v202, v[246:247], s[40:41] offset:512
	global_store_dwordx2 v202, v[248:249], s[40:41] offset:1024
	global_store_dwordx2 v202, v[250:251], s[40:41] offset:1536
	s_add_i32 s58, s58, s8
	s_branch .Lrr2_exit
.Lrr2_exit:
.LBB0_22:
	s_or_b64 exec, exec, s[6:7]
	s_andn2_b64 vcc, exec, s[70:71]
	s_cbranch_vccnz .LBB0_53
	v_mov_b32_e32 v0, v203
	s_mov_b32 s6, s31
	s_cmpk_gt_i32 s6, 0x191f
	s_movk_i32 s17, 0x6480
	s_cbranch_scc1 .LBB0_26
	v_and_b32_e32 v4, 31, v0
	v_readlane_b32 s2, v252, 11
	v_ashrrev_i32_e32 v6, 5, v0
	v_lshlrev_b32_e32 v0, 2, v4
	v_readlane_b32 s3, v252, 12
	v_lshlrev_b32_e32 v7, 2, v6
	v_mul_u32_u24_e32 v8, 0x84, v4
	v_lshl_add_u64 v[2:3], s[2:3], 0, v[0:1]
	s_movk_i32 s2, 0x84
	v_lshlrev_b32_e32 v4, 1, v4
	v_mov_b32_e32 v5, v1
	v_mul_lo_u32 v9, v6, s2
	v_lshl_add_u64 v[4:5], s[48:49], 0, v[4:5]
	s_lshl_b32 s7, s6, 5
	s_lshl_b32 s8, s16, 5
	v_add_u32_e32 v0, v0, v9
	v_add_u32_e32 v7, v7, v8

; DI int TIDX() { int t = threadIdx.x; asm volatile("" : "+v"(t)); return t; }
; DI int BIDX() { int b = blockIdx.x; asm volatile("" : "+s"(b)); return b; }
; DI void rows_resid_norm(const P& p, const float* xlat, const float* xctx, const h16* y, int l, int gate_idx, const float* post_g,
;                         bool do_next, int l2, const float* gain2, int sh_idx, int sc_idx, h16* dst, int nrows) {
;   const int lane = TIDX() & 63;
;   const int gw = BIDX() * 4 + (TIDX() >> 6), nw = gridDim.x * 4;
;   const float* mod = (const float*)(p.ws + OFF_MOD);
;   float* xc = (float*)(p.ws + OFF_XC);
;   for (int row = gw; row < nrows; row += nw) {
;     const float* xr = row < TL ? xlat + (size_t)row * 1024 : xctx + (size_t)(row - TL) * 1024;
;     float* xo = row < TL ? p.out + (size_t)row * 1024 : xc + (size_t)(row - TL) * 1024;
;     const int mrow = row < TL ? (row >> 12) : 8;
;     const float* mr = mod + ((size_t)l * 9 + mrow) * 6144;
;     const float* mr2 = mod + ((size_t)l2 * 9 + mrow) * 6144;
;     f32x4 yv[4], xv[4];
;     float ss = 0.f;
; #pragma unroll
;     for (int i = 0; i < 4; ++i) {
;       h16x4 t = *(const h16x4*)(y + (size_t)row * 1024 + lane * 4 + 256 * i);
;       yv[i].x = (float)t.x; yv[i].y = (float)t.y; yv[i].z = (float)t.z; yv[i].w = (float)t.w;
;       ss += yv[i].x * yv[i].x + yv[i].y * yv[i].y + yv[i].z * yv[i].z + yv[i].w * yv[i].w;
;       xv[i] = *(const f32x4*)(xr + lane * 4 + 256 * i);
;     }
.LBB0_82:
	v_readlane_b32 s38, v255, 3
	v_readlane_b32 s39, v255, 4
	s_lshl_b32 s63, s78, 12
	s_add_u32 s38, s38, s63
	s_addc_u32 s39, s39, 0
	v_readlane_b32 s52, v252, 15
	v_readlane_b32 s53, v252, 16
	s_add_u32 s52, s52, s63
	s_addc_u32 s53, s53, 0
	s_mul_i32 s63, s78, 0x36000
	s_add_u32 s54, s48, 0x2340000
	s_addc_u32 s55, s49, 0
	s_add_u32 s54, s54, s63
	s_addc_u32 s55, s55, 0
	s_add_u32 s42, s54, 0x2000
	s_addc_u32 s43, s55, 0
	s_add_u32 s44, s48, 0x316c000
	s_addc_u32 s45, s49, 0
	v_readlane_b32 s46, v252, 0
	v_readlane_b32 s47, v252, 1
	s_add_u32 s50, s48, 0x252c000
	s_addc_u32 s51, s49, 0
	s_add_u32 s56, s48, 0xf4ec000
	s_addc_u32 s57, s49, 0
	v_and_b32_e32 v0, 63, v203
	v_lshlrev_b32_e32 v202, 3, v0
	v_lshlrev_b32_e32 v0, 4, v0
	global_load_dwordx4 v[80:83], v0, s[38:39]
	global_load_dwordx4 v[84:87], v0, s[38:39] offset:1024
	global_load_dwordx4 v[88:91], v0, s[38:39] offset:2048
	global_load_dwordx4 v[92:95], v0, s[38:39] offset:3072
	v_readfirstlane_b32 s58, v12
	s_nop 3
.Lrr11_start:
	global_load_dwordx4 v[96:99], v0, s[52:53]
	global_load_dwordx4 v[100:103], v0, s[52:53] offset:1024
	global_load_dwordx4 v[104:107], v0, s[52:53] offset:2048
	global_load_dwordx4 v[108:111], v0, s[52:53] offset:3072
	s_lshl_b32 s59, s58, 11
	s_add_u32 s20, s44, s59
	s_addc_u32 s21, s45, 0
	s_sub_u32 s60, s58, 0x8000
	s_cmp_lt_u32 s58, 0x8000
	s_cselect_b32 s60, s58, s60
	s_cselect_b32 s12, s82, s80
	s_cselect_b32 s13, s83, s81
	s_lshl_b32 s60, s60, 12
	s_add_u32 s12, s12, s60
	s_addc_u32 s13, s13, 0
	global_load_dwordx2 v[2:3], v202, s[20:21]
	global_load_dwordx2 v[4:5], v202, s[20:21] offset:512
	global_load_dwordx2 v[6:7], v202, s[20:21] offset:1024
	global_load_dwordx2 v[8:9], v202, s[20:21] offset:1536
	global_load_dwordx4 v[32:35], v0, s[12:13]
	global_load_dwordx4 v[36:39], v0, s[12:13] offset:1024
	global_load_dwordx4 v[40:43], v0, s[12:13] offset:2048
	global_load_dwordx4 v[44:47], v0, s[12:13] offset:3072
	s_add_i32 s61, s58, s2
	s_cmp_lt_i32 s61, s36
	s_cbranch_scc0 .Lrr11_pre0
	s_lshl_b32 s59, s61, 11
	s_add_u32 s20, s44, s59
	s_addc_u32 s21, s45, 0
	s_sub_u32 s60, s61, 0x8000
	s_cmp_lt_u32 s61, 0x8000
	s_cselect_b32 s60, s61, s60
	s_cselect_b32 s12, s82, s80
	s_cselect_b32 s13, s83, s81
	s_lshl_b32 s60, s60, 12
	s_add_u32 s12, s12, s60
	s_addc_u32 s13, s13, 0
	global_load_dwordx2 v[10:11], v202, s[20:21]
	global_load_dwordx2 v[12:13], v202, s[20:21] offset:512
	global_load_dwordx2 v[14:15], v202, s[20:21] offset:1024
	global_load_dwordx2 v[16:17], v202, s[20:21] offset:1536
	global_load_dwordx4 v[48:51], v0, s[12:13]
	global_load_dwordx4 v[52:55], v0, s[12:13] offset:1024
	global_load_dwordx4 v[56:59], v0, s[12:13] offset:2048
	global_load_dwordx4 v[60:63], v0, s[12:13] offset:3072
.Lrr11_pre0:
	s_lshr_b32 s59, s58, 12
	s_cmp_lt_u32 s58, 0x8000
	s_cselect_b32 s59, s59, 8
	s_mul_i32 s59, s59, 0x6000
	s_add_u32 s24, s42, s59
	s_addc_u32 s25, s43, 0
	s_add_u32 s18, s54, s59
	s_addc_u32 s19, s55, 0
	s_add_u32 s34, s18, 0x4000
	s_addc_u32 s35, s19, 0
	s_add_u32 s18, s18, 0x3000
	s_addc_u32 s19, s19, 0
	s_lshl_b32 s59, s58, 11
	s_add_u32 s40, s56, s59
	s_addc_u32 s41, s57, 0
	s_sub_u32 s60, s58, 0x8000
	s_cmp_lt_u32 s58, 0x8000
	s_cselect_b32 s60, s58, s60
	s_cselect_b32 s22, s46, s50
	s_cselect_b32 s23, s47, s51
	s_lshl_b32 s60, s60, 12
	s_add_u32 s22, s22, s60
	s_addc_u32 s23, s23, 0
	global_load_dwordx4 v[112:115], v0, s[24:25]
	global_load_dwordx4 v[116:119], v0, s[24:25] offset:1024
	global_load_dwordx4 v[120:123], v0, s[24:25] offset:2048
	global_load_dwordx4 v[124:127], v0, s[24:25] offset:3072
	global_load_dwordx4 v[162:165], v0, s[34:35]
	global_load_dwordx4 v[166:169], v0, s[34:35] offset:1024
	global_load_dwordx4 v[170:173], v0, s[34:35] offset:2048
	global_load_dwordx4 v[174:177], v0, s[34:35] offset:3072
	global_load_dwordx4 v[178:181], v0, s[18:19]
	global_load_dwordx4 v[182:185], v0, s[18:19] offset:1024
	global_load_dwordx4 v[186:189], v0, s[18:19] offset:2048
	global_load_dwordx4 v[190:193], v0, s[18:19] offset:3072
	s_add_i32 s62, s58, s2
	s_add_i32 s62, s62, s2
	s_cmp_lt_i32 s62, s36
	s_cbranch_scc0 .Lrr11_tail0
	s_lshl_b32 s59, s62, 11
	s_add_u32 s20, s44, s59
	s_addc_u32 s21, s45, 0
	s_sub_u32 s60, s62, 0x8000
	s_cmp_lt_u32 s62, 0x8000
	s_cselect_b32 s60, s62, s60
	s_cselect_b32 s12, s82, s80
	s_cselect_b32 s13, s83, s81
	s_lshl_b32 s60, s60, 12
	s_add_u32 s12, s12, s60
	s_addc_u32 s13, s13, 0
	global_load_dwordx2 v[18:19], v202, s[20:21]
	global_load_dwordx2 v[20:21], v202, s[20:21] offset:512
	global_load_dwordx2 v[22:23], v202, s[20:21] offset:1024
	global_load_dwordx2 v[24:25], v202, s[20:21] offset:1536
	global_load_dwordx4 v[64:67], v0, s[12:13]
	global_load_dwordx4 v[68:71], v0, s[12:13] offset:1024
	global_load_dwordx4 v[72:75], v0, s[12:13] offset:2048
	global_load_dwordx4 v[76:79], v0, s[12:13] offset:3072
	s_waitcnt vmcnt(28)
; DI void rows_resid_norm(const P& p, const float* xlat, const float* xctx, const h16* y, int l, int gate_idx, const float* post_g,
;                         bool do_next, int l2, const float* gain2, int sh_idx, int sc_idx, h16* dst, int nrows) {
;     ...
;     ss = wave_sum(ss);
;     const float rstd = rsqrtf(ss * (1.f / 1024.f) + EPS);
;     float s2 = 0.f;
; #pragma unroll
;     for (int i = 0; i < 4; ++i) {
;       const int c = lane * 4 + 256 * i;
;       f32x4 g = *(const f32x4*)(post_g + c), gt = *(const f32x4*)(mr + gate_idx * 1024 + c);
;       xv[i].x += gt.x * (yv[i].x * rstd * g.x);
;       xv[i].y += gt.y * (yv[i].y * rstd * g.y);
;       xv[i].z += gt.z * (yv[i].z * rstd * g.z);
;       xv[i].w += gt.w * (yv[i].w * rstd * g.w);
;       *(f32x4*)(xo + c) = xv[i];
;       s2 += xv[i].x * xv[i].x + xv[i].y * xv[i].y + xv[i].z * xv[i].z + xv[i].w * xv[i].w;
;     }
;     if (do_next) {
;       s2 = wave_sum(s2);
	v_cvt_f32_f16_e32 v226, v2
	v_cvt_f32_f16_sdwa v227, v2 dst_sel:DWORD dst_unused:UNUSED_PAD src0_sel:WORD_1
	v_cvt_f32_f16_e32 v228, v3
	v_cvt_f32_f16_sdwa v229, v3 dst_sel:DWORD dst_unused:UNUSED_PAD src0_sel:WORD_1
	v_cvt_f32_f16_e32 v230, v4
	v_cvt_f32_f16_sdwa v231, v4 dst_sel:DWORD dst_unused:UNUSED_PAD src0_sel:WORD_1
	v_cvt_f32_f16_e32 v232, v5
	v_cvt_f32_f16_sdwa v233, v5 dst_sel:DWORD dst_unused:UNUSED_PAD src0_sel:WORD_1
	v_cvt_f32_f16_e32 v234, v6
	v_cvt_f32_f16_sdwa v235, v6 dst_sel:DWORD dst_unused:UNUSED_PAD src0_sel:WORD_1
	v_cvt_f32_f16_e32 v236, v7
	v_cvt_f32_f16_sdwa v237, v7 dst_sel:DWORD dst_unused:UNUSED_PAD src0_sel:WORD_1
	v_cvt_f32_f16_e32 v238, v8
	v_cvt_f32_f16_sdwa v239, v8 dst_sel:DWORD dst_unused:UNUSED_PAD src0_sel:WORD_1
	v_cvt_f32_f16_e32 v240, v9
	v_cvt_f32_f16_sdwa v241, v9 dst_sel:DWORD dst_unused:UNUSED_PAD src0_sel:WORD_1
	v_mul_f32_e32 v242, v227, v227
	v_mul_f32_e32 v243, v231, v231
	v_mul_f32_e32 v244, v235, v235
	v_mul_f32_e32 v245, v239, v239
	v_fmac_f32_e32 v242, v226, v226
	v_fmac_f32_e32 v243, v230, v230
	v_fmac_f32_e32 v244, v234, v234
	v_fmac_f32_e32 v245, v238, v238
	v_fmac_f32_e32 v242, v228, v228
	v_fmac_f32_e32 v243, v232, v232
	v_fmac_f32_e32 v244, v236, v236
	v_fmac_f32_e32 v245, v240, v240
	v_fmac_f32_e32 v242, v229, v229
	v_fmac_f32_e32 v243, v233, v233
	v_fmac_f32_e32 v244, v237, v237
	v_fmac_f32_e32 v245, v241, v241
	v_add_f32_e32 v242, v242, v243
	v_add_f32_e32 v242, v242, v244
	v_add_f32_e32 v242, v242, v245
	s_nop 1
	v_add_f32_dpp v242, v242, v242 quad_perm:[1,0,3,2] row_mask:0xf bank_mask:0xf bound_ctrl:1
	s_nop 1
	v_add_f32_dpp v242, v242, v242 quad_perm:[2,3,0,1] row_mask:0xf bank_mask:0xf bound_ctrl:1
	s_nop 1
	v_add_f32_dpp v242, v242, v242 row_half_mirror row_mask:0xf bank_mask:0xf bound_ctrl:1
	s_nop 1
	v_add_f32_dpp v242, v242, v242 row_mirror row_mask:0xf bank_mask:0xf bound_ctrl:1
	s_nop 1
	ds_swizzle_b32 v243, v242 offset:swizzle(SWAP,16)
	s_waitcnt lgkmcnt(0)
	v_add_f32_e32 v242, v242, v243
	v_mov_b32_e32 v243, v242
	s_nop 1
	v_permlane32_swap_b32_e32 v242, v243
	v_add_f32_e32 v242, v242, v243
	v_fmamk_f32 v242, v242, 0x3a800000, v224
	v_rsq_f32_e32 v242, v242
	s_waitcnt vmcnt(8)
	v_mul_f32_e32 v226, v226, v242
	v_mul_f32_e32 v227, v227, v242
	v_mul_f32_e32 v228, v228, v242
	v_mul_f32_e32 v229, v229, v242
	v_mul_f32_e32 v230, v230, v242
	v_mul_f32_e32 v231, v231, v242
	v_mul_f32_e32 v232, v232, v242
	v_mul_f32_e32 v233, v233, v242
	v_mul_f32_e32 v234, v234, v242
	v_mul_f32_e32 v235, v235, v242
	v_mul_f32_e32 v236, v236, v242
	v_mul_f32_e32 v237, v237, v242
	v_mul_f32_e32 v238, v238, v242
	v_mul_f32_e32 v239, v239, v242
	v_mul_f32_e32 v240, v240, v242
	v_mul_f32_e32 v241, v241, v242
	v_mul_f32_e32 v226, v80, v226
	v_mul_f32_e32 v227, v81, v227
	v_mul_f32_e32 v228, v82, v228
	v_mul_f32_e32 v229, v83, v229
	v_mul_f32_e32 v230, v84, v230
	v_mul_f32_e32 v231, v85, v231
	v_mul_f32_e32 v232, v86, v232
	v_mul_f32_e32 v233, v87, v233
	v_mul_f32_e32 v234, v88, v234
	v_mul_f32_e32 v235, v89, v235
	v_mul_f32_e32 v236, v90, v236
	v_mul_f32_e32 v237, v91, v237
	v_mul_f32_e32 v238, v92, v238
	v_mul_f32_e32 v239, v93, v239
	v_mul_f32_e32 v240, v94, v240
	v_mul_f32_e32 v241, v95, v241
	v_fmac_f32_e32 v32, v112, v226
	v_fmac_f32_e32 v33, v113, v227
	v_fmac_f32_e32 v34, v114, v228
	v_fmac_f32_e32 v35, v115, v229
	v_fmac_f32_e32 v36, v116, v230
	v_fmac_f32_e32 v37, v117, v231
	v_fmac_f32_e32 v38, v118, v232
	v_fmac_f32_e32 v39, v119, v233
	v_fmac_f32_e32 v40, v120, v234
	v_fmac_f32_e32 v41, v121, v235
	v_fmac_f32_e32 v42, v122, v236
	v_fmac_f32_e32 v43, v123, v237
	v_fmac_f32_e32 v44, v124, v238
	v_fmac_f32_e32 v45, v125, v239
	v_fmac_f32_e32 v46, v126, v240
	v_fmac_f32_e32 v47, v127, v241
	global_store_dwordx4 v0, v[32:35], s[22:23]
	global_store_dwordx4 v0, v[36:39], s[22:23] offset:1024
	global_store_dwordx4 v0, v[40:43], s[22:23] offset:2048
	global_store_dwordx4 v0, v[44:47], s[22:23] offset:3072
	v_mul_f32_e32 v242, v33, v33
	v_mul_f32_e32 v243, v37, v37
	v_mul_f32_e32 v244, v41, v41
	v_mul_f32_e32 v245, v45, v45
	v_fmac_f32_e32 v242, v32, v32
	v_fmac_f32_e32 v243, v36, v36
	v_fmac_f32_e32 v244, v40, v40
	v_fmac_f32_e32 v245, v44, v44
	v_fmac_f32_e32 v242, v34, v34
	v_fmac_f32_e32 v243, v38, v38
	v_fmac_f32_e32 v244, v42, v42
	v_fmac_f32_e32 v245, v46, v46
	v_fmac_f32_e32 v242, v35, v35
	v_fmac_f32_e32 v243, v39, v39
	v_fmac_f32_e32 v244, v43, v43
	v_fmac_f32_e32 v245, v47, v47
	v_add_f32_e32 v242, v242, v243
	v_add_f32_e32 v242, v242, v244
	v_add_f32_e32 v242, v242, v245
	s_nop 1
	v_add_f32_dpp v242, v242, v242 quad_perm:[1,0,3,2] row_mask:0xf bank_mask:0xf bound_ctrl:1
	s_nop 1
	v_add_f32_dpp v242, v242, v242 quad_perm:[2,3,0,1] row_mask:0xf bank_mask:0xf bound_ctrl:1
	s_nop 1
	v_add_f32_dpp v242, v242, v242 row_half_mirror row_mask:0xf bank_mask:0xf bound_ctrl:1
	s_nop 1
	v_add_f32_dpp v242, v242, v242 row_mirror row_mask:0xf bank_mask:0xf bound_ctrl:1
	s_nop 1
	ds_swizzle_b32 v243, v242 offset:swizzle(SWAP,16)
	s_waitcnt lgkmcnt(0)
; DI void rows_resid_norm(const P& p, const float* xlat, const float* xctx, const h16* y, int l, int gate_idx, const float* post_g,
;                         bool do_next, int l2, const float* gain2, int sh_idx, int sc_idx, h16* dst, int nrows) {
;     ...
;   for (int row = gw; row < nrows; row += nw) {
;     const float* xr = row < TL ? xlat + (size_t)row * 1024 : xctx + (size_t)(row - TL) * 1024;
;     float* xo = row < TL ? p.out + (size_t)row * 1024 : xc + (size_t)(row - TL) * 1024;
;     const int mrow = row < TL ? (row >> 12) : 8;
;     const float* mr = mod + ((size_t)l * 9 + mrow) * 6144;
;     const float* mr2 = mod + ((size_t)l2 * 9 + mrow) * 6144;
;     f32x4 yv[4], xv[4];
;     float ss = 0.f;
; #pragma unroll
;     for (int i = 0; i < 4; ++i) {
;       h16x4 t = *(const h16x4*)(y + (size_t)row * 1024 + lane * 4 + 256 * i);
;       yv[i].x = (float)t.x; yv[i].y = (float)t.y; yv[i].z = (float)t.z; yv[i].w = (float)t.w;
;       ss += yv[i].x * yv[i].x + yv[i].y * yv[i].y + yv[i].z * yv[i].z + yv[i].w * yv[i].w;
;       xv[i] = *(const f32x4*)(xr + lane * 4 + 256 * i);
;     }
;     ...
;       const float r2 = rsqrtf(s2 * (1.f / 1024.f) + EPS);
; #pragma unroll
;       for (int i = 0; i < 4; ++i) {
;         const int c = lane * 4 + 256 * i;
;         f32x4 g = *(const f32x4*)(gain2 + c), sc = *(const f32x4*)(mr2 + sc_idx * 1024 + c), sh = *(const f32x4*)(mr2 + sh_idx * 1024 + c);
;         h16x4 o;
;         o.x = (h16)(xv[i].x * r2 * g.x * (1.f + sc.x) + sh.x);
;         o.y = (h16)(xv[i].y * r2 * g.y * (1.f + sc.y) + sh.y);
;         o.z = (h16)(xv[i].z * r2 * g.z * (1.f + sc.z) + sh.z);
;         o.w = (h16)(xv[i].w * r2 * g.w * (1.f + sc.w) + sh.w);
;         *(h16x4*)(dst + (size_t)row * 1024 + c) = o;
;       }
;     }
	v_add_f32_e32 v242, v242, v243
	v_mov_b32_e32 v243, v242
	s_nop 1
	v_permlane32_swap_b32_e32 v242, v243
	v_add_f32_e32 v242, v242, v243
	v_fmamk_f32 v242, v242, 0x3a800000, v224
	v_rsq_f32_e32 v242, v242
	s_nop 0
	v_mul_f32_e32 v226, v32, v242
	v_mul_f32_e32 v227, v33, v242
	v_mul_f32_e32 v228, v34, v242
	v_mul_f32_e32 v229, v35, v242
	v_mul_f32_e32 v230, v36, v242
	v_mul_f32_e32 v231, v37, v242
	v_mul_f32_e32 v232, v38, v242
	v_mul_f32_e32 v233, v39, v242
	v_mul_f32_e32 v234, v40, v242
	v_mul_f32_e32 v235, v41, v242
	v_mul_f32_e32 v236, v42, v242
	v_mul_f32_e32 v237, v43, v242
	v_mul_f32_e32 v238, v44, v242
	v_mul_f32_e32 v239, v45, v242
	v_mul_f32_e32 v240, v46, v242
	v_mul_f32_e32 v241, v47, v242
	v_mul_f32_e32 v226, v96, v226
	v_mul_f32_e32 v227, v97, v227
	v_mul_f32_e32 v228, v98, v228
	v_mul_f32_e32 v229, v99, v229
	v_mul_f32_e32 v230, v100, v230
	v_mul_f32_e32 v231, v101, v231
	v_mul_f32_e32 v232, v102, v232
	v_mul_f32_e32 v233, v103, v233
	v_mul_f32_e32 v234, v104, v234
	v_mul_f32_e32 v235, v105, v235
	v_mul_f32_e32 v236, v106, v236
	v_mul_f32_e32 v237, v107, v237
	v_mul_f32_e32 v238, v108, v238
	v_mul_f32_e32 v239, v109, v239
	v_mul_f32_e32 v240, v110, v240
	v_mul_f32_e32 v241, v111, v241
	v_add_f32_e32 v162, 1.0, v162
	v_add_f32_e32 v163, 1.0, v163
	v_add_f32_e32 v164, 1.0, v164
	v_add_f32_e32 v165, 1.0, v165
	v_add_f32_e32 v166, 1.0, v166
	v_add_f32_e32 v167, 1.0, v167
	v_add_f32_e32 v168, 1.0, v168
	v_add_f32_e32 v169, 1.0, v169
	v_add_f32_e32 v170, 1.0, v170
	v_add_f32_e32 v171, 1.0, v171
	v_add_f32_e32 v172, 1.0, v172
	v_add_f32_e32 v173, 1.0, v173
	v_add_f32_e32 v174, 1.0, v174
	v_add_f32_e32 v175, 1.0, v175
	v_add_f32_e32 v176, 1.0, v176
	v_add_f32_e32 v177, 1.0, v177
	v_fma_f32 v226, v162, v226, v178
	v_fma_f32 v227, v163, v227, v179
	v_fma_f32 v228, v164, v228, v180
	v_fma_f32 v229, v165, v229, v181
	v_fma_f32 v230, v166, v230, v182
	v_fma_f32 v231, v167, v231, v183
	v_fma_f32 v232, v168, v232, v184
	v_fma_f32 v233, v169, v233, v185
	v_fma_f32 v234, v170, v234, v186
	v_fma_f32 v235, v171, v235, v187
	v_fma_f32 v236, v172, v236, v188
	v_fma_f32 v237, v173, v237, v189
	v_fma_f32 v238, v174, v238, v190
	v_fma_f32 v239, v175, v239, v191
	v_fma_f32 v240, v176, v240, v192
	v_fma_f32 v241, v177, v241, v193
	v_cvt_pk_f16_f32 v244, v226, v227
	v_cvt_pk_f16_f32 v245, v228, v229
	v_cvt_pk_f16_f32 v246, v230, v231
	v_cvt_pk_f16_f32 v247, v232, v233
	v_cvt_pk_f16_f32 v248, v234, v235
	v_cvt_pk_f16_f32 v249, v236, v237
	v_cvt_pk_f16_f32 v250, v238, v239
	v_cvt_pk_f16_f32 v251, v240, v241
	global_store_dwordx2 v202, v[244:245], s[40:41]
	global_store_dwordx2 v202, v[246:247], s[40:41] offset:512
	global_store_dwordx2 v202, v[248:249], s[40:41] offset:1024
	global_store_dwordx2 v202, v[250:251], s[40:41] offset:1536
	s_add_i32 s58, s58, s2
.Lrr11_pre1:
	s_lshr_b32 s59, s58, 12
	s_cmp_lt_u32 s58, 0x8000
	s_cselect_b32 s59, s59, 8
	s_mul_i32 s59, s59, 0x6000
	s_add_u32 s24, s42, s59
	s_addc_u32 s25, s43, 0
	s_add_u32 s18, s54, s59
	s_addc_u32 s19, s55, 0
	s_add_u32 s34, s18, 0x4000
	s_addc_u32 s35, s19, 0
	s_add_u32 s18, s18, 0x3000
	s_addc_u32 s19, s19, 0
	s_lshl_b32 s59, s58, 11
	s_add_u32 s40, s56, s59
	s_addc_u32 s41, s57, 0
	s_sub_u32 s60, s58, 0x8000
	s_cmp_lt_u32 s58, 0x8000
	s_cselect_b32 s60, s58, s60
	s_cselect_b32 s22, s46, s50
	s_cselect_b32 s23, s47, s51
	s_lshl_b32 s60, s60, 12
	s_add_u32 s22, s22, s60
	s_addc_u32 s23, s23, 0
	global_load_dwordx4 v[112:115], v0, s[24:25]
	global_load_dwordx4 v[116:119], v0, s[24:25] offset:1024
	global_load_dwordx4 v[120:123], v0, s[24:25] offset:2048
	global_load_dwordx4 v[124:127], v0, s[24:25] offset:3072
	global_load_dwordx4 v[162:165], v0, s[34:35]
	global_load_dwordx4 v[166:169], v0, s[34:35] offset:1024
	global_load_dwordx4 v[170:173], v0, s[34:35] offset:2048
	global_load_dwordx4 v[174:177], v0, s[34:35] offset:3072
	global_load_dwordx4 v[178:181], v0, s[18:19]
	global_load_dwordx4 v[182:185], v0, s[18:19] offset:1024
	global_load_dwordx4 v[186:189], v0, s[18:19] offset:2048
	global_load_dwordx4 v[190:193], v0, s[18:19] offset:3072
	s_add_i32 s62, s58, s2
	s_add_i32 s62, s62, s2
	s_cmp_lt_i32 s62, s36
	s_cbranch_scc0 .Lrr11_tail1
	s_lshl_b32 s59, s62, 11
	s_add_u32 s20, s44, s59
	s_addc_u32 s21, s45, 0
	s_sub_u32 s60, s62, 0x8000
	s_cmp_lt_u32 s62, 0x8000
	s_cselect_b32 s60, s62, s60
	s_cselect_b32 s12, s82, s80
	s_cselect_b32 s13, s83, s81
	s_lshl_b32 s60, s60, 12
	s_add_u32 s12, s12, s60
	s_addc_u32 s13, s13, 0
	global_load_dwordx2 v[2:3], v202, s[20:21]
	global_load_dwordx2 v[4:5], v202, s[20:21] offset:512
	global_load_dwordx2 v[6:7], v202, s[20:21] offset:1024
	global_load_dwordx2 v[8:9], v202, s[20:21] offset:1536
	global_load_dwordx4 v[32:35], v0, s[12:13]
	global_load_dwordx4 v[36:39], v0, s[12:13] offset:1024
	global_load_dwordx4 v[40:43], v0, s[12:13] offset:2048
	global_load_dwordx4 v[44:47], v0, s[12:13] offset:3072
	s_waitcnt vmcnt(28)
; DI void rows_resid_norm(const P& p, const float* xlat, const float* xctx, const h16* y, int l, int gate_idx, const float* post_g,
;                         bool do_next, int l2, const float* gain2, int sh_idx, int sc_idx, h16* dst, int nrows) {
;     ...
;     ss = wave_sum(ss);
;     const float rstd = rsqrtf(ss * (1.f / 1024.f) + EPS);
;     float s2 = 0.f;
; #pragma unroll
;     for (int i = 0; i < 4; ++i) {
;       const int c = lane * 4 + 256 * i;
;       f32x4 g = *(const f32x4*)(post_g + c), gt = *(const f32x4*)(mr + gate_idx * 1024 + c);
;       xv[i].x += gt.x * (yv[i].x * rstd * g.x);
;       xv[i].y += gt.y * (yv[i].y * rstd * g.y);
;       xv[i].z += gt.z * (yv[i].z * rstd * g.z);
;       xv[i].w += gt.w * (yv[i].w * rstd * g.w);
;       *(f32x4*)(xo + c) = xv[i];
;       s2 += xv[i].x * xv[i].x + xv[i].y * xv[i].y + xv[i].z * xv[i].z + xv[i].w * xv[i].w;
;     }
;     if (do_next) {
;       s2 = wave_sum(s2);
	v_cvt_f32_f16_e32 v226, v10
	v_cvt_f32_f16_sdwa v227, v10 dst_sel:DWORD dst_unused:UNUSED_PAD src0_sel:WORD_1
	v_cvt_f32_f16_e32 v228, v11
	v_cvt_f32_f16_sdwa v229, v11 dst_sel:DWORD dst_unused:UNUSED_PAD src0_sel:WORD_1
	v_cvt_f32_f16_e32 v230, v12
	v_cvt_f32_f16_sdwa v231, v12 dst_sel:DWORD dst_unused:UNUSED_PAD src0_sel:WORD_1
	v_cvt_f32_f16_e32 v232, v13
	v_cvt_f32_f16_sdwa v233, v13 dst_sel:DWORD dst_unused:UNUSED_PAD src0_sel:WORD_1
	v_cvt_f32_f16_e32 v234, v14
	v_cvt_f32_f16_sdwa v235, v14 dst_sel:DWORD dst_unused:UNUSED_PAD src0_sel:WORD_1
	v_cvt_f32_f16_e32 v236, v15
	v_cvt_f32_f16_sdwa v237, v15 dst_sel:DWORD dst_unused:UNUSED_PAD src0_sel:WORD_1
	v_cvt_f32_f16_e32 v238, v16
	v_cvt_f32_f16_sdwa v239, v16 dst_sel:DWORD dst_unused:UNUSED_PAD src0_sel:WORD_1
	v_cvt_f32_f16_e32 v240, v17
	v_cvt_f32_f16_sdwa v241, v17 dst_sel:DWORD dst_unused:UNUSED_PAD src0_sel:WORD_1
	v_mul_f32_e32 v242, v227, v227
	v_mul_f32_e32 v243, v231, v231
	v_mul_f32_e32 v244, v235, v235
	v_mul_f32_e32 v245, v239, v239
	v_fmac_f32_e32 v242, v226, v226
	v_fmac_f32_e32 v243, v230, v230
	v_fmac_f32_e32 v244, v234, v234
	v_fmac_f32_e32 v245, v238, v238
	v_fmac_f32_e32 v242, v228, v228
	v_fmac_f32_e32 v243, v232, v232
	v_fmac_f32_e32 v244, v236, v236
	v_fmac_f32_e32 v245, v240, v240
	v_fmac_f32_e32 v242, v229, v229
	v_fmac_f32_e32 v243, v233, v233
	v_fmac_f32_e32 v244, v237, v237
	v_fmac_f32_e32 v245, v241, v241
	v_add_f32_e32 v242, v242, v243
	v_add_f32_e32 v242, v242, v244
	v_add_f32_e32 v242, v242, v245
	s_nop 1
	v_add_f32_dpp v242, v242, v242 quad_perm:[1,0,3,2] row_mask:0xf bank_mask:0xf bound_ctrl:1
	s_nop 1
	v_add_f32_dpp v242, v242, v242 quad_perm:[2,3,0,1] row_mask:0xf bank_mask:0xf bound_ctrl:1
	s_nop 1
	v_add_f32_dpp v242, v242, v242 row_half_mirror row_mask:0xf bank_mask:0xf bound_ctrl:1
	s_nop 1
	v_add_f32_dpp v242, v242, v242 row_mirror row_mask:0xf bank_mask:0xf bound_ctrl:1
	s_nop 1
	ds_swizzle_b32 v243, v242 offset:swizzle(SWAP,16)
	s_waitcnt lgkmcnt(0)
	v_add_f32_e32 v242, v242, v243
	v_mov_b32_e32 v243, v242
	s_nop 1
	v_permlane32_swap_b32_e32 v242, v243
	v_add_f32_e32 v242, v242, v243
	v_fmamk_f32 v242, v242, 0x3a800000, v224
	v_rsq_f32_e32 v242, v242
	s_waitcnt vmcnt(8)
	v_mul_f32_e32 v226, v226, v242
	v_mul_f32_e32 v227, v227, v242
	v_mul_f32_e32 v228, v228, v242
	v_mul_f32_e32 v229, v229, v242
	v_mul_f32_e32 v230, v230, v242
	v_mul_f32_e32 v231, v231, v242
	v_mul_f32_e32 v232, v232, v242
	v_mul_f32_e32 v233, v233, v242
	v_mul_f32_e32 v234, v234, v242
	v_mul_f32_e32 v235, v235, v242
	v_mul_f32_e32 v236, v236, v242
	v_mul_f32_e32 v237, v237, v242
	v_mul_f32_e32 v238, v238, v242
	v_mul_f32_e32 v239, v239, v242
	v_mul_f32_e32 v240, v240, v242
	v_mul_f32_e32 v241, v241, v242
	v_mul_f32_e32 v226, v80, v226
	v_mul_f32_e32 v227, v81, v227
	v_mul_f32_e32 v228, v82, v228
	v_mul_f32_e32 v229, v83, v229
	v_mul_f32_e32 v230, v84, v230
	v_mul_f32_e32 v231, v85, v231
	v_mul_f32_e32 v232, v86, v232
	v_mul_f32_e32 v233, v87, v233
	v_mul_f32_e32 v234, v88, v234
	v_mul_f32_e32 v235, v89, v235
	v_mul_f32_e32 v236, v90, v236
	v_mul_f32_e32 v237, v91, v237
	v_mul_f32_e32 v238, v92, v238
	v_mul_f32_e32 v239, v93, v239
	v_mul_f32_e32 v240, v94, v240
	v_mul_f32_e32 v241, v95, v241
	v_fmac_f32_e32 v48, v112, v226
	v_fmac_f32_e32 v49, v113, v227
	v_fmac_f32_e32 v50, v114, v228
	v_fmac_f32_e32 v51, v115, v229
	v_fmac_f32_e32 v52, v116, v230
	v_fmac_f32_e32 v53, v117, v231
	v_fmac_f32_e32 v54, v118, v232
	v_fmac_f32_e32 v55, v119, v233
	v_fmac_f32_e32 v56, v120, v234
	v_fmac_f32_e32 v57, v121, v235
	v_fmac_f32_e32 v58, v122, v236
	v_fmac_f32_e32 v59, v123, v237
	v_fmac_f32_e32 v60, v124, v238
	v_fmac_f32_e32 v61, v125, v239
	v_fmac_f32_e32 v62, v126, v240
	v_fmac_f32_e32 v63, v127, v241
	global_store_dwordx4 v0, v[48:51], s[22:23]
	global_store_dwordx4 v0, v[52:55], s[22:23] offset:1024
	global_store_dwordx4 v0, v[56:59], s[22:23] offset:2048
	global_store_dwordx4 v0, v[60:63], s[22:23] offset:3072
	v_mul_f32_e32 v242, v49, v49
	v_mul_f32_e32 v243, v53, v53
	v_mul_f32_e32 v244, v57, v57
	v_mul_f32_e32 v245, v61, v61
	v_fmac_f32_e32 v242, v48, v48
	v_fmac_f32_e32 v243, v52, v52
	v_fmac_f32_e32 v244, v56, v56
	v_fmac_f32_e32 v245, v60, v60
	v_fmac_f32_e32 v242, v50, v50
	v_fmac_f32_e32 v243, v54, v54
	v_fmac_f32_e32 v244, v58, v58
	v_fmac_f32_e32 v245, v62, v62
	v_fmac_f32_e32 v242, v51, v51
	v_fmac_f32_e32 v243, v55, v55
	v_fmac_f32_e32 v244, v59, v59
	v_fmac_f32_e32 v245, v63, v63
	v_add_f32_e32 v242, v242, v243
	v_add_f32_e32 v242, v242, v244
	v_add_f32_e32 v242, v242, v245
	s_nop 1
	v_add_f32_dpp v242, v242, v242 quad_perm:[1,0,3,2] row_mask:0xf bank_mask:0xf bound_ctrl:1
	s_nop 1
	v_add_f32_dpp v242, v242, v242 quad_perm:[2,3,0,1] row_mask:0xf bank_mask:0xf bound_ctrl:1
	s_nop 1
	v_add_f32_dpp v242, v242, v242 row_half_mirror row_mask:0xf bank_mask:0xf bound_ctrl:1
	s_nop 1
	v_add_f32_dpp v242, v242, v242 row_mirror row_mask:0xf bank_mask:0xf bound_ctrl:1
	s_nop 1
	ds_swizzle_b32 v243, v242 offset:swizzle(SWAP,16)
	s_waitcnt lgkmcnt(0)
; DI void rows_resid_norm(const P& p, const float* xlat, const float* xctx, const h16* y, int l, int gate_idx, const float* post_g,
;                         bool do_next, int l2, const float* gain2, int sh_idx, int sc_idx, h16* dst, int nrows) {
;     ...
;   for (int row = gw; row < nrows; row += nw) {
;     const float* xr = row < TL ? xlat + (size_t)row * 1024 : xctx + (size_t)(row - TL) * 1024;
;     float* xo = row < TL ? p.out + (size_t)row * 1024 : xc + (size_t)(row - TL) * 1024;
;     const int mrow = row < TL ? (row >> 12) : 8;
;     const float* mr = mod + ((size_t)l * 9 + mrow) * 6144;
;     const float* mr2 = mod + ((size_t)l2 * 9 + mrow) * 6144;
;     f32x4 yv[4], xv[4];
;     float ss = 0.f;
; #pragma unroll
;     for (int i = 0; i < 4; ++i) {
;       h16x4 t = *(const h16x4*)(y + (size_t)row * 1024 + lane * 4 + 256 * i);
;       yv[i].x = (float)t.x; yv[i].y = (float)t.y; yv[i].z = (float)t.z; yv[i].w = (float)t.w;
;       ss += yv[i].x * yv[i].x + yv[i].y * yv[i].y + yv[i].z * yv[i].z + yv[i].w * yv[i].w;
;       xv[i] = *(const f32x4*)(xr + lane * 4 + 256 * i);
;     }
;     ...
;     if (do_next) {
;       s2 = wave_sum(s2);
;       const float r2 = rsqrtf(s2 * (1.f / 1024.f) + EPS);
; #pragma unroll
;       for (int i = 0; i < 4; ++i) {
;         const int c = lane * 4 + 256 * i;
;         f32x4 g = *(const f32x4*)(gain2 + c), sc = *(const f32x4*)(mr2 + sc_idx * 1024 + c), sh = *(const f32x4*)(mr2 + sh_idx * 1024 + c);
;         h16x4 o;
;         o.x = (h16)(xv[i].x * r2 * g.x * (1.f + sc.x) + sh.x);
;         o.y = (h16)(xv[i].y * r2 * g.y * (1.f + sc.y) + sh.y);
;         o.z = (h16)(xv[i].z * r2 * g.z * (1.f + sc.z) + sh.z);
;         o.w = (h16)(xv[i].w * r2 * g.w * (1.f + sc.w) + sh.w);
;         *(h16x4*)(dst + (size_t)row * 1024 + c) = o;
;       }
;     }
	v_add_f32_e32 v242, v242, v243
	v_mov_b32_e32 v243, v242
	s_nop 1
	v_permlane32_swap_b32_e32 v242, v243
	v_add_f32_e32 v242, v242, v243
	v_fmamk_f32 v242, v242, 0x3a800000, v224
	v_rsq_f32_e32 v242, v242
	s_nop 0
	v_mul_f32_e32 v226, v48, v242
	v_mul_f32_e32 v227, v49, v242
	v_mul_f32_e32 v228, v50, v242
	v_mul_f32_e32 v229, v51, v242
	v_mul_f32_e32 v230, v52, v242
	v_mul_f32_e32 v231, v53, v242
	v_mul_f32_e32 v232, v54, v242
	v_mul_f32_e32 v233, v55, v242
	v_mul_f32_e32 v234, v56, v242
	v_mul_f32_e32 v235, v57, v242
	v_mul_f32_e32 v236, v58, v242
	v_mul_f32_e32 v237, v59, v242
	v_mul_f32_e32 v238, v60, v242
	v_mul_f32_e32 v239, v61, v242
	v_mul_f32_e32 v240, v62, v242
	v_mul_f32_e32 v241, v63, v242
	v_mul_f32_e32 v226, v96, v226
	v_mul_f32_e32 v227, v97, v227
	v_mul_f32_e32 v228, v98, v228
	v_mul_f32_e32 v229, v99, v229
	v_mul_f32_e32 v230, v100, v230
	v_mul_f32_e32 v231, v101, v231
	v_mul_f32_e32 v232, v102, v232
	v_mul_f32_e32 v233, v103, v233
	v_mul_f32_e32 v234, v104, v234
	v_mul_f32_e32 v235, v105, v235
	v_mul_f32_e32 v236, v106, v236
	v_mul_f32_e32 v237, v107, v237
	v_mul_f32_e32 v238, v108, v238
	v_mul_f32_e32 v239, v109, v239
	v_mul_f32_e32 v240, v110, v240
	v_mul_f32_e32 v241, v111, v241
	v_add_f32_e32 v162, 1.0, v162
	v_add_f32_e32 v163, 1.0, v163
	v_add_f32_e32 v164, 1.0, v164
	v_add_f32_e32 v165, 1.0, v165
	v_add_f32_e32 v166, 1.0, v166
	v_add_f32_e32 v167, 1.0, v167
	v_add_f32_e32 v168, 1.0, v168
	v_add_f32_e32 v169, 1.0, v169
	v_add_f32_e32 v170, 1.0, v170
	v_add_f32_e32 v171, 1.0, v171
	v_add_f32_e32 v172, 1.0, v172
	v_add_f32_e32 v173, 1.0, v173
	v_add_f32_e32 v174, 1.0, v174
	v_add_f32_e32 v175, 1.0, v175
	v_add_f32_e32 v176, 1.0, v176
	v_add_f32_e32 v177, 1.0, v177
	v_fma_f32 v226, v162, v226, v178
	v_fma_f32 v227, v163, v227, v179
	v_fma_f32 v228, v164, v228, v180
	v_fma_f32 v229, v165, v229, v181
	v_fma_f32 v230, v166, v230, v182
	v_fma_f32 v231, v167, v231, v183
	v_fma_f32 v232, v168, v232, v184
	v_fma_f32 v233, v169, v233, v185
	v_fma_f32 v234, v170, v234, v186
	v_fma_f32 v235, v171, v235, v187
	v_fma_f32 v236, v172, v236, v188
	v_fma_f32 v237, v173, v237, v189
	v_fma_f32 v238, v174, v238, v190
	v_fma_f32 v239, v175, v239, v191
	v_fma_f32 v240, v176, v240, v192
	v_fma_f32 v241, v177, v241, v193
	v_cvt_pk_f16_f32 v244, v226, v227
	v_cvt_pk_f16_f32 v245, v228, v229
	v_cvt_pk_f16_f32 v246, v230, v231
	v_cvt_pk_f16_f32 v247, v232, v233
	v_cvt_pk_f16_f32 v248, v234, v235
	v_cvt_pk_f16_f32 v249, v236, v237
	v_cvt_pk_f16_f32 v250, v238, v239
	v_cvt_pk_f16_f32 v251, v240, v241
	global_store_dwordx2 v202, v[244:245], s[40:41]
	global_store_dwordx2 v202, v[246:247], s[40:41] offset:512
	global_store_dwordx2 v202, v[248:249], s[40:41] offset:1024
	global_store_dwordx2 v202, v[250:251], s[40:41] offset:1536
	s_add_i32 s58, s58, s2
.Lrr11_l2:
	s_lshr_b32 s59, s58, 12
	s_cmp_lt_u32 s58, 0x8000
	s_cselect_b32 s59, s59, 8
	s_mul_i32 s59, s59, 0x6000
	s_add_u32 s24, s42, s59
	s_addc_u32 s25, s43, 0
	s_add_u32 s18, s54, s59
	s_addc_u32 s19, s55, 0
	s_add_u32 s34, s18, 0x4000
	s_addc_u32 s35, s19, 0
	s_add_u32 s18, s18, 0x3000
	s_addc_u32 s19, s19, 0
	s_lshl_b32 s59, s58, 11
	s_add_u32 s40, s56, s59
	s_addc_u32 s41, s57, 0
	s_sub_u32 s60, s58, 0x8000
	s_cmp_lt_u32 s58, 0x8000
	s_cselect_b32 s60, s58, s60
	s_cselect_b32 s22, s46, s50
	s_cselect_b32 s23, s47, s51
	s_lshl_b32 s60, s60, 12
	s_add_u32 s22, s22, s60
	s_addc_u32 s23, s23, 0
	global_load_dwordx4 v[112:115], v0, s[24:25]
	global_load_dwordx4 v[116:119], v0, s[24:25] offset:1024
	global_load_dwordx4 v[120:123], v0, s[24:25] offset:2048
	global_load_dwordx4 v[124:127], v0, s[24:25] offset:3072
	global_load_dwordx4 v[162:165], v0, s[34:35]
	global_load_dwordx4 v[166:169], v0, s[34:35] offset:1024
	global_load_dwordx4 v[170:173], v0, s[34:35] offset:2048
	global_load_dwordx4 v[174:177], v0, s[34:35] offset:3072
	global_load_dwordx4 v[178:181], v0, s[18:19]
	global_load_dwordx4 v[182:185], v0, s[18:19] offset:1024
	global_load_dwordx4 v[186:189], v0, s[18:19] offset:2048
	global_load_dwordx4 v[190:193], v0, s[18:19] offset:3072
	s_add_i32 s62, s58, s2
	s_add_i32 s62, s62, s2
	s_cmp_lt_i32 s62, s36
	s_cbranch_scc0 .Lrr11_tail2
	s_lshl_b32 s59, s62, 11
	s_add_u32 s20, s44, s59
	s_addc_u32 s21, s45, 0
	s_sub_u32 s60, s62, 0x8000
	s_cmp_lt_u32 s62, 0x8000
	s_cselect_b32 s60, s62, s60
	s_cselect_b32 s12, s82, s80
	s_cselect_b32 s13, s83, s81
	s_lshl_b32 s60, s60, 12
	s_add_u32 s12, s12, s60
	s_addc_u32 s13, s13, 0
	global_load_dwordx2 v[10:11], v202, s[20:21]
	global_load_dwordx2 v[12:13], v202, s[20:21] offset:512
	global_load_dwordx2 v[14:15], v202, s[20:21] offset:1024
	global_load_dwordx2 v[16:17], v202, s[20:21] offset:1536
	global_load_dwordx4 v[48:51], v0, s[12:13]
	global_load_dwordx4 v[52:55], v0, s[12:13] offset:1024
	global_load_dwordx4 v[56:59], v0, s[12:13] offset:2048
	global_load_dwordx4 v[60:63], v0, s[12:13] offset:3072
	s_waitcnt vmcnt(56)
; DI void rows_resid_norm(const P& p, const float* xlat, const float* xctx, const h16* y, int l, int gate_idx, const float* post_g,
;                         bool do_next, int l2, const float* gain2, int sh_idx, int sc_idx, h16* dst, int nrows) {
;     ...
; #pragma unroll
;     for (int i = 0; i < 4; ++i) {
;       h16x4 t = *(const h16x4*)(y + (size_t)row * 1024 + lane * 4 + 256 * i);
;       yv[i].x = (float)t.x; yv[i].y = (float)t.y; yv[i].z = (float)t.z; yv[i].w = (float)t.w;
;       ss += yv[i].x * yv[i].x + yv[i].y * yv[i].y + yv[i].z * yv[i].z + yv[i].w * yv[i].w;
;       xv[i] = *(const f32x4*)(xr + lane * 4 + 256 * i);
;     }
;     ss = wave_sum(ss);
;     const float rstd = rsqrtf(ss * (1.f / 1024.f) + EPS);
;     float s2 = 0.f;
; #pragma unroll
;     for (int i = 0; i < 4; ++i) {
;       const int c = lane * 4 + 256 * i;
;       f32x4 g = *(const f32x4*)(post_g + c), gt = *(const f32x4*)(mr + gate_idx * 1024 + c);
;       xv[i].x += gt.x * (yv[i].x * rstd * g.x);
;       xv[i].y += gt.y * (yv[i].y * rstd * g.y);
;       xv[i].z += gt.z * (yv[i].z * rstd * g.z);
;       xv[i].w += gt.w * (yv[i].w * rstd * g.w);
;       *(f32x4*)(xo + c) = xv[i];
;       s2 += xv[i].x * xv[i].x + xv[i].y * xv[i].y + xv[i].z * xv[i].z + xv[i].w * xv[i].w;
;     }
;     if (do_next) {
;       s2 = wave_sum(s2);
;       const float r2 = rsqrtf(s2 * (1.f / 1024.f) + EPS);
	v_cvt_f32_f16_e32 v226, v18
	v_cvt_f32_f16_sdwa v227, v18 dst_sel:DWORD dst_unused:UNUSED_PAD src0_sel:WORD_1
	v_cvt_f32_f16_e32 v228, v19
	v_cvt_f32_f16_sdwa v229, v19 dst_sel:DWORD dst_unused:UNUSED_PAD src0_sel:WORD_1
	v_cvt_f32_f16_e32 v230, v20
	v_cvt_f32_f16_sdwa v231, v20 dst_sel:DWORD dst_unused:UNUSED_PAD src0_sel:WORD_1
	v_cvt_f32_f16_e32 v232, v21
	v_cvt_f32_f16_sdwa v233, v21 dst_sel:DWORD dst_unused:UNUSED_PAD src0_sel:WORD_1
	v_cvt_f32_f16_e32 v234, v22
	v_cvt_f32_f16_sdwa v235, v22 dst_sel:DWORD dst_unused:UNUSED_PAD src0_sel:WORD_1
	v_cvt_f32_f16_e32 v236, v23
	v_cvt_f32_f16_sdwa v237, v23 dst_sel:DWORD dst_unused:UNUSED_PAD src0_sel:WORD_1
	v_cvt_f32_f16_e32 v238, v24
	v_cvt_f32_f16_sdwa v239, v24 dst_sel:DWORD dst_unused:UNUSED_PAD src0_sel:WORD_1
	v_cvt_f32_f16_e32 v240, v25
	v_cvt_f32_f16_sdwa v241, v25 dst_sel:DWORD dst_unused:UNUSED_PAD src0_sel:WORD_1
	v_mul_f32_e32 v242, v227, v227
	v_mul_f32_e32 v243, v231, v231
	v_mul_f32_e32 v244, v235, v235
	v_mul_f32_e32 v245, v239, v239
	v_fmac_f32_e32 v242, v226, v226
	v_fmac_f32_e32 v243, v230, v230
	v_fmac_f32_e32 v244, v234, v234
	v_fmac_f32_e32 v245, v238, v238
	v_fmac_f32_e32 v242, v228, v228
	v_fmac_f32_e32 v243, v232, v232
	v_fmac_f32_e32 v244, v236, v236
	v_fmac_f32_e32 v245, v240, v240
	v_fmac_f32_e32 v242, v229, v229
	v_fmac_f32_e32 v243, v233, v233
	v_fmac_f32_e32 v244, v237, v237
	v_fmac_f32_e32 v245, v241, v241
	v_add_f32_e32 v242, v242, v243
	v_add_f32_e32 v242, v242, v244
	v_add_f32_e32 v242, v242, v245
	s_nop 1
	v_add_f32_dpp v242, v242, v242 quad_perm:[1,0,3,2] row_mask:0xf bank_mask:0xf bound_ctrl:1
	s_nop 1
	v_add_f32_dpp v242, v242, v242 quad_perm:[2,3,0,1] row_mask:0xf bank_mask:0xf bound_ctrl:1
	s_nop 1
	v_add_f32_dpp v242, v242, v242 row_half_mirror row_mask:0xf bank_mask:0xf bound_ctrl:1
	s_nop 1
	v_add_f32_dpp v242, v242, v242 row_mirror row_mask:0xf bank_mask:0xf bound_ctrl:1
	s_nop 1
	ds_swizzle_b32 v243, v242 offset:swizzle(SWAP,16)
	s_waitcnt lgkmcnt(0)
	v_add_f32_e32 v242, v242, v243
	v_mov_b32_e32 v243, v242
	s_nop 1
	v_permlane32_swap_b32_e32 v242, v243
	v_add_f32_e32 v242, v242, v243
	v_fmamk_f32 v242, v242, 0x3a800000, v224
	v_rsq_f32_e32 v242, v242
	s_waitcnt vmcnt(8)
	v_mul_f32_e32 v226, v226, v242
	v_mul_f32_e32 v227, v227, v242
	v_mul_f32_e32 v228, v228, v242
	v_mul_f32_e32 v229, v229, v242
	v_mul_f32_e32 v230, v230, v242
	v_mul_f32_e32 v231, v231, v242
	v_mul_f32_e32 v232, v232, v242
	v_mul_f32_e32 v233, v233, v242
	v_mul_f32_e32 v234, v234, v242
	v_mul_f32_e32 v235, v235, v242
	v_mul_f32_e32 v236, v236, v242
	v_mul_f32_e32 v237, v237, v242
	v_mul_f32_e32 v238, v238, v242
	v_mul_f32_e32 v239, v239, v242
	v_mul_f32_e32 v240, v240, v242
	v_mul_f32_e32 v241, v241, v242
	v_mul_f32_e32 v226, v80, v226
	v_mul_f32_e32 v227, v81, v227
	v_mul_f32_e32 v228, v82, v228
	v_mul_f32_e32 v229, v83, v229
	v_mul_f32_e32 v230, v84, v230
	v_mul_f32_e32 v231, v85, v231
	v_mul_f32_e32 v232, v86, v232
	v_mul_f32_e32 v233, v87, v233
	v_mul_f32_e32 v234, v88, v234
	v_mul_f32_e32 v235, v89, v235
	v_mul_f32_e32 v236, v90, v236
	v_mul_f32_e32 v237, v91, v237
	v_mul_f32_e32 v238, v92, v238
	v_mul_f32_e32 v239, v93, v239
	v_mul_f32_e32 v240, v94, v240
	v_mul_f32_e32 v241, v95, v241
	v_fmac_f32_e32 v64, v112, v226
	v_fmac_f32_e32 v65, v113, v227
	v_fmac_f32_e32 v66, v114, v228
	v_fmac_f32_e32 v67, v115, v229
	v_fmac_f32_e32 v68, v116, v230
	v_fmac_f32_e32 v69, v117, v231
	v_fmac_f32_e32 v70, v118, v232
	v_fmac_f32_e32 v71, v119, v233
	v_fmac_f32_e32 v72, v120, v234
	v_fmac_f32_e32 v73, v121, v235
	v_fmac_f32_e32 v74, v122, v236
	v_fmac_f32_e32 v75, v123, v237
	v_fmac_f32_e32 v76, v124, v238
	v_fmac_f32_e32 v77, v125, v239
	v_fmac_f32_e32 v78, v126, v240
	v_fmac_f32_e32 v79, v127, v241
	global_store_dwordx4 v0, v[64:67], s[22:23]
	global_store_dwordx4 v0, v[68:71], s[22:23] offset:1024
	global_store_dwordx4 v0, v[72:75], s[22:23] offset:2048
	global_store_dwordx4 v0, v[76:79], s[22:23] offset:3072
	v_mul_f32_e32 v242, v65, v65
	v_mul_f32_e32 v243, v69, v69
	v_mul_f32_e32 v244, v73, v73
	v_mul_f32_e32 v245, v77, v77
	v_fmac_f32_e32 v242, v64, v64
	v_fmac_f32_e32 v243, v68, v68
	v_fmac_f32_e32 v244, v72, v72
	v_fmac_f32_e32 v245, v76, v76
	v_fmac_f32_e32 v242, v66, v66
	v_fmac_f32_e32 v243, v70, v70
	v_fmac_f32_e32 v244, v74, v74
	v_fmac_f32_e32 v245, v78, v78
	v_fmac_f32_e32 v242, v67, v67
	v_fmac_f32_e32 v243, v71, v71
	v_fmac_f32_e32 v244, v75, v75
	v_fmac_f32_e32 v245, v79, v79
	v_add_f32_e32 v242, v242, v243
	v_add_f32_e32 v242, v242, v244
	v_add_f32_e32 v242, v242, v245
	s_nop 1
	v_add_f32_dpp v242, v242, v242 quad_perm:[1,0,3,2] row_mask:0xf bank_mask:0xf bound_ctrl:1
	s_nop 1
	v_add_f32_dpp v242, v242, v242 quad_perm:[2,3,0,1] row_mask:0xf bank_mask:0xf bound_ctrl:1
	s_nop 1
	v_add_f32_dpp v242, v242, v242 row_half_mirror row_mask:0xf bank_mask:0xf bound_ctrl:1
	s_nop 1
	v_add_f32_dpp v242, v242, v242 row_mirror row_mask:0xf bank_mask:0xf bound_ctrl:1
	s_nop 1
	ds_swizzle_b32 v243, v242 offset:swizzle(SWAP,16)
	s_waitcnt lgkmcnt(0)
; DI void rows_resid_norm(const P& p, const float* xlat, const float* xctx, const h16* y, int l, int gate_idx, const float* post_g,
;                         bool do_next, int l2, const float* gain2, int sh_idx, int sc_idx, h16* dst, int nrows) {
;     ...
;   for (int row = gw; row < nrows; row += nw) {
;     const float* xr = row < TL ? xlat + (size_t)row * 1024 : xctx + (size_t)(row - TL) * 1024;
;     float* xo = row < TL ? p.out + (size_t)row * 1024 : xc + (size_t)(row - TL) * 1024;
;     const int mrow = row < TL ? (row >> 12) : 8;
;     const float* mr = mod + ((size_t)l * 9 + mrow) * 6144;
;     const float* mr2 = mod + ((size_t)l2 * 9 + mrow) * 6144;
;     f32x4 yv[4], xv[4];
;     float ss = 0.f;
; #pragma unroll
;     for (int i = 0; i < 4; ++i) {
;       h16x4 t = *(const h16x4*)(y + (size_t)row * 1024 + lane * 4 + 256 * i);
;       yv[i].x = (float)t.x; yv[i].y = (float)t.y; yv[i].z = (float)t.z; yv[i].w = (float)t.w;
;       ss += yv[i].x * yv[i].x + yv[i].y * yv[i].y + yv[i].z * yv[i].z + yv[i].w * yv[i].w;
;       xv[i] = *(const f32x4*)(xr + lane * 4 + 256 * i);
;     }
;     ...
;     if (do_next) {
;       s2 = wave_sum(s2);
;       const float r2 = rsqrtf(s2 * (1.f / 1024.f) + EPS);
; #pragma unroll
;       for (int i = 0; i < 4; ++i) {
;         const int c = lane * 4 + 256 * i;
;         f32x4 g = *(const f32x4*)(gain2 + c), sc = *(const f32x4*)(mr2 + sc_idx * 1024 + c), sh = *(const f32x4*)(mr2 + sh_idx * 1024 + c);
;         h16x4 o;
;         o.x = (h16)(xv[i].x * r2 * g.x * (1.f + sc.x) + sh.x);
;         o.y = (h16)(xv[i].y * r2 * g.y * (1.f + sc.y) + sh.y);
;         o.z = (h16)(xv[i].z * r2 * g.z * (1.f + sc.z) + sh.z);
;         o.w = (h16)(xv[i].w * r2 * g.w * (1.f + sc.w) + sh.w);
;         *(h16x4*)(dst + (size_t)row * 1024 + c) = o;
;       }
;     }
	v_add_f32_e32 v242, v242, v243
	v_mov_b32_e32 v243, v242
	s_nop 1
	v_permlane32_swap_b32_e32 v242, v243
	v_add_f32_e32 v242, v242, v243
	v_fmamk_f32 v242, v242, 0x3a800000, v224
	v_rsq_f32_e32 v242, v242
	s_nop 0
	v_mul_f32_e32 v226, v64, v242
	v_mul_f32_e32 v227, v65, v242
	v_mul_f32_e32 v228, v66, v242
	v_mul_f32_e32 v229, v67, v242
	v_mul_f32_e32 v230, v68, v242
	v_mul_f32_e32 v231, v69, v242
	v_mul_f32_e32 v232, v70, v242
	v_mul_f32_e32 v233, v71, v242
	v_mul_f32_e32 v234, v72, v242
	v_mul_f32_e32 v235, v73, v242
	v_mul_f32_e32 v236, v74, v242
	v_mul_f32_e32 v237, v75, v242
	v_mul_f32_e32 v238, v76, v242
	v_mul_f32_e32 v239, v77, v242
	v_mul_f32_e32 v240, v78, v242
	v_mul_f32_e32 v241, v79, v242
	v_mul_f32_e32 v226, v96, v226
	v_mul_f32_e32 v227, v97, v227
	v_mul_f32_e32 v228, v98, v228
	v_mul_f32_e32 v229, v99, v229
	v_mul_f32_e32 v230, v100, v230
	v_mul_f32_e32 v231, v101, v231
	v_mul_f32_e32 v232, v102, v232
	v_mul_f32_e32 v233, v103, v233
	v_mul_f32_e32 v234, v104, v234
	v_mul_f32_e32 v235, v105, v235
	v_mul_f32_e32 v236, v106, v236
	v_mul_f32_e32 v237, v107, v237
	v_mul_f32_e32 v238, v108, v238
	v_mul_f32_e32 v239, v109, v239
	v_mul_f32_e32 v240, v110, v240
	v_mul_f32_e32 v241, v111, v241
	v_add_f32_e32 v162, 1.0, v162
	v_add_f32_e32 v163, 1.0, v163
	v_add_f32_e32 v164, 1.0, v164
	v_add_f32_e32 v165, 1.0, v165
	v_add_f32_e32 v166, 1.0, v166
	v_add_f32_e32 v167, 1.0, v167
	v_add_f32_e32 v168, 1.0, v168
	v_add_f32_e32 v169, 1.0, v169
	v_add_f32_e32 v170, 1.0, v170
	v_add_f32_e32 v171, 1.0, v171
	v_add_f32_e32 v172, 1.0, v172
	v_add_f32_e32 v173, 1.0, v173
	v_add_f32_e32 v174, 1.0, v174
	v_add_f32_e32 v175, 1.0, v175
	v_add_f32_e32 v176, 1.0, v176
	v_add_f32_e32 v177, 1.0, v177
	v_fma_f32 v226, v162, v226, v178
	v_fma_f32 v227, v163, v227, v179
	v_fma_f32 v228, v164, v228, v180
	v_fma_f32 v229, v165, v229, v181
	v_fma_f32 v230, v166, v230, v182
	v_fma_f32 v231, v167, v231, v183
	v_fma_f32 v232, v168, v232, v184
	v_fma_f32 v233, v169, v233, v185
	v_fma_f32 v234, v170, v234, v186
	v_fma_f32 v235, v171, v235, v187
	v_fma_f32 v236, v172, v236, v188
	v_fma_f32 v237, v173, v237, v189
	v_fma_f32 v238, v174, v238, v190
	v_fma_f32 v239, v175, v239, v191
	v_fma_f32 v240, v176, v240, v192
	v_fma_f32 v241, v177, v241, v193
	v_cvt_pk_f16_f32 v244, v226, v227
	v_cvt_pk_f16_f32 v245, v228, v229
	v_cvt_pk_f16_f32 v246, v230, v231
	v_cvt_pk_f16_f32 v247, v232, v233
	v_cvt_pk_f16_f32 v248, v234, v235
	v_cvt_pk_f16_f32 v249, v236, v237
	v_cvt_pk_f16_f32 v250, v238, v239
	v_cvt_pk_f16_f32 v251, v240, v241
	global_store_dwordx2 v202, v[244:245], s[40:41]
	global_store_dwordx2 v202, v[246:247], s[40:41] offset:512
	global_store_dwordx2 v202, v[248:249], s[40:41] offset:1024
	global_store_dwordx2 v202, v[250:251], s[40:41] offset:1536
	s_add_i32 s58, s58, s2
.Lrr11_l0:
	s_lshr_b32 s59, s58, 12
	s_cmp_lt_u32 s58, 0x8000
	s_cselect_b32 s59, s59, 8
	s_mul_i32 s59, s59, 0x6000
	s_add_u32 s24, s42, s59
	s_addc_u32 s25, s43, 0
	s_add_u32 s18, s54, s59
	s_addc_u32 s19, s55, 0
	s_add_u32 s34, s18, 0x4000
	s_addc_u32 s35, s19, 0
	s_add_u32 s18, s18, 0x3000
	s_addc_u32 s19, s19, 0
	s_lshl_b32 s59, s58, 11
	s_add_u32 s40, s56, s59
	s_addc_u32 s41, s57, 0
	s_sub_u32 s60, s58, 0x8000
	s_cmp_lt_u32 s58, 0x8000
	s_cselect_b32 s60, s58, s60
	s_cselect_b32 s22, s46, s50
	s_cselect_b32 s23, s47, s51
	s_lshl_b32 s60, s60, 12
	s_add_u32 s22, s22, s60
	s_addc_u32 s23, s23, 0
	global_load_dwordx4 v[112:115], v0, s[24:25]
	global_load_dwordx4 v[116:119], v0, s[24:25] offset:1024
	global_load_dwordx4 v[120:123], v0, s[24:25] offset:2048
	global_load_dwordx4 v[124:127], v0, s[24:25] offset:3072
	global_load_dwordx4 v[162:165], v0, s[34:35]
	global_load_dwordx4 v[166:169], v0, s[34:35] offset:1024
	global_load_dwordx4 v[170:173], v0, s[34:35] offset:2048
	global_load_dwordx4 v[174:177], v0, s[34:35] offset:3072
	global_load_dwordx4 v[178:181], v0, s[18:19]
	global_load_dwordx4 v[182:185], v0, s[18:19] offset:1024
	global_load_dwordx4 v[186:189], v0, s[18:19] offset:2048
	global_load_dwordx4 v[190:193], v0, s[18:19] offset:3072
	s_add_i32 s62, s58, s2
	s_add_i32 s62, s62, s2
	s_cmp_lt_i32 s62, s36
	s_cbranch_scc0 .Lrr11_tail0
	s_lshl_b32 s59, s62, 11
	s_add_u32 s20, s44, s59
	s_addc_u32 s21, s45, 0
	s_sub_u32 s60, s62, 0x8000
	s_cmp_lt_u32 s62, 0x8000
	s_cselect_b32 s60, s62, s60
	s_cselect_b32 s12, s82, s80
	s_cselect_b32 s13, s83, s81
	s_lshl_b32 s60, s60, 12
	s_add_u32 s12, s12, s60
	s_addc_u32 s13, s13, 0
	global_load_dwordx2 v[18:19], v202, s[20:21]
	global_load_dwordx2 v[20:21], v202, s[20:21] offset:512
	global_load_dwordx2 v[22:23], v202, s[20:21] offset:1024
	global_load_dwordx2 v[24:25], v202, s[20:21] offset:1536
	global_load_dwordx4 v[64:67], v0, s[12:13]
	global_load_dwordx4 v[68:71], v0, s[12:13] offset:1024
	global_load_dwordx4 v[72:75], v0, s[12:13] offset:2048
	global_load_dwordx4 v[76:79], v0, s[12:13] offset:3072
	s_waitcnt vmcnt(56)
; DI void rows_resid_norm(const P& p, const float* xlat, const float* xctx, const h16* y, int l, int gate_idx, const float* post_g,
;                         bool do_next, int l2, const float* gain2, int sh_idx, int sc_idx, h16* dst, int nrows) {
;     ...
; #pragma unroll
;     for (int i = 0; i < 4; ++i) {
;       h16x4 t = *(const h16x4*)(y + (size_t)row * 1024 + lane * 4 + 256 * i);
;       yv[i].x = (float)t.x; yv[i].y = (float)t.y; yv[i].z = (float)t.z; yv[i].w = (float)t.w;
;       ss += yv[i].x * yv[i].x + yv[i].y * yv[i].y + yv[i].z * yv[i].z + yv[i].w * yv[i].w;
;       xv[i] = *(const f32x4*)(xr + lane * 4 + 256 * i);
;     }
;     ss = wave_sum(ss);
;     const float rstd = rsqrtf(ss * (1.f / 1024.f) + EPS);
;     float s2 = 0.f;
; #pragma unroll
;     for (int i = 0; i < 4; ++i) {
;       const int c = lane * 4 + 256 * i;
;       f32x4 g = *(const f32x4*)(post_g + c), gt = *(const f32x4*)(mr + gate_idx * 1024 + c);
;       xv[i].x += gt.x * (yv[i].x * rstd * g.x);
;       xv[i].y += gt.y * (yv[i].y * rstd * g.y);
;       xv[i].z += gt.z * (yv[i].z * rstd * g.z);
;       xv[i].w += gt.w * (yv[i].w * rstd * g.w);
;       *(f32x4*)(xo + c) = xv[i];
;       s2 += xv[i].x * xv[i].x + xv[i].y * xv[i].y + xv[i].z * xv[i].z + xv[i].w * xv[i].w;
;     }
;     if (do_next) {
;       s2 = wave_sum(s2);
;       const float r2 = rsqrtf(s2 * (1.f / 1024.f) + EPS);
	v_cvt_f32_f16_e32 v226, v2
	v_cvt_f32_f16_sdwa v227, v2 dst_sel:DWORD dst_unused:UNUSED_PAD src0_sel:WORD_1
	v_cvt_f32_f16_e32 v228, v3
	v_cvt_f32_f16_sdwa v229, v3 dst_sel:DWORD dst_unused:UNUSED_PAD src0_sel:WORD_1
	v_cvt_f32_f16_e32 v230, v4
	v_cvt_f32_f16_sdwa v231, v4 dst_sel:DWORD dst_unused:UNUSED_PAD src0_sel:WORD_1
	v_cvt_f32_f16_e32 v232, v5
	v_cvt_f32_f16_sdwa v233, v5 dst_sel:DWORD dst_unused:UNUSED_PAD src0_sel:WORD_1
	v_cvt_f32_f16_e32 v234, v6
	v_cvt_f32_f16_sdwa v235, v6 dst_sel:DWORD dst_unused:UNUSED_PAD src0_sel:WORD_1
	v_cvt_f32_f16_e32 v236, v7
	v_cvt_f32_f16_sdwa v237, v7 dst_sel:DWORD dst_unused:UNUSED_PAD src0_sel:WORD_1
	v_cvt_f32_f16_e32 v238, v8
	v_cvt_f32_f16_sdwa v239, v8 dst_sel:DWORD dst_unused:UNUSED_PAD src0_sel:WORD_1
	v_cvt_f32_f16_e32 v240, v9
	v_cvt_f32_f16_sdwa v241, v9 dst_sel:DWORD dst_unused:UNUSED_PAD src0_sel:WORD_1
	v_mul_f32_e32 v242, v227, v227
	v_mul_f32_e32 v243, v231, v231
	v_mul_f32_e32 v244, v235, v235
	v_mul_f32_e32 v245, v239, v239
	v_fmac_f32_e32 v242, v226, v226
	v_fmac_f32_e32 v243, v230, v230
	v_fmac_f32_e32 v244, v234, v234
	v_fmac_f32_e32 v245, v238, v238
	v_fmac_f32_e32 v242, v228, v228
	v_fmac_f32_e32 v243, v232, v232
	v_fmac_f32_e32 v244, v236, v236
	v_fmac_f32_e32 v245, v240, v240
	v_fmac_f32_e32 v242, v229, v229
	v_fmac_f32_e32 v243, v233, v233
	v_fmac_f32_e32 v244, v237, v237
	v_fmac_f32_e32 v245, v241, v241
	v_add_f32_e32 v242, v242, v243
	v_add_f32_e32 v242, v242, v244
	v_add_f32_e32 v242, v242, v245
	s_nop 1
	v_add_f32_dpp v242, v242, v242 quad_perm:[1,0,3,2] row_mask:0xf bank_mask:0xf bound_ctrl:1
	s_nop 1
	v_add_f32_dpp v242, v242, v242 quad_perm:[2,3,0,1] row_mask:0xf bank_mask:0xf bound_ctrl:1
	s_nop 1
	v_add_f32_dpp v242, v242, v242 row_half_mirror row_mask:0xf bank_mask:0xf bound_ctrl:1
	s_nop 1
	v_add_f32_dpp v242, v242, v242 row_mirror row_mask:0xf bank_mask:0xf bound_ctrl:1
	s_nop 1
	ds_swizzle_b32 v243, v242 offset:swizzle(SWAP,16)
	s_waitcnt lgkmcnt(0)
	v_add_f32_e32 v242, v242, v243
	v_mov_b32_e32 v243, v242
	s_nop 1
	v_permlane32_swap_b32_e32 v242, v243
	v_add_f32_e32 v242, v242, v243
	v_fmamk_f32 v242, v242, 0x3a800000, v224
	v_rsq_f32_e32 v242, v242
	s_waitcnt vmcnt(8)
	v_mul_f32_e32 v226, v226, v242
	v_mul_f32_e32 v227, v227, v242
	v_mul_f32_e32 v228, v228, v242
	v_mul_f32_e32 v229, v229, v242
	v_mul_f32_e32 v230, v230, v242
	v_mul_f32_e32 v231, v231, v242
	v_mul_f32_e32 v232, v232, v242
	v_mul_f32_e32 v233, v233, v242
	v_mul_f32_e32 v234, v234, v242
	v_mul_f32_e32 v235, v235, v242
	v_mul_f32_e32 v236, v236, v242
	v_mul_f32_e32 v237, v237, v242
	v_mul_f32_e32 v238, v238, v242
	v_mul_f32_e32 v239, v239, v242
	v_mul_f32_e32 v240, v240, v242
	v_mul_f32_e32 v241, v241, v242
	v_mul_f32_e32 v226, v80, v226
	v_mul_f32_e32 v227, v81, v227
	v_mul_f32_e32 v228, v82, v228
	v_mul_f32_e32 v229, v83, v229
	v_mul_f32_e32 v230, v84, v230
	v_mul_f32_e32 v231, v85, v231
	v_mul_f32_e32 v232, v86, v232
	v_mul_f32_e32 v233, v87, v233
	v_mul_f32_e32 v234, v88, v234
	v_mul_f32_e32 v235, v89, v235
	v_mul_f32_e32 v236, v90, v236
	v_mul_f32_e32 v237, v91, v237
	v_mul_f32_e32 v238, v92, v238
	v_mul_f32_e32 v239, v93, v239
	v_mul_f32_e32 v240, v94, v240
	v_mul_f32_e32 v241, v95, v241
	v_fmac_f32_e32 v32, v112, v226
	v_fmac_f32_e32 v33, v113, v227
	v_fmac_f32_e32 v34, v114, v228
	v_fmac_f32_e32 v35, v115, v229
	v_fmac_f32_e32 v36, v116, v230
	v_fmac_f32_e32 v37, v117, v231
	v_fmac_f32_e32 v38, v118, v232
	v_fmac_f32_e32 v39, v119, v233
	v_fmac_f32_e32 v40, v120, v234
	v_fmac_f32_e32 v41, v121, v235
	v_fmac_f32_e32 v42, v122, v236
	v_fmac_f32_e32 v43, v123, v237
	v_fmac_f32_e32 v44, v124, v238
	v_fmac_f32_e32 v45, v125, v239
	v_fmac_f32_e32 v46, v126, v240
	v_fmac_f32_e32 v47, v127, v241
	global_store_dwordx4 v0, v[32:35], s[22:23]
	global_store_dwordx4 v0, v[36:39], s[22:23] offset:1024
	global_store_dwordx4 v0, v[40:43], s[22:23] offset:2048
	global_store_dwordx4 v0, v[44:47], s[22:23] offset:3072
	v_mul_f32_e32 v242, v33, v33
	v_mul_f32_e32 v243, v37, v37
	v_mul_f32_e32 v244, v41, v41
	v_mul_f32_e32 v245, v45, v45
	v_fmac_f32_e32 v242, v32, v32
	v_fmac_f32_e32 v243, v36, v36
	v_fmac_f32_e32 v244, v40, v40
	v_fmac_f32_e32 v245, v44, v44
	v_fmac_f32_e32 v242, v34, v34
	v_fmac_f32_e32 v243, v38, v38
	v_fmac_f32_e32 v244, v42, v42
	v_fmac_f32_e32 v245, v46, v46
	v_fmac_f32_e32 v242, v35, v35
	v_fmac_f32_e32 v243, v39, v39
	v_fmac_f32_e32 v244, v43, v43
	v_fmac_f32_e32 v245, v47, v47
	v_add_f32_e32 v242, v242, v243
	v_add_f32_e32 v242, v242, v244
	v_add_f32_e32 v242, v242, v245
	s_nop 1
	v_add_f32_dpp v242, v242, v242 quad_perm:[1,0,3,2] row_mask:0xf bank_mask:0xf bound_ctrl:1
	s_nop 1
	v_add_f32_dpp v242, v242, v242 quad_perm:[2,3,0,1] row_mask:0xf bank_mask:0xf bound_ctrl:1
	s_nop 1
	v_add_f32_dpp v242, v242, v242 row_half_mirror row_mask:0xf bank_mask:0xf bound_ctrl:1
	s_nop 1
	v_add_f32_dpp v242, v242, v242 row_mirror row_mask:0xf bank_mask:0xf bound_ctrl:1
	s_nop 1
	ds_swizzle_b32 v243, v242 offset:swizzle(SWAP,16)
	s_waitcnt lgkmcnt(0)
; DI void rows_resid_norm(const P& p, const float* xlat, const float* xctx, const h16* y, int l, int gate_idx, const float* post_g,
;                         bool do_next, int l2, const float* gain2, int sh_idx, int sc_idx, h16* dst, int nrows) {
;     ...
;   for (int row = gw; row < nrows; row += nw) {
;     const float* xr = row < TL ? xlat + (size_t)row * 1024 : xctx + (size_t)(row - TL) * 1024;
;     float* xo = row < TL ? p.out + (size_t)row * 1024 : xc + (size_t)(row - TL) * 1024;
;     const int mrow = row < TL ? (row >> 12) : 8;
;     const float* mr = mod + ((size_t)l * 9 + mrow) * 6144;
;     const float* mr2 = mod + ((size_t)l2 * 9 + mrow) * 6144;
;     f32x4 yv[4], xv[4];
;     float ss = 0.f;
; #pragma unroll
;     for (int i = 0; i < 4; ++i) {
;       h16x4 t = *(const h16x4*)(y + (size_t)row * 1024 + lane * 4 + 256 * i);
;       yv[i].x = (float)t.x; yv[i].y = (float)t.y; yv[i].z = (float)t.z; yv[i].w = (float)t.w;
;       ss += yv[i].x * yv[i].x + yv[i].y * yv[i].y + yv[i].z * yv[i].z + yv[i].w * yv[i].w;
;       xv[i] = *(const f32x4*)(xr + lane * 4 + 256 * i);
;     }
;     ...
;     if (do_next) {
;       s2 = wave_sum(s2);
;       const float r2 = rsqrtf(s2 * (1.f / 1024.f) + EPS);
; #pragma unroll
;       for (int i = 0; i < 4; ++i) {
;         const int c = lane * 4 + 256 * i;
;         f32x4 g = *(const f32x4*)(gain2 + c), sc = *(const f32x4*)(mr2 + sc_idx * 1024 + c), sh = *(const f32x4*)(mr2 + sh_idx * 1024 + c);
;         h16x4 o;
;         o.x = (h16)(xv[i].x * r2 * g.x * (1.f + sc.x) + sh.x);
;         o.y = (h16)(xv[i].y * r2 * g.y * (1.f + sc.y) + sh.y);
;         o.z = (h16)(xv[i].z * r2 * g.z * (1.f + sc.z) + sh.z);
;         o.w = (h16)(xv[i].w * r2 * g.w * (1.f + sc.w) + sh.w);
;         *(h16x4*)(dst + (size_t)row * 1024 + c) = o;
;       }
;     }
	v_add_f32_e32 v242, v242, v243
	v_mov_b32_e32 v243, v242
	s_nop 1
	v_permlane32_swap_b32_e32 v242, v243
	v_add_f32_e32 v242, v242, v243
	v_fmamk_f32 v242, v242, 0x3a800000, v224
	v_rsq_f32_e32 v242, v242
	s_nop 0
	v_mul_f32_e32 v226, v32, v242
	v_mul_f32_e32 v227, v33, v242
	v_mul_f32_e32 v228, v34, v242
	v_mul_f32_e32 v229, v35, v242
	v_mul_f32_e32 v230, v36, v242
	v_mul_f32_e32 v231, v37, v242
	v_mul_f32_e32 v232, v38, v242
	v_mul_f32_e32 v233, v39, v242
	v_mul_f32_e32 v234, v40, v242
	v_mul_f32_e32 v235, v41, v242
	v_mul_f32_e32 v236, v42, v242
	v_mul_f32_e32 v237, v43, v242
	v_mul_f32_e32 v238, v44, v242
	v_mul_f32_e32 v239, v45, v242
	v_mul_f32_e32 v240, v46, v242
	v_mul_f32_e32 v241, v47, v242
	v_mul_f32_e32 v226, v96, v226
	v_mul_f32_e32 v227, v97, v227
	v_mul_f32_e32 v228, v98, v228
	v_mul_f32_e32 v229, v99, v229
	v_mul_f32_e32 v230, v100, v230
	v_mul_f32_e32 v231, v101, v231
	v_mul_f32_e32 v232, v102, v232
	v_mul_f32_e32 v233, v103, v233
	v_mul_f32_e32 v234, v104, v234
	v_mul_f32_e32 v235, v105, v235
	v_mul_f32_e32 v236, v106, v236
	v_mul_f32_e32 v237, v107, v237
	v_mul_f32_e32 v238, v108, v238
	v_mul_f32_e32 v239, v109, v239
	v_mul_f32_e32 v240, v110, v240
	v_mul_f32_e32 v241, v111, v241
	v_add_f32_e32 v162, 1.0, v162
	v_add_f32_e32 v163, 1.0, v163
	v_add_f32_e32 v164, 1.0, v164
	v_add_f32_e32 v165, 1.0, v165
	v_add_f32_e32 v166, 1.0, v166
	v_add_f32_e32 v167, 1.0, v167
	v_add_f32_e32 v168, 1.0, v168
	v_add_f32_e32 v169, 1.0, v169
	v_add_f32_e32 v170, 1.0, v170
	v_add_f32_e32 v171, 1.0, v171
	v_add_f32_e32 v172, 1.0, v172
	v_add_f32_e32 v173, 1.0, v173
	v_add_f32_e32 v174, 1.0, v174
	v_add_f32_e32 v175, 1.0, v175
	v_add_f32_e32 v176, 1.0, v176
	v_add_f32_e32 v177, 1.0, v177
	v_fma_f32 v226, v162, v226, v178
	v_fma_f32 v227, v163, v227, v179
	v_fma_f32 v228, v164, v228, v180
	v_fma_f32 v229, v165, v229, v181
	v_fma_f32 v230, v166, v230, v182
	v_fma_f32 v231, v167, v231, v183
	v_fma_f32 v232, v168, v232, v184
	v_fma_f32 v233, v169, v233, v185
	v_fma_f32 v234, v170, v234, v186
	v_fma_f32 v235, v171, v235, v187
	v_fma_f32 v236, v172, v236, v188
	v_fma_f32 v237, v173, v237, v189
	v_fma_f32 v238, v174, v238, v190
	v_fma_f32 v239, v175, v239, v191
	v_fma_f32 v240, v176, v240, v192
	v_fma_f32 v241, v177, v241, v193
	v_cvt_pk_f16_f32 v244, v226, v227
	v_cvt_pk_f16_f32 v245, v228, v229
	v_cvt_pk_f16_f32 v246, v230, v231
	v_cvt_pk_f16_f32 v247, v232, v233
	v_cvt_pk_f16_f32 v248, v234, v235
	v_cvt_pk_f16_f32 v249, v236, v237
	v_cvt_pk_f16_f32 v250, v238, v239
	v_cvt_pk_f16_f32 v251, v240, v241
	global_store_dwordx2 v202, v[244:245], s[40:41]
	global_store_dwordx2 v202, v[246:247], s[40:41] offset:512
	global_store_dwordx2 v202, v[248:249], s[40:41] offset:1024
	global_store_dwordx2 v202, v[250:251], s[40:41] offset:1536
	s_add_i32 s58, s58, s2
.Lrr11_l1:
	s_lshr_b32 s59, s58, 12
	s_cmp_lt_u32 s58, 0x8000
	s_cselect_b32 s59, s59, 8
	s_mul_i32 s59, s59, 0x6000
	s_add_u32 s24, s42, s59
	s_addc_u32 s25, s43, 0
	s_add_u32 s18, s54, s59
	s_addc_u32 s19, s55, 0
	s_add_u32 s34, s18, 0x4000
	s_addc_u32 s35, s19, 0
	s_add_u32 s18, s18, 0x3000
	s_addc_u32 s19, s19, 0
	s_lshl_b32 s59, s58, 11
	s_add_u32 s40, s56, s59
	s_addc_u32 s41, s57, 0
	s_sub_u32 s60, s58, 0x8000
	s_cmp_lt_u32 s58, 0x8000
	s_cselect_b32 s60, s58, s60
	s_cselect_b32 s22, s46, s50
	s_cselect_b32 s23, s47, s51
	s_lshl_b32 s60, s60, 12
	s_add_u32 s22, s22, s60
	s_addc_u32 s23, s23, 0
	global_load_dwordx4 v[112:115], v0, s[24:25]
	global_load_dwordx4 v[116:119], v0, s[24:25] offset:1024
	global_load_dwordx4 v[120:123], v0, s[24:25] offset:2048
	global_load_dwordx4 v[124:127], v0, s[24:25] offset:3072
	global_load_dwordx4 v[162:165], v0, s[34:35]
	global_load_dwordx4 v[166:169], v0, s[34:35] offset:1024
	global_load_dwordx4 v[170:173], v0, s[34:35] offset:2048
	global_load_dwordx4 v[174:177], v0, s[34:35] offset:3072
	global_load_dwordx4 v[178:181], v0, s[18:19]
	global_load_dwordx4 v[182:185], v0, s[18:19] offset:1024
	global_load_dwordx4 v[186:189], v0, s[18:19] offset:2048
	global_load_dwordx4 v[190:193], v0, s[18:19] offset:3072
	s_add_i32 s62, s58, s2
	s_add_i32 s62, s62, s2
	s_cmp_lt_i32 s62, s36
	s_cbranch_scc0 .Lrr11_tail1
	s_lshl_b32 s59, s62, 11
	s_add_u32 s20, s44, s59
	s_addc_u32 s21, s45, 0
	s_sub_u32 s60, s62, 0x8000
	s_cmp_lt_u32 s62, 0x8000
	s_cselect_b32 s60, s62, s60
	s_cselect_b32 s12, s82, s80
	s_cselect_b32 s13, s83, s81
	s_lshl_b32 s60, s60, 12
	s_add_u32 s12, s12, s60
	s_addc_u32 s13, s13, 0
	global_load_dwordx2 v[2:3], v202, s[20:21]
	global_load_dwordx2 v[4:5], v202, s[20:21] offset:512
	global_load_dwordx2 v[6:7], v202, s[20:21] offset:1024
	global_load_dwordx2 v[8:9], v202, s[20:21] offset:1536
	global_load_dwordx4 v[32:35], v0, s[12:13]
	global_load_dwordx4 v[36:39], v0, s[12:13] offset:1024
	global_load_dwordx4 v[40:43], v0, s[12:13] offset:2048
	global_load_dwordx4 v[44:47], v0, s[12:13] offset:3072
	s_waitcnt vmcnt(56)
; DI void rows_resid_norm(const P& p, const float* xlat, const float* xctx, const h16* y, int l, int gate_idx, const float* post_g,
;                         bool do_next, int l2, const float* gain2, int sh_idx, int sc_idx, h16* dst, int nrows) {
;     ...
; #pragma unroll
;     for (int i = 0; i < 4; ++i) {
;       h16x4 t = *(const h16x4*)(y + (size_t)row * 1024 + lane * 4 + 256 * i);
;       yv[i].x = (float)t.x; yv[i].y = (float)t.y; yv[i].z = (float)t.z; yv[i].w = (float)t.w;
;       ss += yv[i].x * yv[i].x + yv[i].y * yv[i].y + yv[i].z * yv[i].z + yv[i].w * yv[i].w;
;       xv[i] = *(const f32x4*)(xr + lane * 4 + 256 * i);
;     }
;     ss = wave_sum(ss);
;     const float rstd = rsqrtf(ss * (1.f / 1024.f) + EPS);
;     float s2 = 0.f;
; #pragma unroll
;     for (int i = 0; i < 4; ++i) {
;       const int c = lane * 4 + 256 * i;
;       f32x4 g = *(const f32x4*)(post_g + c), gt = *(const f32x4*)(mr + gate_idx * 1024 + c);
;       xv[i].x += gt.x * (yv[i].x * rstd * g.x);
;       xv[i].y += gt.y * (yv[i].y * rstd * g.y);
;       xv[i].z += gt.z * (yv[i].z * rstd * g.z);
;       xv[i].w += gt.w * (yv[i].w * rstd * g.w);
;       *(f32x4*)(xo + c) = xv[i];
;       s2 += xv[i].x * xv[i].x + xv[i].y * xv[i].y + xv[i].z * xv[i].z + xv[i].w * xv[i].w;
;     }
;     if (do_next) {
;       s2 = wave_sum(s2);
;       const float r2 = rsqrtf(s2 * (1.f / 1024.f) + EPS);
	v_cvt_f32_f16_e32 v226, v10
	v_cvt_f32_f16_sdwa v227, v10 dst_sel:DWORD dst_unused:UNUSED_PAD src0_sel:WORD_1
	v_cvt_f32_f16_e32 v228, v11
	v_cvt_f32_f16_sdwa v229, v11 dst_sel:DWORD dst_unused:UNUSED_PAD src0_sel:WORD_1
	v_cvt_f32_f16_e32 v230, v12
	v_cvt_f32_f16_sdwa v231, v12 dst_sel:DWORD dst_unused:UNUSED_PAD src0_sel:WORD_1
	v_cvt_f32_f16_e32 v232, v13
	v_cvt_f32_f16_sdwa v233, v13 dst_sel:DWORD dst_unused:UNUSED_PAD src0_sel:WORD_1
	v_cvt_f32_f16_e32 v234, v14
	v_cvt_f32_f16_sdwa v235, v14 dst_sel:DWORD dst_unused:UNUSED_PAD src0_sel:WORD_1
	v_cvt_f32_f16_e32 v236, v15
	v_cvt_f32_f16_sdwa v237, v15 dst_sel:DWORD dst_unused:UNUSED_PAD src0_sel:WORD_1
	v_cvt_f32_f16_e32 v238, v16
	v_cvt_f32_f16_sdwa v239, v16 dst_sel:DWORD dst_unused:UNUSED_PAD src0_sel:WORD_1
	v_cvt_f32_f16_e32 v240, v17
	v_cvt_f32_f16_sdwa v241, v17 dst_sel:DWORD dst_unused:UNUSED_PAD src0_sel:WORD_1
	v_mul_f32_e32 v242, v227, v227
	v_mul_f32_e32 v243, v231, v231
	v_mul_f32_e32 v244, v235, v235
	v_mul_f32_e32 v245, v239, v239
	v_fmac_f32_e32 v242, v226, v226
	v_fmac_f32_e32 v243, v230, v230
	v_fmac_f32_e32 v244, v234, v234
	v_fmac_f32_e32 v245, v238, v238
	v_fmac_f32_e32 v242, v228, v228
	v_fmac_f32_e32 v243, v232, v232
	v_fmac_f32_e32 v244, v236, v236
	v_fmac_f32_e32 v245, v240, v240
	v_fmac_f32_e32 v242, v229, v229
	v_fmac_f32_e32 v243, v233, v233
	v_fmac_f32_e32 v244, v237, v237
	v_fmac_f32_e32 v245, v241, v241
	v_add_f32_e32 v242, v242, v243
	v_add_f32_e32 v242, v242, v244
	v_add_f32_e32 v242, v242, v245
	s_nop 1
	v_add_f32_dpp v242, v242, v242 quad_perm:[1,0,3,2] row_mask:0xf bank_mask:0xf bound_ctrl:1
	s_nop 1
	v_add_f32_dpp v242, v242, v242 quad_perm:[2,3,0,1] row_mask:0xf bank_mask:0xf bound_ctrl:1
	s_nop 1
	v_add_f32_dpp v242, v242, v242 row_half_mirror row_mask:0xf bank_mask:0xf bound_ctrl:1
	s_nop 1
	v_add_f32_dpp v242, v242, v242 row_mirror row_mask:0xf bank_mask:0xf bound_ctrl:1
	s_nop 1
	ds_swizzle_b32 v243, v242 offset:swizzle(SWAP,16)
	s_waitcnt lgkmcnt(0)
	v_add_f32_e32 v242, v242, v243
	v_mov_b32_e32 v243, v242
	s_nop 1
	v_permlane32_swap_b32_e32 v242, v243
	v_add_f32_e32 v242, v242, v243
	v_fmamk_f32 v242, v242, 0x3a800000, v224
	v_rsq_f32_e32 v242, v242
	s_waitcnt vmcnt(8)
	v_mul_f32_e32 v226, v226, v242
	v_mul_f32_e32 v227, v227, v242
	v_mul_f32_e32 v228, v228, v242
	v_mul_f32_e32 v229, v229, v242
	v_mul_f32_e32 v230, v230, v242
	v_mul_f32_e32 v231, v231, v242
	v_mul_f32_e32 v232, v232, v242
	v_mul_f32_e32 v233, v233, v242
	v_mul_f32_e32 v234, v234, v242
	v_mul_f32_e32 v235, v235, v242
	v_mul_f32_e32 v236, v236, v242
	v_mul_f32_e32 v237, v237, v242
	v_mul_f32_e32 v238, v238, v242
	v_mul_f32_e32 v239, v239, v242
	v_mul_f32_e32 v240, v240, v242
	v_mul_f32_e32 v241, v241, v242
	v_mul_f32_e32 v226, v80, v226
	v_mul_f32_e32 v227, v81, v227
	v_mul_f32_e32 v228, v82, v228
	v_mul_f32_e32 v229, v83, v229
	v_mul_f32_e32 v230, v84, v230
	v_mul_f32_e32 v231, v85, v231
	v_mul_f32_e32 v232, v86, v232
	v_mul_f32_e32 v233, v87, v233
	v_mul_f32_e32 v234, v88, v234
	v_mul_f32_e32 v235, v89, v235
	v_mul_f32_e32 v236, v90, v236
	v_mul_f32_e32 v237, v91, v237
	v_mul_f32_e32 v238, v92, v238
	v_mul_f32_e32 v239, v93, v239
	v_mul_f32_e32 v240, v94, v240
	v_mul_f32_e32 v241, v95, v241
	v_fmac_f32_e32 v48, v112, v226
	v_fmac_f32_e32 v49, v113, v227
	v_fmac_f32_e32 v50, v114, v228
	v_fmac_f32_e32 v51, v115, v229
	v_fmac_f32_e32 v52, v116, v230
	v_fmac_f32_e32 v53, v117, v231
	v_fmac_f32_e32 v54, v118, v232
	v_fmac_f32_e32 v55, v119, v233
	v_fmac_f32_e32 v56, v120, v234
	v_fmac_f32_e32 v57, v121, v235
	v_fmac_f32_e32 v58, v122, v236
	v_fmac_f32_e32 v59, v123, v237
	v_fmac_f32_e32 v60, v124, v238
	v_fmac_f32_e32 v61, v125, v239
	v_fmac_f32_e32 v62, v126, v240
	v_fmac_f32_e32 v63, v127, v241
	global_store_dwordx4 v0, v[48:51], s[22:23]
	global_store_dwordx4 v0, v[52:55], s[22:23] offset:1024
	global_store_dwordx4 v0, v[56:59], s[22:23] offset:2048
	global_store_dwordx4 v0, v[60:63], s[22:23] offset:3072
	v_mul_f32_e32 v242, v49, v49
	v_mul_f32_e32 v243, v53, v53
	v_mul_f32_e32 v244, v57, v57
	v_mul_f32_e32 v245, v61, v61
	v_fmac_f32_e32 v242, v48, v48
	v_fmac_f32_e32 v243, v52, v52
	v_fmac_f32_e32 v244, v56, v56
	v_fmac_f32_e32 v245, v60, v60
	v_fmac_f32_e32 v242, v50, v50
	v_fmac_f32_e32 v243, v54, v54
	v_fmac_f32_e32 v244, v58, v58
	v_fmac_f32_e32 v245, v62, v62
	v_fmac_f32_e32 v242, v51, v51
	v_fmac_f32_e32 v243, v55, v55
	v_fmac_f32_e32 v244, v59, v59
	v_fmac_f32_e32 v245, v63, v63
	v_add_f32_e32 v242, v242, v243
	v_add_f32_e32 v242, v242, v244
	v_add_f32_e32 v242, v242, v245
	s_nop 1
	v_add_f32_dpp v242, v242, v242 quad_perm:[1,0,3,2] row_mask:0xf bank_mask:0xf bound_ctrl:1
	s_nop 1
	v_add_f32_dpp v242, v242, v242 quad_perm:[2,3,0,1] row_mask:0xf bank_mask:0xf bound_ctrl:1
	s_nop 1
	v_add_f32_dpp v242, v242, v242 row_half_mirror row_mask:0xf bank_mask:0xf bound_ctrl:1
	s_nop 1
	v_add_f32_dpp v242, v242, v242 row_mirror row_mask:0xf bank_mask:0xf bound_ctrl:1
	s_nop 1
	ds_swizzle_b32 v243, v242 offset:swizzle(SWAP,16)
	s_waitcnt lgkmcnt(0)
; DI void rows_resid_norm(const P& p, const float* xlat, const float* xctx, const h16* y, int l, int gate_idx, const float* post_g,
;                         bool do_next, int l2, const float* gain2, int sh_idx, int sc_idx, h16* dst, int nrows) {
;     ...
; #pragma unroll
;     for (int i = 0; i < 4; ++i) {
;       h16x4 t = *(const h16x4*)(y + (size_t)row * 1024 + lane * 4 + 256 * i);
;       yv[i].x = (float)t.x; yv[i].y = (float)t.y; yv[i].z = (float)t.z; yv[i].w = (float)t.w;
;       ss += yv[i].x * yv[i].x + yv[i].y * yv[i].y + yv[i].z * yv[i].z + yv[i].w * yv[i].w;
;       xv[i] = *(const f32x4*)(xr + lane * 4 + 256 * i);
;     }
;     ss = wave_sum(ss);
;     const float rstd = rsqrtf(ss * (1.f / 1024.f) + EPS);
;     float s2 = 0.f;
; #pragma unroll
;     for (int i = 0; i < 4; ++i) {
;       const int c = lane * 4 + 256 * i;
;       f32x4 g = *(const f32x4*)(post_g + c), gt = *(const f32x4*)(mr + gate_idx * 1024 + c);
;       xv[i].x += gt.x * (yv[i].x * rstd * g.x);
;       xv[i].y += gt.y * (yv[i].y * rstd * g.y);
;       xv[i].z += gt.z * (yv[i].z * rstd * g.z);
;       xv[i].w += gt.w * (yv[i].w * rstd * g.w);
;       *(f32x4*)(xo + c) = xv[i];
;       s2 += xv[i].x * xv[i].x + xv[i].y * xv[i].y + xv[i].z * xv[i].z + xv[i].w * xv[i].w;
;     }
;     if (do_next) {
;       s2 = wave_sum(s2);
;       const float r2 = rsqrtf(s2 * (1.f / 1024.f) + EPS);
; #pragma unroll
;       for (int i = 0; i < 4; ++i) {
;         const int c = lane * 4 + 256 * i;
;         f32x4 g = *(const f32x4*)(gain2 + c), sc = *(const f32x4*)(mr2 + sc_idx * 1024 + c), sh = *(const f32x4*)(mr2 + sh_idx * 1024 + c);
;         h16x4 o;
;         o.x = (h16)(xv[i].x * r2 * g.x * (1.f + sc.x) + sh.x);
;         o.y = (h16)(xv[i].y * r2 * g.y * (1.f + sc.y) + sh.y);
;         o.z = (h16)(xv[i].z * r2 * g.z * (1.f + sc.z) + sh.z);
;         o.w = (h16)(xv[i].w * r2 * g.w * (1.f + sc.w) + sh.w);
;         *(h16x4*)(dst + (size_t)row * 1024 + c) = o;
;       }
;     }
	v_add_f32_e32 v242, v242, v243
	v_mov_b32_e32 v243, v242
	s_nop 1
	v_permlane32_swap_b32_e32 v242, v243
	v_add_f32_e32 v242, v242, v243
	v_fmamk_f32 v242, v242, 0x3a800000, v224
	v_rsq_f32_e32 v242, v242
	s_nop 0
	v_mul_f32_e32 v226, v48, v242
	v_mul_f32_e32 v227, v49, v242
	v_mul_f32_e32 v228, v50, v242
	v_mul_f32_e32 v229, v51, v242
	v_mul_f32_e32 v230, v52, v242
	v_mul_f32_e32 v231, v53, v242
	v_mul_f32_e32 v232, v54, v242
	v_mul_f32_e32 v233, v55, v242
	v_mul_f32_e32 v234, v56, v242
	v_mul_f32_e32 v235, v57, v242
	v_mul_f32_e32 v236, v58, v242
	v_mul_f32_e32 v237, v59, v242
	v_mul_f32_e32 v238, v60, v242
	v_mul_f32_e32 v239, v61, v242
	v_mul_f32_e32 v240, v62, v242
	v_mul_f32_e32 v241, v63, v242
	v_mul_f32_e32 v226, v96, v226
	v_mul_f32_e32 v227, v97, v227
	v_mul_f32_e32 v228, v98, v228
	v_mul_f32_e32 v229, v99, v229
	v_mul_f32_e32 v230, v100, v230
	v_mul_f32_e32 v231, v101, v231
	v_mul_f32_e32 v232, v102, v232
	v_mul_f32_e32 v233, v103, v233
	v_mul_f32_e32 v234, v104, v234
	v_mul_f32_e32 v235, v105, v235
	v_mul_f32_e32 v236, v106, v236
	v_mul_f32_e32 v237, v107, v237
	v_mul_f32_e32 v238, v108, v238
	v_mul_f32_e32 v239, v109, v239
	v_mul_f32_e32 v240, v110, v240
	v_mul_f32_e32 v241, v111, v241
	v_add_f32_e32 v162, 1.0, v162
	v_add_f32_e32 v163, 1.0, v163
	v_add_f32_e32 v164, 1.0, v164
	v_add_f32_e32 v165, 1.0, v165
	v_add_f32_e32 v166, 1.0, v166
	v_add_f32_e32 v167, 1.0, v167
	v_add_f32_e32 v168, 1.0, v168
	v_add_f32_e32 v169, 1.0, v169
	v_add_f32_e32 v170, 1.0, v170
	v_add_f32_e32 v171, 1.0, v171
	v_add_f32_e32 v172, 1.0, v172
	v_add_f32_e32 v173, 1.0, v173
	v_add_f32_e32 v174, 1.0, v174
	v_add_f32_e32 v175, 1.0, v175
	v_add_f32_e32 v176, 1.0, v176
	v_add_f32_e32 v177, 1.0, v177
	v_fma_f32 v226, v162, v226, v178
	v_fma_f32 v227, v163, v227, v179
	v_fma_f32 v228, v164, v228, v180
	v_fma_f32 v229, v165, v229, v181
	v_fma_f32 v230, v166, v230, v182
	v_fma_f32 v231, v167, v231, v183
	v_fma_f32 v232, v168, v232, v184
	v_fma_f32 v233, v169, v233, v185
	v_fma_f32 v234, v170, v234, v186
	v_fma_f32 v235, v171, v235, v187
	v_fma_f32 v236, v172, v236, v188
	v_fma_f32 v237, v173, v237, v189
	v_fma_f32 v238, v174, v238, v190
	v_fma_f32 v239, v175, v239, v191
	v_fma_f32 v240, v176, v240, v192
	v_fma_f32 v241, v177, v241, v193
	v_cvt_pk_f16_f32 v244, v226, v227
	v_cvt_pk_f16_f32 v245, v228, v229
	v_cvt_pk_f16_f32 v246, v230, v231
	v_cvt_pk_f16_f32 v247, v232, v233
	v_cvt_pk_f16_f32 v248, v234, v235
	v_cvt_pk_f16_f32 v249, v236, v237
	v_cvt_pk_f16_f32 v250, v238, v239
	v_cvt_pk_f16_f32 v251, v240, v241
	global_store_dwordx2 v202, v[244:245], s[40:41]
	global_store_dwordx2 v202, v[246:247], s[40:41] offset:512
	global_store_dwordx2 v202, v[248:249], s[40:41] offset:1024
	global_store_dwordx2 v202, v[250:251], s[40:41] offset:1536
	s_add_i32 s58, s58, s2
	s_branch .Lrr11_l2
.Lrr11_tail0:
	s_waitcnt vmcnt(12)
	v_cvt_f32_f16_e32 v226, v2
	v_cvt_f32_f16_sdwa v227, v2 dst_sel:DWORD dst_unused:UNUSED_PAD src0_sel:WORD_1
	v_cvt_f32_f16_e32 v228, v3
	v_cvt_f32_f16_sdwa v229, v3 dst_sel:DWORD dst_unused:UNUSED_PAD src0_sel:WORD_1
	v_cvt_f32_f16_e32 v230, v4
	v_cvt_f32_f16_sdwa v231, v4 dst_sel:DWORD dst_unused:UNUSED_PAD src0_sel:WORD_1
	v_cvt_f32_f16_e32 v232, v5
	v_cvt_f32_f16_sdwa v233, v5 dst_sel:DWORD dst_unused:UNUSED_PAD src0_sel:WORD_1
	v_cvt_f32_f16_e32 v234, v6
	v_cvt_f32_f16_sdwa v235, v6 dst_sel:DWORD dst_unused:UNUSED_PAD src0_sel:WORD_1
	v_cvt_f32_f16_e32 v236, v7
	v_cvt_f32_f16_sdwa v237, v7 dst_sel:DWORD dst_unused:UNUSED_PAD src0_sel:WORD_1
	v_cvt_f32_f16_e32 v238, v8
	v_cvt_f32_f16_sdwa v239, v8 dst_sel:DWORD dst_unused:UNUSED_PAD src0_sel:WORD_1
	v_cvt_f32_f16_e32 v240, v9
	v_cvt_f32_f16_sdwa v241, v9 dst_sel:DWORD dst_unused:UNUSED_PAD src0_sel:WORD_1
	v_mul_f32_e32 v242, v227, v227
	v_mul_f32_e32 v243, v231, v231
	v_mul_f32_e32 v244, v235, v235
	v_mul_f32_e32 v245, v239, v239
	v_fmac_f32_e32 v242, v226, v226
	v_fmac_f32_e32 v243, v230, v230
	v_fmac_f32_e32 v244, v234, v234
	v_fmac_f32_e32 v245, v238, v238
	v_fmac_f32_e32 v242, v228, v228
	v_fmac_f32_e32 v243, v232, v232
	v_fmac_f32_e32 v244, v236, v236
	v_fmac_f32_e32 v245, v240, v240
	v_fmac_f32_e32 v242, v229, v229
	v_fmac_f32_e32 v243, v233, v233
	v_fmac_f32_e32 v244, v237, v237
	v_fmac_f32_e32 v245, v241, v241
	v_add_f32_e32 v242, v242, v243
	v_add_f32_e32 v242, v242, v244
	v_add_f32_e32 v242, v242, v245
	s_nop 1
	v_add_f32_dpp v242, v242, v242 quad_perm:[1,0,3,2] row_mask:0xf bank_mask:0xf bound_ctrl:1
	s_nop 1
	v_add_f32_dpp v242, v242, v242 quad_perm:[2,3,0,1] row_mask:0xf bank_mask:0xf bound_ctrl:1
	s_nop 1
	v_add_f32_dpp v242, v242, v242 row_half_mirror row_mask:0xf bank_mask:0xf bound_ctrl:1
	s_nop 1
	v_add_f32_dpp v242, v242, v242 row_mirror row_mask:0xf bank_mask:0xf bound_ctrl:1
	s_nop 1
	ds_swizzle_b32 v243, v242 offset:swizzle(SWAP,16)
	s_waitcnt lgkmcnt(0)
	v_add_f32_e32 v242, v242, v243
	v_mov_b32_e32 v243, v242
	s_nop 1
	v_permlane32_swap_b32_e32 v242, v243
	v_add_f32_e32 v242, v242, v243
	v_fmamk_f32 v242, v242, 0x3a800000, v224
	v_rsq_f32_e32 v242, v242
	s_waitcnt vmcnt(0)
; DI void rows_resid_norm(const P& p, const float* xlat, const float* xctx, const h16* y, int l, int gate_idx, const float* post_g,
;                         bool do_next, int l2, const float* gain2, int sh_idx, int sc_idx, h16* dst, int nrows) {
;     ...
;     const float rstd = rsqrtf(ss * (1.f / 1024.f) + EPS);
;     float s2 = 0.f;
; #pragma unroll
;     for (int i = 0; i < 4; ++i) {
;       const int c = lane * 4 + 256 * i;
;       f32x4 g = *(const f32x4*)(post_g + c), gt = *(const f32x4*)(mr + gate_idx * 1024 + c);
;       xv[i].x += gt.x * (yv[i].x * rstd * g.x);
;       xv[i].y += gt.y * (yv[i].y * rstd * g.y);
;       xv[i].z += gt.z * (yv[i].z * rstd * g.z);
;       xv[i].w += gt.w * (yv[i].w * rstd * g.w);
;       *(f32x4*)(xo + c) = xv[i];
;       s2 += xv[i].x * xv[i].x + xv[i].y * xv[i].y + xv[i].z * xv[i].z + xv[i].w * xv[i].w;
;     }
;     if (do_next) {
;       s2 = wave_sum(s2);
;       const float r2 = rsqrtf(s2 * (1.f / 1024.f) + EPS);
; #pragma unroll
;       for (int i = 0; i < 4; ++i) {
;         const int c = lane * 4 + 256 * i;
;         f32x4 g = *(const f32x4*)(gain2 + c), sc = *(const f32x4*)(mr2 + sc_idx * 1024 + c), sh = *(const f32x4*)(mr2 + sh_idx * 1024 + c);
;         h16x4 o;
;         o.x = (h16)(xv[i].x * r2 * g.x * (1.f + sc.x) + sh.x);
;         o.y = (h16)(xv[i].y * r2 * g.y * (1.f + sc.y) + sh.y);
;         o.z = (h16)(xv[i].z * r2 * g.z * (1.f + sc.z) + sh.z);
;         o.w = (h16)(xv[i].w * r2 * g.w * (1.f + sc.w) + sh.w);
;         *(h16x4*)(dst + (size_t)row * 1024 + c) = o;
;       }
;     }
	v_mul_f32_e32 v226, v226, v242
	v_mul_f32_e32 v227, v227, v242
	v_mul_f32_e32 v228, v228, v242
	v_mul_f32_e32 v229, v229, v242
	v_mul_f32_e32 v230, v230, v242
	v_mul_f32_e32 v231, v231, v242
	v_mul_f32_e32 v232, v232, v242
	v_mul_f32_e32 v233, v233, v242
	v_mul_f32_e32 v234, v234, v242
	v_mul_f32_e32 v235, v235, v242
	v_mul_f32_e32 v236, v236, v242
	v_mul_f32_e32 v237, v237, v242
	v_mul_f32_e32 v238, v238, v242
	v_mul_f32_e32 v239, v239, v242
	v_mul_f32_e32 v240, v240, v242
	v_mul_f32_e32 v241, v241, v242
	v_mul_f32_e32 v226, v80, v226
	v_mul_f32_e32 v227, v81, v227
	v_mul_f32_e32 v228, v82, v228
	v_mul_f32_e32 v229, v83, v229
	v_mul_f32_e32 v230, v84, v230
	v_mul_f32_e32 v231, v85, v231
	v_mul_f32_e32 v232, v86, v232
	v_mul_f32_e32 v233, v87, v233
	v_mul_f32_e32 v234, v88, v234
	v_mul_f32_e32 v235, v89, v235
	v_mul_f32_e32 v236, v90, v236
	v_mul_f32_e32 v237, v91, v237
	v_mul_f32_e32 v238, v92, v238
	v_mul_f32_e32 v239, v93, v239
	v_mul_f32_e32 v240, v94, v240
	v_mul_f32_e32 v241, v95, v241
	v_fmac_f32_e32 v32, v112, v226
	v_fmac_f32_e32 v33, v113, v227
	v_fmac_f32_e32 v34, v114, v228
	v_fmac_f32_e32 v35, v115, v229
	v_fmac_f32_e32 v36, v116, v230
	v_fmac_f32_e32 v37, v117, v231
	v_fmac_f32_e32 v38, v118, v232
	v_fmac_f32_e32 v39, v119, v233
	v_fmac_f32_e32 v40, v120, v234
	v_fmac_f32_e32 v41, v121, v235
	v_fmac_f32_e32 v42, v122, v236
	v_fmac_f32_e32 v43, v123, v237
	v_fmac_f32_e32 v44, v124, v238
	v_fmac_f32_e32 v45, v125, v239
	v_fmac_f32_e32 v46, v126, v240
	v_fmac_f32_e32 v47, v127, v241
	global_store_dwordx4 v0, v[32:35], s[22:23]
	global_store_dwordx4 v0, v[36:39], s[22:23] offset:1024
	global_store_dwordx4 v0, v[40:43], s[22:23] offset:2048
	global_store_dwordx4 v0, v[44:47], s[22:23] offset:3072
	v_mul_f32_e32 v242, v33, v33
	v_mul_f32_e32 v243, v37, v37
	v_mul_f32_e32 v244, v41, v41
	v_mul_f32_e32 v245, v45, v45
	v_fmac_f32_e32 v242, v32, v32
	v_fmac_f32_e32 v243, v36, v36
	v_fmac_f32_e32 v244, v40, v40
	v_fmac_f32_e32 v245, v44, v44
	v_fmac_f32_e32 v242, v34, v34
	v_fmac_f32_e32 v243, v38, v38
	v_fmac_f32_e32 v244, v42, v42
	v_fmac_f32_e32 v245, v46, v46
	v_fmac_f32_e32 v242, v35, v35
	v_fmac_f32_e32 v243, v39, v39
	v_fmac_f32_e32 v244, v43, v43
	v_fmac_f32_e32 v245, v47, v47
	v_add_f32_e32 v242, v242, v243
	v_add_f32_e32 v242, v242, v244
	v_add_f32_e32 v242, v242, v245
	s_nop 1
	v_add_f32_dpp v242, v242, v242 quad_perm:[1,0,3,2] row_mask:0xf bank_mask:0xf bound_ctrl:1
	s_nop 1
	v_add_f32_dpp v242, v242, v242 quad_perm:[2,3,0,1] row_mask:0xf bank_mask:0xf bound_ctrl:1
	s_nop 1
	v_add_f32_dpp v242, v242, v242 row_half_mirror row_mask:0xf bank_mask:0xf bound_ctrl:1
	s_nop 1
	v_add_f32_dpp v242, v242, v242 row_mirror row_mask:0xf bank_mask:0xf bound_ctrl:1
	s_nop 1
	ds_swizzle_b32 v243, v242 offset:swizzle(SWAP,16)
	s_waitcnt lgkmcnt(0)
	v_add_f32_e32 v242, v242, v243
	v_mov_b32_e32 v243, v242
	s_nop 1
	v_permlane32_swap_b32_e32 v242, v243
	v_add_f32_e32 v242, v242, v243
	v_fmamk_f32 v242, v242, 0x3a800000, v224
	v_rsq_f32_e32 v242, v242
	s_nop 0
	v_mul_f32_e32 v226, v32, v242
	v_mul_f32_e32 v227, v33, v242
	v_mul_f32_e32 v228, v34, v242
	v_mul_f32_e32 v229, v35, v242
	v_mul_f32_e32 v230, v36, v242
	v_mul_f32_e32 v231, v37, v242
	v_mul_f32_e32 v232, v38, v242
	v_mul_f32_e32 v233, v39, v242
	v_mul_f32_e32 v234, v40, v242
	v_mul_f32_e32 v235, v41, v242
	v_mul_f32_e32 v236, v42, v242
	v_mul_f32_e32 v237, v43, v242
	v_mul_f32_e32 v238, v44, v242
	v_mul_f32_e32 v239, v45, v242
	v_mul_f32_e32 v240, v46, v242
	v_mul_f32_e32 v241, v47, v242
	v_mul_f32_e32 v226, v96, v226
	v_mul_f32_e32 v227, v97, v227
	v_mul_f32_e32 v228, v98, v228
	v_mul_f32_e32 v229, v99, v229
	v_mul_f32_e32 v230, v100, v230
	v_mul_f32_e32 v231, v101, v231
	v_mul_f32_e32 v232, v102, v232
	v_mul_f32_e32 v233, v103, v233
	v_mul_f32_e32 v234, v104, v234
	v_mul_f32_e32 v235, v105, v235
	v_mul_f32_e32 v236, v106, v236
	v_mul_f32_e32 v237, v107, v237
	v_mul_f32_e32 v238, v108, v238
	v_mul_f32_e32 v239, v109, v239
	v_mul_f32_e32 v240, v110, v240
	v_mul_f32_e32 v241, v111, v241
	v_add_f32_e32 v162, 1.0, v162
	v_add_f32_e32 v163, 1.0, v163
	v_add_f32_e32 v164, 1.0, v164
	v_add_f32_e32 v165, 1.0, v165
	v_add_f32_e32 v166, 1.0, v166
	v_add_f32_e32 v167, 1.0, v167
	v_add_f32_e32 v168, 1.0, v168
	v_add_f32_e32 v169, 1.0, v169
	v_add_f32_e32 v170, 1.0, v170
	v_add_f32_e32 v171, 1.0, v171
	v_add_f32_e32 v172, 1.0, v172
	v_add_f32_e32 v173, 1.0, v173
	v_add_f32_e32 v174, 1.0, v174
	v_add_f32_e32 v175, 1.0, v175
	v_add_f32_e32 v176, 1.0, v176
	v_add_f32_e32 v177, 1.0, v177
	v_fma_f32 v226, v162, v226, v178
	v_fma_f32 v227, v163, v227, v179
	v_fma_f32 v228, v164, v228, v180
	v_fma_f32 v229, v165, v229, v181
	v_fma_f32 v230, v166, v230, v182
	v_fma_f32 v231, v167, v231, v183
	v_fma_f32 v232, v168, v232, v184
	v_fma_f32 v233, v169, v233, v185
	v_fma_f32 v234, v170, v234, v186
	v_fma_f32 v235, v171, v235, v187
	v_fma_f32 v236, v172, v236, v188
	v_fma_f32 v237, v173, v237, v189
	v_fma_f32 v238, v174, v238, v190
	v_fma_f32 v239, v175, v239, v191
	v_fma_f32 v240, v176, v240, v192
	v_fma_f32 v241, v177, v241, v193
	v_cvt_pk_f16_f32 v244, v226, v227
	v_cvt_pk_f16_f32 v245, v228, v229
	v_cvt_pk_f16_f32 v246, v230, v231
	v_cvt_pk_f16_f32 v247, v232, v233
	v_cvt_pk_f16_f32 v248, v234, v235
	v_cvt_pk_f16_f32 v249, v236, v237
	v_cvt_pk_f16_f32 v250, v238, v239
	v_cvt_pk_f16_f32 v251, v240, v241
	global_store_dwordx2 v202, v[244:245], s[40:41]
	global_store_dwordx2 v202, v[246:247], s[40:41] offset:512
	global_store_dwordx2 v202, v[248:249], s[40:41] offset:1024
	global_store_dwordx2 v202, v[250:251], s[40:41] offset:1536
	s_add_i32 s58, s58, s2
	s_cmp_lt_i32 s58, s36
	s_cbranch_scc0 .Lrr1_exit
; DI void rows_resid_norm(const P& p, const float* xlat, const float* xctx, const h16* y, int l, int gate_idx, const float* post_g,
;                         bool do_next, int l2, const float* gain2, int sh_idx, int sc_idx, h16* dst, int nrows) {
;     ...
;   for (int row = gw; row < nrows; row += nw) {
;     const float* xr = row < TL ? xlat + (size_t)row * 1024 : xctx + (size_t)(row - TL) * 1024;
;     float* xo = row < TL ? p.out + (size_t)row * 1024 : xc + (size_t)(row - TL) * 1024;
;     const int mrow = row < TL ? (row >> 12) : 8;
;     const float* mr = mod + ((size_t)l * 9 + mrow) * 6144;
;     const float* mr2 = mod + ((size_t)l2 * 9 + mrow) * 6144;
;     f32x4 yv[4], xv[4];
;     float ss = 0.f;
; #pragma unroll
;     for (int i = 0; i < 4; ++i) {
;       h16x4 t = *(const h16x4*)(y + (size_t)row * 1024 + lane * 4 + 256 * i);
;       yv[i].x = (float)t.x; yv[i].y = (float)t.y; yv[i].z = (float)t.z; yv[i].w = (float)t.w;
;       ss += yv[i].x * yv[i].x + yv[i].y * yv[i].y + yv[i].z * yv[i].z + yv[i].w * yv[i].w;
;       xv[i] = *(const f32x4*)(xr + lane * 4 + 256 * i);
;     }
;     ss = wave_sum(ss);
;     const float rstd = rsqrtf(ss * (1.f / 1024.f) + EPS);
;     float s2 = 0.f;
; #pragma unroll
;     for (int i = 0; i < 4; ++i) {
;       const int c = lane * 4 + 256 * i;
;       f32x4 g = *(const f32x4*)(post_g + c), gt = *(const f32x4*)(mr + gate_idx * 1024 + c);
;       xv[i].x += gt.x * (yv[i].x * rstd * g.x);
;       xv[i].y += gt.y * (yv[i].y * rstd * g.y);
;       xv[i].z += gt.z * (yv[i].z * rstd * g.z);
;       xv[i].w += gt.w * (yv[i].w * rstd * g.w);
;       *(f32x4*)(xo + c) = xv[i];
;       s2 += xv[i].x * xv[i].x + xv[i].y * xv[i].y + xv[i].z * xv[i].z + xv[i].w * xv[i].w;
;     }
;     if (do_next) {
;       s2 = wave_sum(s2);
;       const float r2 = rsqrtf(s2 * (1.f / 1024.f) + EPS);
	s_lshr_b32 s59, s58, 12
	s_cmp_lt_u32 s58, 0x8000
	s_cselect_b32 s59, s59, 8
	s_mul_i32 s59, s59, 0x6000
	s_add_u32 s24, s42, s59
	s_addc_u32 s25, s43, 0
	s_add_u32 s18, s54, s59
	s_addc_u32 s19, s55, 0
	s_add_u32 s34, s18, 0x4000
	s_addc_u32 s35, s19, 0
	s_add_u32 s18, s18, 0x3000
	s_addc_u32 s19, s19, 0
	s_lshl_b32 s59, s58, 11
	s_add_u32 s40, s56, s59
	s_addc_u32 s41, s57, 0
	s_sub_u32 s60, s58, 0x8000
	s_cmp_lt_u32 s58, 0x8000
	s_cselect_b32 s60, s58, s60
	s_cselect_b32 s22, s46, s50
	s_cselect_b32 s23, s47, s51
	s_lshl_b32 s60, s60, 12
	s_add_u32 s22, s22, s60
	s_addc_u32 s23, s23, 0
	global_load_dwordx4 v[112:115], v0, s[24:25]
	global_load_dwordx4 v[116:119], v0, s[24:25] offset:1024
	global_load_dwordx4 v[120:123], v0, s[24:25] offset:2048
	global_load_dwordx4 v[124:127], v0, s[24:25] offset:3072
	global_load_dwordx4 v[162:165], v0, s[34:35]
	global_load_dwordx4 v[166:169], v0, s[34:35] offset:1024
	global_load_dwordx4 v[170:173], v0, s[34:35] offset:2048
	global_load_dwordx4 v[174:177], v0, s[34:35] offset:3072
	global_load_dwordx4 v[178:181], v0, s[18:19]
	global_load_dwordx4 v[182:185], v0, s[18:19] offset:1024
	global_load_dwordx4 v[186:189], v0, s[18:19] offset:2048
	global_load_dwordx4 v[190:193], v0, s[18:19] offset:3072
	s_waitcnt vmcnt(12)
	v_cvt_f32_f16_e32 v226, v10
	v_cvt_f32_f16_sdwa v227, v10 dst_sel:DWORD dst_unused:UNUSED_PAD src0_sel:WORD_1
	v_cvt_f32_f16_e32 v228, v11
	v_cvt_f32_f16_sdwa v229, v11 dst_sel:DWORD dst_unused:UNUSED_PAD src0_sel:WORD_1
	v_cvt_f32_f16_e32 v230, v12
	v_cvt_f32_f16_sdwa v231, v12 dst_sel:DWORD dst_unused:UNUSED_PAD src0_sel:WORD_1
	v_cvt_f32_f16_e32 v232, v13
	v_cvt_f32_f16_sdwa v233, v13 dst_sel:DWORD dst_unused:UNUSED_PAD src0_sel:WORD_1
	v_cvt_f32_f16_e32 v234, v14
	v_cvt_f32_f16_sdwa v235, v14 dst_sel:DWORD dst_unused:UNUSED_PAD src0_sel:WORD_1
	v_cvt_f32_f16_e32 v236, v15
	v_cvt_f32_f16_sdwa v237, v15 dst_sel:DWORD dst_unused:UNUSED_PAD src0_sel:WORD_1
	v_cvt_f32_f16_e32 v238, v16
	v_cvt_f32_f16_sdwa v239, v16 dst_sel:DWORD dst_unused:UNUSED_PAD src0_sel:WORD_1
	v_cvt_f32_f16_e32 v240, v17
	v_cvt_f32_f16_sdwa v241, v17 dst_sel:DWORD dst_unused:UNUSED_PAD src0_sel:WORD_1
	v_mul_f32_e32 v242, v227, v227
	v_mul_f32_e32 v243, v231, v231
	v_mul_f32_e32 v244, v235, v235
	v_mul_f32_e32 v245, v239, v239
	v_fmac_f32_e32 v242, v226, v226
	v_fmac_f32_e32 v243, v230, v230
	v_fmac_f32_e32 v244, v234, v234
	v_fmac_f32_e32 v245, v238, v238
	v_fmac_f32_e32 v242, v228, v228
	v_fmac_f32_e32 v243, v232, v232
	v_fmac_f32_e32 v244, v236, v236
	v_fmac_f32_e32 v245, v240, v240
	v_fmac_f32_e32 v242, v229, v229
	v_fmac_f32_e32 v243, v233, v233
	v_fmac_f32_e32 v244, v237, v237
	v_fmac_f32_e32 v245, v241, v241
	v_add_f32_e32 v242, v242, v243
	v_add_f32_e32 v242, v242, v244
	v_add_f32_e32 v242, v242, v245
	s_nop 1
	v_add_f32_dpp v242, v242, v242 quad_perm:[1,0,3,2] row_mask:0xf bank_mask:0xf bound_ctrl:1
	s_nop 1
	v_add_f32_dpp v242, v242, v242 quad_perm:[2,3,0,1] row_mask:0xf bank_mask:0xf bound_ctrl:1
	s_nop 1
	v_add_f32_dpp v242, v242, v242 row_half_mirror row_mask:0xf bank_mask:0xf bound_ctrl:1
	s_nop 1
	v_add_f32_dpp v242, v242, v242 row_mirror row_mask:0xf bank_mask:0xf bound_ctrl:1
	s_nop 1
	ds_swizzle_b32 v243, v242 offset:swizzle(SWAP,16)
	s_waitcnt lgkmcnt(0)
	v_add_f32_e32 v242, v242, v243
	v_mov_b32_e32 v243, v242
	s_nop 1
	v_permlane32_swap_b32_e32 v242, v243
	v_add_f32_e32 v242, v242, v243
	v_fmamk_f32 v242, v242, 0x3a800000, v224
	v_rsq_f32_e32 v242, v242
	s_waitcnt vmcnt(0)
	v_mul_f32_e32 v226, v226, v242
	v_mul_f32_e32 v227, v227, v242
	v_mul_f32_e32 v228, v228, v242
	v_mul_f32_e32 v229, v229, v242
	v_mul_f32_e32 v230, v230, v242
	v_mul_f32_e32 v231, v231, v242
	v_mul_f32_e32 v232, v232, v242
	v_mul_f32_e32 v233, v233, v242
	v_mul_f32_e32 v234, v234, v242
	v_mul_f32_e32 v235, v235, v242
	v_mul_f32_e32 v236, v236, v242
	v_mul_f32_e32 v237, v237, v242
	v_mul_f32_e32 v238, v238, v242
	v_mul_f32_e32 v239, v239, v242
	v_mul_f32_e32 v240, v240, v242
	v_mul_f32_e32 v241, v241, v242
	v_mul_f32_e32 v226, v80, v226
	v_mul_f32_e32 v227, v81, v227
	v_mul_f32_e32 v228, v82, v228
	v_mul_f32_e32 v229, v83, v229
	v_mul_f32_e32 v230, v84, v230
	v_mul_f32_e32 v231, v85, v231
	v_mul_f32_e32 v232, v86, v232
	v_mul_f32_e32 v233, v87, v233
	v_mul_f32_e32 v234, v88, v234
	v_mul_f32_e32 v235, v89, v235
	v_mul_f32_e32 v236, v90, v236
	v_mul_f32_e32 v237, v91, v237
	v_mul_f32_e32 v238, v92, v238
	v_mul_f32_e32 v239, v93, v239
	v_mul_f32_e32 v240, v94, v240
	v_mul_f32_e32 v241, v95, v241
	v_fmac_f32_e32 v48, v112, v226
	v_fmac_f32_e32 v49, v113, v227
	v_fmac_f32_e32 v50, v114, v228
	v_fmac_f32_e32 v51, v115, v229
	v_fmac_f32_e32 v52, v116, v230
	v_fmac_f32_e32 v53, v117, v231
	v_fmac_f32_e32 v54, v118, v232
	v_fmac_f32_e32 v55, v119, v233
	v_fmac_f32_e32 v56, v120, v234
	v_fmac_f32_e32 v57, v121, v235
	v_fmac_f32_e32 v58, v122, v236
	v_fmac_f32_e32 v59, v123, v237
	v_fmac_f32_e32 v60, v124, v238
	v_fmac_f32_e32 v61, v125, v239
	v_fmac_f32_e32 v62, v126, v240
	v_fmac_f32_e32 v63, v127, v241
	global_store_dwordx4 v0, v[48:51], s[22:23]
	global_store_dwordx4 v0, v[52:55], s[22:23] offset:1024
	global_store_dwordx4 v0, v[56:59], s[22:23] offset:2048
	global_store_dwordx4 v0, v[60:63], s[22:23] offset:3072
	v_mul_f32_e32 v242, v49, v49
	v_mul_f32_e32 v243, v53, v53
	v_mul_f32_e32 v244, v57, v57
	v_mul_f32_e32 v245, v61, v61
	v_fmac_f32_e32 v242, v48, v48
	v_fmac_f32_e32 v243, v52, v52
	v_fmac_f32_e32 v244, v56, v56
	v_fmac_f32_e32 v245, v60, v60
	v_fmac_f32_e32 v242, v50, v50
	v_fmac_f32_e32 v243, v54, v54
	v_fmac_f32_e32 v244, v58, v58
	v_fmac_f32_e32 v245, v62, v62
	v_fmac_f32_e32 v242, v51, v51
	v_fmac_f32_e32 v243, v55, v55
	v_fmac_f32_e32 v244, v59, v59
	v_fmac_f32_e32 v245, v63, v63
	v_add_f32_e32 v242, v242, v243
	v_add_f32_e32 v242, v242, v244
	v_add_f32_e32 v242, v242, v245
	s_nop 1
	v_add_f32_dpp v242, v242, v242 quad_perm:[1,0,3,2] row_mask:0xf bank_mask:0xf bound_ctrl:1
	s_nop 1
	v_add_f32_dpp v242, v242, v242 quad_perm:[2,3,0,1] row_mask:0xf bank_mask:0xf bound_ctrl:1
	s_nop 1
	v_add_f32_dpp v242, v242, v242 row_half_mirror row_mask:0xf bank_mask:0xf bound_ctrl:1
	s_nop 1
	v_add_f32_dpp v242, v242, v242 row_mirror row_mask:0xf bank_mask:0xf bound_ctrl:1
	s_nop 1
	ds_swizzle_b32 v243, v242 offset:swizzle(SWAP,16)
	s_waitcnt lgkmcnt(0)
; DI void rows_resid_norm(const P& p, const float* xlat, const float* xctx, const h16* y, int l, int gate_idx, const float* post_g,
;                         bool do_next, int l2, const float* gain2, int sh_idx, int sc_idx, h16* dst, int nrows) {
;     ...
; #pragma unroll
;     for (int i = 0; i < 4; ++i) {
;       h16x4 t = *(const h16x4*)(y + (size_t)row * 1024 + lane * 4 + 256 * i);
;       yv[i].x = (float)t.x; yv[i].y = (float)t.y; yv[i].z = (float)t.z; yv[i].w = (float)t.w;
;       ss += yv[i].x * yv[i].x + yv[i].y * yv[i].y + yv[i].z * yv[i].z + yv[i].w * yv[i].w;
;       xv[i] = *(const f32x4*)(xr + lane * 4 + 256 * i);
;     }
;     ss = wave_sum(ss);
;     const float rstd = rsqrtf(ss * (1.f / 1024.f) + EPS);
;     float s2 = 0.f;
; #pragma unroll
;     for (int i = 0; i < 4; ++i) {
;     ...
;     if (do_next) {
;       s2 = wave_sum(s2);
;       const float r2 = rsqrtf(s2 * (1.f / 1024.f) + EPS);
; #pragma unroll
;       for (int i = 0; i < 4; ++i) {
;         const int c = lane * 4 + 256 * i;
;         f32x4 g = *(const f32x4*)(gain2 + c), sc = *(const f32x4*)(mr2 + sc_idx * 1024 + c), sh = *(const f32x4*)(mr2 + sh_idx * 1024 + c);
;         h16x4 o;
;         o.x = (h16)(xv[i].x * r2 * g.x * (1.f + sc.x) + sh.x);
;         o.y = (h16)(xv[i].y * r2 * g.y * (1.f + sc.y) + sh.y);
;         o.z = (h16)(xv[i].z * r2 * g.z * (1.f + sc.z) + sh.z);
;         o.w = (h16)(xv[i].w * r2 * g.w * (1.f + sc.w) + sh.w);
;         *(h16x4*)(dst + (size_t)row * 1024 + c) = o;
;       }
;     }
	v_add_f32_e32 v242, v242, v243
	v_mov_b32_e32 v243, v242
	s_nop 1
	v_permlane32_swap_b32_e32 v242, v243
	v_add_f32_e32 v242, v242, v243
	v_fmamk_f32 v242, v242, 0x3a800000, v224
	v_rsq_f32_e32 v242, v242
	s_nop 0
	v_mul_f32_e32 v226, v48, v242
	v_mul_f32_e32 v227, v49, v242
	v_mul_f32_e32 v228, v50, v242
	v_mul_f32_e32 v229, v51, v242
	v_mul_f32_e32 v230, v52, v242
	v_mul_f32_e32 v231, v53, v242
	v_mul_f32_e32 v232, v54, v242
	v_mul_f32_e32 v233, v55, v242
	v_mul_f32_e32 v234, v56, v242
	v_mul_f32_e32 v235, v57, v242
	v_mul_f32_e32 v236, v58, v242
	v_mul_f32_e32 v237, v59, v242
	v_mul_f32_e32 v238, v60, v242
	v_mul_f32_e32 v239, v61, v242
	v_mul_f32_e32 v240, v62, v242
	v_mul_f32_e32 v241, v63, v242
	v_mul_f32_e32 v226, v96, v226
	v_mul_f32_e32 v227, v97, v227
	v_mul_f32_e32 v228, v98, v228
	v_mul_f32_e32 v229, v99, v229
	v_mul_f32_e32 v230, v100, v230
	v_mul_f32_e32 v231, v101, v231
	v_mul_f32_e32 v232, v102, v232
	v_mul_f32_e32 v233, v103, v233
	v_mul_f32_e32 v234, v104, v234
	v_mul_f32_e32 v235, v105, v235
	v_mul_f32_e32 v236, v106, v236
	v_mul_f32_e32 v237, v107, v237
	v_mul_f32_e32 v238, v108, v238
	v_mul_f32_e32 v239, v109, v239
	v_mul_f32_e32 v240, v110, v240
	v_mul_f32_e32 v241, v111, v241
	v_add_f32_e32 v162, 1.0, v162
	v_add_f32_e32 v163, 1.0, v163
	v_add_f32_e32 v164, 1.0, v164
	v_add_f32_e32 v165, 1.0, v165
	v_add_f32_e32 v166, 1.0, v166
	v_add_f32_e32 v167, 1.0, v167
	v_add_f32_e32 v168, 1.0, v168
	v_add_f32_e32 v169, 1.0, v169
	v_add_f32_e32 v170, 1.0, v170
	v_add_f32_e32 v171, 1.0, v171
	v_add_f32_e32 v172, 1.0, v172
	v_add_f32_e32 v173, 1.0, v173
	v_add_f32_e32 v174, 1.0, v174
	v_add_f32_e32 v175, 1.0, v175
	v_add_f32_e32 v176, 1.0, v176
	v_add_f32_e32 v177, 1.0, v177
	v_fma_f32 v226, v162, v226, v178
	v_fma_f32 v227, v163, v227, v179
	v_fma_f32 v228, v164, v228, v180
	v_fma_f32 v229, v165, v229, v181
	v_fma_f32 v230, v166, v230, v182
	v_fma_f32 v231, v167, v231, v183
	v_fma_f32 v232, v168, v232, v184
	v_fma_f32 v233, v169, v233, v185
	v_fma_f32 v234, v170, v234, v186
	v_fma_f32 v235, v171, v235, v187
	v_fma_f32 v236, v172, v236, v188
	v_fma_f32 v237, v173, v237, v189
	v_fma_f32 v238, v174, v238, v190
	v_fma_f32 v239, v175, v239, v191
	v_fma_f32 v240, v176, v240, v192
	v_fma_f32 v241, v177, v241, v193
	v_cvt_pk_f16_f32 v244, v226, v227
	v_cvt_pk_f16_f32 v245, v228, v229
	v_cvt_pk_f16_f32 v246, v230, v231
	v_cvt_pk_f16_f32 v247, v232, v233
	v_cvt_pk_f16_f32 v248, v234, v235
	v_cvt_pk_f16_f32 v249, v236, v237
	v_cvt_pk_f16_f32 v250, v238, v239
	v_cvt_pk_f16_f32 v251, v240, v241
	global_store_dwordx2 v202, v[244:245], s[40:41]
	global_store_dwordx2 v202, v[246:247], s[40:41] offset:512
	global_store_dwordx2 v202, v[248:249], s[40:41] offset:1024
	global_store_dwordx2 v202, v[250:251], s[40:41] offset:1536
	s_add_i32 s58, s58, s2
	s_branch .Lrr1_exit
.Lrr11_tail1:
	s_waitcnt vmcnt(12)
	v_cvt_f32_f16_e32 v226, v10
	v_cvt_f32_f16_sdwa v227, v10 dst_sel:DWORD dst_unused:UNUSED_PAD src0_sel:WORD_1
	v_cvt_f32_f16_e32 v228, v11
	v_cvt_f32_f16_sdwa v229, v11 dst_sel:DWORD dst_unused:UNUSED_PAD src0_sel:WORD_1
	v_cvt_f32_f16_e32 v230, v12
	v_cvt_f32_f16_sdwa v231, v12 dst_sel:DWORD dst_unused:UNUSED_PAD src0_sel:WORD_1
	v_cvt_f32_f16_e32 v232, v13
	v_cvt_f32_f16_sdwa v233, v13 dst_sel:DWORD dst_unused:UNUSED_PAD src0_sel:WORD_1
	v_cvt_f32_f16_e32 v234, v14
	v_cvt_f32_f16_sdwa v235, v14 dst_sel:DWORD dst_unused:UNUSED_PAD src0_sel:WORD_1
	v_cvt_f32_f16_e32 v236, v15
	v_cvt_f32_f16_sdwa v237, v15 dst_sel:DWORD dst_unused:UNUSED_PAD src0_sel:WORD_1
	v_cvt_f32_f16_e32 v238, v16
	v_cvt_f32_f16_sdwa v239, v16 dst_sel:DWORD dst_unused:UNUSED_PAD src0_sel:WORD_1
	v_cvt_f32_f16_e32 v240, v17
	v_cvt_f32_f16_sdwa v241, v17 dst_sel:DWORD dst_unused:UNUSED_PAD src0_sel:WORD_1
	v_mul_f32_e32 v242, v227, v227
	v_mul_f32_e32 v243, v231, v231
	v_mul_f32_e32 v244, v235, v235
	v_mul_f32_e32 v245, v239, v239
	v_fmac_f32_e32 v242, v226, v226
	v_fmac_f32_e32 v243, v230, v230
	v_fmac_f32_e32 v244, v234, v234
	v_fmac_f32_e32 v245, v238, v238
	v_fmac_f32_e32 v242, v228, v228
	v_fmac_f32_e32 v243, v232, v232
	v_fmac_f32_e32 v244, v236, v236
	v_fmac_f32_e32 v245, v240, v240
	v_fmac_f32_e32 v242, v229, v229
	v_fmac_f32_e32 v243, v233, v233
	v_fmac_f32_e32 v244, v237, v237
	v_fmac_f32_e32 v245, v241, v241
	v_add_f32_e32 v242, v242, v243
	v_add_f32_e32 v242, v242, v244
	v_add_f32_e32 v242, v242, v245
	s_nop 1
	v_add_f32_dpp v242, v242, v242 quad_perm:[1,0,3,2] row_mask:0xf bank_mask:0xf bound_ctrl:1
	s_nop 1
	v_add_f32_dpp v242, v242, v242 quad_perm:[2,3,0,1] row_mask:0xf bank_mask:0xf bound_ctrl:1
	s_nop 1
	v_add_f32_dpp v242, v242, v242 row_half_mirror row_mask:0xf bank_mask:0xf bound_ctrl:1
	s_nop 1
	v_add_f32_dpp v242, v242, v242 row_mirror row_mask:0xf bank_mask:0xf bound_ctrl:1
	s_nop 1
	ds_swizzle_b32 v243, v242 offset:swizzle(SWAP,16)
	s_waitcnt lgkmcnt(0)
	v_add_f32_e32 v242, v242, v243
	v_mov_b32_e32 v243, v242
	s_nop 1
	v_permlane32_swap_b32_e32 v242, v243
	v_add_f32_e32 v242, v242, v243
	v_fmamk_f32 v242, v242, 0x3a800000, v224
	v_rsq_f32_e32 v242, v242
	s_waitcnt vmcnt(0)
; DI void rows_resid_norm(const P& p, const float* xlat, const float* xctx, const h16* y, int l, int gate_idx, const float* post_g,
;                         bool do_next, int l2, const float* gain2, int sh_idx, int sc_idx, h16* dst, int nrows) {
;     ...
;     const float rstd = rsqrtf(ss * (1.f / 1024.f) + EPS);
;     float s2 = 0.f;
; #pragma unroll
;     for (int i = 0; i < 4; ++i) {
;       const int c = lane * 4 + 256 * i;
;       f32x4 g = *(const f32x4*)(post_g + c), gt = *(const f32x4*)(mr + gate_idx * 1024 + c);
;       xv[i].x += gt.x * (yv[i].x * rstd * g.x);
;       xv[i].y += gt.y * (yv[i].y * rstd * g.y);
;       xv[i].z += gt.z * (yv[i].z * rstd * g.z);
;       xv[i].w += gt.w * (yv[i].w * rstd * g.w);
;       *(f32x4*)(xo + c) = xv[i];
;       s2 += xv[i].x * xv[i].x + xv[i].y * xv[i].y + xv[i].z * xv[i].z + xv[i].w * xv[i].w;
;     }
;     if (do_next) {
;       s2 = wave_sum(s2);
;       const float r2 = rsqrtf(s2 * (1.f / 1024.f) + EPS);
; #pragma unroll
;       for (int i = 0; i < 4; ++i) {
;         const int c = lane * 4 + 256 * i;
;         f32x4 g = *(const f32x4*)(gain2 + c), sc = *(const f32x4*)(mr2 + sc_idx * 1024 + c), sh = *(const f32x4*)(mr2 + sh_idx * 1024 + c);
;         h16x4 o;
;         o.x = (h16)(xv[i].x * r2 * g.x * (1.f + sc.x) + sh.x);
;         o.y = (h16)(xv[i].y * r2 * g.y * (1.f + sc.y) + sh.y);
;         o.z = (h16)(xv[i].z * r2 * g.z * (1.f + sc.z) + sh.z);
;         o.w = (h16)(xv[i].w * r2 * g.w * (1.f + sc.w) + sh.w);
;         *(h16x4*)(dst + (size_t)row * 1024 + c) = o;
;       }
;     }
	v_mul_f32_e32 v226, v226, v242
	v_mul_f32_e32 v227, v227, v242
	v_mul_f32_e32 v228, v228, v242
	v_mul_f32_e32 v229, v229, v242
	v_mul_f32_e32 v230, v230, v242
	v_mul_f32_e32 v231, v231, v242
	v_mul_f32_e32 v232, v232, v242
	v_mul_f32_e32 v233, v233, v242
	v_mul_f32_e32 v234, v234, v242
	v_mul_f32_e32 v235, v235, v242
	v_mul_f32_e32 v236, v236, v242
	v_mul_f32_e32 v237, v237, v242
	v_mul_f32_e32 v238, v238, v242
	v_mul_f32_e32 v239, v239, v242
	v_mul_f32_e32 v240, v240, v242
	v_mul_f32_e32 v241, v241, v242
	v_mul_f32_e32 v226, v80, v226
	v_mul_f32_e32 v227, v81, v227
	v_mul_f32_e32 v228, v82, v228
	v_mul_f32_e32 v229, v83, v229
	v_mul_f32_e32 v230, v84, v230
	v_mul_f32_e32 v231, v85, v231
	v_mul_f32_e32 v232, v86, v232
	v_mul_f32_e32 v233, v87, v233
	v_mul_f32_e32 v234, v88, v234
	v_mul_f32_e32 v235, v89, v235
	v_mul_f32_e32 v236, v90, v236
	v_mul_f32_e32 v237, v91, v237
	v_mul_f32_e32 v238, v92, v238
	v_mul_f32_e32 v239, v93, v239
	v_mul_f32_e32 v240, v94, v240
	v_mul_f32_e32 v241, v95, v241
	v_fmac_f32_e32 v48, v112, v226
	v_fmac_f32_e32 v49, v113, v227
	v_fmac_f32_e32 v50, v114, v228
	v_fmac_f32_e32 v51, v115, v229
	v_fmac_f32_e32 v52, v116, v230
	v_fmac_f32_e32 v53, v117, v231
	v_fmac_f32_e32 v54, v118, v232
	v_fmac_f32_e32 v55, v119, v233
	v_fmac_f32_e32 v56, v120, v234
	v_fmac_f32_e32 v57, v121, v235
	v_fmac_f32_e32 v58, v122, v236
	v_fmac_f32_e32 v59, v123, v237
	v_fmac_f32_e32 v60, v124, v238
	v_fmac_f32_e32 v61, v125, v239
	v_fmac_f32_e32 v62, v126, v240
	v_fmac_f32_e32 v63, v127, v241
	global_store_dwordx4 v0, v[48:51], s[22:23]
	global_store_dwordx4 v0, v[52:55], s[22:23] offset:1024
	global_store_dwordx4 v0, v[56:59], s[22:23] offset:2048
	global_store_dwordx4 v0, v[60:63], s[22:23] offset:3072
	v_mul_f32_e32 v242, v49, v49
	v_mul_f32_e32 v243, v53, v53
	v_mul_f32_e32 v244, v57, v57
	v_mul_f32_e32 v245, v61, v61
	v_fmac_f32_e32 v242, v48, v48
	v_fmac_f32_e32 v243, v52, v52
	v_fmac_f32_e32 v244, v56, v56
	v_fmac_f32_e32 v245, v60, v60
	v_fmac_f32_e32 v242, v50, v50
	v_fmac_f32_e32 v243, v54, v54
	v_fmac_f32_e32 v244, v58, v58
	v_fmac_f32_e32 v245, v62, v62
	v_fmac_f32_e32 v242, v51, v51
	v_fmac_f32_e32 v243, v55, v55
	v_fmac_f32_e32 v244, v59, v59
	v_fmac_f32_e32 v245, v63, v63
	v_add_f32_e32 v242, v242, v243
	v_add_f32_e32 v242, v242, v244
	v_add_f32_e32 v242, v242, v245
	s_nop 1
	v_add_f32_dpp v242, v242, v242 quad_perm:[1,0,3,2] row_mask:0xf bank_mask:0xf bound_ctrl:1
	s_nop 1
	v_add_f32_dpp v242, v242, v242 quad_perm:[2,3,0,1] row_mask:0xf bank_mask:0xf bound_ctrl:1
	s_nop 1
	v_add_f32_dpp v242, v242, v242 row_half_mirror row_mask:0xf bank_mask:0xf bound_ctrl:1
	s_nop 1
	v_add_f32_dpp v242, v242, v242 row_mirror row_mask:0xf bank_mask:0xf bound_ctrl:1
	s_nop 1
	ds_swizzle_b32 v243, v242 offset:swizzle(SWAP,16)
	s_waitcnt lgkmcnt(0)
	v_add_f32_e32 v242, v242, v243
	v_mov_b32_e32 v243, v242
	s_nop 1
	v_permlane32_swap_b32_e32 v242, v243
	v_add_f32_e32 v242, v242, v243
	v_fmamk_f32 v242, v242, 0x3a800000, v224
	v_rsq_f32_e32 v242, v242
	s_nop 0
	v_mul_f32_e32 v226, v48, v242
	v_mul_f32_e32 v227, v49, v242
	v_mul_f32_e32 v228, v50, v242
	v_mul_f32_e32 v229, v51, v242
	v_mul_f32_e32 v230, v52, v242
	v_mul_f32_e32 v231, v53, v242
	v_mul_f32_e32 v232, v54, v242
	v_mul_f32_e32 v233, v55, v242
	v_mul_f32_e32 v234, v56, v242
	v_mul_f32_e32 v235, v57, v242
	v_mul_f32_e32 v236, v58, v242
	v_mul_f32_e32 v237, v59, v242
	v_mul_f32_e32 v238, v60, v242
	v_mul_f32_e32 v239, v61, v242
	v_mul_f32_e32 v240, v62, v242
	v_mul_f32_e32 v241, v63, v242
	v_mul_f32_e32 v226, v96, v226
	v_mul_f32_e32 v227, v97, v227
	v_mul_f32_e32 v228, v98, v228
	v_mul_f32_e32 v229, v99, v229
	v_mul_f32_e32 v230, v100, v230
	v_mul_f32_e32 v231, v101, v231
	v_mul_f32_e32 v232, v102, v232
	v_mul_f32_e32 v233, v103, v233
	v_mul_f32_e32 v234, v104, v234
	v_mul_f32_e32 v235, v105, v235
	v_mul_f32_e32 v236, v106, v236
	v_mul_f32_e32 v237, v107, v237
	v_mul_f32_e32 v238, v108, v238
	v_mul_f32_e32 v239, v109, v239
	v_mul_f32_e32 v240, v110, v240
	v_mul_f32_e32 v241, v111, v241
	v_add_f32_e32 v162, 1.0, v162
	v_add_f32_e32 v163, 1.0, v163
	v_add_f32_e32 v164, 1.0, v164
	v_add_f32_e32 v165, 1.0, v165
	v_add_f32_e32 v166, 1.0, v166
	v_add_f32_e32 v167, 1.0, v167
	v_add_f32_e32 v168, 1.0, v168
	v_add_f32_e32 v169, 1.0, v169
	v_add_f32_e32 v170, 1.0, v170
	v_add_f32_e32 v171, 1.0, v171
	v_add_f32_e32 v172, 1.0, v172
	v_add_f32_e32 v173, 1.0, v173
	v_add_f32_e32 v174, 1.0, v174
	v_add_f32_e32 v175, 1.0, v175
	v_add_f32_e32 v176, 1.0, v176
	v_add_f32_e32 v177, 1.0, v177
	v_fma_f32 v226, v162, v226, v178
	v_fma_f32 v227, v163, v227, v179
	v_fma_f32 v228, v164, v228, v180
	v_fma_f32 v229, v165, v229, v181
	v_fma_f32 v230, v166, v230, v182
	v_fma_f32 v231, v167, v231, v183
	v_fma_f32 v232, v168, v232, v184
	v_fma_f32 v233, v169, v233, v185
	v_fma_f32 v234, v170, v234, v186
	v_fma_f32 v235, v171, v235, v187
	v_fma_f32 v236, v172, v236, v188
	v_fma_f32 v237, v173, v237, v189
	v_fma_f32 v238, v174, v238, v190
	v_fma_f32 v239, v175, v239, v191
	v_fma_f32 v240, v176, v240, v192
	v_fma_f32 v241, v177, v241, v193
	v_cvt_pk_f16_f32 v244, v226, v227
	v_cvt_pk_f16_f32 v245, v228, v229
	v_cvt_pk_f16_f32 v246, v230, v231
	v_cvt_pk_f16_f32 v247, v232, v233
	v_cvt_pk_f16_f32 v248, v234, v235
	v_cvt_pk_f16_f32 v249, v236, v237
	v_cvt_pk_f16_f32 v250, v238, v239
	v_cvt_pk_f16_f32 v251, v240, v241
	global_store_dwordx2 v202, v[244:245], s[40:41]
	global_store_dwordx2 v202, v[246:247], s[40:41] offset:512
	global_store_dwordx2 v202, v[248:249], s[40:41] offset:1024
	global_store_dwordx2 v202, v[250:251], s[40:41] offset:1536
	s_add_i32 s58, s58, s2
	s_cmp_lt_i32 s58, s36
	s_cbranch_scc0 .Lrr1_exit
; DI void rows_resid_norm(const P& p, const float* xlat, const float* xctx, const h16* y, int l, int gate_idx, const float* post_g,
;                         bool do_next, int l2, const float* gain2, int sh_idx, int sc_idx, h16* dst, int nrows) {
;     ...
;   for (int row = gw; row < nrows; row += nw) {
;     const float* xr = row < TL ? xlat + (size_t)row * 1024 : xctx + (size_t)(row - TL) * 1024;
;     float* xo = row < TL ? p.out + (size_t)row * 1024 : xc + (size_t)(row - TL) * 1024;
;     const int mrow = row < TL ? (row >> 12) : 8;
;     const float* mr = mod + ((size_t)l * 9 + mrow) * 6144;
;     const float* mr2 = mod + ((size_t)l2 * 9 + mrow) * 6144;
;     f32x4 yv[4], xv[4];
;     float ss = 0.f;
; #pragma unroll
;     for (int i = 0; i < 4; ++i) {
;       h16x4 t = *(const h16x4*)(y + (size_t)row * 1024 + lane * 4 + 256 * i);
;       yv[i].x = (float)t.x; yv[i].y = (float)t.y; yv[i].z = (float)t.z; yv[i].w = (float)t.w;
;       ss += yv[i].x * yv[i].x + yv[i].y * yv[i].y + yv[i].z * yv[i].z + yv[i].w * yv[i].w;
;       xv[i] = *(const f32x4*)(xr + lane * 4 + 256 * i);
;     }
;     ss = wave_sum(ss);
;     const float rstd = rsqrtf(ss * (1.f / 1024.f) + EPS);
;     float s2 = 0.f;
; #pragma unroll
;     for (int i = 0; i < 4; ++i) {
;       const int c = lane * 4 + 256 * i;
;       f32x4 g = *(const f32x4*)(post_g + c), gt = *(const f32x4*)(mr + gate_idx * 1024 + c);
;       xv[i].x += gt.x * (yv[i].x * rstd * g.x);
;       xv[i].y += gt.y * (yv[i].y * rstd * g.y);
;       xv[i].z += gt.z * (yv[i].z * rstd * g.z);
;       xv[i].w += gt.w * (yv[i].w * rstd * g.w);
;       *(f32x4*)(xo + c) = xv[i];
;       s2 += xv[i].x * xv[i].x + xv[i].y * xv[i].y + xv[i].z * xv[i].z + xv[i].w * xv[i].w;
;     }
;     if (do_next) {
;       s2 = wave_sum(s2);
;       const float r2 = rsqrtf(s2 * (1.f / 1024.f) + EPS);
	s_lshr_b32 s59, s58, 12
	s_cmp_lt_u32 s58, 0x8000
	s_cselect_b32 s59, s59, 8
	s_mul_i32 s59, s59, 0x6000
	s_add_u32 s24, s42, s59
	s_addc_u32 s25, s43, 0
	s_add_u32 s18, s54, s59
	s_addc_u32 s19, s55, 0
	s_add_u32 s34, s18, 0x4000
	s_addc_u32 s35, s19, 0
	s_add_u32 s18, s18, 0x3000
	s_addc_u32 s19, s19, 0
	s_lshl_b32 s59, s58, 11
	s_add_u32 s40, s56, s59
	s_addc_u32 s41, s57, 0
	s_sub_u32 s60, s58, 0x8000
	s_cmp_lt_u32 s58, 0x8000
	s_cselect_b32 s60, s58, s60
	s_cselect_b32 s22, s46, s50
	s_cselect_b32 s23, s47, s51
	s_lshl_b32 s60, s60, 12
	s_add_u32 s22, s22, s60
	s_addc_u32 s23, s23, 0
	global_load_dwordx4 v[112:115], v0, s[24:25]
	global_load_dwordx4 v[116:119], v0, s[24:25] offset:1024
	global_load_dwordx4 v[120:123], v0, s[24:25] offset:2048
	global_load_dwordx4 v[124:127], v0, s[24:25] offset:3072
	global_load_dwordx4 v[162:165], v0, s[34:35]
	global_load_dwordx4 v[166:169], v0, s[34:35] offset:1024
	global_load_dwordx4 v[170:173], v0, s[34:35] offset:2048
	global_load_dwordx4 v[174:177], v0, s[34:35] offset:3072
	global_load_dwordx4 v[178:181], v0, s[18:19]
	global_load_dwordx4 v[182:185], v0, s[18:19] offset:1024
	global_load_dwordx4 v[186:189], v0, s[18:19] offset:2048
	global_load_dwordx4 v[190:193], v0, s[18:19] offset:3072
	s_waitcnt vmcnt(12)
	v_cvt_f32_f16_e32 v226, v18
	v_cvt_f32_f16_sdwa v227, v18 dst_sel:DWORD dst_unused:UNUSED_PAD src0_sel:WORD_1
	v_cvt_f32_f16_e32 v228, v19
	v_cvt_f32_f16_sdwa v229, v19 dst_sel:DWORD dst_unused:UNUSED_PAD src0_sel:WORD_1
	v_cvt_f32_f16_e32 v230, v20
	v_cvt_f32_f16_sdwa v231, v20 dst_sel:DWORD dst_unused:UNUSED_PAD src0_sel:WORD_1
	v_cvt_f32_f16_e32 v232, v21
	v_cvt_f32_f16_sdwa v233, v21 dst_sel:DWORD dst_unused:UNUSED_PAD src0_sel:WORD_1
	v_cvt_f32_f16_e32 v234, v22
	v_cvt_f32_f16_sdwa v235, v22 dst_sel:DWORD dst_unused:UNUSED_PAD src0_sel:WORD_1
	v_cvt_f32_f16_e32 v236, v23
	v_cvt_f32_f16_sdwa v237, v23 dst_sel:DWORD dst_unused:UNUSED_PAD src0_sel:WORD_1
	v_cvt_f32_f16_e32 v238, v24
	v_cvt_f32_f16_sdwa v239, v24 dst_sel:DWORD dst_unused:UNUSED_PAD src0_sel:WORD_1
	v_cvt_f32_f16_e32 v240, v25
	v_cvt_f32_f16_sdwa v241, v25 dst_sel:DWORD dst_unused:UNUSED_PAD src0_sel:WORD_1
	v_mul_f32_e32 v242, v227, v227
	v_mul_f32_e32 v243, v231, v231
	v_mul_f32_e32 v244, v235, v235
	v_mul_f32_e32 v245, v239, v239
	v_fmac_f32_e32 v242, v226, v226
	v_fmac_f32_e32 v243, v230, v230
	v_fmac_f32_e32 v244, v234, v234
	v_fmac_f32_e32 v245, v238, v238
	v_fmac_f32_e32 v242, v228, v228
	v_fmac_f32_e32 v243, v232, v232
	v_fmac_f32_e32 v244, v236, v236
	v_fmac_f32_e32 v245, v240, v240
	v_fmac_f32_e32 v242, v229, v229
	v_fmac_f32_e32 v243, v233, v233
	v_fmac_f32_e32 v244, v237, v237
	v_fmac_f32_e32 v245, v241, v241
	v_add_f32_e32 v242, v242, v243
	v_add_f32_e32 v242, v242, v244
	v_add_f32_e32 v242, v242, v245
	s_nop 1
	v_add_f32_dpp v242, v242, v242 quad_perm:[1,0,3,2] row_mask:0xf bank_mask:0xf bound_ctrl:1
	s_nop 1
	v_add_f32_dpp v242, v242, v242 quad_perm:[2,3,0,1] row_mask:0xf bank_mask:0xf bound_ctrl:1
	s_nop 1
	v_add_f32_dpp v242, v242, v242 row_half_mirror row_mask:0xf bank_mask:0xf bound_ctrl:1
	s_nop 1
	v_add_f32_dpp v242, v242, v242 row_mirror row_mask:0xf bank_mask:0xf bound_ctrl:1
	s_nop 1
	ds_swizzle_b32 v243, v242 offset:swizzle(SWAP,16)
	s_waitcnt lgkmcnt(0)
	v_add_f32_e32 v242, v242, v243
	v_mov_b32_e32 v243, v242
	s_nop 1
	v_permlane32_swap_b32_e32 v242, v243
	v_add_f32_e32 v242, v242, v243
	v_fmamk_f32 v242, v242, 0x3a800000, v224
	v_rsq_f32_e32 v242, v242
	s_waitcnt vmcnt(0)
	v_mul_f32_e32 v226, v226, v242
	v_mul_f32_e32 v227, v227, v242
	v_mul_f32_e32 v228, v228, v242
	v_mul_f32_e32 v229, v229, v242
	v_mul_f32_e32 v230, v230, v242
	v_mul_f32_e32 v231, v231, v242
	v_mul_f32_e32 v232, v232, v242
	v_mul_f32_e32 v233, v233, v242
	v_mul_f32_e32 v234, v234, v242
	v_mul_f32_e32 v235, v235, v242
	v_mul_f32_e32 v236, v236, v242
	v_mul_f32_e32 v237, v237, v242
	v_mul_f32_e32 v238, v238, v242
	v_mul_f32_e32 v239, v239, v242
	v_mul_f32_e32 v240, v240, v242
	v_mul_f32_e32 v241, v241, v242
	v_mul_f32_e32 v226, v80, v226
	v_mul_f32_e32 v227, v81, v227
	v_mul_f32_e32 v228, v82, v228
	v_mul_f32_e32 v229, v83, v229
	v_mul_f32_e32 v230, v84, v230
	v_mul_f32_e32 v231, v85, v231
	v_mul_f32_e32 v232, v86, v232
	v_mul_f32_e32 v233, v87, v233
	v_mul_f32_e32 v234, v88, v234
	v_mul_f32_e32 v235, v89, v235
	v_mul_f32_e32 v236, v90, v236
	v_mul_f32_e32 v237, v91, v237
	v_mul_f32_e32 v238, v92, v238
	v_mul_f32_e32 v239, v93, v239
	v_mul_f32_e32 v240, v94, v240
	v_mul_f32_e32 v241, v95, v241
	v_fmac_f32_e32 v64, v112, v226
	v_fmac_f32_e32 v65, v113, v227
	v_fmac_f32_e32 v66, v114, v228
	v_fmac_f32_e32 v67, v115, v229
	v_fmac_f32_e32 v68, v116, v230
	v_fmac_f32_e32 v69, v117, v231
	v_fmac_f32_e32 v70, v118, v232
	v_fmac_f32_e32 v71, v119, v233
	v_fmac_f32_e32 v72, v120, v234
	v_fmac_f32_e32 v73, v121, v235
	v_fmac_f32_e32 v74, v122, v236
	v_fmac_f32_e32 v75, v123, v237
	v_fmac_f32_e32 v76, v124, v238
	v_fmac_f32_e32 v77, v125, v239
	v_fmac_f32_e32 v78, v126, v240
	v_fmac_f32_e32 v79, v127, v241
	global_store_dwordx4 v0, v[64:67], s[22:23]
	global_store_dwordx4 v0, v[68:71], s[22:23] offset:1024
	global_store_dwordx4 v0, v[72:75], s[22:23] offset:2048
	global_store_dwordx4 v0, v[76:79], s[22:23] offset:3072
	v_mul_f32_e32 v242, v65, v65
	v_mul_f32_e32 v243, v69, v69
	v_mul_f32_e32 v244, v73, v73
	v_mul_f32_e32 v245, v77, v77
	v_fmac_f32_e32 v242, v64, v64
	v_fmac_f32_e32 v243, v68, v68
	v_fmac_f32_e32 v244, v72, v72
	v_fmac_f32_e32 v245, v76, v76
	v_fmac_f32_e32 v242, v66, v66
	v_fmac_f32_e32 v243, v70, v70
	v_fmac_f32_e32 v244, v74, v74
	v_fmac_f32_e32 v245, v78, v78
	v_fmac_f32_e32 v242, v67, v67
	v_fmac_f32_e32 v243, v71, v71
	v_fmac_f32_e32 v244, v75, v75
	v_fmac_f32_e32 v245, v79, v79
	v_add_f32_e32 v242, v242, v243
	v_add_f32_e32 v242, v242, v244
	v_add_f32_e32 v242, v242, v245
	s_nop 1
	v_add_f32_dpp v242, v242, v242 quad_perm:[1,0,3,2] row_mask:0xf bank_mask:0xf bound_ctrl:1
	s_nop 1
	v_add_f32_dpp v242, v242, v242 quad_perm:[2,3,0,1] row_mask:0xf bank_mask:0xf bound_ctrl:1
	s_nop 1
	v_add_f32_dpp v242, v242, v242 row_half_mirror row_mask:0xf bank_mask:0xf bound_ctrl:1
	s_nop 1
	v_add_f32_dpp v242, v242, v242 row_mirror row_mask:0xf bank_mask:0xf bound_ctrl:1
	s_nop 1
	ds_swizzle_b32 v243, v242 offset:swizzle(SWAP,16)
	s_waitcnt lgkmcnt(0)
; DI void rows_resid_norm(const P& p, const float* xlat, const float* xctx, const h16* y, int l, int gate_idx, const float* post_g,
;                         bool do_next, int l2, const float* gain2, int sh_idx, int sc_idx, h16* dst, int nrows) {
;     ...
; #pragma unroll
;     for (int i = 0; i < 4; ++i) {
;       h16x4 t = *(const h16x4*)(y + (size_t)row * 1024 + lane * 4 + 256 * i);
;       yv[i].x = (float)t.x; yv[i].y = (float)t.y; yv[i].z = (float)t.z; yv[i].w = (float)t.w;
;       ss += yv[i].x * yv[i].x + yv[i].y * yv[i].y + yv[i].z * yv[i].z + yv[i].w * yv[i].w;
;       xv[i] = *(const f32x4*)(xr + lane * 4 + 256 * i);
;     }
;     ss = wave_sum(ss);
;     const float rstd = rsqrtf(ss * (1.f / 1024.f) + EPS);
;     float s2 = 0.f;
; #pragma unroll
;     for (int i = 0; i < 4; ++i) {
;     ...
;     if (do_next) {
;       s2 = wave_sum(s2);
;       const float r2 = rsqrtf(s2 * (1.f / 1024.f) + EPS);
; #pragma unroll
;       for (int i = 0; i < 4; ++i) {
;         const int c = lane * 4 + 256 * i;
;         f32x4 g = *(const f32x4*)(gain2 + c), sc = *(const f32x4*)(mr2 + sc_idx * 1024 + c), sh = *(const f32x4*)(mr2 + sh_idx * 1024 + c);
;         h16x4 o;
;         o.x = (h16)(xv[i].x * r2 * g.x * (1.f + sc.x) + sh.x);
;         o.y = (h16)(xv[i].y * r2 * g.y * (1.f + sc.y) + sh.y);
;         o.z = (h16)(xv[i].z * r2 * g.z * (1.f + sc.z) + sh.z);
;         o.w = (h16)(xv[i].w * r2 * g.w * (1.f + sc.w) + sh.w);
;         *(h16x4*)(dst + (size_t)row * 1024 + c) = o;
;       }
;     }
	v_add_f32_e32 v242, v242, v243
	v_mov_b32_e32 v243, v242
	s_nop 1
	v_permlane32_swap_b32_e32 v242, v243
	v_add_f32_e32 v242, v242, v243
	v_fmamk_f32 v242, v242, 0x3a800000, v224
	v_rsq_f32_e32 v242, v242
	s_nop 0
	v_mul_f32_e32 v226, v64, v242
	v_mul_f32_e32 v227, v65, v242
	v_mul_f32_e32 v228, v66, v242
	v_mul_f32_e32 v229, v67, v242
	v_mul_f32_e32 v230, v68, v242
	v_mul_f32_e32 v231, v69, v242
	v_mul_f32_e32 v232, v70, v242
	v_mul_f32_e32 v233, v71, v242
	v_mul_f32_e32 v234, v72, v242
	v_mul_f32_e32 v235, v73, v242
	v_mul_f32_e32 v236, v74, v242
	v_mul_f32_e32 v237, v75, v242
	v_mul_f32_e32 v238, v76, v242
	v_mul_f32_e32 v239, v77, v242
	v_mul_f32_e32 v240, v78, v242
	v_mul_f32_e32 v241, v79, v242
	v_mul_f32_e32 v226, v96, v226
	v_mul_f32_e32 v227, v97, v227
	v_mul_f32_e32 v228, v98, v228
	v_mul_f32_e32 v229, v99, v229
	v_mul_f32_e32 v230, v100, v230
	v_mul_f32_e32 v231, v101, v231
	v_mul_f32_e32 v232, v102, v232
	v_mul_f32_e32 v233, v103, v233
	v_mul_f32_e32 v234, v104, v234
	v_mul_f32_e32 v235, v105, v235
	v_mul_f32_e32 v236, v106, v236
	v_mul_f32_e32 v237, v107, v237
	v_mul_f32_e32 v238, v108, v238
	v_mul_f32_e32 v239, v109, v239
	v_mul_f32_e32 v240, v110, v240
	v_mul_f32_e32 v241, v111, v241
	v_add_f32_e32 v162, 1.0, v162
	v_add_f32_e32 v163, 1.0, v163
	v_add_f32_e32 v164, 1.0, v164
	v_add_f32_e32 v165, 1.0, v165
	v_add_f32_e32 v166, 1.0, v166
	v_add_f32_e32 v167, 1.0, v167
	v_add_f32_e32 v168, 1.0, v168
	v_add_f32_e32 v169, 1.0, v169
	v_add_f32_e32 v170, 1.0, v170
	v_add_f32_e32 v171, 1.0, v171
	v_add_f32_e32 v172, 1.0, v172
	v_add_f32_e32 v173, 1.0, v173
	v_add_f32_e32 v174, 1.0, v174
	v_add_f32_e32 v175, 1.0, v175
	v_add_f32_e32 v176, 1.0, v176
	v_add_f32_e32 v177, 1.0, v177
	v_fma_f32 v226, v162, v226, v178
	v_fma_f32 v227, v163, v227, v179
	v_fma_f32 v228, v164, v228, v180
	v_fma_f32 v229, v165, v229, v181
	v_fma_f32 v230, v166, v230, v182
	v_fma_f32 v231, v167, v231, v183
	v_fma_f32 v232, v168, v232, v184
	v_fma_f32 v233, v169, v233, v185
	v_fma_f32 v234, v170, v234, v186
	v_fma_f32 v235, v171, v235, v187
	v_fma_f32 v236, v172, v236, v188
	v_fma_f32 v237, v173, v237, v189
	v_fma_f32 v238, v174, v238, v190
	v_fma_f32 v239, v175, v239, v191
	v_fma_f32 v240, v176, v240, v192
	v_fma_f32 v241, v177, v241, v193
	v_cvt_pk_f16_f32 v244, v226, v227
	v_cvt_pk_f16_f32 v245, v228, v229
	v_cvt_pk_f16_f32 v246, v230, v231
	v_cvt_pk_f16_f32 v247, v232, v233
	v_cvt_pk_f16_f32 v248, v234, v235
	v_cvt_pk_f16_f32 v249, v236, v237
	v_cvt_pk_f16_f32 v250, v238, v239
	v_cvt_pk_f16_f32 v251, v240, v241
	global_store_dwordx2 v202, v[244:245], s[40:41]
	global_store_dwordx2 v202, v[246:247], s[40:41] offset:512
	global_store_dwordx2 v202, v[248:249], s[40:41] offset:1024
	global_store_dwordx2 v202, v[250:251], s[40:41] offset:1536
	s_add_i32 s58, s58, s2
	s_branch .Lrr1_exit
.Lrr11_tail2:
	s_waitcnt vmcnt(12)
	v_cvt_f32_f16_e32 v226, v18
	v_cvt_f32_f16_sdwa v227, v18 dst_sel:DWORD dst_unused:UNUSED_PAD src0_sel:WORD_1
	v_cvt_f32_f16_e32 v228, v19
	v_cvt_f32_f16_sdwa v229, v19 dst_sel:DWORD dst_unused:UNUSED_PAD src0_sel:WORD_1
	v_cvt_f32_f16_e32 v230, v20
	v_cvt_f32_f16_sdwa v231, v20 dst_sel:DWORD dst_unused:UNUSED_PAD src0_sel:WORD_1
	v_cvt_f32_f16_e32 v232, v21
	v_cvt_f32_f16_sdwa v233, v21 dst_sel:DWORD dst_unused:UNUSED_PAD src0_sel:WORD_1
	v_cvt_f32_f16_e32 v234, v22
	v_cvt_f32_f16_sdwa v235, v22 dst_sel:DWORD dst_unused:UNUSED_PAD src0_sel:WORD_1
	v_cvt_f32_f16_e32 v236, v23
	v_cvt_f32_f16_sdwa v237, v23 dst_sel:DWORD dst_unused:UNUSED_PAD src0_sel:WORD_1
	v_cvt_f32_f16_e32 v238, v24
	v_cvt_f32_f16_sdwa v239, v24 dst_sel:DWORD dst_unused:UNUSED_PAD src0_sel:WORD_1
	v_cvt_f32_f16_e32 v240, v25
	v_cvt_f32_f16_sdwa v241, v25 dst_sel:DWORD dst_unused:UNUSED_PAD src0_sel:WORD_1
	v_mul_f32_e32 v242, v227, v227
	v_mul_f32_e32 v243, v231, v231
	v_mul_f32_e32 v244, v235, v235
	v_mul_f32_e32 v245, v239, v239
	v_fmac_f32_e32 v242, v226, v226
	v_fmac_f32_e32 v243, v230, v230
	v_fmac_f32_e32 v244, v234, v234
	v_fmac_f32_e32 v245, v238, v238
	v_fmac_f32_e32 v242, v228, v228
	v_fmac_f32_e32 v243, v232, v232
	v_fmac_f32_e32 v244, v236, v236
	v_fmac_f32_e32 v245, v240, v240
	v_fmac_f32_e32 v242, v229, v229
	v_fmac_f32_e32 v243, v233, v233
	v_fmac_f32_e32 v244, v237, v237
	v_fmac_f32_e32 v245, v241, v241
	v_add_f32_e32 v242, v242, v243
	v_add_f32_e32 v242, v242, v244
	v_add_f32_e32 v242, v242, v245
	s_nop 1
	v_add_f32_dpp v242, v242, v242 quad_perm:[1,0,3,2] row_mask:0xf bank_mask:0xf bound_ctrl:1
	s_nop 1
	v_add_f32_dpp v242, v242, v242 quad_perm:[2,3,0,1] row_mask:0xf bank_mask:0xf bound_ctrl:1
	s_nop 1
	v_add_f32_dpp v242, v242, v242 row_half_mirror row_mask:0xf bank_mask:0xf bound_ctrl:1
	s_nop 1
	v_add_f32_dpp v242, v242, v242 row_mirror row_mask:0xf bank_mask:0xf bound_ctrl:1
	s_nop 1
	ds_swizzle_b32 v243, v242 offset:swizzle(SWAP,16)
	s_waitcnt lgkmcnt(0)
	v_add_f32_e32 v242, v242, v243
	v_mov_b32_e32 v243, v242
	s_nop 1
	v_permlane32_swap_b32_e32 v242, v243
	v_add_f32_e32 v242, v242, v243
	v_fmamk_f32 v242, v242, 0x3a800000, v224
	v_rsq_f32_e32 v242, v242
	s_waitcnt vmcnt(0)
; DI void rows_resid_norm(const P& p, const float* xlat, const float* xctx, const h16* y, int l, int gate_idx, const float* post_g,
;                         bool do_next, int l2, const float* gain2, int sh_idx, int sc_idx, h16* dst, int nrows) {
;     ...
;     const float rstd = rsqrtf(ss * (1.f / 1024.f) + EPS);
;     float s2 = 0.f;
; #pragma unroll
;     for (int i = 0; i < 4; ++i) {
;       const int c = lane * 4 + 256 * i;
;       f32x4 g = *(const f32x4*)(post_g + c), gt = *(const f32x4*)(mr + gate_idx * 1024 + c);
;       xv[i].x += gt.x * (yv[i].x * rstd * g.x);
;       xv[i].y += gt.y * (yv[i].y * rstd * g.y);
;       xv[i].z += gt.z * (yv[i].z * rstd * g.z);
;       xv[i].w += gt.w * (yv[i].w * rstd * g.w);
;       *(f32x4*)(xo + c) = xv[i];
;       s2 += xv[i].x * xv[i].x + xv[i].y * xv[i].y + xv[i].z * xv[i].z + xv[i].w * xv[i].w;
;     }
;     if (do_next) {
;       s2 = wave_sum(s2);
;       const float r2 = rsqrtf(s2 * (1.f / 1024.f) + EPS);
; #pragma unroll
;       for (int i = 0; i < 4; ++i) {
;         const int c = lane * 4 + 256 * i;
;         f32x4 g = *(const f32x4*)(gain2 + c), sc = *(const f32x4*)(mr2 + sc_idx * 1024 + c), sh = *(const f32x4*)(mr2 + sh_idx * 1024 + c);
;         h16x4 o;
;         o.x = (h16)(xv[i].x * r2 * g.x * (1.f + sc.x) + sh.x);
;         o.y = (h16)(xv[i].y * r2 * g.y * (1.f + sc.y) + sh.y);
;         o.z = (h16)(xv[i].z * r2 * g.z * (1.f + sc.z) + sh.z);
;         o.w = (h16)(xv[i].w * r2 * g.w * (1.f + sc.w) + sh.w);
;         *(h16x4*)(dst + (size_t)row * 1024 + c) = o;
;       }
;     }
	v_mul_f32_e32 v226, v226, v242
	v_mul_f32_e32 v227, v227, v242
	v_mul_f32_e32 v228, v228, v242
	v_mul_f32_e32 v229, v229, v242
	v_mul_f32_e32 v230, v230, v242
	v_mul_f32_e32 v231, v231, v242
	v_mul_f32_e32 v232, v232, v242
	v_mul_f32_e32 v233, v233, v242
	v_mul_f32_e32 v234, v234, v242
	v_mul_f32_e32 v235, v235, v242
	v_mul_f32_e32 v236, v236, v242
	v_mul_f32_e32 v237, v237, v242
	v_mul_f32_e32 v238, v238, v242
	v_mul_f32_e32 v239, v239, v242
	v_mul_f32_e32 v240, v240, v242
	v_mul_f32_e32 v241, v241, v242
	v_mul_f32_e32 v226, v80, v226
	v_mul_f32_e32 v227, v81, v227
	v_mul_f32_e32 v228, v82, v228
	v_mul_f32_e32 v229, v83, v229
	v_mul_f32_e32 v230, v84, v230
	v_mul_f32_e32 v231, v85, v231
	v_mul_f32_e32 v232, v86, v232
	v_mul_f32_e32 v233, v87, v233
	v_mul_f32_e32 v234, v88, v234
	v_mul_f32_e32 v235, v89, v235
	v_mul_f32_e32 v236, v90, v236
	v_mul_f32_e32 v237, v91, v237
	v_mul_f32_e32 v238, v92, v238
	v_mul_f32_e32 v239, v93, v239
	v_mul_f32_e32 v240, v94, v240
	v_mul_f32_e32 v241, v95, v241
	v_fmac_f32_e32 v64, v112, v226
	v_fmac_f32_e32 v65, v113, v227
	v_fmac_f32_e32 v66, v114, v228
	v_fmac_f32_e32 v67, v115, v229
	v_fmac_f32_e32 v68, v116, v230
	v_fmac_f32_e32 v69, v117, v231
	v_fmac_f32_e32 v70, v118, v232
	v_fmac_f32_e32 v71, v119, v233
	v_fmac_f32_e32 v72, v120, v234
	v_fmac_f32_e32 v73, v121, v235
	v_fmac_f32_e32 v74, v122, v236
	v_fmac_f32_e32 v75, v123, v237
	v_fmac_f32_e32 v76, v124, v238
	v_fmac_f32_e32 v77, v125, v239
	v_fmac_f32_e32 v78, v126, v240
	v_fmac_f32_e32 v79, v127, v241
	global_store_dwordx4 v0, v[64:67], s[22:23]
	global_store_dwordx4 v0, v[68:71], s[22:23] offset:1024
	global_store_dwordx4 v0, v[72:75], s[22:23] offset:2048
	global_store_dwordx4 v0, v[76:79], s[22:23] offset:3072
	v_mul_f32_e32 v242, v65, v65
	v_mul_f32_e32 v243, v69, v69
	v_mul_f32_e32 v244, v73, v73
	v_mul_f32_e32 v245, v77, v77
	v_fmac_f32_e32 v242, v64, v64
	v_fmac_f32_e32 v243, v68, v68
	v_fmac_f32_e32 v244, v72, v72
	v_fmac_f32_e32 v245, v76, v76
	v_fmac_f32_e32 v242, v66, v66
	v_fmac_f32_e32 v243, v70, v70
	v_fmac_f32_e32 v244, v74, v74
	v_fmac_f32_e32 v245, v78, v78
	v_fmac_f32_e32 v242, v67, v67
	v_fmac_f32_e32 v243, v71, v71
	v_fmac_f32_e32 v244, v75, v75
	v_fmac_f32_e32 v245, v79, v79
	v_add_f32_e32 v242, v242, v243
	v_add_f32_e32 v242, v242, v244
	v_add_f32_e32 v242, v242, v245
	s_nop 1
	v_add_f32_dpp v242, v242, v242 quad_perm:[1,0,3,2] row_mask:0xf bank_mask:0xf bound_ctrl:1
	s_nop 1
	v_add_f32_dpp v242, v242, v242 quad_perm:[2,3,0,1] row_mask:0xf bank_mask:0xf bound_ctrl:1
	s_nop 1
	v_add_f32_dpp v242, v242, v242 row_half_mirror row_mask:0xf bank_mask:0xf bound_ctrl:1
	s_nop 1
	v_add_f32_dpp v242, v242, v242 row_mirror row_mask:0xf bank_mask:0xf bound_ctrl:1
	s_nop 1
	ds_swizzle_b32 v243, v242 offset:swizzle(SWAP,16)
	s_waitcnt lgkmcnt(0)
	v_add_f32_e32 v242, v242, v243
	v_mov_b32_e32 v243, v242
	s_nop 1
	v_permlane32_swap_b32_e32 v242, v243
	v_add_f32_e32 v242, v242, v243
	v_fmamk_f32 v242, v242, 0x3a800000, v224
	v_rsq_f32_e32 v242, v242
	s_nop 0
	v_mul_f32_e32 v226, v64, v242
	v_mul_f32_e32 v227, v65, v242
	v_mul_f32_e32 v228, v66, v242
	v_mul_f32_e32 v229, v67, v242
	v_mul_f32_e32 v230, v68, v242
	v_mul_f32_e32 v231, v69, v242
	v_mul_f32_e32 v232, v70, v242
	v_mul_f32_e32 v233, v71, v242
	v_mul_f32_e32 v234, v72, v242
	v_mul_f32_e32 v235, v73, v242
	v_mul_f32_e32 v236, v74, v242
	v_mul_f32_e32 v237, v75, v242
	v_mul_f32_e32 v238, v76, v242
	v_mul_f32_e32 v239, v77, v242
	v_mul_f32_e32 v240, v78, v242
	v_mul_f32_e32 v241, v79, v242
	v_mul_f32_e32 v226, v96, v226
	v_mul_f32_e32 v227, v97, v227
	v_mul_f32_e32 v228, v98, v228
	v_mul_f32_e32 v229, v99, v229
	v_mul_f32_e32 v230, v100, v230
	v_mul_f32_e32 v231, v101, v231
	v_mul_f32_e32 v232, v102, v232
	v_mul_f32_e32 v233, v103, v233
	v_mul_f32_e32 v234, v104, v234
	v_mul_f32_e32 v235, v105, v235
	v_mul_f32_e32 v236, v106, v236
	v_mul_f32_e32 v237, v107, v237
	v_mul_f32_e32 v238, v108, v238
	v_mul_f32_e32 v239, v109, v239
	v_mul_f32_e32 v240, v110, v240
	v_mul_f32_e32 v241, v111, v241
	v_add_f32_e32 v162, 1.0, v162
	v_add_f32_e32 v163, 1.0, v163
	v_add_f32_e32 v164, 1.0, v164
	v_add_f32_e32 v165, 1.0, v165
	v_add_f32_e32 v166, 1.0, v166
	v_add_f32_e32 v167, 1.0, v167
	v_add_f32_e32 v168, 1.0, v168
	v_add_f32_e32 v169, 1.0, v169
	v_add_f32_e32 v170, 1.0, v170
	v_add_f32_e32 v171, 1.0, v171
	v_add_f32_e32 v172, 1.0, v172
	v_add_f32_e32 v173, 1.0, v173
	v_add_f32_e32 v174, 1.0, v174
	v_add_f32_e32 v175, 1.0, v175
	v_add_f32_e32 v176, 1.0, v176
	v_add_f32_e32 v177, 1.0, v177
	v_fma_f32 v226, v162, v226, v178
	v_fma_f32 v227, v163, v227, v179
	v_fma_f32 v228, v164, v228, v180
	v_fma_f32 v229, v165, v229, v181
	v_fma_f32 v230, v166, v230, v182
	v_fma_f32 v231, v167, v231, v183
	v_fma_f32 v232, v168, v232, v184
	v_fma_f32 v233, v169, v233, v185
	v_fma_f32 v234, v170, v234, v186
	v_fma_f32 v235, v171, v235, v187
	v_fma_f32 v236, v172, v236, v188
	v_fma_f32 v237, v173, v237, v189
	v_fma_f32 v238, v174, v238, v190
	v_fma_f32 v239, v175, v239, v191
	v_fma_f32 v240, v176, v240, v192
	v_fma_f32 v241, v177, v241, v193
	v_cvt_pk_f16_f32 v244, v226, v227
	v_cvt_pk_f16_f32 v245, v228, v229
	v_cvt_pk_f16_f32 v246, v230, v231
	v_cvt_pk_f16_f32 v247, v232, v233
	v_cvt_pk_f16_f32 v248, v234, v235
	v_cvt_pk_f16_f32 v249, v236, v237
	v_cvt_pk_f16_f32 v250, v238, v239
	v_cvt_pk_f16_f32 v251, v240, v241
	global_store_dwordx2 v202, v[244:245], s[40:41]
	global_store_dwordx2 v202, v[246:247], s[40:41] offset:512
	global_store_dwordx2 v202, v[248:249], s[40:41] offset:1024
	global_store_dwordx2 v202, v[250:251], s[40:41] offset:1536
	s_add_i32 s58, s58, s2
	s_cmp_lt_i32 s58, s36
	s_cbranch_scc0 .Lrr1_exit
; DI void rows_resid_norm(const P& p, const float* xlat, const float* xctx, const h16* y, int l, int gate_idx, const float* post_g,
;                         bool do_next, int l2, const float* gain2, int sh_idx, int sc_idx, h16* dst, int nrows) {
;     ...
;   for (int row = gw; row < nrows; row += nw) {
;     const float* xr = row < TL ? xlat + (size_t)row * 1024 : xctx + (size_t)(row - TL) * 1024;
;     float* xo = row < TL ? p.out + (size_t)row * 1024 : xc + (size_t)(row - TL) * 1024;
;     const int mrow = row < TL ? (row >> 12) : 8;
;     const float* mr = mod + ((size_t)l * 9 + mrow) * 6144;
;     const float* mr2 = mod + ((size_t)l2 * 9 + mrow) * 6144;
;     f32x4 yv[4], xv[4];
;     float ss = 0.f;
; #pragma unroll
;     for (int i = 0; i < 4; ++i) {
;       h16x4 t = *(const h16x4*)(y + (size_t)row * 1024 + lane * 4 + 256 * i);
;       yv[i].x = (float)t.x; yv[i].y = (float)t.y; yv[i].z = (float)t.z; yv[i].w = (float)t.w;
;       ss += yv[i].x * yv[i].x + yv[i].y * yv[i].y + yv[i].z * yv[i].z + yv[i].w * yv[i].w;
;       xv[i] = *(const f32x4*)(xr + lane * 4 + 256 * i);
;     }
;     ss = wave_sum(ss);
;     const float rstd = rsqrtf(ss * (1.f / 1024.f) + EPS);
;     float s2 = 0.f;
; #pragma unroll
;     for (int i = 0; i < 4; ++i) {
	s_lshr_b32 s59, s58, 12
	s_cmp_lt_u32 s58, 0x8000
	s_cselect_b32 s59, s59, 8
	s_mul_i32 s59, s59, 0x6000
	s_add_u32 s24, s42, s59
	s_addc_u32 s25, s43, 0
	s_add_u32 s18, s54, s59
	s_addc_u32 s19, s55, 0
	s_add_u32 s34, s18, 0x4000
	s_addc_u32 s35, s19, 0
	s_add_u32 s18, s18, 0x3000
	s_addc_u32 s19, s19, 0
	s_lshl_b32 s59, s58, 11
	s_add_u32 s40, s56, s59
	s_addc_u32 s41, s57, 0
	s_sub_u32 s60, s58, 0x8000
	s_cmp_lt_u32 s58, 0x8000
	s_cselect_b32 s60, s58, s60
	s_cselect_b32 s22, s46, s50
	s_cselect_b32 s23, s47, s51
	s_lshl_b32 s60, s60, 12
	s_add_u32 s22, s22, s60
	s_addc_u32 s23, s23, 0
	global_load_dwordx4 v[112:115], v0, s[24:25]
	global_load_dwordx4 v[116:119], v0, s[24:25] offset:1024
	global_load_dwordx4 v[120:123], v0, s[24:25] offset:2048
	global_load_dwordx4 v[124:127], v0, s[24:25] offset:3072
	global_load_dwordx4 v[162:165], v0, s[34:35]
	global_load_dwordx4 v[166:169], v0, s[34:35] offset:1024
	global_load_dwordx4 v[170:173], v0, s[34:35] offset:2048
	global_load_dwordx4 v[174:177], v0, s[34:35] offset:3072
	global_load_dwordx4 v[178:181], v0, s[18:19]
	global_load_dwordx4 v[182:185], v0, s[18:19] offset:1024
	global_load_dwordx4 v[186:189], v0, s[18:19] offset:2048
	global_load_dwordx4 v[190:193], v0, s[18:19] offset:3072
	s_waitcnt vmcnt(12)
	v_cvt_f32_f16_e32 v226, v2
	v_cvt_f32_f16_sdwa v227, v2 dst_sel:DWORD dst_unused:UNUSED_PAD src0_sel:WORD_1
	v_cvt_f32_f16_e32 v228, v3
	v_cvt_f32_f16_sdwa v229, v3 dst_sel:DWORD dst_unused:UNUSED_PAD src0_sel:WORD_1
	v_cvt_f32_f16_e32 v230, v4
	v_cvt_f32_f16_sdwa v231, v4 dst_sel:DWORD dst_unused:UNUSED_PAD src0_sel:WORD_1
	v_cvt_f32_f16_e32 v232, v5
	v_cvt_f32_f16_sdwa v233, v5 dst_sel:DWORD dst_unused:UNUSED_PAD src0_sel:WORD_1
	v_cvt_f32_f16_e32 v234, v6
	v_cvt_f32_f16_sdwa v235, v6 dst_sel:DWORD dst_unused:UNUSED_PAD src0_sel:WORD_1
	v_cvt_f32_f16_e32 v236, v7
	v_cvt_f32_f16_sdwa v237, v7 dst_sel:DWORD dst_unused:UNUSED_PAD src0_sel:WORD_1
	v_cvt_f32_f16_e32 v238, v8
	v_cvt_f32_f16_sdwa v239, v8 dst_sel:DWORD dst_unused:UNUSED_PAD src0_sel:WORD_1
	v_cvt_f32_f16_e32 v240, v9
	v_cvt_f32_f16_sdwa v241, v9 dst_sel:DWORD dst_unused:UNUSED_PAD src0_sel:WORD_1
	v_mul_f32_e32 v242, v227, v227
	v_mul_f32_e32 v243, v231, v231
	v_mul_f32_e32 v244, v235, v235
	v_mul_f32_e32 v245, v239, v239
	v_fmac_f32_e32 v242, v226, v226
	v_fmac_f32_e32 v243, v230, v230
	v_fmac_f32_e32 v244, v234, v234
	v_fmac_f32_e32 v245, v238, v238
	v_fmac_f32_e32 v242, v228, v228
	v_fmac_f32_e32 v243, v232, v232
	v_fmac_f32_e32 v244, v236, v236
	v_fmac_f32_e32 v245, v240, v240
	v_fmac_f32_e32 v242, v229, v229
	v_fmac_f32_e32 v243, v233, v233
	v_fmac_f32_e32 v244, v237, v237
	v_fmac_f32_e32 v245, v241, v241
	v_add_f32_e32 v242, v242, v243
	v_add_f32_e32 v242, v242, v244
	v_add_f32_e32 v242, v242, v245
	s_nop 1
	v_add_f32_dpp v242, v242, v242 quad_perm:[1,0,3,2] row_mask:0xf bank_mask:0xf bound_ctrl:1
	s_nop 1
	v_add_f32_dpp v242, v242, v242 quad_perm:[2,3,0,1] row_mask:0xf bank_mask:0xf bound_ctrl:1
	s_nop 1
	v_add_f32_dpp v242, v242, v242 row_half_mirror row_mask:0xf bank_mask:0xf bound_ctrl:1
	s_nop 1
	v_add_f32_dpp v242, v242, v242 row_mirror row_mask:0xf bank_mask:0xf bound_ctrl:1
	s_nop 1
	ds_swizzle_b32 v243, v242 offset:swizzle(SWAP,16)
	s_waitcnt lgkmcnt(0)
	v_add_f32_e32 v242, v242, v243
	v_mov_b32_e32 v243, v242
	s_nop 1
	v_permlane32_swap_b32_e32 v242, v243
	v_add_f32_e32 v242, v242, v243
	v_fmamk_f32 v242, v242, 0x3a800000, v224
	v_rsq_f32_e32 v242, v242
	s_waitcnt vmcnt(0)
; DI void rows_resid_norm(const P& p, const float* xlat, const float* xctx, const h16* y, int l, int gate_idx, const float* post_g,
;                         bool do_next, int l2, const float* gain2, int sh_idx, int sc_idx, h16* dst, int nrows) {
;     ...
;       const int c = lane * 4 + 256 * i;
;       f32x4 g = *(const f32x4*)(post_g + c), gt = *(const f32x4*)(mr + gate_idx * 1024 + c);
;       xv[i].x += gt.x * (yv[i].x * rstd * g.x);
;       xv[i].y += gt.y * (yv[i].y * rstd * g.y);
;       xv[i].z += gt.z * (yv[i].z * rstd * g.z);
;       xv[i].w += gt.w * (yv[i].w * rstd * g.w);
;       *(f32x4*)(xo + c) = xv[i];
;       s2 += xv[i].x * xv[i].x + xv[i].y * xv[i].y + xv[i].z * xv[i].z + xv[i].w * xv[i].w;
;     }
;     if (do_next) {
;       s2 = wave_sum(s2);
;       const float r2 = rsqrtf(s2 * (1.f / 1024.f) + EPS);
; #pragma unroll
;       for (int i = 0; i < 4; ++i) {
;         const int c = lane * 4 + 256 * i;
;         f32x4 g = *(const f32x4*)(gain2 + c), sc = *(const f32x4*)(mr2 + sc_idx * 1024 + c), sh = *(const f32x4*)(mr2 + sh_idx * 1024 + c);
;         h16x4 o;
;         o.x = (h16)(xv[i].x * r2 * g.x * (1.f + sc.x) + sh.x);
;         o.y = (h16)(xv[i].y * r2 * g.y * (1.f + sc.y) + sh.y);
;         o.z = (h16)(xv[i].z * r2 * g.z * (1.f + sc.z) + sh.z);
;         o.w = (h16)(xv[i].w * r2 * g.w * (1.f + sc.w) + sh.w);
;         *(h16x4*)(dst + (size_t)row * 1024 + c) = o;
;       }
;     }
	v_mul_f32_e32 v226, v226, v242
	v_mul_f32_e32 v227, v227, v242
	v_mul_f32_e32 v228, v228, v242
	v_mul_f32_e32 v229, v229, v242
	v_mul_f32_e32 v230, v230, v242
	v_mul_f32_e32 v231, v231, v242
	v_mul_f32_e32 v232, v232, v242
	v_mul_f32_e32 v233, v233, v242
	v_mul_f32_e32 v234, v234, v242
	v_mul_f32_e32 v235, v235, v242
	v_mul_f32_e32 v236, v236, v242
	v_mul_f32_e32 v237, v237, v242
	v_mul_f32_e32 v238, v238, v242
	v_mul_f32_e32 v239, v239, v242
	v_mul_f32_e32 v240, v240, v242
	v_mul_f32_e32 v241, v241, v242
	v_mul_f32_e32 v226, v80, v226
	v_mul_f32_e32 v227, v81, v227
	v_mul_f32_e32 v228, v82, v228
	v_mul_f32_e32 v229, v83, v229
	v_mul_f32_e32 v230, v84, v230
	v_mul_f32_e32 v231, v85, v231
	v_mul_f32_e32 v232, v86, v232
	v_mul_f32_e32 v233, v87, v233
	v_mul_f32_e32 v234, v88, v234
	v_mul_f32_e32 v235, v89, v235
	v_mul_f32_e32 v236, v90, v236
	v_mul_f32_e32 v237, v91, v237
	v_mul_f32_e32 v238, v92, v238
	v_mul_f32_e32 v239, v93, v239
	v_mul_f32_e32 v240, v94, v240
	v_mul_f32_e32 v241, v95, v241
	v_fmac_f32_e32 v32, v112, v226
	v_fmac_f32_e32 v33, v113, v227
	v_fmac_f32_e32 v34, v114, v228
	v_fmac_f32_e32 v35, v115, v229
	v_fmac_f32_e32 v36, v116, v230
	v_fmac_f32_e32 v37, v117, v231
	v_fmac_f32_e32 v38, v118, v232
	v_fmac_f32_e32 v39, v119, v233
	v_fmac_f32_e32 v40, v120, v234
	v_fmac_f32_e32 v41, v121, v235
	v_fmac_f32_e32 v42, v122, v236
	v_fmac_f32_e32 v43, v123, v237
	v_fmac_f32_e32 v44, v124, v238
	v_fmac_f32_e32 v45, v125, v239
	v_fmac_f32_e32 v46, v126, v240
	v_fmac_f32_e32 v47, v127, v241
	global_store_dwordx4 v0, v[32:35], s[22:23]
	global_store_dwordx4 v0, v[36:39], s[22:23] offset:1024
	global_store_dwordx4 v0, v[40:43], s[22:23] offset:2048
	global_store_dwordx4 v0, v[44:47], s[22:23] offset:3072
	v_mul_f32_e32 v242, v33, v33
	v_mul_f32_e32 v243, v37, v37
	v_mul_f32_e32 v244, v41, v41
	v_mul_f32_e32 v245, v45, v45
	v_fmac_f32_e32 v242, v32, v32
	v_fmac_f32_e32 v243, v36, v36
	v_fmac_f32_e32 v244, v40, v40
	v_fmac_f32_e32 v245, v44, v44
	v_fmac_f32_e32 v242, v34, v34
	v_fmac_f32_e32 v243, v38, v38
	v_fmac_f32_e32 v244, v42, v42
	v_fmac_f32_e32 v245, v46, v46
	v_fmac_f32_e32 v242, v35, v35
	v_fmac_f32_e32 v243, v39, v39
	v_fmac_f32_e32 v244, v43, v43
	v_fmac_f32_e32 v245, v47, v47
	v_add_f32_e32 v242, v242, v243
	v_add_f32_e32 v242, v242, v244
	v_add_f32_e32 v242, v242, v245
	s_nop 1
	v_add_f32_dpp v242, v242, v242 quad_perm:[1,0,3,2] row_mask:0xf bank_mask:0xf bound_ctrl:1
	s_nop 1
	v_add_f32_dpp v242, v242, v242 quad_perm:[2,3,0,1] row_mask:0xf bank_mask:0xf bound_ctrl:1
	s_nop 1
	v_add_f32_dpp v242, v242, v242 row_half_mirror row_mask:0xf bank_mask:0xf bound_ctrl:1
	s_nop 1
	v_add_f32_dpp v242, v242, v242 row_mirror row_mask:0xf bank_mask:0xf bound_ctrl:1
	s_nop 1
	ds_swizzle_b32 v243, v242 offset:swizzle(SWAP,16)
	s_waitcnt lgkmcnt(0)
	v_add_f32_e32 v242, v242, v243
	v_mov_b32_e32 v243, v242
	s_nop 1
	v_permlane32_swap_b32_e32 v242, v243
	v_add_f32_e32 v242, v242, v243
	v_fmamk_f32 v242, v242, 0x3a800000, v224
	v_rsq_f32_e32 v242, v242
	s_nop 0
	v_mul_f32_e32 v226, v32, v242
	v_mul_f32_e32 v227, v33, v242
	v_mul_f32_e32 v228, v34, v242
	v_mul_f32_e32 v229, v35, v242
	v_mul_f32_e32 v230, v36, v242
	v_mul_f32_e32 v231, v37, v242
	v_mul_f32_e32 v232, v38, v242
	v_mul_f32_e32 v233, v39, v242
	v_mul_f32_e32 v234, v40, v242
	v_mul_f32_e32 v235, v41, v242
	v_mul_f32_e32 v236, v42, v242
	v_mul_f32_e32 v237, v43, v242
	v_mul_f32_e32 v238, v44, v242
	v_mul_f32_e32 v239, v45, v242
	v_mul_f32_e32 v240, v46, v242
	v_mul_f32_e32 v241, v47, v242
	v_mul_f32_e32 v226, v96, v226
	v_mul_f32_e32 v227, v97, v227
	v_mul_f32_e32 v228, v98, v228
	v_mul_f32_e32 v229, v99, v229
	v_mul_f32_e32 v230, v100, v230
	v_mul_f32_e32 v231, v101, v231
	v_mul_f32_e32 v232, v102, v232
	v_mul_f32_e32 v233, v103, v233
	v_mul_f32_e32 v234, v104, v234
	v_mul_f32_e32 v235, v105, v235
	v_mul_f32_e32 v236, v106, v236
	v_mul_f32_e32 v237, v107, v237
	v_mul_f32_e32 v238, v108, v238
	v_mul_f32_e32 v239, v109, v239
	v_mul_f32_e32 v240, v110, v240
	v_mul_f32_e32 v241, v111, v241
	v_add_f32_e32 v162, 1.0, v162
	v_add_f32_e32 v163, 1.0, v163
	v_add_f32_e32 v164, 1.0, v164
	v_add_f32_e32 v165, 1.0, v165
	v_add_f32_e32 v166, 1.0, v166
	v_add_f32_e32 v167, 1.0, v167
	v_add_f32_e32 v168, 1.0, v168
	v_add_f32_e32 v169, 1.0, v169
	v_add_f32_e32 v170, 1.0, v170
	v_add_f32_e32 v171, 1.0, v171
	v_add_f32_e32 v172, 1.0, v172
	v_add_f32_e32 v173, 1.0, v173
	v_add_f32_e32 v174, 1.0, v174
	v_add_f32_e32 v175, 1.0, v175
	v_add_f32_e32 v176, 1.0, v176
	v_add_f32_e32 v177, 1.0, v177
	v_fma_f32 v226, v162, v226, v178
	v_fma_f32 v227, v163, v227, v179
	v_fma_f32 v228, v164, v228, v180
	v_fma_f32 v229, v165, v229, v181
	v_fma_f32 v230, v166, v230, v182
	v_fma_f32 v231, v167, v231, v183
	v_fma_f32 v232, v168, v232, v184
	v_fma_f32 v233, v169, v233, v185
	v_fma_f32 v234, v170, v234, v186
	v_fma_f32 v235, v171, v235, v187
	v_fma_f32 v236, v172, v236, v188
	v_fma_f32 v237, v173, v237, v189
	v_fma_f32 v238, v174, v238, v190
	v_fma_f32 v239, v175, v239, v191
	v_fma_f32 v240, v176, v240, v192
	v_fma_f32 v241, v177, v241, v193
	v_cvt_pk_f16_f32 v244, v226, v227
	v_cvt_pk_f16_f32 v245, v228, v229
	v_cvt_pk_f16_f32 v246, v230, v231
	v_cvt_pk_f16_f32 v247, v232, v233
	v_cvt_pk_f16_f32 v248, v234, v235
	v_cvt_pk_f16_f32 v249, v236, v237
	v_cvt_pk_f16_f32 v250, v238, v239
	v_cvt_pk_f16_f32 v251, v240, v241
	global_store_dwordx2 v202, v[244:245], s[40:41]
	global_store_dwordx2 v202, v[246:247], s[40:41] offset:512
	global_store_dwordx2 v202, v[248:249], s[40:41] offset:1024
	global_store_dwordx2 v202, v[250:251], s[40:41] offset:1536
	s_add_i32 s58, s58, s2
	s_branch .Lrr1_exit
.Lrr1_exit:
.LBB0_83:
	s_mov_b32 s64, 0x800000
	s_or_b64 exec, exec, s[6:7]
	s_mov_b32 s31, s33
